# SGU: pipelined b_s loads (5 in flight), double-buffered A-fragment ds_reads, tr_read waits merged; all flat_* memory ops converted to global_*
# baseline (speedup 1.0000x reference)
; __device__ __forceinline__ void st8(bf16_t* p, const float (&v)[8]) { u32x4 w; w.x = pk2(v[0], v[1]); w.y = pk2(v[2], v[3]); w.z = pk2(v[4], v[5]); w.w = pk2(v[6], v[7]); *(u32x4*)p = w; }
;     __device__ __forceinline__ void operator()(const f32x4 (&acc)[2][2][4][2], const Unit& u, int wr, int wc, int fr, int fq) const {
;         if (!dl) return;
;         const int row0 = u.pm * 256 + wr * 64 + fr, col0 = u.pn * 256 + wc * 32 + 8 * fq;
;         const float* gp = gate + (size_t)(u.pm >> 4) * 6144 + col0;
;         f32x4 g[2][2];
; #pragma unroll
;         for (int bj = 0; bj < 2; ++bj)
; #pragma unroll
;             for (int n = 0; n < 2; ++n) g[bj][n] = *(const f32x4*)(gp + bj * 128 + n * 4);
; #pragma unroll
;         for (int ai = 0; ai < 2; ++ai)
; #pragma unroll
;             for (int m = 0; m < 4; ++m) { bf16_t* rp = dl + (size_t)(row0 + ai * 128 + m * 16) * DM + col0;
; #pragma unroll
;                 for (int bj = 0; bj < 2; ++bj) { float o[8];
; #pragma unroll
;                     for (int j = 0; j < 4; ++j) { o[j] = g[bj][0][j] * acc[ai][bj][m][0][j]; o[4 + j] = g[bj][1][j] * acc[ai][bj][m][1][j]; }
;                     st8(rp + bj * 128, o); } }
.LBB0_98:
	s_ashr_i32 s2, s59, 4
	s_mul_hi_i32 s3, s2, 0x6000
	s_mulk_i32 s2, 0x6000
	v_lshl_or_b32 v156, s60, 8, v164
	s_add_u32 s2, s54, s2
	s_addc_u32 s3, s55, s3
	v_ashrrev_i32_e32 v157, 31, v156
	v_lshl_add_u64 v[118:119], v[156:157], 2, s[2:3]
	global_load_dwordx4 v[122:125], v[118:119], off
	global_load_dwordx4 v[126:129], v[118:119], off offset:16
	global_load_dwordx4 v[114:117], v[118:119], off offset:512
	s_nop 0
	global_load_dwordx4 v[118:121], v[118:119], off offset:528
	v_lshl_add_u32 v160, s59, 8, v162
	v_ashrrev_i32_e32 v161, 31, v160
	v_lshlrev_b64 v[158:159], 12, v[160:161]
	v_lshl_add_u64 v[166:167], s[16:17], 0, v[158:159]
	v_lshlrev_b64 v[158:159], 1, v[156:157]
	v_lshl_add_u64 v[156:157], v[166:167], 0, v[158:159]
	s_mov_b64 s[2:3], 0x80000
	s_mov_b64 s[24:25], -1
	s_waitcnt vmcnt(0) lgkmcnt(0)
	v_mul_f32_e32 v142, v142, v122
	v_mul_f32_e32 v161, v138, v126
	v_mul_f32_e32 v138, v143, v123
	v_mul_f32_e32 v143, v139, v127
	v_mul_f32_e32 v139, v144, v124
	v_mul_f32_e32 v144, v140, v128
	v_mul_f32_e32 v140, v145, v125
	v_mul_f32_e32 v141, v141, v129
	v_cvt_pk_bf16_f32 v138, v142, v138
	v_cvt_pk_bf16_f32 v139, v139, v140
	v_cvt_pk_bf16_f32 v140, v161, v143
	v_cvt_pk_bf16_f32 v141, v144, v141
	global_store_dwordx4 v[156:157], v[138:141], off
	v_mul_f32_e32 v134, v134, v114
	v_mul_f32_e32 v133, v133, v121
	v_mul_f32_e32 v138, v130, v118
	v_mul_f32_e32 v130, v135, v115
	v_mul_f32_e32 v135, v131, v119
	v_mul_f32_e32 v131, v136, v116
	v_mul_f32_e32 v136, v132, v120
	v_mul_f32_e32 v132, v137, v117
	v_cvt_pk_bf16_f32 v130, v134, v130
	v_cvt_pk_bf16_f32 v131, v131, v132
	v_cvt_pk_bf16_f32 v132, v138, v135
	v_cvt_pk_bf16_f32 v133, v136, v133
	global_store_dwordx4 v[156:157], v[130:133], off offset:256
	v_mul_f32_e32 v110, v110, v122
	v_mul_f32_e32 v109, v109, v129
	v_or_b32_e32 v130, 16, v160
	v_ashrrev_i32_e32 v131, 31, v130
	v_lshlrev_b64 v[130:131], 12, v[130:131]
	v_lshl_add_u64 v[130:131], s[16:17], 0, v[130:131]
	v_mul_f32_e32 v132, v106, v126
	v_mul_f32_e32 v106, v111, v123
	v_lshl_add_u64 v[130:131], v[130:131], 0, v[158:159]
	v_mul_f32_e32 v111, v107, v127
	v_mul_f32_e32 v107, v112, v124
	v_mul_f32_e32 v112, v108, v128
	v_mul_f32_e32 v108, v113, v125
	v_cvt_pk_bf16_f32 v106, v110, v106
	v_cvt_pk_bf16_f32 v107, v107, v108
	v_cvt_pk_bf16_f32 v108, v132, v111
	v_cvt_pk_bf16_f32 v109, v112, v109
	global_store_dwordx4 v[130:131], v[106:109], off
	v_mul_f32_e32 v102, v102, v114
	v_mul_f32_e32 v101, v101, v121
	v_mul_f32_e32 v106, v98, v118
	v_mul_f32_e32 v98, v103, v115
	v_mul_f32_e32 v103, v99, v119
	v_mul_f32_e32 v99, v104, v116
	v_mul_f32_e32 v104, v100, v120
	v_mul_f32_e32 v100, v105, v117
	v_cvt_pk_bf16_f32 v98, v102, v98
	v_cvt_pk_bf16_f32 v99, v99, v100
	v_cvt_pk_bf16_f32 v100, v106, v103
	v_cvt_pk_bf16_f32 v101, v104, v101
	global_store_dwordx4 v[130:131], v[98:101], off offset:256
	v_mul_f32_e32 v94, v94, v122
	v_mul_f32_e32 v93, v93, v129
	v_or_b32_e32 v98, 32, v160
	v_ashrrev_i32_e32 v99, 31, v98
	v_lshlrev_b64 v[98:99], 12, v[98:99]
	v_lshl_add_u64 v[98:99], s[16:17], 0, v[98:99]
	v_mul_f32_e32 v100, v90, v126
	v_mul_f32_e32 v90, v95, v123
	v_lshl_add_u64 v[98:99], v[98:99], 0, v[158:159]
	v_mul_f32_e32 v95, v91, v127
	v_mul_f32_e32 v91, v96, v124
	v_mul_f32_e32 v96, v92, v128
	v_mul_f32_e32 v92, v97, v125
	v_cvt_pk_bf16_f32 v90, v94, v90
	v_cvt_pk_bf16_f32 v91, v91, v92
	v_cvt_pk_bf16_f32 v92, v100, v95
	v_cvt_pk_bf16_f32 v93, v96, v93
	global_store_dwordx4 v[98:99], v[90:93], off
	v_mul_f32_e32 v82, v82, v114
	v_mul_f32_e32 v77, v77, v121
	v_mul_f32_e32 v90, v74, v118
	v_mul_f32_e32 v74, v83, v115
	v_mul_f32_e32 v83, v75, v119
	v_mul_f32_e32 v75, v84, v116
	v_mul_f32_e32 v84, v76, v120
	v_mul_f32_e32 v76, v85, v117
	v_cvt_pk_bf16_f32 v74, v82, v74
	v_cvt_pk_bf16_f32 v75, v75, v76
	v_cvt_pk_bf16_f32 v76, v90, v83
	v_cvt_pk_bf16_f32 v77, v84, v77
	global_store_dwordx4 v[98:99], v[74:77], off offset:256
	v_mul_f32_e32 v81, v81, v129
	v_mul_f32_e32 v70, v70, v114
	v_or_b32_e32 v74, 48, v160
	v_ashrrev_i32_e32 v75, 31, v74
	v_lshlrev_b64 v[74:75], 12, v[74:75]
	v_lshl_add_u64 v[74:75], s[16:17], 0, v[74:75]
	v_lshl_add_u64 v[82:83], v[74:75], 0, v[158:159]
	v_mul_f32_e32 v74, v86, v122
	v_mul_f32_e32 v76, v78, v126
	v_mul_f32_e32 v75, v87, v123
	v_mul_f32_e32 v77, v79, v127
	v_cvt_pk_bf16_f32 v74, v74, v75
	v_mul_f32_e32 v78, v88, v124
	v_mul_f32_e32 v79, v80, v128
	v_mul_f32_e32 v80, v89, v125
	v_cvt_pk_bf16_f32 v75, v78, v80
	v_cvt_pk_bf16_f32 v76, v76, v77
	v_cvt_pk_bf16_f32 v77, v79, v81
	global_store_dwordx4 v[82:83], v[74:77], off
	v_mul_f32_e32 v69, v69, v121
; #define PG8_BAR __builtin_amdgcn_s_barrier()
; __device__ __forceinline__ void st8(bf16_t* p, const float (&v)[8]) { u32x4 w; w.x = pk2(v[0], v[1]); w.y = pk2(v[2], v[3]); w.z = pk2(v[4], v[5]); w.w = pk2(v[6], v[7]); *(u32x4*)p = w; }
; template <class Epi, class Sched, bool ALIGN_EPI = false, bool SP2 = false>
; __device__ __forceinline__ void gemm_phase(PG8_LAS unsigned char* lds, const Gemm g, const Sched& S, const Epi& E) {
;     ...
;         if (!has_next) break;
; #pragma unroll
;         for (int a = 0; a < 2; ++a)
; #pragma unroll
;             for (int b = 0; b < 2; ++b)
; #pragma unroll
;                 for (int m = 0; m < 4; ++m)
; #pragma unroll
;                     for (int n = 0; n < 2; ++n) acc[a][b][m][n] = (f32x4){0.f, 0.f, 0.f, 0.f};
;         cur = nxt; cA = nA; cB = nB; ++ui;
;         if constexpr (ALIGN_EPI) { if (wr == 1) PG8_BAR; }
;     __device__ __forceinline__ void operator()(const f32x4 (&acc)[2][2][4][2], const Unit& u, int wr, int wc, int fr, int fq) const {
;     ...
;         for (int ai = 0; ai < 2; ++ai)
; #pragma unroll
;             for (int m = 0; m < 4; ++m) { bf16_t* rp = dl + (size_t)(row0 + ai * 128 + m * 16) * DM + col0;
; #pragma unroll
;                 for (int bj = 0; bj < 2; ++bj) { float o[8];
; #pragma unroll
;                     for (int j = 0; j < 4; ++j) { o[j] = g[bj][0][j] * acc[ai][bj][m][0][j]; o[4 + j] = g[bj][1][j] * acc[ai][bj][m][1][j]; }
;                     st8(rp + bj * 128, o); } }
	v_mul_f32_e32 v62, v62, v122
	v_mul_f32_e32 v74, v66, v118
	v_mul_f32_e32 v66, v71, v115
	v_mul_f32_e32 v71, v67, v119
	v_mul_f32_e32 v67, v72, v116
	v_mul_f32_e32 v72, v68, v120
	v_mul_f32_e32 v68, v73, v117
	v_cvt_pk_bf16_f32 v66, v70, v66
	v_cvt_pk_bf16_f32 v67, v67, v68
	v_cvt_pk_bf16_f32 v68, v74, v71
	v_cvt_pk_bf16_f32 v69, v72, v69
	global_store_dwordx4 v[82:83], v[66:69], off offset:256
	v_mul_f32_e32 v61, v61, v129
	v_mul_f32_e32 v46, v46, v114
	v_lshl_add_u64 v[66:67], v[156:157], 0, s[2:3]
	v_mul_f32_e32 v68, v58, v126
	v_mul_f32_e32 v58, v63, v123
	s_mov_b32 s2, 0x80000
	v_mul_f32_e32 v63, v59, v127
	v_mul_f32_e32 v59, v64, v124
	v_mul_f32_e32 v64, v60, v128
	v_mul_f32_e32 v60, v65, v125
	v_cvt_pk_bf16_f32 v58, v62, v58
	v_add_co_u32_e32 v62, vcc, s2, v156
	v_cvt_pk_bf16_f32 v59, v59, v60
	v_cvt_pk_bf16_f32 v60, v68, v63
	v_cvt_pk_bf16_f32 v61, v64, v61
	v_mul_f32_e32 v45, v45, v121
	s_nop 0
	v_addc_co_u32_e32 v63, vcc, 0, v157, vcc
	global_store_dwordx4 v[62:63], v[58:61], off
	s_mov_b64 s[2:3], 0x90000
	v_mul_f32_e32 v30, v30, v114
	v_mul_f32_e32 v58, v42, v118
	v_mul_f32_e32 v42, v47, v115
	v_mul_f32_e32 v47, v43, v119
	v_mul_f32_e32 v43, v48, v116
	v_mul_f32_e32 v48, v44, v120
	v_mul_f32_e32 v44, v49, v117
	v_cvt_pk_bf16_f32 v42, v46, v42
	v_cvt_pk_bf16_f32 v43, v43, v44
	v_cvt_pk_bf16_f32 v44, v58, v47
	v_cvt_pk_bf16_f32 v45, v48, v45
	global_store_dwordx4 v[66:67], v[42:45], off offset:256
	v_mul_f32_e32 v48, v56, v124
	v_mul_f32_e32 v49, v52, v128
	v_mul_f32_e32 v42, v54, v122
	v_mul_f32_e32 v43, v55, v123
	v_mul_f32_e32 v44, v50, v126
	v_mul_f32_e32 v45, v51, v127
	v_mul_f32_e32 v50, v57, v125
	v_cvt_pk_bf16_f32 v42, v42, v43
	v_cvt_pk_bf16_f32 v43, v48, v50
	v_add_co_u32_e32 v48, vcc, s76, v156
	v_mul_f32_e32 v51, v53, v129
	v_cvt_pk_bf16_f32 v44, v44, v45
	v_cvt_pk_bf16_f32 v45, v49, v51
	s_nop 0
	v_addc_co_u32_e32 v49, vcc, 0, v157, vcc
	global_store_dwordx4 v[48:49], v[42:45], off
	v_lshl_add_u64 v[46:47], v[156:157], 0, s[2:3]
	v_mul_f32_e32 v29, v29, v121
	v_mul_f32_e32 v42, v26, v118
	v_mul_f32_e32 v26, v31, v115
	v_mul_f32_e32 v31, v27, v119
	v_mul_f32_e32 v27, v32, v116
	v_mul_f32_e32 v32, v28, v120
	v_mul_f32_e32 v28, v33, v117
	v_cvt_pk_bf16_f32 v26, v30, v26
	v_cvt_pk_bf16_f32 v27, v27, v28
	s_mov_b64 s[2:3], 0xa0000
	v_cvt_pk_bf16_f32 v28, v42, v31
	v_cvt_pk_bf16_f32 v29, v32, v29
	global_store_dwordx4 v[46:47], v[26:29], off offset:256
	v_lshl_add_u64 v[30:31], v[156:157], 0, s[2:3]
	v_mul_f32_e32 v32, v40, v124
	v_mul_f32_e32 v26, v38, v122
	v_mul_f32_e32 v27, v39, v123
	s_mov_b32 s2, 0xa0000
	v_mul_f32_e32 v28, v34, v126
	v_mul_f32_e32 v29, v35, v127
	v_mul_f32_e32 v33, v36, v128
	v_mul_f32_e32 v34, v41, v125
	v_cvt_pk_bf16_f32 v26, v26, v27
	v_cvt_pk_bf16_f32 v27, v32, v34
	v_add_co_u32_e32 v32, vcc, s2, v156
	v_mul_f32_e32 v35, v37, v129
	v_cvt_pk_bf16_f32 v28, v28, v29
	v_cvt_pk_bf16_f32 v29, v33, v35
	s_nop 0
	v_addc_co_u32_e32 v33, vcc, 0, v157, vcc
	global_store_dwordx4 v[32:33], v[26:29], off
	v_mul_f32_e32 v14, v14, v114
	v_mul_f32_e32 v13, v13, v121
	v_mul_f32_e32 v26, v10, v118
	v_mul_f32_e32 v10, v15, v115
	v_mul_f32_e32 v15, v11, v119
	v_mul_f32_e32 v11, v16, v116
	v_mul_f32_e32 v16, v12, v120
	v_mul_f32_e32 v12, v17, v117
	v_cvt_pk_bf16_f32 v10, v14, v10
	v_cvt_pk_bf16_f32 v11, v11, v12
	s_mov_b64 s[2:3], 0xb0000
	v_cvt_pk_bf16_f32 v12, v26, v15
	v_cvt_pk_bf16_f32 v13, v16, v13
	global_store_dwordx4 v[30:31], v[10:13], off offset:256
	v_lshl_add_u64 v[14:15], v[156:157], 0, s[2:3]
	v_mul_f32_e32 v16, v24, v124
	v_mul_f32_e32 v10, v22, v122
	v_mul_f32_e32 v11, v23, v123
	s_mov_b32 s2, 0xb0000
	v_mul_f32_e32 v12, v18, v126
	v_mul_f32_e32 v13, v19, v127
	v_mul_f32_e32 v17, v20, v128
	v_mul_f32_e32 v18, v25, v125
	v_cvt_pk_bf16_f32 v10, v10, v11
	v_cvt_pk_bf16_f32 v11, v16, v18
	v_add_co_u32_e32 v16, vcc, s2, v156
	v_mul_f32_e32 v19, v21, v129
	v_cvt_pk_bf16_f32 v12, v12, v13
	v_cvt_pk_bf16_f32 v13, v17, v19
	s_nop 0
	v_addc_co_u32_e32 v17, vcc, 0, v157, vcc
	global_store_dwordx4 v[16:17], v[10:13], off
	v_mul_f32_e32 v5, v5, v121
	s_andn2_b64 vcc, exec, s[40:41]
	v_mul_f32_e32 v10, v2, v118
	v_mul_f32_e32 v2, v7, v115
	v_mul_f32_e32 v7, v3, v119
	v_mul_f32_e32 v3, v8, v116
	v_mul_f32_e32 v8, v4, v120
	v_mul_f32_e32 v4, v9, v117
	v_mul_f32_e32 v6, v6, v114
	v_cvt_pk_bf16_f32 v2, v6, v2
	v_cvt_pk_bf16_f32 v3, v3, v4
	v_cvt_pk_bf16_f32 v4, v10, v7
	v_cvt_pk_bf16_f32 v5, v8, v5
	global_store_dwordx4 v[14:15], v[2:5], off offset:256
	s_cbranch_vccnz .LBB0_87
	s_andn2_b64 vcc, exec, s[12:13]
	s_cbranch_vccnz .LBB0_86
	s_barrier
	s_branch .LBB0_86

; #define LAS __attribute__((address_space(3)))
; __device__ __forceinline__ unsigned pk2(float lo, float hi) { unsigned r; asm("v_cvt_pk_bf16_f32 %0, %1, %2" : "=v"(r) : "v"(lo), "v"(hi)); return r; }
; __device__ __forceinline__ float bf_lo(unsigned u) { return __uint_as_float(u << 16); }
; __device__ __forceinline__ float bf_hi(unsigned u) { return __uint_as_float(u & 0xffff0000u); }
; __device__ __forceinline__ void phase_sgu(const Params& P, LAS unsigned char* lds, int layer_i) {
;     ...
;         for (int i = 0; i < 4; ++i) { const int n = tid + 512 * i, row = n >> 4, ch = n & 15;
;             *(LAS u32x4*)(lds + SG_A + off_b(row, ch)) = *(const u32x4*)(wsb + ((size_t)g * 128 + row) * 128 + ch * 8); }
;         __syncthreads();
; #pragma unroll
;         for (int i = 0; i < 8; ++i) { const int n = tid + 512 * i, row = n >> 5, cc = n & 31, c0 = g * 256 + cc * 8;
;             const u32x4 v = gvr[i];
;             const float mu = st[2 * row], rs = st[2 * row + 1];
;             const f32x4 g0 = *(const f32x4*)(lng + c0), g1 = *(const f32x4*)(lng + c0 + 4), b0 = *(const f32x4*)(lnb + c0), b1 = *(const f32x4*)(lnb + c0 + 4);
;             u32x4 o;
;             o.x = pk2((bf_lo(v.x) - mu) * rs * g0.x + b0.x, (bf_hi(v.x) - mu) * rs * g0.y + b0.y); o.y = pk2((bf_lo(v.y) - mu) * rs * g0.z + b0.z, (bf_hi(v.y) - mu) * rs * g0.w + b0.w);
;             o.z = pk2((bf_lo(v.z) - mu) * rs * g1.x + b1.x, (bf_hi(v.z) - mu) * rs * g1.y + b1.y); o.w = pk2((bf_lo(v.w) - mu) * rs * g1.z + b1.z, (bf_hi(v.w) - mu) * rs * g1.w + b1.w);
;             *(LAS u32x4*)(lds + SG_B + (cc >> 4) * 32768 + off_b(row, cc & 15)) = o; }
.LBB0_107:
	s_or_b64 exec, exec, s[12:13]
	s_lshl_b32 s30, s2, 7
	s_waitcnt lgkmcnt(0)
	s_lshl_b32 s4, s2, 8
	s_add_i32 s5, 0, 0x20800
	v_lshlrev_b32_e32 v51, 16, v46
	v_and_b32_e32 v46, 0xffff0000, v46
	s_lshl_b32 s12, s4, 1
	s_mov_b32 s13, s31
	s_add_i32 s16, s16, s62
	s_cmpk_gt_i32 s16, 0x3ff
	s_waitcnt vmcnt(0) lgkmcnt(0)
	ds_write_b128 v211, v[82:85]
	ds_write_b128 v212, v[86:89]
	ds_write_b128 v213, v[90:93]
	ds_write_b128 v214, v[94:97]
	v_or_b32_e32 v22, s4, v187
	v_lshlrev_b32_e32 v50, 2, v22
	v_lshlrev_b32_e32 v22, 3, v138
	v_add_u32_e32 v22, s5, v22
	s_waitcnt lgkmcnt(0)
	s_barrier
	ds_read_b64 v[52:53], v22
	global_load_dwordx4 v[22:25], v50, s[44:45] offset:16
	global_load_dwordx4 v[34:37], v50, s[44:45]
	global_load_dwordx4 v[30:33], v50, s[46:47] offset:16
	global_load_dwordx4 v[38:41], v50, s[46:47]
	s_waitcnt lgkmcnt(0)
	v_sub_f32_e32 v51, v51, v52
	v_sub_f32_e32 v46, v46, v52
	v_mul_f32_e32 v51, v53, v51
	v_mul_f32_e32 v46, v53, v46
	s_waitcnt vmcnt(0)
	v_fma_f32 v51, v51, v34, v38
	v_fma_f32 v46, v46, v35, v39
	v_cvt_pk_bf16_f32 v46, v51, v46
	v_lshlrev_b32_e32 v51, 16, v47
	v_and_b32_e32 v47, 0xffff0000, v47
	v_sub_f32_e32 v51, v51, v52
	v_sub_f32_e32 v47, v47, v52
	v_mul_f32_e32 v51, v53, v51
	v_mul_f32_e32 v47, v53, v47
	v_fma_f32 v51, v51, v36, v40
	v_fma_f32 v47, v47, v37, v41
	v_cvt_pk_bf16_f32 v47, v51, v47
	v_lshlrev_b32_e32 v51, 16, v48
	v_and_b32_e32 v48, 0xffff0000, v48
	v_sub_f32_e32 v51, v51, v52
	v_sub_f32_e32 v48, v48, v52
	v_mul_f32_e32 v51, v53, v51
	v_mul_f32_e32 v48, v53, v48
	v_fma_f32 v51, v51, v22, v30
	v_fma_f32 v48, v48, v23, v31
	v_cvt_pk_bf16_f32 v48, v51, v48
	v_lshlrev_b32_e32 v51, 16, v49
	v_and_b32_e32 v49, 0xffff0000, v49
	v_sub_f32_e32 v49, v49, v52
	v_sub_f32_e32 v51, v51, v52
	v_mul_f32_e32 v49, v53, v49
	v_mul_f32_e32 v51, v53, v51
	v_fma_f32 v49, v49, v25, v33
	v_fma_f32 v51, v51, v24, v32
	v_cvt_pk_bf16_f32 v49, v51, v49
	ds_write_b128 v215, v[46:49] offset:32768
	v_lshlrev_b32_e32 v46, 3, v140
	v_add_u32_e32 v46, s5, v46
	ds_read_b64 v[46:47], v46
	v_lshlrev_b32_e32 v48, 16, v42
	v_and_b32_e32 v42, 0xffff0000, v42
	s_waitcnt lgkmcnt(0)
	v_sub_f32_e32 v48, v48, v46
	v_sub_f32_e32 v42, v42, v46
	v_mul_f32_e32 v48, v47, v48
	v_mul_f32_e32 v42, v47, v42
	v_fma_f32 v48, v48, v34, v38
	v_fma_f32 v42, v42, v35, v39
	v_cvt_pk_bf16_f32 v42, v48, v42
	v_lshlrev_b32_e32 v48, 16, v43
	v_and_b32_e32 v43, 0xffff0000, v43
	v_sub_f32_e32 v48, v48, v46
	v_sub_f32_e32 v43, v43, v46
	v_mul_f32_e32 v48, v47, v48
	v_mul_f32_e32 v43, v47, v43
	v_fma_f32 v48, v48, v36, v40
	v_fma_f32 v43, v43, v37, v41
	v_cvt_pk_bf16_f32 v43, v48, v43
	v_lshlrev_b32_e32 v48, 16, v44
	v_and_b32_e32 v44, 0xffff0000, v44
	v_sub_f32_e32 v48, v48, v46
	v_sub_f32_e32 v44, v44, v46
	v_mul_f32_e32 v48, v47, v48
	v_mul_f32_e32 v44, v47, v44
	v_fma_f32 v48, v48, v22, v30
	v_fma_f32 v44, v44, v23, v31
	v_cvt_pk_bf16_f32 v44, v48, v44
	v_lshlrev_b32_e32 v48, 16, v45
	v_and_b32_e32 v45, 0xffff0000, v45
	v_sub_f32_e32 v45, v45, v46
	v_sub_f32_e32 v48, v48, v46
	v_mul_f32_e32 v45, v47, v45
	v_mul_f32_e32 v48, v47, v48
	v_fma_f32 v45, v45, v25, v33
	v_fma_f32 v48, v48, v24, v32
	v_cvt_pk_bf16_f32 v45, v48, v45
	ds_write_b128 v216, v[42:45] offset:32768
	v_add_u32_e32 v42, s5, v0
	ds_read_b64 v[42:43], v42
	v_lshlrev_b32_e32 v44, 16, v26
	v_and_b32_e32 v26, 0xffff0000, v26
	s_waitcnt lgkmcnt(0)
	v_sub_f32_e32 v44, v44, v42
	v_sub_f32_e32 v26, v26, v42
	v_mul_f32_e32 v44, v43, v44
	v_mul_f32_e32 v26, v43, v26
	v_fma_f32 v44, v44, v34, v38
	v_fma_f32 v26, v26, v35, v39
	v_cvt_pk_bf16_f32 v26, v44, v26
	v_lshlrev_b32_e32 v44, 16, v27
	v_and_b32_e32 v27, 0xffff0000, v27
	v_sub_f32_e32 v44, v44, v42
	v_sub_f32_e32 v27, v27, v42
	v_mul_f32_e32 v44, v43, v44
	v_mul_f32_e32 v27, v43, v27
	v_fma_f32 v44, v44, v36, v40
	v_fma_f32 v27, v27, v37, v41
	v_cvt_pk_bf16_f32 v27, v44, v27
	v_lshlrev_b32_e32 v44, 16, v28
	v_and_b32_e32 v28, 0xffff0000, v28
	v_sub_f32_e32 v44, v44, v42
	v_sub_f32_e32 v28, v28, v42
	v_mul_f32_e32 v44, v43, v44
	v_mul_f32_e32 v28, v43, v28
	v_fma_f32 v44, v44, v22, v30
	v_fma_f32 v28, v28, v23, v31
	v_cvt_pk_bf16_f32 v28, v44, v28
	v_lshlrev_b32_e32 v44, 16, v29
	v_and_b32_e32 v29, 0xffff0000, v29
	v_sub_f32_e32 v29, v29, v42
	v_sub_f32_e32 v44, v44, v42
	v_mul_f32_e32 v29, v43, v29
	v_mul_f32_e32 v44, v43, v44
	v_fma_f32 v29, v29, v25, v33
	v_fma_f32 v44, v44, v24, v32
	v_cvt_pk_bf16_f32 v29, v44, v29
	ds_write_b128 v217, v[26:29] offset:32768
	v_add_u32_e32 v26, s5, v189
	ds_read_b64 v[26:27], v26
	v_lshlrev_b32_e32 v28, 16, v18
	v_and_b32_e32 v18, 0xffff0000, v18
	s_waitcnt lgkmcnt(0)
	v_sub_f32_e32 v28, v28, v26
	v_sub_f32_e32 v18, v18, v26
	v_mul_f32_e32 v28, v27, v28
	v_mul_f32_e32 v18, v27, v18
	v_fma_f32 v28, v28, v34, v38
	v_fma_f32 v18, v18, v35, v39
	v_cvt_pk_bf16_f32 v18, v28, v18
	v_lshlrev_b32_e32 v28, 16, v19
	v_and_b32_e32 v19, 0xffff0000, v19
	v_sub_f32_e32 v28, v28, v26
	v_sub_f32_e32 v19, v19, v26
	v_mul_f32_e32 v28, v27, v28
	v_mul_f32_e32 v19, v27, v19
	v_fma_f32 v28, v28, v36, v40
	v_fma_f32 v19, v19, v37, v41
	v_cvt_pk_bf16_f32 v19, v28, v19
	v_lshlrev_b32_e32 v28, 16, v20
	v_and_b32_e32 v20, 0xffff0000, v20
	v_sub_f32_e32 v28, v28, v26
	v_sub_f32_e32 v20, v20, v26
	v_mul_f32_e32 v28, v27, v28
	v_mul_f32_e32 v20, v27, v20
	v_fma_f32 v28, v28, v22, v30
	v_fma_f32 v20, v20, v23, v31
	v_cvt_pk_bf16_f32 v20, v28, v20
	v_lshlrev_b32_e32 v28, 16, v21
	v_and_b32_e32 v21, 0xffff0000, v21
	v_sub_f32_e32 v21, v21, v26
	v_sub_f32_e32 v28, v28, v26
	v_mul_f32_e32 v21, v27, v21
	v_mul_f32_e32 v28, v27, v28
	v_fma_f32 v21, v21, v25, v33
	v_fma_f32 v28, v28, v24, v32
	v_cvt_pk_bf16_f32 v21, v28, v21
	ds_write_b128 v218, v[18:21] offset:32768
	v_add_u32_e32 v18, s5, v190
	ds_read_b64 v[18:19], v18
	v_lshlrev_b32_e32 v20, 16, v14
	v_and_b32_e32 v14, 0xffff0000, v14
	v_lshlrev_b32_e32 v28, 16, v6
	v_and_b32_e32 v6, 0xffff0000, v6
	s_waitcnt lgkmcnt(0)
; #define LAS __attribute__((address_space(3)))
; __device__ __forceinline__ unsigned pk2(float lo, float hi) { unsigned r; asm("v_cvt_pk_bf16_f32 %0, %1, %2" : "=v"(r) : "v"(lo), "v"(hi)); return r; }
; __device__ __forceinline__ float bf_lo(unsigned u) { return __uint_as_float(u << 16); }
; __device__ __forceinline__ float bf_hi(unsigned u) { return __uint_as_float(u & 0xffff0000u); }
; __device__ __forceinline__ void phase_sgu(const Params& P, LAS unsigned char* lds, int layer_i) {
;     ...
;         for (int i = 0; i < 8; ++i) { const int n = tid + 512 * i, row = n >> 5, cc = n & 31, c0 = g * 256 + cc * 8;
;             const u32x4 v = gvr[i];
;             const float mu = st[2 * row], rs = st[2 * row + 1];
;             const f32x4 g0 = *(const f32x4*)(lng + c0), g1 = *(const f32x4*)(lng + c0 + 4), b0 = *(const f32x4*)(lnb + c0), b1 = *(const f32x4*)(lnb + c0 + 4);
;             u32x4 o;
;             o.x = pk2((bf_lo(v.x) - mu) * rs * g0.x + b0.x, (bf_hi(v.x) - mu) * rs * g0.y + b0.y); o.y = pk2((bf_lo(v.y) - mu) * rs * g0.z + b0.z, (bf_hi(v.y) - mu) * rs * g0.w + b0.w);
;             o.z = pk2((bf_lo(v.z) - mu) * rs * g1.x + b1.x, (bf_hi(v.z) - mu) * rs * g1.y + b1.y); o.w = pk2((bf_lo(v.w) - mu) * rs * g1.z + b1.z, (bf_hi(v.w) - mu) * rs * g1.w + b1.w);
;             *(LAS u32x4*)(lds + SG_B + (cc >> 4) * 32768 + off_b(row, cc & 15)) = o; }
;         __syncthreads();
	v_sub_f32_e32 v20, v20, v18
	v_sub_f32_e32 v14, v14, v18
	v_mul_f32_e32 v20, v19, v20
	v_mul_f32_e32 v14, v19, v14
	v_fma_f32 v20, v20, v34, v38
	v_fma_f32 v14, v14, v35, v39
	v_cvt_pk_bf16_f32 v14, v20, v14
	v_lshlrev_b32_e32 v20, 16, v15
	v_and_b32_e32 v15, 0xffff0000, v15
	v_sub_f32_e32 v20, v20, v18
	v_sub_f32_e32 v15, v15, v18
	v_mul_f32_e32 v20, v19, v20
	v_mul_f32_e32 v15, v19, v15
	v_fma_f32 v20, v20, v36, v40
	v_fma_f32 v15, v15, v37, v41
	v_cvt_pk_bf16_f32 v15, v20, v15
	v_lshlrev_b32_e32 v20, 16, v16
	v_and_b32_e32 v16, 0xffff0000, v16
	v_sub_f32_e32 v20, v20, v18
	v_sub_f32_e32 v16, v16, v18
	v_mul_f32_e32 v20, v19, v20
	v_mul_f32_e32 v16, v19, v16
	v_fma_f32 v20, v20, v22, v30
	v_fma_f32 v16, v16, v23, v31
	v_cvt_pk_bf16_f32 v16, v20, v16
	v_lshlrev_b32_e32 v20, 16, v17
	v_and_b32_e32 v17, 0xffff0000, v17
	v_sub_f32_e32 v17, v17, v18
	v_sub_f32_e32 v20, v20, v18
	v_mul_f32_e32 v17, v19, v17
	v_mul_f32_e32 v20, v19, v20
	v_fma_f32 v17, v17, v25, v33
	v_fma_f32 v20, v20, v24, v32
	v_cvt_pk_bf16_f32 v17, v20, v17
	ds_write_b128 v219, v[14:17] offset:32768
	v_add_u32_e32 v14, s5, v191
	ds_read_b64 v[14:15], v14
	v_lshlrev_b32_e32 v16, 16, v10
	v_and_b32_e32 v10, 0xffff0000, v10
	s_waitcnt lgkmcnt(0)
	v_sub_f32_e32 v16, v16, v14
	v_sub_f32_e32 v10, v10, v14
	v_mul_f32_e32 v16, v15, v16
	v_mul_f32_e32 v10, v15, v10
	v_fma_f32 v16, v16, v34, v38
	v_fma_f32 v10, v10, v35, v39
	v_cvt_pk_bf16_f32 v10, v16, v10
	v_lshlrev_b32_e32 v16, 16, v11
	v_sub_f32_e32 v16, v16, v14
	v_and_b32_e32 v11, 0xffff0000, v11
	v_mul_f32_e32 v16, v15, v16
	v_sub_f32_e32 v11, v11, v14
	v_fma_f32 v16, v16, v36, v40
	v_mul_f32_e32 v11, v15, v11
	v_fmac_f32_e32 v41, v11, v37
	v_cvt_pk_bf16_f32 v11, v16, v41
	v_lshlrev_b32_e32 v16, 16, v12
	v_and_b32_e32 v12, 0xffff0000, v12
	v_sub_f32_e32 v16, v16, v14
	v_sub_f32_e32 v12, v12, v14
	v_mul_f32_e32 v16, v15, v16
	v_mul_f32_e32 v12, v15, v12
	v_fma_f32 v16, v16, v22, v30
	v_fma_f32 v12, v12, v23, v31
	v_cvt_pk_bf16_f32 v12, v16, v12
	v_lshlrev_b32_e32 v16, 16, v13
	v_and_b32_e32 v13, 0xffff0000, v13
	v_sub_f32_e32 v16, v16, v14
	v_sub_f32_e32 v13, v13, v14
	v_mul_f32_e32 v16, v15, v16
	v_mul_f32_e32 v13, v15, v13
	v_fma_f32 v16, v16, v24, v32
	v_fmac_f32_e32 v33, v13, v25
	v_cvt_pk_bf16_f32 v13, v16, v33
	ds_write_b128 v220, v[10:13] offset:32768
	v_add_u32_e32 v10, s5, v192
	ds_read_b64 v[26:27], v10
	global_load_dwordx4 v[10:13], v50, s[44:45] offset:16
	global_load_dwordx4 v[18:21], v50, s[44:45]
	global_load_dwordx4 v[14:17], v50, s[46:47] offset:16
	global_load_dwordx4 v[22:25], v50, s[46:47]
	s_waitcnt lgkmcnt(0)
	v_sub_f32_e32 v28, v28, v26
	v_sub_f32_e32 v6, v6, v26
	v_mul_f32_e32 v28, v27, v28
	v_mul_f32_e32 v6, v27, v6
	s_waitcnt vmcnt(0)
	v_fma_f32 v28, v28, v18, v22
	v_fma_f32 v6, v6, v19, v23
	v_cvt_pk_bf16_f32 v6, v28, v6
	v_lshlrev_b32_e32 v28, 16, v7
	v_and_b32_e32 v7, 0xffff0000, v7
	v_sub_f32_e32 v28, v28, v26
	v_sub_f32_e32 v7, v7, v26
	v_mul_f32_e32 v28, v27, v28
	v_mul_f32_e32 v7, v27, v7
	v_fma_f32 v28, v28, v20, v24
	v_fma_f32 v7, v7, v21, v25
	v_cvt_pk_bf16_f32 v7, v28, v7
	v_lshlrev_b32_e32 v28, 16, v8
	v_and_b32_e32 v8, 0xffff0000, v8
	v_sub_f32_e32 v28, v28, v26
	v_sub_f32_e32 v8, v8, v26
	v_mul_f32_e32 v28, v27, v28
	v_mul_f32_e32 v8, v27, v8
	v_fma_f32 v28, v28, v10, v14
	v_fma_f32 v8, v8, v11, v15
	v_cvt_pk_bf16_f32 v8, v28, v8
	v_lshlrev_b32_e32 v28, 16, v9
	v_and_b32_e32 v9, 0xffff0000, v9
	v_sub_f32_e32 v9, v9, v26
	v_sub_f32_e32 v28, v28, v26
	v_mul_f32_e32 v9, v27, v9
	v_mul_f32_e32 v28, v27, v28
	v_fma_f32 v9, v9, v13, v17
	v_fma_f32 v28, v28, v12, v16
	v_cvt_pk_bf16_f32 v9, v28, v9
	ds_write_b128 v221, v[6:9] offset:32768
	v_add_u32_e32 v6, s5, v193
	ds_read_b64 v[6:7], v6
	v_lshlrev_b32_e32 v8, 16, v2
	v_and_b32_e32 v2, 0xffff0000, v2
	s_waitcnt lgkmcnt(0)
	v_sub_f32_e32 v8, v8, v6
	v_sub_f32_e32 v2, v2, v6
	v_mul_f32_e32 v8, v7, v8
	v_mul_f32_e32 v2, v7, v2
	v_fma_f32 v8, v8, v18, v22
	v_fma_f32 v2, v2, v19, v23
	v_cvt_pk_bf16_f32 v2, v8, v2
	v_lshlrev_b32_e32 v8, 16, v3
	v_sub_f32_e32 v8, v8, v6
	v_and_b32_e32 v3, 0xffff0000, v3
	v_mul_f32_e32 v8, v7, v8
	v_sub_f32_e32 v3, v3, v6
	v_fma_f32 v8, v8, v20, v24
	v_mul_f32_e32 v3, v7, v3
	v_fmac_f32_e32 v25, v3, v21
	v_cvt_pk_bf16_f32 v3, v8, v25
	v_lshlrev_b32_e32 v8, 16, v4
	v_and_b32_e32 v4, 0xffff0000, v4
	v_sub_f32_e32 v8, v8, v6
	v_sub_f32_e32 v4, v4, v6
	v_mul_f32_e32 v8, v7, v8
	v_mul_f32_e32 v4, v7, v4
	v_fma_f32 v8, v8, v10, v14
	v_fma_f32 v4, v4, v11, v15
	v_cvt_pk_bf16_f32 v4, v8, v4
	v_lshlrev_b32_e32 v8, 16, v5
	v_and_b32_e32 v5, 0xffff0000, v5
	v_sub_f32_e32 v8, v8, v6
	v_sub_f32_e32 v5, v5, v6
	v_mul_f32_e32 v8, v7, v8
	v_mul_f32_e32 v5, v7, v5
	v_fma_f32 v8, v8, v12, v16
	v_fmac_f32_e32 v17, v5, v13
	v_cvt_pk_bf16_f32 v5, v8, v17
	ds_write_b128 v222, v[2:5] offset:32768
	v_lshl_add_u64 v[2:3], v[134:135], 0, s[12:13]
	v_lshl_add_u64 v[4:5], v[2:3], 0, v[176:177]
	s_waitcnt lgkmcnt(0)
	s_barrier
; #define LAS __attribute__((address_space(3)))
; __device__ __forceinline__ u16x4 tr_read(unsigned lds_addr) { u16x4 r; asm volatile("ds_read_b64_tr_b16 %0, %1\n\ts_waitcnt lgkmcnt(0)" : "=&v"(r) : "v"(lds_addr) : "memory"); return r; }
; #define MFMA32(a, b, c) __builtin_amdgcn_mfma_f32_32x32x16_bf16((a), (b), (c), 0, 0, 0)
; __device__ __forceinline__ void phase_sgu(const Params& P, LAS unsigned char* lds, int layer_i) {
;     ...
;         u32x4 uzr[8];
; #pragma unroll
;         for (int i = 0; i < 8; ++i) { const int n = tid + 512 * i, row = n >> 5, cc = n & 31; uzr[i] = *(const u32x4*)(uz + (row0 + row) * DM + g * 256 + cc * 8); }
;         const unsigned h = lane >> 5, blk = (lane >> 4) & 1, qq = (lane & 15) >> 2, pp = lane & 3;
;         const unsigned bimg = lbase + SG_B + (wave >> 2) * 32768; const int ct = wave & 3;
;         bf16x8 bf[8];
; #pragma unroll
;         for (int ks = 0; ks < 8; ++ks) {
;             const u16x4 t0 = tr_read(bimg + off_b(16 * ks + 8 * h + qq, 4 * ct + 2 * blk + (pp >> 1)) + 8 * (pp & 1));
;             const u16x4 t1 = tr_read(bimg + off_b(16 * ks + 8 * h + 4 + qq, 4 * ct + 2 * blk + (pp >> 1)) + 8 * (pp & 1));
;             bf[ks] = cat4(t0, t1); }
;         f32x16 acc[4];
; #pragma unroll
;         for (int tt = 0; tt < 4; ++tt) {
; #pragma unroll
;             for (int i = 0; i < 16; ++i) acc[tt][i] = 0.f;
; #pragma unroll
;             for (int ks = 0; ks < 8; ++ks) { const bf16x8 af = *(const LAS bf16x8*)(lds + SG_A + off_b(32 * tt + (lane & 31), 2 * ks + h)); acc[tt] = MFMA32(af, bf[ks], acc[tt]); }
;         }
	global_load_dwordx4 v[82:85], v[4:5], off
	v_lshl_add_u64 v[4:5], v[2:3], 0, v[174:175]
	global_load_dwordx4 v[74:77], v[4:5], off
	v_lshl_add_u64 v[4:5], v[2:3], 0, v[172:173]
	global_load_dwordx4 v[70:73], v[4:5], off
	v_lshl_add_u64 v[4:5], v[2:3], 0, v[170:171]
	global_load_dwordx4 v[66:69], v[4:5], off
	v_lshl_add_u64 v[4:5], v[2:3], 0, v[168:169]
	global_load_dwordx4 v[90:93], v[4:5], off
	v_lshl_add_u64 v[4:5], v[2:3], 0, v[166:167]
	global_load_dwordx4 v[86:89], v[4:5], off
	v_lshl_add_u64 v[4:5], v[2:3], 0, v[164:165]
	v_lshl_add_u64 v[2:3], v[2:3], 0, v[162:163]
	global_load_dwordx4 v[78:81], v[4:5], off
	global_load_dwordx4 v[94:97], v[2:3], off
	ds_read_b64_tr_b16 v[2:3], v194
	ds_read_b64_tr_b16 v[4:5], v195
	ds_read_b64_tr_b16 v[122:123], v196
	ds_read_b64_tr_b16 v[124:125], v197
	ds_read_b64_tr_b16 v[118:119], v198
	ds_read_b64_tr_b16 v[120:121], v199
	ds_read_b64_tr_b16 v[114:115], v200
	ds_read_b64_tr_b16 v[116:117], v201
	ds_read_b64_tr_b16 v[110:111], v202
	ds_read_b64_tr_b16 v[112:113], v203
	ds_read_b64_tr_b16 v[98:99], v204
	ds_read_b64_tr_b16 v[100:101], v205
	ds_read_b64_tr_b16 v[102:103], v206
	ds_read_b64_tr_b16 v[104:105], v207
	ds_read_b64_tr_b16 v[106:107], v208
	ds_read_b64_tr_b16 v[108:109], v209
	s_waitcnt lgkmcnt(0)
	ds_read_b128 v[6:9], v223
	ds_read_b128 v[248:251], v224 offset:24576
	ds_read_b128 v[10:13], v224
	s_waitcnt lgkmcnt(1)
	v_mfma_f32_32x32x16_bf16 v[50:65], v[6:9], v[2:5], 0
	ds_read_b128 v[6:9], v225
	s_waitcnt lgkmcnt(1)
	v_mfma_f32_32x32x16_bf16 v[50:65], v[10:13], v[122:125], v[50:65]
	ds_read_b128 v[10:13], v226
	s_waitcnt lgkmcnt(1)
	v_mfma_f32_32x32x16_bf16 v[50:65], v[6:9], v[118:121], v[50:65]
	ds_read_b128 v[6:9], v227
	s_waitcnt lgkmcnt(1)
	v_mfma_f32_32x32x16_bf16 v[50:65], v[10:13], v[114:117], v[50:65]
	ds_read_b128 v[10:13], v228
	s_waitcnt lgkmcnt(1)
	v_mfma_f32_32x32x16_bf16 v[50:65], v[6:9], v[110:113], v[50:65]
	ds_read_b128 v[6:9], v229
	s_waitcnt lgkmcnt(1)
	v_mfma_f32_32x32x16_bf16 v[50:65], v[10:13], v[98:101], v[50:65]
	ds_read_b128 v[10:13], v230
	s_waitcnt lgkmcnt(1)
	v_mfma_f32_32x32x16_bf16 v[50:65], v[6:9], v[102:105], v[50:65]
	ds_read_b128 v[6:9], v223 offset:8192
	s_waitcnt lgkmcnt(1)
	v_mfma_f32_32x32x16_bf16 v[50:65], v[10:13], v[106:109], v[50:65]
	ds_read_b128 v[10:13], v224 offset:8192
	s_waitcnt lgkmcnt(1)
	v_mfma_f32_32x32x16_bf16 v[34:49], v[6:9], v[2:5], 0
	ds_read_b128 v[6:9], v225 offset:8192
	s_waitcnt lgkmcnt(1)
	v_mfma_f32_32x32x16_bf16 v[34:49], v[10:13], v[122:125], v[34:49]
	ds_read_b128 v[10:13], v226 offset:8192
	s_waitcnt lgkmcnt(1)
	v_mfma_f32_32x32x16_bf16 v[34:49], v[6:9], v[118:121], v[34:49]
	ds_read_b128 v[6:9], v227 offset:8192
	s_waitcnt lgkmcnt(1)
	v_mfma_f32_32x32x16_bf16 v[34:49], v[10:13], v[114:117], v[34:49]
	ds_read_b128 v[10:13], v228 offset:8192
	s_waitcnt lgkmcnt(1)
	v_mfma_f32_32x32x16_bf16 v[34:49], v[6:9], v[110:113], v[34:49]
	ds_read_b128 v[6:9], v229 offset:8192
	s_waitcnt lgkmcnt(1)
	v_mfma_f32_32x32x16_bf16 v[34:49], v[10:13], v[98:101], v[34:49]
	ds_read_b128 v[10:13], v230 offset:8192
	s_waitcnt lgkmcnt(1)
	v_mfma_f32_32x32x16_bf16 v[34:49], v[6:9], v[102:105], v[34:49]
	ds_read_b128 v[6:9], v223 offset:16384
	s_waitcnt lgkmcnt(1)
	v_mfma_f32_32x32x16_bf16 v[34:49], v[10:13], v[106:109], v[34:49]
	ds_read_b128 v[10:13], v224 offset:16384
	s_waitcnt lgkmcnt(1)
	v_mfma_f32_32x32x16_bf16 v[18:33], v[6:9], v[2:5], 0
	ds_read_b128 v[6:9], v225 offset:16384
	s_waitcnt lgkmcnt(1)
	v_mfma_f32_32x32x16_bf16 v[18:33], v[10:13], v[122:125], v[18:33]
	ds_read_b128 v[10:13], v226 offset:16384
	s_waitcnt lgkmcnt(1)
	v_mfma_f32_32x32x16_bf16 v[18:33], v[6:9], v[118:121], v[18:33]
	ds_read_b128 v[6:9], v227 offset:16384
	s_waitcnt lgkmcnt(1)
	v_mfma_f32_32x32x16_bf16 v[18:33], v[10:13], v[114:117], v[18:33]
	ds_read_b128 v[10:13], v228 offset:16384
	s_waitcnt lgkmcnt(1)
	v_mfma_f32_32x32x16_bf16 v[18:33], v[6:9], v[110:113], v[18:33]
	ds_read_b128 v[6:9], v229 offset:16384
	s_waitcnt lgkmcnt(1)
	v_mfma_f32_32x32x16_bf16 v[18:33], v[10:13], v[98:101], v[18:33]
	ds_read_b128 v[10:13], v230 offset:16384
	s_waitcnt lgkmcnt(1)
	v_mfma_f32_32x32x16_bf16 v[18:33], v[6:9], v[102:105], v[18:33]
	ds_read_b128 v[6:9], v223 offset:24576
	s_waitcnt lgkmcnt(1)
	v_mfma_f32_32x32x16_bf16 v[18:33], v[10:13], v[106:109], v[18:33]
	s_waitcnt lgkmcnt(0)
	v_mfma_f32_32x32x16_bf16 v[2:17], v[6:9], v[2:5], 0
	v_mfma_f32_32x32x16_bf16 v[2:17], v[248:251], v[122:125], v[2:17]
	ds_read_b128 v[122:125], v225 offset:24576
	ds_read_b128 v[248:251], v226 offset:24576
	s_waitcnt lgkmcnt(1)
	v_mfma_f32_32x32x16_bf16 v[2:17], v[122:125], v[118:121], v[2:17]
	ds_read_b128 v[118:121], v227 offset:24576
	s_waitcnt lgkmcnt(1)
	v_mfma_f32_32x32x16_bf16 v[2:17], v[248:251], v[114:117], v[2:17]
	ds_read_b128 v[114:117], v228 offset:24576
	s_waitcnt lgkmcnt(1)
	v_mfma_f32_32x32x16_bf16 v[2:17], v[118:121], v[110:113], v[2:17]
	ds_read_b128 v[110:113], v229 offset:24576
	s_waitcnt lgkmcnt(1)
	v_mfma_f32_32x32x16_bf16 v[2:17], v[114:117], v[98:101], v[2:17]
	ds_read_b128 v[98:101], v230 offset:24576
	s_waitcnt lgkmcnt(1)
	v_mfma_f32_32x32x16_bf16 v[2:17], v[110:113], v[102:105], v[2:17]
	s_waitcnt lgkmcnt(0)
	s_barrier
; #define LAS __attribute__((address_space(3)))
; __device__ __forceinline__ void phase_sgu(const Params& P, LAS unsigned char* lds, int layer_i) {
;     ...
; #pragma unroll
;         for (int tt = 0; tt < 4; ++tt)
; #pragma unroll
;             for (int i = 0; i < 16; ++i) { const int t = 32 * tt + (i & 3) + 8 * (i >> 2) + 4 * h;
;                 *(LAS float*)(lds + t * SG_MIX_STRIDE + (32 * wave + (lane & 31)) * 4) = acc[tt][i] + bs[g * 128 + t]; }
	v_mfma_f32_32x32x16_bf16 v[2:17], v[98:101], v[106:109], v[2:17]
	v_or_b32_e32 v98, s30, v188
	v_lshlrev_b32_e32 v98, 2, v98
	global_load_dwordx4 v[110:113], v98, s[48:49]
	global_load_dwordx4 v[114:117], v98, s[48:49] offset:32
	global_load_dwordx4 v[118:121], v98, s[48:49] offset:64
	global_load_dwordx4 v[122:125], v98, s[48:49] offset:96
	global_load_dwordx4 v[248:251], v98, s[48:49] offset:128
	s_waitcnt vmcnt(4)
	v_add_f32_e32 v50, v50, v110
	ds_write_b32 v231, v50
	v_add_f32_e32 v50, v51, v111
	ds_write_b32 v232, v50
	v_add_f32_e32 v50, v52, v112
	ds_write_b32 v232, v50 offset:1040
	v_add_f32_e32 v50, v53, v113
	ds_write_b32 v232, v50 offset:2080
	global_load_dwordx4 v[110:113], v98, s[48:49] offset:160
	s_waitcnt vmcnt(4)
	v_add_f32_e32 v50, v54, v114
	ds_write_b32 v232, v50 offset:7280
	v_add_f32_e32 v50, v55, v115
	ds_write_b32 v232, v50 offset:8320
	v_add_f32_e32 v50, v56, v116
	ds_write_b32 v232, v50 offset:9360
	v_add_f32_e32 v50, v57, v117
	ds_write_b32 v233, v50
	global_load_dwordx4 v[114:117], v98, s[48:49] offset:192
	s_waitcnt vmcnt(4)
	v_add_f32_e32 v50, v58, v118
	ds_write_b32 v233, v50 offset:5200
	v_add_f32_e32 v50, v59, v119
	ds_write_b32 v233, v50 offset:6240
	v_add_f32_e32 v50, v60, v120
	ds_write_b32 v233, v50 offset:7280
	v_add_f32_e32 v50, v61, v121
	ds_write_b32 v233, v50 offset:8320
	global_load_dwordx4 v[118:121], v98, s[48:49] offset:224
	s_waitcnt vmcnt(4)
	v_add_f32_e32 v50, v62, v122
	ds_write_b32 v233, v50 offset:13520
	v_add_f32_e32 v50, v63, v123
	ds_write_b32 v234, v50
	v_add_f32_e32 v50, v64, v124
	ds_write_b32 v234, v50 offset:1040
	v_add_f32_e32 v50, v65, v125
	ds_write_b32 v234, v50 offset:2080
	global_load_dwordx4 v[122:125], v98, s[48:49] offset:256
	s_waitcnt vmcnt(4)
	v_add_f32_e32 v34, v34, v248
	ds_write_b32 v234, v34 offset:7280
	v_add_f32_e32 v34, v35, v249
	ds_write_b32 v234, v34 offset:8320
	v_add_f32_e32 v34, v36, v250
	ds_write_b32 v234, v34 offset:9360
	v_add_f32_e32 v34, v37, v251
	ds_write_b32 v235, v34
	global_load_dwordx4 v[248:251], v98, s[48:49] offset:288
	s_waitcnt vmcnt(4)
	v_add_f32_e32 v34, v38, v110
	ds_write_b32 v235, v34 offset:5200
	v_add_f32_e32 v34, v39, v111
	ds_write_b32 v235, v34 offset:6240
	v_add_f32_e32 v34, v40, v112
	ds_write_b32 v235, v34 offset:7280
	v_add_f32_e32 v34, v41, v113
	ds_write_b32 v235, v34 offset:8320
	global_load_dwordx4 v[110:113], v98, s[48:49] offset:320
	s_waitcnt vmcnt(4)
	v_add_f32_e32 v34, v42, v114
	ds_write_b32 v235, v34 offset:13520
	v_add_f32_e32 v34, v43, v115
	ds_write_b32 v236, v34
	v_add_f32_e32 v34, v44, v116
	ds_write_b32 v236, v34 offset:1040
	v_add_f32_e32 v34, v45, v117
	ds_write_b32 v236, v34 offset:2080
	global_load_dwordx4 v[114:117], v98, s[48:49] offset:352
	s_waitcnt vmcnt(4)
	v_add_f32_e32 v34, v46, v118
	ds_write_b32 v236, v34 offset:7280
	v_add_f32_e32 v34, v47, v119
	ds_write_b32 v236, v34 offset:8320
	v_add_f32_e32 v34, v48, v120
	ds_write_b32 v236, v34 offset:9360
	v_add_f32_e32 v34, v49, v121
	ds_write_b32 v237, v34
	global_load_dwordx4 v[118:121], v98, s[48:49] offset:384
	s_waitcnt vmcnt(4)
	v_add_f32_e32 v18, v18, v122
	ds_write_b32 v237, v18 offset:5200
	v_add_f32_e32 v18, v19, v123
	ds_write_b32 v237, v18 offset:6240
	v_add_f32_e32 v18, v20, v124
	ds_write_b32 v237, v18 offset:7280
	v_add_f32_e32 v18, v21, v125
	ds_write_b32 v237, v18 offset:8320
	global_load_dwordx4 v[122:125], v98, s[48:49] offset:416
	s_waitcnt vmcnt(4)
	v_add_f32_e32 v18, v22, v248
	ds_write_b32 v237, v18 offset:13520
	v_add_f32_e32 v18, v23, v249
	ds_write_b32 v237, v18 offset:14560
	v_add_f32_e32 v18, v24, v250
	ds_write_b32 v237, v18 offset:15600
	v_add_f32_e32 v18, v25, v251
	ds_write_b32 v237, v18 offset:16640
	global_load_dwordx4 v[248:251], v98, s[48:49] offset:448
	s_waitcnt vmcnt(4)
	v_add_f32_e32 v18, v26, v110
	ds_write_b32 v237, v18 offset:21840
	v_add_f32_e32 v18, v27, v111
	ds_write_b32 v237, v18 offset:22880
	v_add_f32_e32 v18, v28, v112
	ds_write_b32 v237, v18 offset:23920
	v_add_f32_e32 v18, v29, v113
	ds_write_b32 v237, v18 offset:24960
	global_load_dwordx4 v[110:113], v98, s[48:49] offset:480
	s_waitcnt vmcnt(4)
	v_add_f32_e32 v18, v30, v114
	ds_write_b32 v237, v18 offset:30160
	v_add_f32_e32 v18, v31, v115
	ds_write_b32 v237, v18 offset:31200
	v_add_f32_e32 v18, v32, v116
	ds_write_b32 v237, v18 offset:32240
	v_add_f32_e32 v18, v33, v117
	ds_write_b32 v237, v18 offset:33280
	s_waitcnt vmcnt(3)
	v_add_f32_e32 v2, v2, v118
	ds_write_b32 v237, v2 offset:38480
	v_add_f32_e32 v2, v3, v119
	ds_write_b32 v237, v2 offset:39520
	v_add_f32_e32 v2, v4, v120
	ds_write_b32 v237, v2 offset:40560
	v_add_f32_e32 v2, v5, v121
	ds_write_b32 v237, v2 offset:41600
	s_waitcnt vmcnt(2)
	v_add_f32_e32 v2, v6, v122
	ds_write_b32 v237, v2 offset:46800
	v_add_f32_e32 v2, v7, v123
	ds_write_b32 v237, v2 offset:47840
	v_add_f32_e32 v2, v8, v124
	ds_write_b32 v237, v2 offset:48880
	v_add_f32_e32 v2, v9, v125
	ds_write_b32 v237, v2 offset:49920
	s_waitcnt vmcnt(1)
	v_add_f32_e32 v2, v10, v248
	ds_write_b32 v237, v2 offset:55120
	v_add_f32_e32 v2, v11, v249
	ds_write_b32 v237, v2 offset:56160
	v_add_f32_e32 v2, v12, v250
	ds_write_b32 v237, v2 offset:57200
	v_add_f32_e32 v2, v13, v251
	ds_write_b32 v237, v2 offset:58240
	v_lshlrev_b32_e32 v12, 16, v82
	v_lshl_add_u64 v[10:11], v[136:137], 0, s[12:13]
	s_waitcnt vmcnt(0)
	v_add_f32_e32 v2, v14, v110
	ds_write_b32 v237, v2 offset:63440
	v_add_f32_e32 v2, v15, v111
	ds_write_b32 v237, v2 offset:64480
	v_add_f32_e32 v2, v16, v112
	ds_write_b32 v237, v2 offset:65520
	v_add_f32_e32 v2, v17, v113
	ds_write_b32 v238, v2 offset:61360
	s_waitcnt lgkmcnt(0)
	s_barrier
; #define LAS __attribute__((address_space(3)))
; __device__ __forceinline__ unsigned pk2(float lo, float hi) { unsigned r; asm("v_cvt_pk_bf16_f32 %0, %1, %2" : "=v"(r) : "v"(lo), "v"(hi)); return r; }
; __device__ __forceinline__ float bf_lo(unsigned u) { return __uint_as_float(u << 16); }
; __device__ __forceinline__ float bf_hi(unsigned u) { return __uint_as_float(u & 0xffff0000u); }
; __device__ __forceinline__ void phase_sgu(const Params& P, LAS unsigned char* lds, int layer_i) {
;     ...
; #pragma unroll
;         for (int i = 0; i < 8; ++i) { const int n = tid + 512 * i, row = n >> 5, cc = n & 31;
;             const f32x4 m0 = *(const LAS f32x4*)(lds + row * SG_MIX_STRIDE + cc * 32), m1 = *(const LAS f32x4*)(lds + row * SG_MIX_STRIDE + cc * 32 + 16);
;             const size_t o = (row0 + row) * DM + g * 256 + cc * 8;
;             const u32x4 u = uzr[i];
;             u32x4 y; y.x = pk2(bf_lo(u.x) * m0.x, bf_hi(u.x) * m0.y); y.y = pk2(bf_lo(u.y) * m0.z, bf_hi(u.y) * m0.w); y.z = pk2(bf_lo(u.z) * m1.x, bf_hi(u.z) * m1.y); y.w = pk2(bf_lo(u.w) * m1.z, bf_hi(u.w) * m1.w);
;             *(u32x4*)(Y + o) = y; }
	ds_read_b128 v[2:5], v239
	ds_read_b128 v[6:9], v239 offset:16
	s_waitcnt lgkmcnt(1)
	v_mul_f32_e32 v2, v2, v12
	v_and_b32_e32 v12, 0xffff0000, v82
	v_mul_f32_e32 v3, v3, v12
	v_cvt_pk_bf16_f32 v2, v2, v3
	v_lshlrev_b32_e32 v3, 16, v83
	v_mul_f32_e32 v3, v4, v3
	v_and_b32_e32 v4, 0xffff0000, v83
	v_mul_f32_e32 v4, v5, v4
	v_cvt_pk_bf16_f32 v3, v3, v4
	v_lshlrev_b32_e32 v4, 16, v84
	v_and_b32_e32 v5, 0xffff0000, v84
	s_waitcnt lgkmcnt(0)
	v_mul_f32_e32 v4, v6, v4
	v_mul_f32_e32 v5, v7, v5
	v_cvt_pk_bf16_f32 v4, v4, v5
	v_lshlrev_b32_e32 v5, 16, v85
	v_and_b32_e32 v6, 0xffff0000, v85
	v_mul_f32_e32 v5, v8, v5
	v_mul_f32_e32 v6, v9, v6
	v_cvt_pk_bf16_f32 v5, v5, v6
	v_lshl_add_u64 v[6:7], v[10:11], 0, v[176:177]
	global_store_dwordx4 v[6:7], v[2:5], off
	ds_read_b128 v[2:5], v240
	ds_read_b128 v[6:9], v240 offset:16
	v_lshlrev_b32_e32 v12, 16, v74
	s_waitcnt lgkmcnt(0)
	v_mul_f32_e32 v2, v2, v12
	v_and_b32_e32 v12, 0xffff0000, v74
	v_mul_f32_e32 v3, v3, v12
	v_cvt_pk_bf16_f32 v2, v2, v3
	v_lshlrev_b32_e32 v3, 16, v75
	v_mul_f32_e32 v3, v4, v3
	v_and_b32_e32 v4, 0xffff0000, v75
	v_mul_f32_e32 v4, v5, v4
	v_cvt_pk_bf16_f32 v3, v3, v4
	v_lshlrev_b32_e32 v4, 16, v76
	v_and_b32_e32 v5, 0xffff0000, v76
	v_mul_f32_e32 v4, v6, v4
	v_mul_f32_e32 v5, v7, v5
	v_cvt_pk_bf16_f32 v4, v4, v5
	v_lshlrev_b32_e32 v5, 16, v77
	v_and_b32_e32 v6, 0xffff0000, v77
	v_mul_f32_e32 v5, v8, v5
	v_mul_f32_e32 v6, v9, v6
	v_cvt_pk_bf16_f32 v5, v5, v6
	v_lshl_add_u64 v[6:7], v[10:11], 0, v[174:175]
	global_store_dwordx4 v[6:7], v[2:5], off
	ds_read_b128 v[2:5], v241
	ds_read_b128 v[6:9], v241 offset:16
	v_lshlrev_b32_e32 v12, 16, v70
	s_waitcnt lgkmcnt(0)
	v_mul_f32_e32 v2, v2, v12
	v_and_b32_e32 v12, 0xffff0000, v70
	v_mul_f32_e32 v3, v3, v12
	v_cvt_pk_bf16_f32 v2, v2, v3
	v_lshlrev_b32_e32 v3, 16, v71
	v_mul_f32_e32 v3, v4, v3
	v_and_b32_e32 v4, 0xffff0000, v71
	v_mul_f32_e32 v4, v5, v4
	v_cvt_pk_bf16_f32 v3, v3, v4
	v_lshlrev_b32_e32 v4, 16, v72
	v_and_b32_e32 v5, 0xffff0000, v72
	v_mul_f32_e32 v4, v6, v4
	v_mul_f32_e32 v5, v7, v5
	v_cvt_pk_bf16_f32 v4, v4, v5
	v_lshlrev_b32_e32 v5, 16, v73
	v_and_b32_e32 v6, 0xffff0000, v73
	v_mul_f32_e32 v5, v8, v5
	v_mul_f32_e32 v6, v9, v6
	v_cvt_pk_bf16_f32 v5, v5, v6
	v_lshl_add_u64 v[6:7], v[10:11], 0, v[172:173]
	global_store_dwordx4 v[6:7], v[2:5], off
	ds_read_b128 v[2:5], v242
	ds_read_b128 v[6:9], v242 offset:16
	v_lshlrev_b32_e32 v12, 16, v66
	s_waitcnt lgkmcnt(0)
	v_mul_f32_e32 v2, v2, v12
	v_and_b32_e32 v12, 0xffff0000, v66
	v_mul_f32_e32 v3, v3, v12
	v_cvt_pk_bf16_f32 v2, v2, v3
	v_lshlrev_b32_e32 v3, 16, v67
	v_mul_f32_e32 v3, v4, v3
	v_and_b32_e32 v4, 0xffff0000, v67
	v_mul_f32_e32 v4, v5, v4
	v_cvt_pk_bf16_f32 v3, v3, v4
	v_lshlrev_b32_e32 v4, 16, v68
	v_and_b32_e32 v5, 0xffff0000, v68
	v_mul_f32_e32 v4, v6, v4
	v_mul_f32_e32 v5, v7, v5
	v_cvt_pk_bf16_f32 v4, v4, v5
	v_lshlrev_b32_e32 v5, 16, v69
	v_and_b32_e32 v6, 0xffff0000, v69
	v_mul_f32_e32 v5, v8, v5
	v_mul_f32_e32 v6, v9, v6
	v_cvt_pk_bf16_f32 v5, v5, v6
	v_lshl_add_u64 v[6:7], v[10:11], 0, v[170:171]
	global_store_dwordx4 v[6:7], v[2:5], off
	ds_read_b128 v[2:5], v243
	ds_read_b128 v[6:9], v243 offset:16
	v_lshlrev_b32_e32 v12, 16, v90
	s_waitcnt lgkmcnt(0)
	v_mul_f32_e32 v2, v2, v12
	v_and_b32_e32 v12, 0xffff0000, v90
	v_mul_f32_e32 v3, v3, v12
	v_cvt_pk_bf16_f32 v2, v2, v3
	v_lshlrev_b32_e32 v3, 16, v91
	v_mul_f32_e32 v3, v4, v3
	v_and_b32_e32 v4, 0xffff0000, v91
	v_mul_f32_e32 v4, v5, v4
	v_cvt_pk_bf16_f32 v3, v3, v4
	v_lshlrev_b32_e32 v4, 16, v92
	v_and_b32_e32 v5, 0xffff0000, v92
	v_mul_f32_e32 v4, v6, v4
	v_mul_f32_e32 v5, v7, v5
	v_cvt_pk_bf16_f32 v4, v4, v5
	v_lshlrev_b32_e32 v5, 16, v93
	v_and_b32_e32 v6, 0xffff0000, v93
	v_mul_f32_e32 v5, v8, v5
	v_mul_f32_e32 v6, v9, v6
	v_cvt_pk_bf16_f32 v5, v5, v6
	v_lshl_add_u64 v[6:7], v[10:11], 0, v[168:169]
	global_store_dwordx4 v[6:7], v[2:5], off
	ds_read_b128 v[2:5], v244
	ds_read_b128 v[6:9], v244 offset:16
	v_lshlrev_b32_e32 v12, 16, v86
	s_waitcnt lgkmcnt(0)
	v_mul_f32_e32 v2, v2, v12
	v_and_b32_e32 v12, 0xffff0000, v86
	v_mul_f32_e32 v3, v3, v12
	v_cvt_pk_bf16_f32 v2, v2, v3
	v_lshlrev_b32_e32 v3, 16, v87
	v_mul_f32_e32 v3, v4, v3
	v_and_b32_e32 v4, 0xffff0000, v87
	v_mul_f32_e32 v4, v5, v4
	v_cvt_pk_bf16_f32 v3, v3, v4
	v_lshlrev_b32_e32 v4, 16, v88
	v_and_b32_e32 v5, 0xffff0000, v88
	v_mul_f32_e32 v4, v6, v4
	v_mul_f32_e32 v5, v7, v5
	v_cvt_pk_bf16_f32 v4, v4, v5
	v_lshlrev_b32_e32 v5, 16, v89
	v_and_b32_e32 v6, 0xffff0000, v89
	v_mul_f32_e32 v5, v8, v5
	v_mul_f32_e32 v6, v9, v6
	v_cvt_pk_bf16_f32 v5, v5, v6
	v_lshl_add_u64 v[6:7], v[10:11], 0, v[166:167]
	global_store_dwordx4 v[6:7], v[2:5], off
	ds_read_b128 v[2:5], v245
	ds_read_b128 v[6:9], v245 offset:16
	v_lshlrev_b32_e32 v12, 16, v78
	s_waitcnt lgkmcnt(0)
	v_mul_f32_e32 v2, v2, v12
	v_and_b32_e32 v12, 0xffff0000, v78
	v_mul_f32_e32 v3, v3, v12
	v_cvt_pk_bf16_f32 v2, v2, v3
	v_lshlrev_b32_e32 v3, 16, v79
	v_mul_f32_e32 v3, v4, v3
	v_and_b32_e32 v4, 0xffff0000, v79
	v_mul_f32_e32 v4, v5, v4
	v_cvt_pk_bf16_f32 v3, v3, v4
	v_lshlrev_b32_e32 v4, 16, v80
	v_and_b32_e32 v5, 0xffff0000, v80
	v_mul_f32_e32 v4, v6, v4
	v_mul_f32_e32 v5, v7, v5
	v_cvt_pk_bf16_f32 v4, v4, v5
	v_lshlrev_b32_e32 v5, 16, v81
	v_and_b32_e32 v6, 0xffff0000, v81
	v_mul_f32_e32 v5, v8, v5
	v_mul_f32_e32 v6, v9, v6
	v_cvt_pk_bf16_f32 v5, v5, v6
	v_lshl_add_u64 v[6:7], v[10:11], 0, v[164:165]
	global_store_dwordx4 v[6:7], v[2:5], off
	ds_read_b128 v[2:5], v246
	ds_read_b128 v[6:9], v246 offset:16
	v_lshlrev_b32_e32 v12, 16, v94
	s_waitcnt lgkmcnt(0)
	v_mul_f32_e32 v2, v2, v12
	v_and_b32_e32 v12, 0xffff0000, v94
	v_mul_f32_e32 v3, v3, v12
	v_cvt_pk_bf16_f32 v2, v2, v3
	v_lshlrev_b32_e32 v3, 16, v95
	v_mul_f32_e32 v3, v4, v3
	v_and_b32_e32 v4, 0xffff0000, v95
	v_mul_f32_e32 v4, v5, v4
	v_cvt_pk_bf16_f32 v3, v3, v4
	v_lshlrev_b32_e32 v4, 16, v96
	v_and_b32_e32 v5, 0xffff0000, v96
	v_mul_f32_e32 v4, v6, v4
	v_mul_f32_e32 v5, v7, v5
	v_cvt_pk_bf16_f32 v4, v4, v5
	v_lshlrev_b32_e32 v5, 16, v97
	v_and_b32_e32 v6, 0xffff0000, v97
	v_mul_f32_e32 v5, v8, v5
	v_mul_f32_e32 v6, v9, v6
	v_cvt_pk_bf16_f32 v5, v5, v6
	v_lshl_add_u64 v[6:7], v[10:11], 0, v[162:163]
	global_store_dwordx4 v[6:7], v[2:5], off
	s_waitcnt lgkmcnt(0)
	s_barrier
	s_cbranch_scc1 .LBB0_110

; __device__ __forceinline__ void phase_attn_items(const Params& P, LAS unsigned char* lds) {
;     ...
;         const int dlog = 2 * pat, r = pat == 0 ? 0 : (pat == 1 ? rc >> 2 : rc), ch8 = pat == 0 ? rc : (pat == 1 ? rc & 3 : 0);
;         const int ntile = (SEQ >> dlog) >> 5, ql = lane & 31, h = lane >> 5;
;         const size_t rowbase = (size_t)b * SEQ;
;         const size_t hb = (size_t)hh * 256;
;     ...
;         const int trow = (tid >> 4) & 31, tch = tid & 15;
;         const unsigned roff = (unsigned)((trow << dlog) * AW + tch * 8) * 2u;
;         const unsigned loff = off_b(trow, tch);
;         u32x4 kk[12];
; #pragma unroll
;         for (int i = 0; i < 12; ++i) { const int T = 8 * ch8 - 2 + i; if (T >= 0 && T < ntile) kk[i] = *(const u32x4*)(TILE_BASE(Kb, T) + roff); else kk[i] = (u32x4){0u, 0u, 0u, 0u}; }
.LBB0_125:
	s_andn2_b64 vcc, exec, s[24:25]
	s_cbranch_vccnz .LBB0_114
	s_lshl_b32 s98, s26, 1
	s_ashr_i32 s2, s9, 2
	s_and_b32 s3, s9, 3
	s_cmp_eq_u32 s26, 1
	s_cselect_b32 s2, s2, s9
	s_cselect_b32 s3, s3, 0
	s_cmp_eq_u32 s26, 0
	s_cselect_b32 s30, 0, s2
	s_cselect_b32 s99, s9, s3
	s_ashr_i32 s13, s12, 31
	s_lshl_b64 s[2:3], s[12:13], 12
	s_ashr_i32 s17, s16, 31
	s_lshl_b32 s13, s99, 3
	s_ashr_i32 s33, s30, 31
	s_lshr_b32 s27, 0x80, s98
	s_lshl_b64 s[44:45], s[16:17], 8
	s_add_i32 s20, s13, -2
	v_readlane_b32 s5, v247, 5
	s_add_u32 s24, s5, s44
	v_readlane_b32 s5, v247, 6
	s_addc_u32 s25, s5, s45
	s_add_u32 s42, s2, s30
	s_addc_u32 s43, s3, s33
	v_lshlrev_b32_e32 v0, s98, v167
	s_cmp_gt_i32 s99, 0
	v_lshl_or_b32 v0, v0, 11, v168
	s_cselect_b64 s[2:3], -1, 0
	s_cmp_le_i32 s13, s27
	v_lshl_add_u64 v[50:51], s[24:25], 0, v[0:1]
	s_cselect_b64 s[24:25], -1, 0
	s_and_b64 s[2:3], s[2:3], s[24:25]
	v_cndmask_b32_e64 v3, 0, 1, s[2:3]
	s_mov_b32 s4, s90
	v_mov_b32_e32 v2, 0
	v_cmp_ne_u32_e64 s[40:41], 1, v3
	s_andn2_b64 vcc, exec, s[2:3]
	v_mov_b32_e32 v6, 0
	v_mov_b32_e32 v7, 0
	v_mov_b32_e32 v8, 0
	v_mov_b32_e32 v9, 0
	s_cbranch_vccnz .LBB0_128
	s_lshl_b32 s30, s20, 5
	s_lshl_b64 s[2:3], s[30:31], s98
	s_add_u32 s2, s2, s42
	s_addc_u32 s3, s3, s43
	s_lshl_b64 s[2:3], s[2:3], 11
	v_lshl_add_u64 v[4:5], v[50:51], 0, s[2:3]
	global_load_dwordx4 v[6:9], v[4:5], off
.LBB0_128:
	s_mov_b32 s59, s91
	s_mov_b32 s58, s78
	s_add_i32 s90, s13, -1
	s_and_b64 vcc, exec, s[40:41]
	v_mov_b32_e32 v10, 0
	v_mov_b32_e32 v11, 0
	v_mov_b32_e32 v12, 0
	v_mov_b32_e32 v13, 0
	s_cbranch_vccnz .LBB0_130
	s_lshl_b32 s30, s90, 5
	s_lshl_b64 s[2:3], s[30:31], s98
	s_add_u32 s2, s2, s42
	s_addc_u32 s3, s3, s43
	s_lshl_b64 s[2:3], s[2:3], 11
	v_lshl_add_u64 v[4:5], v[50:51], 0, s[2:3]
	global_load_dwordx4 v[10:13], v[4:5], off
.LBB0_130:
	s_cmp_lt_i32 s13, s27
	s_mov_b32 s78, s37
	s_mov_b32 s91, s36
	s_cselect_b64 s[46:47], -1, 0
	s_cmp_ge_i32 s13, s27
	v_mov_b32_e32 v3, 0
	v_mov_b32_e32 v4, 0
	v_mov_b32_e32 v5, 0
	s_cbranch_scc1 .LBB0_132
	s_lshl_b32 s30, s99, 8
	s_lshl_b64 s[2:3], s[30:31], s98
	s_add_u32 s2, s2, s42
	s_addc_u32 s3, s3, s43
	s_lshl_b64 s[2:3], s[2:3], 11
	v_lshl_add_u64 v[2:3], v[50:51], 0, s[2:3]
	global_load_dwordx4 v[2:5], v[2:3], off
.LBB0_132:
	s_or_b32 s3, s13, 1
	s_cmp_lt_i32 s3, s27
	s_mov_b64 s[36:37], s[88:89]
	v_mov_b32_e32 v14, 0
	s_cselect_b64 s[48:49], -1, 0
	s_cmp_ge_i32 s3, s27
	v_mov_b32_e32 v18, 0
	v_mov_b32_e32 v19, 0
	v_mov_b32_e32 v20, 0
	v_mov_b32_e32 v21, 0
	s_cbranch_scc1 .LBB0_134
	s_lshl_b32 s30, s3, 5
	s_lshl_b64 s[24:25], s[30:31], s98
	s_add_u32 s24, s24, s42
	s_addc_u32 s25, s25, s43
	s_lshl_b64 s[24:25], s[24:25], 11
	v_lshl_add_u64 v[16:17], v[50:51], 0, s[24:25]
	global_load_dwordx4 v[18:21], v[16:17], off
.LBB0_134:
	s_or_b32 s89, s13, 2
	s_cmp_lt_i32 s89, s27
	s_mov_b64 s[86:87], s[68:69]
	s_cselect_b64 s[50:51], -1, 0
	s_cmp_ge_i32 s89, s27
	v_mov_b32_e32 v15, 0
	v_mov_b32_e32 v16, 0
	v_mov_b32_e32 v17, 0
	s_cbranch_scc1 .LBB0_136
	s_lshl_b32 s30, s89, 5
	s_lshl_b64 s[24:25], s[30:31], s98
	s_add_u32 s24, s24, s42
	s_addc_u32 s25, s25, s43
	s_lshl_b64 s[24:25], s[24:25], 11
	v_lshl_add_u64 v[14:15], v[50:51], 0, s[24:25]
	global_load_dwordx4 v[14:17], v[14:15], off
.LBB0_136:
	s_or_b32 s33, s13, 3
	s_cmp_lt_i32 s33, s27
	s_mov_b64 s[68:69], s[96:97]
	v_mov_b32_e32 v22, 0
	s_cselect_b64 s[52:53], -1, 0
	s_cmp_ge_i32 s33, s27
	v_mov_b32_e32 v26, 0
	v_mov_b32_e32 v27, 0
	v_mov_b32_e32 v28, 0
	v_mov_b32_e32 v29, 0
	s_cbranch_scc1 .LBB0_138
	s_lshl_b32 s30, s33, 5
	s_lshl_b64 s[24:25], s[30:31], s98
	s_add_u32 s24, s24, s42
	s_addc_u32 s25, s25, s43
	s_lshl_b64 s[24:25], s[24:25], 11
	v_lshl_add_u64 v[24:25], v[50:51], 0, s[24:25]
	global_load_dwordx4 v[26:29], v[24:25], off
.LBB0_138:
	s_or_b32 s77, s13, 4
	s_cmp_lt_i32 s77, s27
	s_mov_b64 s[96:97], s[92:93]
	s_cselect_b64 s[54:55], -1, 0
	s_cmp_ge_i32 s77, s27
	v_mov_b32_e32 v23, 0
	v_mov_b32_e32 v24, 0
	v_mov_b32_e32 v25, 0
	s_cbranch_scc1 .LBB0_140
	s_lshl_b32 s30, s77, 5
	s_lshl_b64 s[24:25], s[30:31], s98
	s_add_u32 s24, s24, s42
	s_addc_u32 s25, s25, s43
	s_lshl_b64 s[24:25], s[24:25], 11
	v_lshl_add_u64 v[22:23], v[50:51], 0, s[24:25]
	global_load_dwordx4 v[22:25], v[22:23], off
.LBB0_140:
	s_or_b32 s92, s13, 5
	s_cmp_lt_i32 s92, s27
	v_mov_b32_e32 v30, 0
	s_cselect_b64 s[56:57], -1, 0
	s_cmp_ge_i32 s92, s27
	v_mov_b32_e32 v34, 0
	v_mov_b32_e32 v35, 0
	v_mov_b32_e32 v36, 0
	v_mov_b32_e32 v37, 0
	s_cbranch_scc1 .LBB0_142
	s_lshl_b32 s30, s92, 5
	s_lshl_b64 s[24:25], s[30:31], s98
	s_add_u32 s24, s24, s42
	s_addc_u32 s25, s25, s43
	s_lshl_b64 s[24:25], s[24:25], 11
	v_lshl_add_u64 v[32:33], v[50:51], 0, s[24:25]
	global_load_dwordx4 v[34:37], v[32:33], off
.LBB0_142:
	s_or_b32 s2, s13, 6
	s_cmp_lt_i32 s2, s27
	s_cselect_b64 s[60:61], -1, 0
	s_cmp_ge_i32 s2, s27
	v_mov_b32_e32 v31, 0
	v_mov_b32_e32 v32, 0
	v_mov_b32_e32 v33, 0
	s_cbranch_scc1 .LBB0_144
	s_lshl_b32 s30, s2, 5
	s_lshl_b64 s[24:25], s[30:31], s98
	s_add_u32 s24, s24, s42
	s_addc_u32 s25, s25, s43
	s_lshl_b64 s[24:25], s[24:25], 11
	v_lshl_add_u64 v[30:31], v[50:51], 0, s[24:25]
	global_load_dwordx4 v[30:33], v[30:31], off
.LBB0_144:
	s_or_b32 s93, s13, 7
	s_cmp_lt_i32 s93, s27
	s_mov_b32 s5, s94
	v_mov_b32_e32 v38, 0
	s_cselect_b64 s[24:25], -1, 0
	s_cmp_ge_i32 s93, s27
	v_mov_b32_e32 v42, 0
	v_mov_b32_e32 v43, 0
	v_mov_b32_e32 v44, 0
	v_mov_b32_e32 v45, 0
	s_cbranch_scc1 .LBB0_146
	s_lshl_b32 s30, s93, 5
	s_lshl_b64 s[64:65], s[30:31], s98
	s_add_u32 s64, s64, s42
	s_addc_u32 s65, s65, s43
	s_lshl_b64 s[64:65], s[64:65], 11
	v_lshl_add_u64 v[40:41], v[50:51], 0, s[64:65]
	global_load_dwordx4 v[42:45], v[40:41], off
; #define LAS __attribute__((address_space(3)))
; __device__ __forceinline__ void phase_attn_items(const Params& P, LAS unsigned char* lds) {
;     ...
;         u32x4 kk[12];
; #pragma unroll
;         for (int i = 0; i < 12; ++i) { const int T = 8 * ch8 - 2 + i; if (T >= 0 && T < ntile) kk[i] = *(const u32x4*)(TILE_BASE(Kb, T) + roff); else kk[i] = (u32x4){0u, 0u, 0u, 0u}; }
;         const int qt = 8 * ch8 + wave;
;         const size_t qrow = rowbase + ((size_t)(32 * qt + ql) << dlog) + r;
;         bf16x8 qf[8];
;         { const bf16_t* Qp = Q + qrow * AW + hh * 128 + 8 * h;
; #pragma unroll
;           for (int ks = 0; ks < 8; ++ks) qf[ks] = *(const bf16x8*)(Qp + 16 * ks); }
; #pragma unroll
;         for (int i = 0; i < 12; ++i) *(LAS u32x4*)(lds + i * 8192 + loff) = kk[i];
;         u32x4 vv[12];
; #pragma unroll
;         for (int i = 0; i < 12; ++i) { const int T = 8 * ch8 - 2 + i; if (T >= 0 && T < ntile) vv[i] = *(const u32x4*)(TILE_BASE(Vb, T) + roff); else vv[i] = (u32x4){0u, 0u, 0u, 0u}; }
.LBB0_146:
	s_add_i32 s94, s13, 8
	s_cmp_lt_i32 s94, s27
	s_mov_b32 s88, s95
	s_cselect_b64 s[64:65], -1, 0
	s_cmp_ge_i32 s94, s27
	v_mov_b32_e32 v39, 0
	v_mov_b32_e32 v40, 0
	v_mov_b32_e32 v41, 0
	s_cbranch_scc1 .LBB0_148
	s_lshl_b32 s30, s94, 5
	s_lshl_b64 s[66:67], s[30:31], s98
	s_add_u32 s66, s66, s42
	s_addc_u32 s67, s67, s43
	s_lshl_b64 s[66:67], s[66:67], 11
	v_lshl_add_u64 v[38:39], v[50:51], 0, s[66:67]
	global_load_dwordx4 v[38:41], v[38:39], off
.LBB0_148:
	s_add_i32 s95, s13, 9
	s_cmp_lt_i32 s95, s27
	v_mov_b32_e32 v82, 0
	s_cselect_b64 s[66:67], -1, 0
	s_cmp_ge_i32 s95, s27
	v_mov_b32_e32 v46, 0
	v_mov_b32_e32 v47, 0
	v_mov_b32_e32 v48, 0
	v_mov_b32_e32 v49, 0
	s_cbranch_scc1 .LBB0_150
	s_lshl_b32 s30, s95, 5
	s_lshl_b64 s[72:73], s[30:31], s98
	s_add_u32 s72, s72, s42
	s_addc_u32 s73, s73, s43
	s_lshl_b64 s[72:73], s[72:73], 11
	v_lshl_add_u64 v[46:47], v[50:51], 0, s[72:73]
	global_load_dwordx4 v[46:49], v[46:47], off
.LBB0_150:
	v_readlane_b32 s30, v247, 13
	v_and_b32_e32 v165, 31, v174
	s_add_i32 s13, s13, s30
	v_lshl_or_b32 v50, s13, 5, v165
	v_ashrrev_i32_e32 v51, 31, v50
	v_lshlrev_b64 v[50:51], s98, v[50:51]
	v_lshl_add_u64 v[162:163], v[50:51], 0, s[42:43]
	v_readlane_b32 s72, v247, 3
	v_lshlrev_b64 v[50:51], 11, v[162:163]
	v_readlane_b32 s73, v247, 4
	v_ashrrev_i32_e32 v164, 5, v174
	v_lshlrev_b32_e32 v52, 3, v164
	v_lshl_add_u64 v[50:51], s[72:73], 0, v[50:51]
	s_lshl_b32 s72, s16, 7
	s_ashr_i32 s73, s72, 31
	v_lshl_add_u64 v[50:51], s[72:73], 1, v[50:51]
	v_ashrrev_i32_e32 v53, 31, v52
	v_lshl_add_u64 v[50:51], v[52:53], 1, v[50:51]
	global_load_dwordx4 v[158:161], v[50:51], off
	global_load_dwordx4 v[154:157], v[50:51], off offset:32
	global_load_dwordx4 v[150:153], v[50:51], off offset:64
	global_load_dwordx4 v[146:149], v[50:51], off offset:96
	global_load_dwordx4 v[142:145], v[50:51], off offset:128
	global_load_dwordx4 v[138:141], v[50:51], off offset:160
	global_load_dwordx4 v[134:137], v[50:51], off offset:192
	global_load_dwordx4 v[130:133], v[50:51], off offset:224
	v_readlane_b32 s30, v247, 7
	s_add_u32 s44, s30, s44
	v_readlane_b32 s30, v247, 8
	s_addc_u32 s45, s30, s45
	s_waitcnt vmcnt(0) lgkmcnt(0)
	ds_write_b128 v169, v[6:9]
	ds_write_b128 v169, v[10:13] offset:8192
	ds_write_b128 v169, v[2:5] offset:16384
	ds_write_b128 v169, v[18:21] offset:24576
	ds_write_b128 v169, v[14:17] offset:32768
	ds_write_b128 v169, v[26:29] offset:40960
	ds_write_b128 v169, v[22:25] offset:49152
	ds_write_b128 v169, v[34:37] offset:57344
	ds_write_b128 v170, v[30:33]
	ds_write_b128 v171, v[42:45]
	ds_write_b128 v172, v[38:41]
	ds_write_b128 v173, v[46:49]
	v_lshl_add_u64 v[4:5], s[44:45], 0, v[0:1]
	s_and_b64 vcc, exec, s[40:41]
	v_mov_b32_e32 v83, 0
	v_mov_b32_e32 v84, 0
	v_mov_b32_e32 v85, 0
	s_cbranch_vccnz .LBB0_152
	s_lshl_b32 s30, s20, 5
	s_lshl_b64 s[44:45], s[30:31], s98
	s_add_u32 s44, s44, s42
	s_addc_u32 s45, s45, s43
	s_lshl_b64 s[44:45], s[44:45], 11
	v_lshl_add_u64 v[2:3], v[4:5], 0, s[44:45]
	global_load_dwordx4 v[82:85], v[2:3], off
.LBB0_152:
	v_mov_b32_e32 v86, 0
	s_and_b64 vcc, exec, s[40:41]
	v_mov_b32_e32 v90, 0
	v_mov_b32_e32 v91, 0
	v_mov_b32_e32 v92, 0
	v_mov_b32_e32 v93, 0
	s_cbranch_vccnz .LBB0_154
	s_lshl_b32 s30, s90, 5
	s_lshl_b64 s[40:41], s[30:31], s98
	s_add_u32 s40, s40, s42
	s_addc_u32 s41, s41, s43
	s_lshl_b64 s[40:41], s[40:41], 11
	v_lshl_add_u64 v[2:3], v[4:5], 0, s[40:41]
	global_load_dwordx4 v[90:93], v[2:3], off
.LBB0_154:
	s_andn2_b64 vcc, exec, s[46:47]
	v_mov_b32_e32 v87, 0
	v_mov_b32_e32 v88, 0
	v_mov_b32_e32 v89, 0
	s_cbranch_vccnz .LBB0_156
	s_lshl_b32 s30, s99, 8
	s_lshl_b64 s[40:41], s[30:31], s98
	s_add_u32 s40, s40, s42
	s_addc_u32 s41, s41, s43
	s_lshl_b64 s[40:41], s[40:41], 11
	v_lshl_add_u64 v[2:3], v[4:5], 0, s[40:41]
	global_load_dwordx4 v[86:89], v[2:3], off
; __device__ __forceinline__ void phase_attn_items(const Params& P, LAS unsigned char* lds) {
;     ...
;         u32x4 vv[12];
; #pragma unroll
;         for (int i = 0; i < 12; ++i) { const int T = 8 * ch8 - 2 + i; if (T >= 0 && T < ntile) vv[i] = *(const u32x4*)(TILE_BASE(Vb, T) + roff); else vv[i] = (u32x4){0u, 0u, 0u, 0u}; }
.LBB0_156:
	v_mov_b32_e32 v94, 0
	s_andn2_b64 vcc, exec, s[48:49]
	v_mov_b32_e32 v98, 0
	v_mov_b32_e32 v99, 0
	v_mov_b32_e32 v100, 0
	v_mov_b32_e32 v101, 0
	s_mov_b32 s90, s4
	s_cbranch_vccnz .LBB0_158
	s_lshl_b32 s30, s3, 5
	s_lshl_b64 s[40:41], s[30:31], s98
	s_add_u32 s40, s40, s42
	s_addc_u32 s41, s41, s43
	s_lshl_b64 s[40:41], s[40:41], 11
	v_lshl_add_u64 v[2:3], v[4:5], 0, s[40:41]
	global_load_dwordx4 v[98:101], v[2:3], off
.LBB0_158:
	s_andn2_b64 vcc, exec, s[50:51]
	v_mov_b32_e32 v95, 0
	v_mov_b32_e32 v96, 0
	v_mov_b32_e32 v97, 0
	s_cbranch_vccnz .LBB0_160
	s_lshl_b32 s30, s89, 5
	s_lshl_b64 s[40:41], s[30:31], s98
	s_add_u32 s40, s40, s42
	s_addc_u32 s41, s41, s43
	s_lshl_b64 s[40:41], s[40:41], 11
	v_lshl_add_u64 v[2:3], v[4:5], 0, s[40:41]
	global_load_dwordx4 v[94:97], v[2:3], off
.LBB0_160:
	v_mov_b32_e32 v102, 0
	s_andn2_b64 vcc, exec, s[52:53]
	v_mov_b32_e32 v106, 0
	v_mov_b32_e32 v107, 0
	v_mov_b32_e32 v108, 0
	v_mov_b32_e32 v109, 0
	s_cbranch_vccnz .LBB0_162
	s_lshl_b32 s30, s33, 5
	s_lshl_b64 s[40:41], s[30:31], s98
	s_add_u32 s40, s40, s42
	s_addc_u32 s41, s41, s43
	s_lshl_b64 s[40:41], s[40:41], 11
	v_lshl_add_u64 v[2:3], v[4:5], 0, s[40:41]
	global_load_dwordx4 v[106:109], v[2:3], off
.LBB0_162:
	s_andn2_b64 vcc, exec, s[54:55]
	v_mov_b32_e32 v103, 0
	v_mov_b32_e32 v104, 0
	v_mov_b32_e32 v105, 0
	s_cbranch_vccnz .LBB0_164
	s_lshl_b32 s30, s77, 5
	s_lshl_b64 s[40:41], s[30:31], s98
	s_add_u32 s40, s40, s42
	s_addc_u32 s41, s41, s43
	s_lshl_b64 s[40:41], s[40:41], 11
	v_lshl_add_u64 v[2:3], v[4:5], 0, s[40:41]
	global_load_dwordx4 v[102:105], v[2:3], off
.LBB0_164:
	v_mov_b32_e32 v110, 0
	s_andn2_b64 vcc, exec, s[56:57]
	v_mov_b32_e32 v114, 0
	v_mov_b32_e32 v115, 0
	v_mov_b32_e32 v116, 0
	v_mov_b32_e32 v117, 0
	s_cbranch_vccnz .LBB0_166
	s_lshl_b32 s30, s92, 5
	s_lshl_b64 s[40:41], s[30:31], s98
	s_add_u32 s40, s40, s42
	s_addc_u32 s41, s41, s43
	s_lshl_b64 s[40:41], s[40:41], 11
	v_lshl_add_u64 v[2:3], v[4:5], 0, s[40:41]
	global_load_dwordx4 v[114:117], v[2:3], off
.LBB0_166:
	s_andn2_b64 vcc, exec, s[60:61]
	v_mov_b32_e32 v111, 0
	v_mov_b32_e32 v112, 0
	v_mov_b32_e32 v113, 0
	s_cbranch_vccnz .LBB0_168
	s_lshl_b32 s30, s2, 5
	s_lshl_b64 s[2:3], s[30:31], s98
	s_add_u32 s2, s2, s42
	s_addc_u32 s3, s3, s43
	s_lshl_b64 s[2:3], s[2:3], 11
	v_lshl_add_u64 v[2:3], v[4:5], 0, s[2:3]
	global_load_dwordx4 v[110:113], v[2:3], off
.LBB0_168:
	v_mov_b32_e32 v118, 0
	s_andn2_b64 vcc, exec, s[24:25]
	v_mov_b32_e32 v122, 0
	v_mov_b32_e32 v123, 0
	v_mov_b32_e32 v124, 0
	v_mov_b32_e32 v125, 0
	s_cbranch_vccnz .LBB0_170
	s_lshl_b32 s30, s93, 5
	s_lshl_b64 s[2:3], s[30:31], s98
	s_add_u32 s2, s2, s42
	s_addc_u32 s3, s3, s43
	s_lshl_b64 s[2:3], s[2:3], 11
	v_lshl_add_u64 v[2:3], v[4:5], 0, s[2:3]
	global_load_dwordx4 v[122:125], v[2:3], off
.LBB0_170:
	s_andn2_b64 vcc, exec, s[64:65]
	v_mov_b32_e32 v119, 0
	v_mov_b32_e32 v120, 0
	v_mov_b32_e32 v121, 0
	s_cbranch_vccnz .LBB0_172
	s_lshl_b32 s30, s94, 5
	s_lshl_b64 s[2:3], s[30:31], s98
	s_add_u32 s2, s2, s42
	s_addc_u32 s3, s3, s43
	s_lshl_b64 s[2:3], s[2:3], 11
	v_lshl_add_u64 v[2:3], v[4:5], 0, s[2:3]
	global_load_dwordx4 v[118:121], v[2:3], off
.LBB0_172:
	v_mov_b32_e32 v2, 0
	s_andn2_b64 vcc, exec, s[66:67]
	v_mov_b32_e32 v126, 0
	v_mov_b32_e32 v127, 0
	v_mov_b32_e32 v128, 0
	v_mov_b32_e32 v129, 0
	s_mov_b64 s[92:93], s[96:97]
	s_cbranch_vccnz .LBB0_174
	s_lshl_b32 s30, s95, 5
	s_lshl_b64 s[2:3], s[30:31], s98
	s_add_u32 s2, s2, s42
	s_addc_u32 s3, s3, s43
	s_lshl_b64 s[2:3], s[2:3], 11
	v_lshl_add_u64 v[4:5], v[4:5], 0, s[2:3]
	global_load_dwordx4 v[126:129], v[4:5], off

; __device__ __forceinline__ unsigned pk2(float lo, float hi) { unsigned r; asm("v_cvt_pk_bf16_f32 %0, %1, %2" : "=v"(r) : "v"(lo), "v"(hi)); return r; }
; __device__ __forceinline__ void phase_attn_items(const Params& P, LAS unsigned char* lds) {
;     ...
;         const float inv = 1.f / sum;
;         bf16_t* op = OpB + (size_t)pat * MTOK * AW + qrow * AW + hh * 128 + 4 * h;
; #pragma unroll
;         for (int c = 0; c < 4; ++c)
; #pragma unroll
;             for (int g = 0; g < 4; ++g) { u32x2 w; w.x = pk2(O[c][4 * g] * inv, O[c][4 * g + 1] * inv); w.y = pk2(O[c][4 * g + 2] * inv, O[c][4 * g + 3] * inv);
;                 *(u32x2*)(op + 32 * c + 8 * g) = w; }
;         if (h == 0) LseB[(size_t)pat * MTOK * 8 + qrow * 8 + hh] = (mx + __builtin_amdgcn_logf(sum)) * LN2F;
.LBB0_195:
	v_add_f32_e32 v0, v81, v165
	v_div_scale_f32 v4, s[2:3], v0, v0, 1.0
	v_rcp_f32_e32 v5, v4
	s_ashr_i32 s27, s26, 31
	s_lshl_b64 s[2:3], s[26:27], 25
	v_readlane_b32 s4, v247, 9
	v_fma_f32 v6, -v4, v5, 1.0
	v_fmac_f32_e32 v5, v6, v5
	v_div_scale_f32 v6, vcc, 1.0, v0, 1.0
	v_mul_f32_e32 v7, v6, v5
	v_fma_f32 v8, -v4, v7, v6
	v_fmac_f32_e32 v7, v8, v5
	v_fma_f32 v4, -v4, v7, v6
	v_div_fmas_f32 v4, v4, v5, v7
	s_add_u32 s2, s4, s2
	v_readlane_b32 s4, v247, 10
	v_lshlrev_b64 v[2:3], 10, v[162:163]
	v_div_fixup_f32 v6, v4, v0, 1.0
	s_addc_u32 s3, s4, s3
	v_lshl_add_u64 v[2:3], v[2:3], 1, s[2:3]
	v_lshl_add_u64 v[2:3], s[72:73], 1, v[2:3]
	v_ashrrev_i32_e32 v165, 31, v164
	v_lshl_add_u64 v[2:3], v[164:165], 1, v[2:3]
	v_lshl_add_u64 v[2:3], v[164:165], 1, v[2:3]
	v_pk_mul_f32 v[64:65], v[64:65], v[6:7] op_sel_hi:[1,0]
	v_pk_mul_f32 v[66:67], v[66:67], v[6:7] op_sel_hi:[1,0]
	v_pk_mul_f32 v[68:69], v[68:69], v[6:7] op_sel_hi:[1,0]
	v_pk_mul_f32 v[70:71], v[70:71], v[6:7] op_sel_hi:[1,0]
	v_cvt_pk_bf16_f32 v192, v64, v65
	v_cvt_pk_bf16_f32 v193, v66, v67
	v_cvt_pk_bf16_f32 v194, v68, v69
	v_cvt_pk_bf16_f32 v195, v70, v71
	s_nop 1
	v_permlane32_swap_b32 v192, v194
	v_permlane32_swap_b32 v193, v195
	global_store_dwordx4 v[2:3], v[192:195], off
	v_pk_mul_f32 v[72:73], v[72:73], v[6:7] op_sel_hi:[1,0]
	v_pk_mul_f32 v[74:75], v[74:75], v[6:7] op_sel_hi:[1,0]
	v_pk_mul_f32 v[76:77], v[76:77], v[6:7] op_sel_hi:[1,0]
	v_pk_mul_f32 v[78:79], v[78:79], v[6:7] op_sel_hi:[1,0]
	v_cvt_pk_bf16_f32 v196, v72, v73
	v_cvt_pk_bf16_f32 v197, v74, v75
	v_cvt_pk_bf16_f32 v198, v76, v77
	v_cvt_pk_bf16_f32 v199, v78, v79
	s_nop 1
	v_permlane32_swap_b32 v196, v198
	v_permlane32_swap_b32 v197, v199
	global_store_dwordx4 v[2:3], v[196:199], off offset:32
	v_pk_mul_f32 v[48:49], v[48:49], v[6:7] op_sel_hi:[1,0]
	v_pk_mul_f32 v[50:51], v[50:51], v[6:7] op_sel_hi:[1,0]
	v_pk_mul_f32 v[52:53], v[52:53], v[6:7] op_sel_hi:[1,0]
	v_pk_mul_f32 v[54:55], v[54:55], v[6:7] op_sel_hi:[1,0]
	v_cvt_pk_bf16_f32 v200, v48, v49
	v_cvt_pk_bf16_f32 v201, v50, v51
	v_cvt_pk_bf16_f32 v202, v52, v53
	v_cvt_pk_bf16_f32 v203, v54, v55
	s_nop 1
	v_permlane32_swap_b32 v200, v202
	v_permlane32_swap_b32 v201, v203
	global_store_dwordx4 v[2:3], v[200:203], off offset:64
	v_pk_mul_f32 v[56:57], v[56:57], v[6:7] op_sel_hi:[1,0]
	v_pk_mul_f32 v[58:59], v[58:59], v[6:7] op_sel_hi:[1,0]
	v_pk_mul_f32 v[60:61], v[60:61], v[6:7] op_sel_hi:[1,0]
	v_pk_mul_f32 v[62:63], v[62:63], v[6:7] op_sel_hi:[1,0]
	v_cvt_pk_bf16_f32 v204, v56, v57
	v_cvt_pk_bf16_f32 v205, v58, v59
	v_cvt_pk_bf16_f32 v206, v60, v61
	v_cvt_pk_bf16_f32 v207, v62, v63
	s_nop 1
	v_permlane32_swap_b32 v204, v206
	v_permlane32_swap_b32 v205, v207
	global_store_dwordx4 v[2:3], v[204:207], off offset:96
	v_pk_mul_f32 v[32:33], v[32:33], v[6:7] op_sel_hi:[1,0]
	v_pk_mul_f32 v[34:35], v[34:35], v[6:7] op_sel_hi:[1,0]
	v_pk_mul_f32 v[36:37], v[36:37], v[6:7] op_sel_hi:[1,0]
	v_pk_mul_f32 v[38:39], v[38:39], v[6:7] op_sel_hi:[1,0]
	v_cvt_pk_bf16_f32 v192, v32, v33
	v_cvt_pk_bf16_f32 v193, v34, v35
	v_cvt_pk_bf16_f32 v194, v36, v37
	v_cvt_pk_bf16_f32 v195, v38, v39
	s_nop 1
	v_permlane32_swap_b32 v192, v194
	v_permlane32_swap_b32 v193, v195
	global_store_dwordx4 v[2:3], v[192:195], off offset:128
	v_pk_mul_f32 v[40:41], v[40:41], v[6:7] op_sel_hi:[1,0]
	v_pk_mul_f32 v[42:43], v[42:43], v[6:7] op_sel_hi:[1,0]
	v_pk_mul_f32 v[44:45], v[44:45], v[6:7] op_sel_hi:[1,0]
	v_pk_mul_f32 v[46:47], v[46:47], v[6:7] op_sel_hi:[1,0]
	v_cvt_pk_bf16_f32 v196, v40, v41
	v_cvt_pk_bf16_f32 v197, v42, v43
	v_cvt_pk_bf16_f32 v198, v44, v45
	v_cvt_pk_bf16_f32 v199, v46, v47
	s_nop 1
	v_permlane32_swap_b32 v196, v198
	v_permlane32_swap_b32 v197, v199
	global_store_dwordx4 v[2:3], v[196:199], off offset:160
	v_pk_mul_f32 v[16:17], v[16:17], v[6:7] op_sel_hi:[1,0]
	v_pk_mul_f32 v[18:19], v[18:19], v[6:7] op_sel_hi:[1,0]
	v_pk_mul_f32 v[20:21], v[20:21], v[6:7] op_sel_hi:[1,0]
	v_pk_mul_f32 v[22:23], v[22:23], v[6:7] op_sel_hi:[1,0]
	v_cvt_pk_bf16_f32 v200, v16, v17
	v_cvt_pk_bf16_f32 v201, v18, v19
	v_cvt_pk_bf16_f32 v202, v20, v21
	v_cvt_pk_bf16_f32 v203, v22, v23
	s_nop 1
	v_permlane32_swap_b32 v200, v202
	v_permlane32_swap_b32 v201, v203
	global_store_dwordx4 v[2:3], v[200:203], off offset:192
	v_pk_mul_f32 v[24:25], v[24:25], v[6:7] op_sel_hi:[1,0]
	v_pk_mul_f32 v[26:27], v[26:27], v[6:7] op_sel_hi:[1,0]
	v_pk_mul_f32 v[28:29], v[28:29], v[6:7] op_sel_hi:[1,0]
	v_pk_mul_f32 v[30:31], v[30:31], v[6:7] op_sel_hi:[1,0]
	v_cvt_pk_bf16_f32 v204, v24, v25
	v_cvt_pk_bf16_f32 v205, v26, v27
	v_cvt_pk_bf16_f32 v206, v28, v29
	v_cvt_pk_bf16_f32 v207, v30, v31
	s_nop 1
	v_permlane32_swap_b32 v204, v206
	v_permlane32_swap_b32 v205, v207
	global_store_dwordx4 v[2:3], v[204:207], off offset:224
	v_cmp_gt_u32_e32 vcc, 32, v174
	s_and_saveexec_b64 s[24:25], vcc
	s_cbranch_execz .LBB0_113
	v_log_f32_e32 v0, v0
	s_lshl_b64 s[2:3], s[26:27], 19
	v_readlane_b32 s4, v247, 11
	s_add_u32 s2, s4, s2
	v_readlane_b32 s4, v247, 12
	s_addc_u32 s3, s4, s3
	v_lshlrev_b64 v[2:3], 5, v[162:163]
	v_add_f32_e32 v0, v80, v0
	v_lshl_add_u64 v[2:3], s[2:3], 0, v[2:3]
	v_mul_f32_e32 v0, 0x3f317218, v0
	v_lshl_add_u64 v[2:3], s[16:17], 2, v[2:3]
	global_store_dword v[2:3], v0, off
	s_branch .LBB0_113

; __device__ __forceinline__ unsigned pk2(float lo, float hi) { unsigned r; asm("v_cvt_pk_bf16_f32 %0, %1, %2" : "=v"(r) : "v"(lo), "v"(hi)); return r; }
; __device__ __forceinline__ float bf_lo(unsigned u) { return __uint_as_float(u << 16); }
; __device__ __forceinline__ void phase_combine(const Params& P, int layer_i) {
;     ...
;             const int pos = s0 + pass * 32 + (tid2 >> 4); const size_t row = (size_t)b * SEQ + pos;
;             const float l0 = Lse[row * 8 + hh], l1 = Lse[(size_t)MTOK * 8 + row * 8 + hh], l2 = Lse[(size_t)2 * MTOK * 8 + row * 8 + hh];
;             const float lm = fmaxf(l0, fmaxf(l1, l2));
;             float e0 = fexp2((l0 - lm) * 1.4426950408889634f), e1 = fexp2((l1 - lm) * 1.4426950408889634f), e2 = fexp2((l2 - lm) * 1.4426950408889634f);
;             const float ei = 1.f / (e0 + e1 + e2); e0 *= ei; e1 *= ei; e2 *= ei;
;             const u32x4 a0 = *(const u32x4*)(Op + row * AW + col), a1 = *(const u32x4*)(Op + (size_t)MTOK * AW + row * AW + col), a2 = *(const u32x4*)(Op + (size_t)2 * MTOK * AW + row * AW + col);
;             const u32x4 zz = *(const u32x4*)(sza + row * AW + col);
;             u32x4 ya;
; #pragma unroll
;             for (int e = 0; e < 4; ++e) {
;                 const float lo = (e0 * bf_lo(a0[e]) + e1 * bf_lo(a1[e]) + e2 * bf_lo(a2[e])) * bf_lo(zz[e]);
;                 const float hi = (e0 * bf_hi(a0[e]) + e1 * bf_hi(a1[e]) + e2 * bf_hi(a2[e])) * bf_hi(zz[e]);
;                 ya[e] = pk2(lo, hi); }
;             *(u32x4*)(Y + row * DM + col) = ya;
;             const u32x4 pc = *(const u32x4*)(pp + row * AW + col);
;             u32x4 pm = (u32x4){0u, 0u, 0u, 0u}, pn = (u32x4){0u, 0u, 0u, 0u};
;             if (pos > 0) pm = *(const u32x4*)(pp + (row - 1) * AW + col);
;             if (pos < SEQ - 1) pn = *(const u32x4*)(pp + (row + 1) * AW + col);
;             const u32x4 gg = *(const u32x4*)(gz + row * AW + col);
;             u32x4 yb;
; #pragma unroll
;             for (int e = 0; e < 4; ++e) {
;                 const float lo = bf_lo(gg[e]) * (w0[2 * e] * bf_lo(pm[e]) + w1[2 * e] * bf_lo(pc[e]) + w2[2 * e] * bf_lo(pn[e]));
;                 const float hi = bf_hi(gg[e]) * (w0[2 * e + 1] * bf_hi(pm[e]) + w1[2 * e + 1] * bf_hi(pc[e]) + w2[2 * e + 1] * bf_hi(pn[e]));
;                 yb[e] = pk2(lo, hi); }
;             *(u32x4*)(Y + row * DM + AW + col) = yb;
.LBB0_254:
	s_or_b64 exec, exec, s[24:25]
	v_add_co_u32_e32 v32, vcc, 0x176e4000, v56
	s_waitcnt vmcnt(0) lgkmcnt(0)
	v_lshlrev_b32_e32 v35, 16, v26
	v_addc_co_u32_e32 v33, vcc, 0, v57, vcc
	global_load_dwordx4 v[56:59], v[32:33], off
	v_lshlrev_b32_e32 v33, 16, v22
	v_lshlrev_b32_e32 v32, 16, v18
	v_pk_mul_f32 v[32:33], v[54:55], v[32:33]
	v_and_b32_e32 v26, 0xffff0000, v26
	v_fma_f32 v32, v10, v35, v32
	v_add_f32_e32 v32, v32, v33
	v_and_b32_e32 v33, 0xffff0000, v22
	v_lshlrev_b32_e32 v22, 16, v27
	v_and_b32_e32 v27, 0xffff0000, v27
	s_add_i32 s6, s6, 64
	v_lshl_add_u64 v[36:37], v[36:37], 0, s[34:35]
	v_lshl_add_u64 v[38:39], v[38:39], 0, s[28:29]
	v_lshl_add_u64 v[40:41], v[40:41], 0, s[38:39]
	v_lshl_add_u64 v[42:43], v[42:43], 0, s[34:35]
	v_lshl_add_u64 v[44:45], v[44:45], 0, s[28:29]
	v_lshl_add_u64 v[46:47], v[46:47], 0, s[38:39]
	s_cmpk_eq_i32 s6, 0x200
	s_waitcnt vmcnt(0) lgkmcnt(0)
	v_lshlrev_b32_e32 v0, 16, v56
	v_mul_f32_e32 v0, v32, v0
	v_and_b32_e32 v32, 0xffff0000, v18
	v_pk_mul_f32 v[32:33], v[6:7], v[32:33]
	v_and_b32_e32 v35, 0xffff0000, v56
	v_fma_f32 v18, v11, v26, v32
	v_add_f32_e32 v18, v18, v33
	v_lshlrev_b32_e32 v33, 16, v23
	v_lshlrev_b32_e32 v32, 16, v19
	v_pk_mul_f32 v[32:33], v[52:53], v[32:33]
	v_mul_f32_e32 v18, v18, v35
	v_fma_f32 v22, v12, v22, v32
	v_cvt_pk_bf16_f32 v18, v0, v18
	v_lshlrev_b32_e32 v0, 16, v57
	v_add_f32_e32 v22, v22, v33
	v_mul_f32_e32 v0, v22, v0
	v_and_b32_e32 v23, 0xffff0000, v23
	v_and_b32_e32 v22, 0xffff0000, v19
	v_pk_mul_f32 v[22:23], v[8:9], v[22:23]
	v_and_b32_e32 v26, 0xffff0000, v57
	v_fma_f32 v19, v13, v27, v22
	v_add_f32_e32 v19, v19, v23
	v_lshlrev_b32_e32 v23, 16, v24
	v_lshlrev_b32_e32 v22, 16, v20
	v_mul_f32_e32 v19, v19, v26
	v_lshlrev_b32_e32 v26, 16, v28
	v_pk_mul_f32 v[22:23], v[50:51], v[22:23]
	v_cvt_pk_bf16_f32 v19, v0, v19
	v_lshlrev_b32_e32 v0, 16, v58
	v_fma_f32 v22, v14, v26, v22
	v_add_f32_e32 v22, v22, v23
	v_mul_f32_e32 v0, v22, v0
	v_and_b32_e32 v23, 0xffff0000, v24
	v_and_b32_e32 v22, 0xffff0000, v20
	v_and_b32_e32 v27, 0xffff0000, v28
	v_pk_mul_f32 v[22:23], v[2:3], v[22:23]
	v_and_b32_e32 v26, 0xffff0000, v58
	v_fma_f32 v20, v15, v27, v22
	v_add_f32_e32 v20, v20, v23
	v_lshlrev_b32_e32 v23, 16, v25
	v_lshlrev_b32_e32 v22, 16, v21
	v_lshlrev_b32_e32 v24, 16, v29
	v_pk_mul_f32 v[22:23], v[48:49], v[22:23]
	v_mul_f32_e32 v20, v20, v26
	v_fma_f32 v22, v16, v24, v22
	v_cvt_pk_bf16_f32 v20, v0, v20
	v_lshlrev_b32_e32 v0, 16, v59
	v_add_f32_e32 v22, v22, v23
	v_mul_f32_e32 v0, v22, v0
	v_and_b32_e32 v23, 0xffff0000, v25
	v_and_b32_e32 v22, 0xffff0000, v21
	v_and_b32_e32 v26, 0xffff0000, v29
	v_pk_mul_f32 v[22:23], v[4:5], v[22:23]
	v_and_b32_e32 v24, 0xffff0000, v59
	v_fma_f32 v21, v17, v26, v22
	v_add_f32_e32 v21, v21, v23
	v_add_co_u32_e32 v22, vcc, 0x96e4000, v30
	v_mul_f32_e32 v21, v21, v24
	s_nop 0
	v_addc_co_u32_e32 v23, vcc, 0, v31, vcc
	v_cvt_pk_bf16_f32 v21, v0, v21
	global_store_dwordx4 v[22:23], v[18:21], off offset:2048
	s_cbranch_scc1 .LBB0_252
.LBB0_255:
	s_nop 0
	v_lshl_add_u64 v[18:19], s[12:13], 0, v[46:47]
	v_add_co_u32_e32 v20, vcc, 0x1f6e4000, v18
	v_lshl_add_u64 v[56:57], s[12:13], 0, v[42:43]
	s_nop 0
	v_addc_co_u32_e32 v21, vcc, 0, v19, vcc
	global_load_dword v22, v[20:21], off
	v_add_co_u32_e32 v20, vcc, 0x1f764000, v18
	v_add_u32_e32 v0, s6, v34
	s_nop 0
	v_addc_co_u32_e32 v21, vcc, 0, v19, vcc
	v_add_co_u32_e32 v18, vcc, 0x1f7e4000, v18
	global_load_dword v20, v[20:21], off
	s_nop 0
	v_addc_co_u32_e32 v19, vcc, 0, v19, vcc
	global_load_dword v18, v[18:19], off
	s_waitcnt vmcnt(0) lgkmcnt(0)
	v_max3_f32 v19, v22, v20, v18
	v_sub_f32_e32 v21, v22, v19
	v_sub_f32_e32 v20, v20, v19
	v_mul_f32_e32 v21, 0x3fb8aa3b, v21
	v_mul_f32_e32 v20, 0x3fb8aa3b, v20
	v_sub_f32_e32 v18, v18, v19
	v_exp_f32_e32 v59, v21
	v_exp_f32_e32 v20, v20
	v_mul_f32_e32 v18, 0x3fb8aa3b, v18
	v_exp_f32_e32 v58, v18
	v_add_f32_e32 v18, v59, v20
	v_add_f32_e32 v18, v58, v18
	v_div_scale_f32 v19, s[2:3], v18, v18, 1.0
	v_rcp_f32_e32 v21, v19
	s_nop 0
	v_fma_f32 v22, -v19, v21, 1.0
	v_fmac_f32_e32 v21, v22, v21
	v_div_scale_f32 v22, vcc, 1.0, v18, 1.0
	v_mul_f32_e32 v23, v22, v21
	v_fma_f32 v24, -v19, v23, v22
	v_fmac_f32_e32 v23, v24, v21
	v_fma_f32 v19, -v19, v23, v22
	v_div_fmas_f32 v19, v19, v21, v23
	v_div_fixup_f32 v64, v19, v18, 1.0
	v_add_co_u32_e32 v18, vcc, s79, v56
	v_mul_f32_e32 v35, v20, v64
	s_nop 0
	v_addc_co_u32_e32 v19, vcc, 0, v57, vcc
	v_add_co_u32_e32 v22, vcc, s80, v56
	global_load_dwordx4 v[18:21], v[18:19], off
	s_nop 0
	v_addc_co_u32_e32 v23, vcc, 0, v57, vcc
	v_add_co_u32_e32 v26, vcc, s81, v56
	global_load_dwordx4 v[22:25], v[22:23], off
	s_nop 0
	v_addc_co_u32_e32 v27, vcc, 0, v57, vcc
	v_add_co_u32_e32 v30, vcc, s82, v56
	global_load_dwordx4 v[26:29], v[26:27], off
	s_nop 0
	v_addc_co_u32_e32 v31, vcc, 0, v57, vcc
	global_load_dwordx4 v[30:33], v[30:31], off
	s_waitcnt vmcnt(0) lgkmcnt(0)
; __device__ __forceinline__ unsigned pk2(float lo, float hi) { unsigned r; asm("v_cvt_pk_bf16_f32 %0, %1, %2" : "=v"(r) : "v"(lo), "v"(hi)); return r; }
; __device__ __forceinline__ float bf_lo(unsigned u) { return __uint_as_float(u << 16); }
; __device__ __forceinline__ void phase_combine(const Params& P, int layer_i) {
;     ...
;             const int pos = s0 + pass * 32 + (tid2 >> 4); const size_t row = (size_t)b * SEQ + pos;
;             const float l0 = Lse[row * 8 + hh], l1 = Lse[(size_t)MTOK * 8 + row * 8 + hh], l2 = Lse[(size_t)2 * MTOK * 8 + row * 8 + hh];
;             const float lm = fmaxf(l0, fmaxf(l1, l2));
;             float e0 = fexp2((l0 - lm) * 1.4426950408889634f), e1 = fexp2((l1 - lm) * 1.4426950408889634f), e2 = fexp2((l2 - lm) * 1.4426950408889634f);
;             const float ei = 1.f / (e0 + e1 + e2); e0 *= ei; e1 *= ei; e2 *= ei;
;             const u32x4 a0 = *(const u32x4*)(Op + row * AW + col), a1 = *(const u32x4*)(Op + (size_t)MTOK * AW + row * AW + col), a2 = *(const u32x4*)(Op + (size_t)2 * MTOK * AW + row * AW + col);
;             const u32x4 zz = *(const u32x4*)(sza + row * AW + col);
;             u32x4 ya;
; #pragma unroll
;             for (int e = 0; e < 4; ++e) {
;                 const float lo = (e0 * bf_lo(a0[e]) + e1 * bf_lo(a1[e]) + e2 * bf_lo(a2[e])) * bf_lo(zz[e]);
;                 const float hi = (e0 * bf_hi(a0[e]) + e1 * bf_hi(a1[e]) + e2 * bf_hi(a2[e])) * bf_hi(zz[e]);
;                 ya[e] = pk2(lo, hi); }
;             *(u32x4*)(Y + row * DM + col) = ya;
;             const u32x4 pc = *(const u32x4*)(pp + row * AW + col);
;             u32x4 pm = (u32x4){0u, 0u, 0u, 0u}, pn = (u32x4){0u, 0u, 0u, 0u};
;             if (pos > 0) pm = *(const u32x4*)(pp + (row - 1) * AW + col);
;             if (pos < SEQ - 1) pn = *(const u32x4*)(pp + (row + 1) * AW + col);
;             const u32x4 gg = *(const u32x4*)(gz + row * AW + col);
;             u32x4 yb;
; #pragma unroll
;             for (int e = 0; e < 4; ++e) {
;                 const float lo = bf_lo(gg[e]) * (w0[2 * e] * bf_lo(pm[e]) + w1[2 * e] * bf_lo(pc[e]) + w2[2 * e] * bf_lo(pn[e]));
;                 const float hi = bf_hi(gg[e]) * (w0[2 * e + 1] * bf_hi(pm[e]) + w1[2 * e + 1] * bf_hi(pc[e]) + w2[2 * e + 1] * bf_hi(pn[e]));
;                 yb[e] = pk2(lo, hi); }
;             *(u32x4*)(Y + row * DM + AW + col) = yb;
	v_lshlrev_b32_e32 v63, 16, v22
	v_and_b32_e32 v66, 0xffff0000, v22
	v_lshlrev_b32_e32 v68, 16, v23
	v_and_b32_e32 v70, 0xffff0000, v23
	v_lshlrev_b32_e32 v72, 16, v24
	v_and_b32_e32 v24, 0xffff0000, v24
	v_lshlrev_b32_e32 v74, 16, v25
	v_lshlrev_b32_e32 v65, 16, v30
	v_and_b32_e32 v67, 0xffff0000, v30
	v_lshlrev_b32_e32 v69, 16, v31
	v_and_b32_e32 v71, 0xffff0000, v31
	v_pk_mul_f32 v[22:23], v[58:59], v[64:65] op_sel_hi:[1,0]
	v_lshlrev_b32_e32 v31, 16, v18
	v_lshlrev_b32_e32 v30, 16, v26
	v_pk_mul_f32 v[30:31], v[22:23], v[30:31]
	v_lshlrev_b32_e32 v73, 16, v32
	v_fma_f32 v31, v35, v63, v31
	v_add_f32_e32 v30, v30, v31
	v_mul_f32_e32 v58, v30, v65
	v_and_b32_e32 v31, 0xffff0000, v18
	v_and_b32_e32 v30, 0xffff0000, v26
	v_pk_mul_f32 v[30:31], v[22:23], v[30:31]
	v_and_b32_e32 v32, 0xffff0000, v32
	v_fma_f32 v18, v35, v66, v31
	v_add_f32_e32 v18, v30, v18
	v_lshlrev_b32_e32 v31, 16, v19
	v_lshlrev_b32_e32 v30, 16, v27
	v_pk_mul_f32 v[30:31], v[22:23], v[30:31]
	v_mul_f32_e32 v18, v18, v67
	v_fma_f32 v26, v35, v68, v31
	v_add_f32_e32 v26, v30, v26
	v_and_b32_e32 v31, 0xffff0000, v19
	v_and_b32_e32 v30, 0xffff0000, v27
	v_cvt_pk_bf16_f32 v18, v58, v18
	v_mul_f32_e32 v58, v26, v69
	v_pk_mul_f32 v[26:27], v[22:23], v[30:31]
	s_nop 0
	v_fma_f32 v19, v35, v70, v27
	v_add_f32_e32 v19, v26, v19
	v_lshlrev_b32_e32 v27, 16, v20
	v_lshlrev_b32_e32 v26, 16, v28
	v_pk_mul_f32 v[26:27], v[22:23], v[26:27]
	v_mul_f32_e32 v19, v19, v71
	v_fma_f32 v27, v35, v72, v27
	v_add_f32_e32 v26, v26, v27
	v_mul_f32_e32 v30, v26, v73
	v_and_b32_e32 v27, 0xffff0000, v20
	v_and_b32_e32 v26, 0xffff0000, v28
	v_pk_mul_f32 v[26:27], v[22:23], v[26:27]
	v_cvt_pk_bf16_f32 v19, v58, v19
	v_mov_b32_e32 v28, 0
	v_fma_f32 v20, v35, v24, v27
	v_add_f32_e32 v20, v26, v20
	v_lshlrev_b32_e32 v27, 16, v21
	v_lshlrev_b32_e32 v26, 16, v29
	v_pk_mul_f32 v[26:27], v[22:23], v[26:27]
	v_mul_f32_e32 v20, v20, v32
	v_fma_f32 v24, v35, v74, v27
	v_add_f32_e32 v24, v26, v24
	v_lshlrev_b32_e32 v26, 16, v33
	v_mul_f32_e32 v26, v24, v26
	v_and_b32_e32 v27, 0xffff0000, v25
	v_and_b32_e32 v25, 0xffff0000, v21
	v_and_b32_e32 v24, 0xffff0000, v29
	v_pk_mul_f32 v[22:23], v[22:23], v[24:25]
	v_cvt_pk_bf16_f32 v20, v30, v20
	v_lshl_add_u64 v[30:31], s[12:13], 0, v[44:45]
	v_fma_f32 v21, v35, v27, v23
	v_add_f32_e32 v21, v22, v21
	v_and_b32_e32 v22, 0xffff0000, v33
	v_mul_f32_e32 v21, v21, v22
	v_add_co_u32_e32 v22, vcc, 0x96e4000, v30
	v_cvt_pk_bf16_f32 v21, v26, v21
	v_mov_b32_e32 v26, 0
	s_nop 0
	v_addc_co_u32_e32 v23, vcc, 0, v31, vcc
	global_store_dwordx4 v[22:23], v[18:21], off
	v_mov_b32_e32 v22, 0
	v_mov_b32_e32 v27, 0
	v_add_co_u32_e32 v18, vcc, 0x156e4000, v56
	v_mov_b32_e32 v29, 0
	s_nop 0
	v_addc_co_u32_e32 v19, vcc, 0, v57, vcc
	global_load_dwordx4 v[18:21], v[18:19], off
	v_cmp_lt_i32_e32 vcc, 0, v0
	s_and_saveexec_b64 s[24:25], vcc
	s_cbranch_execz .LBB0_257
	v_add_co_u32_e32 v24, vcc, 0x156e3000, v56
	s_nop 1
	v_addc_co_u32_e32 v25, vcc, 0, v57, vcc
	global_load_dwordx4 v[26:29], v[24:25], off offset:2048
.LBB0_257:
	s_or_b64 exec, exec, s[24:25]
	v_cmp_gt_i32_e32 vcc, s84, v0
	v_mov_b32_e32 v23, 0
	v_mov_b32_e32 v24, 0
	v_mov_b32_e32 v25, 0
	s_and_saveexec_b64 s[24:25], vcc
	s_cbranch_execz .LBB0_259
	v_add_co_u32_e32 v22, vcc, 0x156e4000, v56
	s_nop 1
	v_addc_co_u32_e32 v23, vcc, 0, v57, vcc
	global_load_dwordx4 v[22:25], v[22:23], off offset:2048
.LBB0_259:
	s_or_b64 exec, exec, s[24:25]
	v_add_co_u32_e32 v32, vcc, 0x176e4000, v56
	s_waitcnt vmcnt(0) lgkmcnt(0)
	v_lshlrev_b32_e32 v63, 16, v26
	v_addc_co_u32_e32 v33, vcc, 0, v57, vcc
	global_load_dwordx4 v[56:59], v[32:33], off
	v_lshlrev_b32_e32 v33, 16, v22
	v_lshlrev_b32_e32 v32, 16, v18
	v_pk_mul_f32 v[32:33], v[54:55], v[32:33]
	v_and_b32_e32 v26, 0xffff0000, v26
	v_fma_f32 v32, v10, v63, v32
	v_add_f32_e32 v32, v32, v33
	v_and_b32_e32 v33, 0xffff0000, v22
	s_mov_b32 s2, 0x1f6e4000
	v_add_u32_e32 v0, 32, v0
	s_waitcnt vmcnt(0) lgkmcnt(0)
	v_lshlrev_b32_e32 v35, 16, v56
	v_mul_f32_e32 v35, v32, v35
	v_and_b32_e32 v32, 0xffff0000, v18
	v_pk_mul_f32 v[32:33], v[6:7], v[32:33]
	v_lshlrev_b32_e32 v22, 16, v57
	v_fma_f32 v18, v11, v26, v32
	v_add_f32_e32 v18, v18, v33
	v_lshlrev_b32_e32 v33, 16, v23
	v_lshlrev_b32_e32 v32, 16, v19
	v_lshlrev_b32_e32 v26, 16, v27
	v_pk_mul_f32 v[32:33], v[52:53], v[32:33]
	v_and_b32_e32 v23, 0xffff0000, v23
	v_fma_f32 v26, v12, v26, v32
	v_add_f32_e32 v26, v26, v33
	v_mul_f32_e32 v26, v26, v22
	v_and_b32_e32 v22, 0xffff0000, v19
	v_and_b32_e32 v27, 0xffff0000, v27
	v_pk_mul_f32 v[22:23], v[8:9], v[22:23]
	v_and_b32_e32 v32, 0xffff0000, v57
	v_fma_f32 v19, v13, v27, v22
	v_add_f32_e32 v19, v19, v23
	v_lshlrev_b32_e32 v23, 16, v24
	v_lshlrev_b32_e32 v22, 16, v20
	v_lshlrev_b32_e32 v27, 16, v28
	v_pk_mul_f32 v[22:23], v[50:51], v[22:23]
	v_mul_f32_e32 v19, v19, v32
	v_fma_f32 v22, v14, v27, v22
	v_cvt_pk_bf16_f32 v19, v26, v19
	v_lshlrev_b32_e32 v26, 16, v58
	v_add_f32_e32 v22, v22, v23
	v_mul_f32_e32 v26, v22, v26
	v_and_b32_e32 v23, 0xffff0000, v24
	v_and_b32_e32 v22, 0xffff0000, v20
	v_and_b32_e32 v28, 0xffff0000, v28
	v_pk_mul_f32 v[22:23], v[2:3], v[22:23]
	v_and_b32_e32 v27, 0xffff0000, v58
	v_fma_f32 v20, v15, v28, v22
	v_add_f32_e32 v20, v20, v23
	v_mul_f32_e32 v20, v20, v27
	v_lshlrev_b32_e32 v23, 16, v25
	v_lshlrev_b32_e32 v22, 16, v21
	v_cvt_pk_bf16_f32 v20, v26, v20
	v_lshlrev_b32_e32 v26, 16, v29
	v_pk_mul_f32 v[22:23], v[48:49], v[22:23]
	v_lshlrev_b32_e32 v24, 16, v59
	v_fma_f32 v22, v16, v26, v22
	v_add_f32_e32 v22, v22, v23
	v_mul_f32_e32 v24, v22, v24
	v_and_b32_e32 v23, 0xffff0000, v25
	v_and_b32_e32 v22, 0xffff0000, v21
	v_and_b32_e32 v27, 0xffff0000, v29
	v_pk_mul_f32 v[22:23], v[4:5], v[22:23]
	v_and_b32_e32 v56, 0xffff0000, v56
	v_fma_f32 v21, v17, v27, v22
	v_mul_f32_e32 v18, v18, v56
	v_and_b32_e32 v26, 0xffff0000, v59
	v_add_f32_e32 v21, v21, v23
	v_add_co_u32_e32 v22, vcc, s83, v30
	v_cvt_pk_bf16_f32 v18, v35, v18
	v_mul_f32_e32 v21, v21, v26
	s_nop 0
	v_addc_co_u32_e32 v23, vcc, 0, v31, vcc
	v_cvt_pk_bf16_f32 v21, v24, v21
	global_store_dwordx4 v[22:23], v[18:21], off offset:2048
	v_lshl_add_u64 v[56:57], s[12:13], 0, v[36:37]
	s_nop 0
	v_lshl_add_u64 v[18:19], s[12:13], 0, v[40:41]
	v_add_co_u32_e32 v20, vcc, s2, v18
	s_mov_b32 s2, 0x1f764000
	s_nop 0
	v_addc_co_u32_e32 v21, vcc, 0, v19, vcc
	global_load_dword v22, v[20:21], off
	v_add_co_u32_e32 v20, vcc, s2, v18
	s_mov_b32 s2, 0x1f7e4000
	s_nop 0
	v_addc_co_u32_e32 v21, vcc, 0, v19, vcc
	v_add_co_u32_e32 v18, vcc, s2, v18
	global_load_dword v20, v[20:21], off
	s_nop 0
	v_addc_co_u32_e32 v19, vcc, 0, v19, vcc
	global_load_dword v18, v[18:19], off
	s_waitcnt vmcnt(0) lgkmcnt(0)
; __device__ __forceinline__ unsigned pk2(float lo, float hi) { unsigned r; asm("v_cvt_pk_bf16_f32 %0, %1, %2" : "=v"(r) : "v"(lo), "v"(hi)); return r; }
; __device__ __forceinline__ float bf_lo(unsigned u) { return __uint_as_float(u << 16); }
; __device__ __forceinline__ void phase_combine(const Params& P, int layer_i) {
;     ...
;             const int pos = s0 + pass * 32 + (tid2 >> 4); const size_t row = (size_t)b * SEQ + pos;
;             const float l0 = Lse[row * 8 + hh], l1 = Lse[(size_t)MTOK * 8 + row * 8 + hh], l2 = Lse[(size_t)2 * MTOK * 8 + row * 8 + hh];
;             const float lm = fmaxf(l0, fmaxf(l1, l2));
;             float e0 = fexp2((l0 - lm) * 1.4426950408889634f), e1 = fexp2((l1 - lm) * 1.4426950408889634f), e2 = fexp2((l2 - lm) * 1.4426950408889634f);
;             const float ei = 1.f / (e0 + e1 + e2); e0 *= ei; e1 *= ei; e2 *= ei;
;             const u32x4 a0 = *(const u32x4*)(Op + row * AW + col), a1 = *(const u32x4*)(Op + (size_t)MTOK * AW + row * AW + col), a2 = *(const u32x4*)(Op + (size_t)2 * MTOK * AW + row * AW + col);
;             const u32x4 zz = *(const u32x4*)(sza + row * AW + col);
;             u32x4 ya;
; #pragma unroll
;             for (int e = 0; e < 4; ++e) {
;                 const float lo = (e0 * bf_lo(a0[e]) + e1 * bf_lo(a1[e]) + e2 * bf_lo(a2[e])) * bf_lo(zz[e]);
;                 const float hi = (e0 * bf_hi(a0[e]) + e1 * bf_hi(a1[e]) + e2 * bf_hi(a2[e])) * bf_hi(zz[e]);
;                 ya[e] = pk2(lo, hi); }
;             *(u32x4*)(Y + row * DM + col) = ya;
;             const u32x4 pc = *(const u32x4*)(pp + row * AW + col);
;             u32x4 pm = (u32x4){0u, 0u, 0u, 0u}, pn = (u32x4){0u, 0u, 0u, 0u};
;             if (pos > 0) pm = *(const u32x4*)(pp + (row - 1) * AW + col);
;             if (pos < SEQ - 1) pn = *(const u32x4*)(pp + (row + 1) * AW + col);
;             const u32x4 gg = *(const u32x4*)(gz + row * AW + col);
;             u32x4 yb;
; #pragma unroll
;             for (int e = 0; e < 4; ++e) {
;                 const float lo = bf_lo(gg[e]) * (w0[2 * e] * bf_lo(pm[e]) + w1[2 * e] * bf_lo(pc[e]) + w2[2 * e] * bf_lo(pn[e]));
;                 const float hi = bf_hi(gg[e]) * (w0[2 * e + 1] * bf_hi(pm[e]) + w1[2 * e + 1] * bf_hi(pc[e]) + w2[2 * e + 1] * bf_hi(pn[e]));
;                 yb[e] = pk2(lo, hi); }
;             *(u32x4*)(Y + row * DM + AW + col) = yb;
	v_max3_f32 v19, v22, v20, v18
	v_sub_f32_e32 v21, v22, v19
	v_sub_f32_e32 v20, v20, v19
	v_mul_f32_e32 v21, 0x3fb8aa3b, v21
	v_mul_f32_e32 v20, 0x3fb8aa3b, v20
	v_sub_f32_e32 v18, v18, v19
	v_exp_f32_e32 v59, v21
	v_exp_f32_e32 v20, v20
	v_mul_f32_e32 v18, 0x3fb8aa3b, v18
	v_exp_f32_e32 v58, v18
	v_add_f32_e32 v18, v59, v20
	v_add_f32_e32 v18, v58, v18
	v_div_scale_f32 v19, s[2:3], v18, v18, 1.0
	v_rcp_f32_e32 v21, v19
	s_nop 0
	v_fma_f32 v22, -v19, v21, 1.0
	v_fmac_f32_e32 v21, v22, v21
	v_div_scale_f32 v22, vcc, 1.0, v18, 1.0
	v_mul_f32_e32 v23, v22, v21
	v_fma_f32 v24, -v19, v23, v22
	v_fmac_f32_e32 v23, v24, v21
	v_fma_f32 v19, -v19, v23, v22
	v_div_fmas_f32 v19, v19, v21, v23
	v_div_fixup_f32 v64, v19, v18, 1.0
	v_add_co_u32_e32 v18, vcc, s79, v56
	v_mul_f32_e32 v35, v20, v64
	s_nop 0
	v_addc_co_u32_e32 v19, vcc, 0, v57, vcc
	v_add_co_u32_e32 v22, vcc, s80, v56
	global_load_dwordx4 v[18:21], v[18:19], off
	s_nop 0
	v_addc_co_u32_e32 v23, vcc, 0, v57, vcc
	v_add_co_u32_e32 v26, vcc, s81, v56
	global_load_dwordx4 v[22:25], v[22:23], off
	s_nop 0
	v_addc_co_u32_e32 v27, vcc, 0, v57, vcc
	v_add_co_u32_e32 v30, vcc, s82, v56
	global_load_dwordx4 v[26:29], v[26:27], off
	s_nop 0
	v_addc_co_u32_e32 v31, vcc, 0, v57, vcc
	global_load_dwordx4 v[30:33], v[30:31], off
	s_waitcnt vmcnt(0) lgkmcnt(0)
	v_lshlrev_b32_e32 v63, 16, v22
	v_and_b32_e32 v66, 0xffff0000, v22
	v_lshlrev_b32_e32 v68, 16, v23
	v_and_b32_e32 v70, 0xffff0000, v23
	v_lshlrev_b32_e32 v72, 16, v24
	v_and_b32_e32 v24, 0xffff0000, v24
	v_lshlrev_b32_e32 v74, 16, v25
	v_lshlrev_b32_e32 v65, 16, v30
	v_and_b32_e32 v67, 0xffff0000, v30
	v_lshlrev_b32_e32 v69, 16, v31
	v_and_b32_e32 v71, 0xffff0000, v31
	v_pk_mul_f32 v[22:23], v[58:59], v[64:65] op_sel_hi:[1,0]
	v_lshlrev_b32_e32 v31, 16, v18
	v_lshlrev_b32_e32 v30, 16, v26
	v_pk_mul_f32 v[30:31], v[22:23], v[30:31]
	v_lshlrev_b32_e32 v73, 16, v32
	v_fma_f32 v31, v35, v63, v31
	v_add_f32_e32 v30, v30, v31
	v_mul_f32_e32 v58, v30, v65
	v_and_b32_e32 v31, 0xffff0000, v18
	v_and_b32_e32 v30, 0xffff0000, v26
	v_pk_mul_f32 v[30:31], v[22:23], v[30:31]
	v_and_b32_e32 v32, 0xffff0000, v32
	v_fma_f32 v18, v35, v66, v31
	v_add_f32_e32 v18, v30, v18
	v_lshlrev_b32_e32 v31, 16, v19
	v_lshlrev_b32_e32 v30, 16, v27
	v_pk_mul_f32 v[30:31], v[22:23], v[30:31]
	v_mul_f32_e32 v18, v18, v67
	v_fma_f32 v26, v35, v68, v31
	v_add_f32_e32 v26, v30, v26
	v_and_b32_e32 v31, 0xffff0000, v19
	v_and_b32_e32 v30, 0xffff0000, v27
	v_cvt_pk_bf16_f32 v18, v58, v18
	v_mul_f32_e32 v58, v26, v69
	v_pk_mul_f32 v[26:27], v[22:23], v[30:31]
	s_nop 0
	v_fma_f32 v19, v35, v70, v27
	v_add_f32_e32 v19, v26, v19
	v_lshlrev_b32_e32 v27, 16, v20
	v_lshlrev_b32_e32 v26, 16, v28
	v_pk_mul_f32 v[26:27], v[22:23], v[26:27]
	v_mul_f32_e32 v19, v19, v71
	v_fma_f32 v27, v35, v72, v27
	v_add_f32_e32 v26, v26, v27
	v_mul_f32_e32 v30, v26, v73
	v_and_b32_e32 v27, 0xffff0000, v20
	v_and_b32_e32 v26, 0xffff0000, v28
	v_pk_mul_f32 v[26:27], v[22:23], v[26:27]
	v_cvt_pk_bf16_f32 v19, v58, v19
	v_mov_b32_e32 v28, 0
	v_fma_f32 v20, v35, v24, v27
	v_add_f32_e32 v20, v26, v20
	v_lshlrev_b32_e32 v27, 16, v21
	v_lshlrev_b32_e32 v26, 16, v29
	v_pk_mul_f32 v[26:27], v[22:23], v[26:27]
	v_mul_f32_e32 v20, v20, v32
	v_fma_f32 v24, v35, v74, v27
	v_add_f32_e32 v24, v26, v24
	v_lshlrev_b32_e32 v26, 16, v33
	v_mul_f32_e32 v26, v24, v26
	v_and_b32_e32 v27, 0xffff0000, v25
	v_and_b32_e32 v25, 0xffff0000, v21
	v_and_b32_e32 v24, 0xffff0000, v29
	v_pk_mul_f32 v[22:23], v[22:23], v[24:25]
	v_cvt_pk_bf16_f32 v20, v30, v20
	v_lshl_add_u64 v[30:31], s[12:13], 0, v[38:39]
	v_fma_f32 v21, v35, v27, v23
	v_add_f32_e32 v21, v22, v21
	v_and_b32_e32 v22, 0xffff0000, v33
	v_mul_f32_e32 v21, v21, v22
	v_add_co_u32_e32 v22, vcc, 0x96e4000, v30
	v_cvt_pk_bf16_f32 v21, v26, v21
	v_mov_b32_e32 v26, 0
	s_nop 0
	v_addc_co_u32_e32 v23, vcc, 0, v31, vcc
	global_store_dwordx4 v[22:23], v[18:21], off
	v_mov_b32_e32 v22, 0
	v_mov_b32_e32 v27, 0
	v_add_co_u32_e32 v18, vcc, 0x156e4000, v56
	v_mov_b32_e32 v29, 0
	s_nop 0
	v_addc_co_u32_e32 v19, vcc, 0, v57, vcc
	global_load_dwordx4 v[18:21], v[18:19], off
	v_cmp_lt_i32_e32 vcc, 0, v0
	s_and_saveexec_b64 s[24:25], vcc
	s_cbranch_execz .LBB0_261
	v_add_co_u32_e32 v24, vcc, 0x156e3000, v56
	s_nop 1
	v_addc_co_u32_e32 v25, vcc, 0, v57, vcc
	global_load_dwordx4 v[26:29], v[24:25], off offset:2048
.LBB0_261:
	s_or_b64 exec, exec, s[24:25]
	v_cmp_gt_i32_e32 vcc, s84, v0
	v_mov_b32_e32 v23, 0
	v_mov_b32_e32 v24, 0
	v_mov_b32_e32 v25, 0
	s_and_saveexec_b64 s[24:25], vcc
	s_cbranch_execz .LBB0_254
	v_add_co_u32_e32 v22, vcc, 0x156e4000, v56
	s_nop 1
	v_addc_co_u32_e32 v23, vcc, 0, v57, vcc
	global_load_dwordx4 v[22:25], v[22:23], off offset:2048
	s_branch .LBB0_254

; __device__ __forceinline__ unsigned pk2(float lo, float hi) { unsigned r; asm("v_cvt_pk_bf16_f32 %0, %1, %2" : "=v"(r) : "v"(lo), "v"(hi)); return r; }
; __device__ __forceinline__ void phase_norm(const float* xin, const _Float16* xin_h, const bf16_t* dl, _Float16* xout, const float* g, const float* mod  , bf16_t* h) {
;     ...
;             for (int j = 0; j < 8; ++j) s += (v[q][j].x * v[q][j].x + v[q][j].y * v[q][j].y) + (v[q][j].z * v[q][j].z + v[q][j].w * v[q][j].w);
;             const float rstd = 1.f / sqrtf(wave_sum(s) * (1.f / DM) + 1e-6f);
;             const float* mb = mod + (size_t)(row >> 12) * 6144;
;             u32x2* o8 = (u32x2*)(h + (size_t)row * DM) + lane;
; #pragma unroll
;             for (int j = 0; j < 8; ++j) { const int c = 4 * lane + 256 * j;
;                 const f32x4 gg = *(const f32x4*)(g + c), sh = *(const f32x4*)(mb + c), sc = *(const f32x4*)(mb + 2048 + c);
;                 const f32x4 y = v[q][j] * rstd * gg * (1.f + sc) + sh;
;                 u32x2 w; w.x = pk2(y.x, y.y); w.y = pk2(y.z, y.w); o8[64 * j] = w; } }
.LBB0_273:
	v_pk_mul_f32 v[138:139], v[138:139], v[138:139]
	v_pk_mul_f32 v[60:61], v[60:61], v[60:61]
	v_pk_mul_f32 v[48:49], v[48:49], v[48:49]
	v_pk_fma_f32 v[64:65], v[64:65], v[64:65], v[138:139]
	v_pk_fma_f32 v[56:57], v[56:57], v[56:57], v[60:61]
	v_pk_fma_f32 v[48:49], v[52:53], v[52:53], v[48:49]
	v_pk_add_f32 v[56:57], v[56:57], v[64:65]
	v_pk_add_f32 v[48:49], v[48:49], v[48:49] op_sel_hi:[0,1]
	v_pk_add_f32 v[56:57], v[56:57], v[56:57] op_sel_hi:[0,1]
	v_mul_f32_e32 v48, v18, v18
	v_pk_fma_f32 v[52:53], v[18:19], v[18:19], v[48:49] op_sel_hi:[1,1,0]
	v_mul_f32_e32 v61, v20, v20
	v_mul_f32_e32 v45, v21, v21
	v_mul_f32_e32 v56, v14, v14
	v_mul_f32_e32 v48, v15, v15
	v_mov_b32_e32 v60, v44
	v_pk_add_f32 v[48:49], v[48:49], v[56:57]
	v_mul_f32_e32 v56, v44, v44
	v_pk_add_f32 v[44:45], v[44:45], v[60:61]
	v_mul_f32_e32 v52, v16, v16
	v_mov_b32_e32 v57, v45
	v_pk_mul_f32 v[36:37], v[36:37], v[36:37]
	v_pk_add_f32 v[44:45], v[56:57], v[52:53]
	v_pk_fma_f32 v[36:37], v[40:41], v[40:41], v[36:37]
	v_pk_add_f32 v[44:45], v[44:45], v[48:49]
	v_pk_add_f32 v[36:37], v[36:37], v[36:37] op_sel_hi:[0,1]
	v_pk_add_f32 v[44:45], v[44:45], v[44:45] op_sel_hi:[0,1]
	v_mul_f32_e32 v36, v6, v6
	v_pk_fma_f32 v[40:41], v[6:7], v[6:7], v[36:37] op_sel_hi:[1,1,0]
	v_mul_f32_e32 v49, v8, v8
	v_mul_f32_e32 v35, v9, v9
	v_mul_f32_e32 v44, v2, v2
	v_mul_f32_e32 v36, v3, v3
	v_mov_b32_e32 v48, v34
	v_pk_add_f32 v[36:37], v[36:37], v[44:45]
	v_mul_f32_e32 v44, v34, v34
	v_pk_add_f32 v[34:35], v[34:35], v[48:49]
	v_mul_f32_e32 v40, v4, v4
	v_mov_b32_e32 v45, v35
	v_pk_add_f32 v[34:35], v[44:45], v[40:41]
	s_mov_b32 s2, 0xf800000
	v_pk_add_f32 v[34:35], v[34:35], v[36:37]
	global_load_dwordx4 v[138:141], v[80:81], off
	v_add_f32_e32 v34, v34, v35
	ds_bpermute_b32 v35, v79, v34
	v_mov_b32_e32 v63, v1
	v_mov_b32_e32 v59, v1
	v_mov_b32_e32 v55, v1
	v_mov_b32_e32 v51, v1
	s_waitcnt lgkmcnt(0)
	v_add_f32_e32 v34, v34, v35
	ds_bpermute_b32 v35, v83, v34
	v_mov_b32_e32 v47, v1
	v_mov_b32_e32 v43, v1
	s_waitcnt lgkmcnt(0)
	v_add_f32_e32 v34, v34, v35
	ds_bpermute_b32 v35, v85, v34
	s_waitcnt lgkmcnt(0)
	v_add_f32_e32 v34, v34, v35
	ds_bpermute_b32 v35, v87, v34
	s_waitcnt lgkmcnt(0)
	v_add_f32_e32 v34, v34, v35
	ds_bpermute_b32 v35, v89, v34
	s_waitcnt lgkmcnt(0)
	v_add_f32_e32 v34, v34, v35
	ds_bpermute_b32 v35, v93, v34
	s_waitcnt lgkmcnt(0)
	v_add_f32_e32 v34, v34, v35
	v_fmamk_f32 v34, v34, 0x3a000000, v181
	v_cmp_gt_f32_e32 vcc, s2, v34
	v_mul_f32_e32 v35, 0x4f800000, v34
	s_nop 0
	v_cndmask_b32_e32 v34, v34, v35, vcc
	v_sqrt_f32_e32 v35, v34
	s_nop 0
	v_add_u32_e32 v36, -1, v35
	v_fma_f32 v37, -v36, v35, v34
	v_cmp_ge_f32_e64 s[40:41], 0, v37
	v_add_u32_e32 v37, 1, v35
	s_nop 0
	v_cndmask_b32_e64 v36, v35, v36, s[40:41]
	v_fma_f32 v35, -v37, v35, v34
	v_cmp_lt_f32_e64 s[40:41], 0, v35
	s_nop 1
	v_cndmask_b32_e64 v35, v36, v37, s[40:41]
	v_mul_f32_e32 v36, 0x37800000, v35
	v_cndmask_b32_e32 v35, v35, v36, vcc
	v_cmp_class_f32_e32 vcc, v34, v180
	s_nop 1
	v_cndmask_b32_e32 v34, v35, v34, vcc
	v_div_scale_f32 v35, s[2:3], v34, v34, 1.0
	v_rcp_f32_e32 v36, v35
	s_ashr_i32 s2, s12, 12
	s_mul_hi_i32 s3, s2, 0x6000
	s_mulk_i32 s2, 0x6000
	v_fma_f32 v37, -v35, v36, 1.0
	s_add_u32 s16, s33, s2
	v_fmac_f32_e32 v36, v37, v36
	v_div_scale_f32 v37, vcc, 1.0, v34, 1.0
	s_addc_u32 s17, s58, s3
	s_lshl_b64 s[2:3], s[12:13], 12
	v_mul_f32_e32 v39, v37, v36
	s_add_u32 s12, s16, 0x2000
	v_fma_f32 v40, -v35, v39, v37
	s_addc_u32 s13, s17, 0
	v_fmac_f32_e32 v39, v40, v36
	v_lshl_add_u64 v[40:41], s[16:17], 0, v[0:1]
	v_lshl_add_u64 v[44:45], s[12:13], 0, v[0:1]
	global_load_dwordx4 v[142:145], v[40:41], off
	global_load_dwordx4 v[146:149], v[44:45], off
	v_fma_f32 v35, -v35, v39, v37
	v_div_fmas_f32 v35, v35, v36, v39
	v_div_fixup_f32 v34, v35, v34, 1.0
	v_pk_mul_f32 v[30:31], v[30:31], v[34:35] op_sel_hi:[1,0]
	v_pk_mul_f32 v[32:33], v[32:33], v[34:35] op_sel_hi:[1,0]
	s_waitcnt vmcnt(0)
	v_pk_mul_f32 v[30:31], v[138:139], v[30:31]
	v_lshl_add_u64 v[36:37], v[76:77], 0, s[2:3]
	v_pk_mul_f32 v[32:33], v[140:141], v[32:33]
	v_pk_mul_f32 v[28:29], v[28:29], v[34:35] op_sel_hi:[1,0]
	v_pk_mul_f32 v[26:27], v[26:27], v[34:35] op_sel_hi:[1,0]
	v_pk_mul_f32 v[24:25], v[24:25], v[34:35] op_sel_hi:[1,0]
	v_pk_mul_f32 v[22:23], v[22:23], v[34:35] op_sel_hi:[1,0]
	v_pk_mul_f32 v[20:21], v[20:21], v[34:35] op_sel_hi:[1,0]
	v_pk_mul_f32 v[18:19], v[18:19], v[34:35] op_sel_hi:[1,0]
	v_pk_mul_f32 v[16:17], v[16:17], v[34:35] op_sel_hi:[1,0]
	v_pk_mul_f32 v[14:15], v[14:15], v[34:35] op_sel_hi:[1,0]
	v_pk_mul_f32 v[12:13], v[12:13], v[34:35] op_sel_hi:[1,0]
	v_pk_mul_f32 v[10:11], v[10:11], v[34:35] op_sel_hi:[1,0]
	v_pk_mul_f32 v[8:9], v[8:9], v[34:35] op_sel_hi:[1,0]
	v_pk_mul_f32 v[6:7], v[6:7], v[34:35] op_sel_hi:[1,0]
	v_mov_b32_e32 v39, v1
	v_pk_mul_f32 v[4:5], v[4:5], v[34:35] op_sel_hi:[1,0]
	v_pk_mul_f32 v[2:3], v[2:3], v[34:35] op_sel_hi:[1,0]
	s_waitcnt lgkmcnt(0)
; __device__ __forceinline__ unsigned pk2(float lo, float hi) { unsigned r; asm("v_cvt_pk_bf16_f32 %0, %1, %2" : "=v"(r) : "v"(lo), "v"(hi)); return r; }
; __device__ __forceinline__ void phase_norm(const float* xin, const _Float16* xin_h, const bf16_t* dl, _Float16* xout, const float* g, const float* mod  , bf16_t* h) {
;     ...
; #pragma unroll
;             for (int j = 0; j < 8; ++j) { const int c = 4 * lane + 256 * j;
;                 const f32x4 gg = *(const f32x4*)(g + c), sh = *(const f32x4*)(mb + c), sc = *(const f32x4*)(mb + 2048 + c);
;                 const f32x4 y = v[q][j] * rstd * gg * (1.f + sc) + sh;
;                 u32x2 w; w.x = pk2(y.x, y.y); w.y = pk2(y.z, y.w); o8[64 * j] = w; } }
	v_pk_add_f32 v[48:49], v[146:147], 1.0 op_sel_hi:[1,0]
	v_pk_add_f32 v[44:45], v[148:149], 1.0 op_sel_hi:[1,0]
	v_pk_fma_f32 v[30:31], v[48:49], v[30:31], v[142:143]
	v_pk_fma_f32 v[32:33], v[44:45], v[32:33], v[144:145]
	v_cvt_pk_bf16_f32 v30, v30, v31
	v_lshl_add_u64 v[44:45], s[12:13], 0, v[62:63]
	v_cvt_pk_bf16_f32 v31, v32, v33
	global_store_dwordx2 v[36:37], v[30:31], off
	global_load_dwordx4 v[30:33], v[80:81], off offset:1024
	s_nop 0
	global_load_dwordx4 v[138:141], v[40:41], off offset:1024
	global_load_dwordx4 v[60:63], v[44:45], off
	v_lshl_add_u64 v[44:45], s[12:13], 0, v[58:59]
	s_waitcnt vmcnt(0)
	v_pk_mul_f32 v[26:27], v[30:31], v[26:27]
	v_pk_mul_f32 v[28:29], v[32:33], v[28:29]
	s_waitcnt lgkmcnt(0)
	v_pk_add_f32 v[32:33], v[60:61], 1.0 op_sel_hi:[1,0]
	v_pk_add_f32 v[30:31], v[62:63], 1.0 op_sel_hi:[1,0]
	v_pk_fma_f32 v[26:27], v[32:33], v[26:27], v[138:139]
	v_pk_fma_f32 v[28:29], v[30:31], v[28:29], v[140:141]
	v_cvt_pk_bf16_f32 v26, v26, v27
	s_nop 0
	v_cvt_pk_bf16_f32 v27, v28, v29
	global_store_dwordx2 v[36:37], v[26:27], off offset:512
	global_load_dwordx4 v[26:29], v[80:81], off offset:2048
	s_nop 0
	global_load_dwordx4 v[30:33], v[40:41], off offset:2048
	global_load_dwordx4 v[56:59], v[44:45], off
	s_waitcnt vmcnt(0)
	v_pk_mul_f32 v[22:23], v[26:27], v[22:23]
	v_pk_mul_f32 v[24:25], v[28:29], v[24:25]
	s_waitcnt lgkmcnt(0)
	v_pk_add_f32 v[28:29], v[56:57], 1.0 op_sel_hi:[1,0]
	v_pk_add_f32 v[26:27], v[58:59], 1.0 op_sel_hi:[1,0]
	v_pk_fma_f32 v[22:23], v[28:29], v[22:23], v[30:31]
	v_pk_fma_f32 v[24:25], v[26:27], v[24:25], v[32:33]
	v_cvt_pk_bf16_f32 v22, v22, v23
	v_lshl_add_u64 v[30:31], s[12:13], 0, v[54:55]
	v_cvt_pk_bf16_f32 v23, v24, v25
	global_store_dwordx2 v[36:37], v[22:23], off offset:1024
	global_load_dwordx4 v[22:25], v[80:81], off offset:3072
	s_nop 0
	global_load_dwordx4 v[26:29], v[40:41], off offset:3072
	s_waitcnt vmcnt(0)
	v_pk_mul_f32 v[18:19], v[18:19], v[22:23]
	global_load_dwordx4 v[30:33], v[30:31], off
	v_pk_mul_f32 v[20:21], v[20:21], v[24:25]
	s_waitcnt vmcnt(0) lgkmcnt(0)
	v_pk_add_f32 v[24:25], v[30:31], 1.0 op_sel_hi:[1,0]
	v_pk_add_f32 v[22:23], v[32:33], 1.0 op_sel_hi:[1,0]
	v_pk_fma_f32 v[18:19], v[18:19], v[24:25], v[26:27]
	v_pk_fma_f32 v[20:21], v[20:21], v[22:23], v[28:29]
	v_cvt_pk_bf16_f32 v18, v18, v19
	v_lshl_add_u64 v[22:23], s[16:17], 0, v[50:51]
	v_cvt_pk_bf16_f32 v19, v20, v21
	global_store_dwordx2 v[36:37], v[18:19], off offset:1536
	v_lshl_add_u64 v[26:27], s[12:13], 0, v[50:51]
	global_load_dwordx4 v[18:21], v[90:91], off
	s_waitcnt vmcnt(0)
	v_pk_mul_f32 v[14:15], v[14:15], v[18:19]
	global_load_dwordx4 v[22:25], v[22:23], off
	v_pk_mul_f32 v[16:17], v[16:17], v[20:21]
	global_load_dwordx4 v[26:29], v[26:27], off
	s_waitcnt vmcnt(0) lgkmcnt(0)
	v_pk_add_f32 v[20:21], v[26:27], 1.0 op_sel_hi:[1,0]
	v_pk_add_f32 v[18:19], v[28:29], 1.0 op_sel_hi:[1,0]
	v_pk_fma_f32 v[14:15], v[14:15], v[20:21], v[22:23]
	v_pk_fma_f32 v[16:17], v[16:17], v[18:19], v[24:25]
	v_cvt_pk_bf16_f32 v14, v14, v15
	v_lshl_add_u64 v[18:19], s[16:17], 0, v[46:47]
	v_cvt_pk_bf16_f32 v15, v16, v17
	global_store_dwordx2 v[36:37], v[14:15], off offset:2048
	v_lshl_add_u64 v[22:23], s[12:13], 0, v[46:47]
	global_load_dwordx4 v[14:17], v[94:95], off
	s_waitcnt vmcnt(0)
	v_pk_mul_f32 v[10:11], v[10:11], v[14:15]
	global_load_dwordx4 v[18:21], v[18:19], off
	v_pk_mul_f32 v[12:13], v[12:13], v[16:17]
	global_load_dwordx4 v[22:25], v[22:23], off
	s_waitcnt vmcnt(0) lgkmcnt(0)
	v_pk_add_f32 v[16:17], v[22:23], 1.0 op_sel_hi:[1,0]
	v_pk_add_f32 v[14:15], v[24:25], 1.0 op_sel_hi:[1,0]
	v_pk_fma_f32 v[10:11], v[10:11], v[16:17], v[18:19]
	v_pk_fma_f32 v[12:13], v[12:13], v[14:15], v[20:21]
	v_cvt_pk_bf16_f32 v10, v10, v11
	v_lshl_add_u64 v[14:15], s[16:17], 0, v[42:43]
	v_cvt_pk_bf16_f32 v11, v12, v13
	global_store_dwordx2 v[36:37], v[10:11], off offset:2560
	v_lshl_add_u64 v[18:19], s[12:13], 0, v[42:43]
	global_load_dwordx4 v[10:13], v[98:99], off
	s_waitcnt vmcnt(0)
	v_pk_mul_f32 v[6:7], v[6:7], v[10:11]
	global_load_dwordx4 v[14:17], v[14:15], off
	v_pk_mul_f32 v[8:9], v[8:9], v[12:13]
	global_load_dwordx4 v[18:21], v[18:19], off
	s_waitcnt vmcnt(0) lgkmcnt(0)
	v_pk_add_f32 v[12:13], v[18:19], 1.0 op_sel_hi:[1,0]
	v_pk_add_f32 v[10:11], v[20:21], 1.0 op_sel_hi:[1,0]
	v_pk_fma_f32 v[6:7], v[6:7], v[12:13], v[14:15]
	v_pk_fma_f32 v[8:9], v[8:9], v[10:11], v[16:17]
	v_cvt_pk_bf16_f32 v6, v6, v7
	v_lshl_add_u64 v[10:11], s[16:17], 0, v[38:39]
	v_cvt_pk_bf16_f32 v7, v8, v9
	global_store_dwordx2 v[36:37], v[6:7], off offset:3072
	v_lshl_add_u64 v[14:15], s[12:13], 0, v[38:39]
	global_load_dwordx4 v[6:9], v[102:103], off
	s_waitcnt vmcnt(0)
	v_pk_mul_f32 v[2:3], v[2:3], v[6:7]
	global_load_dwordx4 v[10:13], v[10:11], off
	v_pk_mul_f32 v[4:5], v[4:5], v[8:9]
	global_load_dwordx4 v[14:17], v[14:15], off
	s_waitcnt vmcnt(0) lgkmcnt(0)
	v_pk_add_f32 v[8:9], v[14:15], 1.0 op_sel_hi:[1,0]
	v_pk_add_f32 v[6:7], v[16:17], 1.0 op_sel_hi:[1,0]
	v_pk_fma_f32 v[2:3], v[2:3], v[8:9], v[10:11]
	v_pk_fma_f32 v[4:5], v[4:5], v[6:7], v[12:13]
	v_cvt_pk_bf16_f32 v2, v2, v3
	s_nop 0
	v_cvt_pk_bf16_f32 v3, v4, v5
	global_store_dwordx2 v[36:37], v[2:3], off offset:3584

; __device__ __forceinline__ void phase_norm(const float* xin, const _Float16* xin_h, const bf16_t* dl, _Float16* xout, const float* g, const float* mod  , bf16_t* h) {
;     ...
;     for (int row0 = blockIdx.x * NWAVES + wave; row0 < MTOK; row0 += 2 * NW) {
;         f32x4 v[2][8]; u32x2 d[2][8];
; #pragma unroll
;         for (int q = 0; q < 2; ++q) { const int row = min(row0 + q * NW, MTOK - 1);
;             if (xin_h) { const f16x4* xr = (const f16x4*)(xin_h + (size_t)row * XH_PITCH) + lane;
; #pragma unroll
;                 for (int j = 0; j < 8; ++j) { const f16x4 t = xr[64 * j]; v[q][j] = (f32x4){(float)t.x, (float)t.y, (float)t.z, (float)t.w}; } }
.LBB0_275:
	v_cndmask_b32_e64 v0, 0, 1, s[48:49]
	v_cmp_ne_u32_e64 s[42:43], 1, v0
	s_andn2_b64 vcc, exec, s[48:49]
	s_cbranch_vccnz .LBB0_294
	v_lshl_add_u64 v[2:3], s[54:55], 0, v[66:67]
	global_load_dwordx2 v[4:5], v[2:3], off
	global_load_dwordx2 v[6:7], v[2:3], off offset:512
	global_load_dwordx2 v[8:9], v[2:3], off offset:1024
	global_load_dwordx2 v[10:11], v[2:3], off offset:1536
	global_load_dwordx2 v[12:13], v[2:3], off offset:2048
	global_load_dwordx2 v[14:15], v[2:3], off offset:2560
	global_load_dwordx2 v[16:17], v[2:3], off offset:3072
	s_nop 0
	global_load_dwordx2 v[2:3], v[2:3], off offset:3584
	s_waitcnt vmcnt(0) lgkmcnt(0)
	v_cvt_f32_f16_e32 v62, v4
	v_cvt_f32_f16_sdwa v63, v4 dst_sel:DWORD dst_unused:UNUSED_PAD src0_sel:WORD_1
	v_cvt_f32_f16_e32 v64, v5
	v_cvt_f32_f16_sdwa v65, v5 dst_sel:DWORD dst_unused:UNUSED_PAD src0_sel:WORD_1
	v_cvt_f32_f16_e32 v58, v6
	v_cvt_f32_f16_sdwa v59, v6 dst_sel:DWORD dst_unused:UNUSED_PAD src0_sel:WORD_1
	v_cvt_f32_f16_e32 v60, v7
	v_cvt_f32_f16_sdwa v61, v7 dst_sel:DWORD dst_unused:UNUSED_PAD src0_sel:WORD_1
	v_cvt_f32_f16_e32 v54, v8
	v_cvt_f32_f16_sdwa v55, v8 dst_sel:DWORD dst_unused:UNUSED_PAD src0_sel:WORD_1
	v_cvt_f32_f16_e32 v56, v9
	v_cvt_f32_f16_sdwa v57, v9 dst_sel:DWORD dst_unused:UNUSED_PAD src0_sel:WORD_1
	v_cvt_f32_f16_e32 v50, v10
	v_cvt_f32_f16_sdwa v51, v10 dst_sel:DWORD dst_unused:UNUSED_PAD src0_sel:WORD_1
	v_cvt_f32_f16_e32 v52, v11
	v_cvt_f32_f16_sdwa v53, v11 dst_sel:DWORD dst_unused:UNUSED_PAD src0_sel:WORD_1
	v_cvt_f32_f16_e32 v46, v12
	v_cvt_f32_f16_sdwa v47, v12 dst_sel:DWORD dst_unused:UNUSED_PAD src0_sel:WORD_1
	v_cvt_f32_f16_e32 v48, v13
	v_cvt_f32_f16_sdwa v49, v13 dst_sel:DWORD dst_unused:UNUSED_PAD src0_sel:WORD_1
	v_cvt_f32_f16_e32 v42, v14
	v_cvt_f32_f16_sdwa v43, v14 dst_sel:DWORD dst_unused:UNUSED_PAD src0_sel:WORD_1
	v_cvt_f32_f16_e32 v44, v15
	v_cvt_f32_f16_sdwa v45, v15 dst_sel:DWORD dst_unused:UNUSED_PAD src0_sel:WORD_1
	v_cvt_f32_f16_e32 v38, v16
	v_cvt_f32_f16_sdwa v39, v16 dst_sel:DWORD dst_unused:UNUSED_PAD src0_sel:WORD_1
	v_cvt_f32_f16_e32 v40, v17
	v_cvt_f32_f16_sdwa v41, v17 dst_sel:DWORD dst_unused:UNUSED_PAD src0_sel:WORD_1
	v_cvt_f32_f16_e32 v34, v2
	v_cvt_f32_f16_sdwa v35, v2 dst_sel:DWORD dst_unused:UNUSED_PAD src0_sel:WORD_1
	v_cvt_f32_f16_e32 v36, v3
	v_cvt_f32_f16_sdwa v37, v3 dst_sel:DWORD dst_unused:UNUSED_PAD src0_sel:WORD_1
	s_cbranch_execnz .LBB0_278

; __device__ __forceinline__ void phase_norm(const float* xin, const _Float16* xin_h, const bf16_t* dl, _Float16* xout, const float* g, const float* mod  , bf16_t* h) {
;     ...
;         for (int q = 0; q < 2; ++q) { const int row = min(row0 + q * NW, MTOK - 1);
;             if (xin_h) { const f16x4* xr = (const f16x4*)(xin_h + (size_t)row * XH_PITCH) + lane;
; #pragma unroll
;                 for (int j = 0; j < 8; ++j) { const f16x4 t = xr[64 * j]; v[q][j] = (f32x4){(float)t.x, (float)t.y, (float)t.z, (float)t.w}; } }
;             else { const f32x4* xr = (const f32x4*)(xin + (size_t)row * DM) + lane;
; #pragma unroll
;                 for (int j = 0; j < 8; ++j) v[q][j] = xr[64 * j]; }
;             if (dl) { const u32x2* dr = (const u32x2*)(dl + (size_t)row * DM) + lane;
; #pragma unroll
;                 for (int j = 0; j < 8; ++j) d[q][j] = dr[64 * j]; } }
.LBB0_278:
	v_cndmask_b32_e64 v0, 0, 1, s[46:47]
	v_cmp_ne_u32_e64 s[40:41], 1, v0
	s_andn2_b64 vcc, exec, s[46:47]
	s_cbranch_vccnz .LBB0_280
	v_lshl_add_u64 v[2:3], s[60:61], 0, v[66:67]
	global_load_dwordx2 v[136:137], v[2:3], off
	global_load_dwordx2 v[134:135], v[2:3], off offset:512
	global_load_dwordx2 v[132:133], v[2:3], off offset:1024
	global_load_dwordx2 v[130:131], v[2:3], off offset:1536
	global_load_dwordx2 v[128:129], v[2:3], off offset:2048
	global_load_dwordx2 v[126:127], v[2:3], off offset:2560
	global_load_dwordx2 v[124:125], v[2:3], off offset:3072
	global_load_dwordx2 v[122:123], v[2:3], off offset:3584
.LBB0_280:
	s_add_i32 s12, s21, s44
	s_min_i32 s16, s12, 0x3fff
	s_ashr_i32 s17, s16, 31
	s_and_b64 vcc, exec, s[42:43]
	s_lshl_b64 s[24:25], s[16:17], 13
	s_cbranch_vccnz .LBB0_295
	v_lshl_add_u64 v[2:3], v[68:69], 0, s[24:25]
	global_load_dwordx2 v[4:5], v[2:3], off
	global_load_dwordx2 v[6:7], v[2:3], off offset:512
	global_load_dwordx2 v[8:9], v[2:3], off offset:1024
	global_load_dwordx2 v[10:11], v[2:3], off offset:1536
	global_load_dwordx2 v[12:13], v[2:3], off offset:2048
	global_load_dwordx2 v[138:139], v[2:3], off offset:2560
	global_load_dwordx2 v[140:141], v[2:3], off offset:3072
	global_load_dwordx2 v[142:143], v[2:3], off offset:3584
	s_waitcnt vmcnt(0) lgkmcnt(0)
	v_cvt_f32_f16_e32 v30, v4
	v_cvt_f32_f16_sdwa v31, v4 dst_sel:DWORD dst_unused:UNUSED_PAD src0_sel:WORD_1
	v_cvt_f32_f16_e32 v32, v5
	v_cvt_f32_f16_sdwa v33, v5 dst_sel:DWORD dst_unused:UNUSED_PAD src0_sel:WORD_1
	v_cvt_f32_f16_e32 v26, v6
	v_cvt_f32_f16_sdwa v27, v6 dst_sel:DWORD dst_unused:UNUSED_PAD src0_sel:WORD_1
	v_cvt_f32_f16_e32 v28, v7
	v_cvt_f32_f16_sdwa v29, v7 dst_sel:DWORD dst_unused:UNUSED_PAD src0_sel:WORD_1
	v_cvt_f32_f16_e32 v22, v8
	v_cvt_f32_f16_sdwa v23, v8 dst_sel:DWORD dst_unused:UNUSED_PAD src0_sel:WORD_1
	v_cvt_f32_f16_e32 v24, v9
	v_cvt_f32_f16_sdwa v25, v9 dst_sel:DWORD dst_unused:UNUSED_PAD src0_sel:WORD_1
	v_cvt_f32_f16_e32 v18, v10
	v_cvt_f32_f16_sdwa v19, v10 dst_sel:DWORD dst_unused:UNUSED_PAD src0_sel:WORD_1
	v_cvt_f32_f16_e32 v20, v11
	v_cvt_f32_f16_sdwa v21, v11 dst_sel:DWORD dst_unused:UNUSED_PAD src0_sel:WORD_1
	v_cvt_f32_f16_e32 v14, v12
	v_cvt_f32_f16_sdwa v15, v12 dst_sel:DWORD dst_unused:UNUSED_PAD src0_sel:WORD_1
	v_cvt_f32_f16_e32 v16, v13
	v_cvt_f32_f16_sdwa v17, v13 dst_sel:DWORD dst_unused:UNUSED_PAD src0_sel:WORD_1
	v_cvt_f32_f16_e32 v10, v138
	v_cvt_f32_f16_sdwa v11, v138 dst_sel:DWORD dst_unused:UNUSED_PAD src0_sel:WORD_1
	v_cvt_f32_f16_e32 v12, v139
	v_cvt_f32_f16_sdwa v13, v139 dst_sel:DWORD dst_unused:UNUSED_PAD src0_sel:WORD_1
	v_cvt_f32_f16_e32 v6, v140
	v_cvt_f32_f16_sdwa v7, v140 dst_sel:DWORD dst_unused:UNUSED_PAD src0_sel:WORD_1
	v_cvt_f32_f16_e32 v8, v141
	v_cvt_f32_f16_sdwa v9, v141 dst_sel:DWORD dst_unused:UNUSED_PAD src0_sel:WORD_1
	v_cvt_f32_f16_e32 v2, v142
	v_cvt_f32_f16_sdwa v3, v142 dst_sel:DWORD dst_unused:UNUSED_PAD src0_sel:WORD_1
	v_cvt_f32_f16_e32 v4, v143
	v_cvt_f32_f16_sdwa v5, v143 dst_sel:DWORD dst_unused:UNUSED_PAD src0_sel:WORD_1
	s_cbranch_execnz .LBB0_283

; __device__ __forceinline__ void phase_norm(const float* xin, const _Float16* xin_h, const bf16_t* dl, _Float16* xout, const float* g, const float* mod  , bf16_t* h) {
;     ...
;             if (dl) { const u32x2* dr = (const u32x2*)(dl + (size_t)row * DM) + lane;
; #pragma unroll
;                 for (int j = 0; j < 8; ++j) d[q][j] = dr[64 * j]; } }
.LBB0_283:
	s_and_b64 vcc, exec, s[40:41]
	s_cbranch_vccnz .LBB0_285
	s_lshl_b64 s[2:3], s[16:17], 12
	v_lshl_add_u64 v[106:107], v[72:73], 0, s[2:3]
	global_load_dwordx2 v[120:121], v[106:107], off
	global_load_dwordx2 v[118:119], v[106:107], off offset:512
	global_load_dwordx2 v[116:117], v[106:107], off offset:1024
	global_load_dwordx2 v[114:115], v[106:107], off offset:1536
	global_load_dwordx2 v[112:113], v[106:107], off offset:2048
	global_load_dwordx2 v[110:111], v[106:107], off offset:2560
	global_load_dwordx2 v[108:109], v[106:107], off offset:3072
	s_nop 0
	global_load_dwordx2 v[106:107], v[106:107], off offset:3584
	s_and_b64 vcc, exec, s[40:41]
	s_cbranch_vccz .LBB0_286
	s_branch .LBB0_287

; __device__ __forceinline__ void phase_norm(const float* xin, const _Float16* xin_h, const bf16_t* dl, _Float16* xout, const float* g, const float* mod  , bf16_t* h) {
;     ...
;             if (xout) { f16x4* xo = (f16x4*)(xout + (size_t)row * XH_PITCH) + lane;
; #pragma unroll
;                 for (int j = 0; j < 8; ++j) xo[64 * j] = (f16x4){(_Float16)v[q][j].x, (_Float16)v[q][j].y, (_Float16)v[q][j].z, (_Float16)v[q][j].w}; }
; #pragma unroll
;             for (int j = 0; j < 8; ++j) s += (v[q][j].x * v[q][j].x + v[q][j].y * v[q][j].y) + (v[q][j].z * v[q][j].z + v[q][j].w * v[q][j].w);
;             const float rstd = 1.f / sqrtf(wave_sum(s) * (1.f / DM) + 1e-6f);
;             const float* mb = mod + (size_t)(row >> 12) * 6144;
;             u32x2* o8 = (u32x2*)(h + (size_t)row * DM) + lane;
; #pragma unroll
;             for (int j = 0; j < 8; ++j) { const int c = 4 * lane + 256 * j;
;                 const f32x4 gg = *(const f32x4*)(g + c), sh = *(const f32x4*)(mb + c), sc = *(const f32x4*)(mb + 2048 + c);
.LBB0_287:
	s_waitcnt vmcnt(0)
	v_mov_b32_e32 v138, v37
	v_mov_b32_e32 v141, v42
	v_mov_b32_e32 v143, v43
	v_mov_b32_e32 v140, v44
	v_mov_b32_e32 v142, v45
	v_mov_b32_e32 v144, v49
	v_mov_b32_e32 v147, v54
	v_mov_b32_e32 v149, v55
	v_mov_b32_e32 v146, v56
	v_mov_b32_e32 v148, v57
	s_and_b64 vcc, exec, s[50:51]
	s_cbranch_vccz .LBB0_289
	v_lshl_add_u64 v[150:151], s[56:57], 0, v[66:67]
	v_cvt_pk_f16_f32 v153, v64, v65
	v_cvt_pk_f16_f32 v152, v62, v63
	global_store_dwordx2 v[150:151], v[152:153], off
	v_cvt_pk_f16_f32 v153, v60, v61
	v_cvt_pk_f16_f32 v152, v58, v59
	global_store_dwordx2 v[150:151], v[152:153], off offset:512
	v_cvt_pk_f16_f32 v153, v146, v148
	v_cvt_pk_f16_f32 v152, v147, v149
	global_store_dwordx2 v[150:151], v[152:153], off offset:1024
	v_cvt_pk_f16_f32 v153, v52, v53
	v_cvt_pk_f16_f32 v152, v50, v51
	global_store_dwordx2 v[150:151], v[152:153], off offset:1536
	v_cvt_pk_f16_f32 v153, v48, v144
	v_cvt_pk_f16_f32 v152, v46, v47
	global_store_dwordx2 v[150:151], v[152:153], off offset:2048
	v_cvt_pk_f16_f32 v153, v140, v142
	v_cvt_pk_f16_f32 v152, v141, v143
	global_store_dwordx2 v[150:151], v[152:153], off offset:2560
	v_cvt_pk_f16_f32 v153, v40, v41
	v_cvt_pk_f16_f32 v152, v38, v39
	global_store_dwordx2 v[150:151], v[152:153], off offset:3072
	v_cvt_pk_f16_f32 v153, v36, v138
	v_cvt_pk_f16_f32 v152, v34, v35
	global_store_dwordx2 v[150:151], v[152:153], off offset:3584
.LBB0_289:
	v_mov_b32_e32 v152, v60
	v_mov_b32_e32 v153, v64
	v_mov_b32_e32 v156, v58
	v_mov_b32_e32 v157, v62
	v_mov_b32_e32 v150, v61
	v_mov_b32_e32 v151, v65
	v_mov_b32_e32 v154, v59
	v_mov_b32_e32 v155, v63
	v_pk_mul_f32 v[156:157], v[156:157], v[156:157]
	v_pk_mul_f32 v[152:153], v[152:153], v[152:153]
	v_pk_fma_f32 v[154:155], v[154:155], v[154:155], v[156:157]
	v_pk_fma_f32 v[150:151], v[150:151], v[150:151], v[152:153]
	v_pk_mul_f32 v[146:147], v[146:147], v[146:147]
	v_pk_add_f32 v[150:151], v[150:151], v[154:155]
	v_pk_fma_f32 v[146:147], v[148:149], v[148:149], v[146:147]
	v_pk_add_f32 v[150:151], v[150:151], v[150:151] op_sel_hi:[0,1]
	v_pk_add_f32 v[146:147], v[146:147], v[146:147] op_sel_hi:[0,1]
	v_mul_f32_e32 v0, v50, v50
	v_mul_f32_e32 v153, v52, v52
	v_mul_f32_e32 v145, v53, v53
	v_mul_f32_e32 v150, v46, v46
	v_mul_f32_e32 v146, v47, v47
	v_mov_b32_e32 v152, v144
	v_pk_fma_f32 v[148:149], v[50:51], v[50:51], v[0:1] op_sel_hi:[1,1,0]
	v_pk_add_f32 v[146:147], v[146:147], v[150:151]
	v_mul_f32_e32 v150, v144, v144
	v_pk_add_f32 v[144:145], v[144:145], v[152:153]
	v_mul_f32_e32 v148, v48, v48
	v_mov_b32_e32 v151, v145
	v_pk_add_f32 v[144:145], v[150:151], v[148:149]
	v_pk_mul_f32 v[140:141], v[140:141], v[140:141]
	v_pk_add_f32 v[144:145], v[144:145], v[146:147]
	v_pk_fma_f32 v[140:141], v[142:143], v[142:143], v[140:141]
	v_pk_add_f32 v[144:145], v[144:145], v[144:145] op_sel_hi:[0,1]
	v_pk_add_f32 v[140:141], v[140:141], v[140:141] op_sel_hi:[0,1]
	v_mul_f32_e32 v0, v38, v38
	v_mul_f32_e32 v147, v40, v40
	v_mul_f32_e32 v139, v41, v41
	v_mul_f32_e32 v144, v34, v34
	v_mul_f32_e32 v140, v35, v35
	v_mov_b32_e32 v146, v138
	v_pk_fma_f32 v[142:143], v[38:39], v[38:39], v[0:1] op_sel_hi:[1,1,0]
	v_pk_add_f32 v[140:141], v[140:141], v[144:145]
	v_mul_f32_e32 v144, v138, v138
	v_pk_add_f32 v[138:139], v[138:139], v[146:147]
	v_mul_f32_e32 v142, v36, v36
	v_mov_b32_e32 v145, v139
	v_pk_add_f32 v[138:139], v[144:145], v[142:143]
	s_mov_b32 s2, 0xf800000
	v_pk_add_f32 v[138:139], v[138:139], v[140:141]
	global_load_dwordx4 v[142:145], v[80:81], off
	v_add_f32_e32 v0, v138, v139
	ds_bpermute_b32 v97, v79, v0
	v_lshl_add_u64 v[154:155], s[52:53], 0, v[66:67]
	s_waitcnt lgkmcnt(0)
	v_add_f32_e32 v0, v0, v97
	ds_bpermute_b32 v97, v83, v0
	s_waitcnt lgkmcnt(0)
	v_add_f32_e32 v0, v0, v97
	ds_bpermute_b32 v97, v85, v0
	s_waitcnt lgkmcnt(0)
	v_add_f32_e32 v0, v0, v97
	ds_bpermute_b32 v97, v87, v0
	s_waitcnt lgkmcnt(0)
	v_add_f32_e32 v0, v0, v97
	ds_bpermute_b32 v97, v89, v0
	s_waitcnt lgkmcnt(0)
	v_add_f32_e32 v0, v0, v97
	ds_bpermute_b32 v97, v93, v0
	s_waitcnt lgkmcnt(0)
	v_add_f32_e32 v0, v0, v97
	v_fmamk_f32 v0, v0, 0x3a000000, v181
	v_cmp_gt_f32_e32 vcc, s2, v0
	v_mul_f32_e32 v97, 0x4f800000, v0
	s_nop 0
	v_cndmask_b32_e32 v0, v0, v97, vcc
	v_sqrt_f32_e32 v97, v0
	s_nop 0
	v_add_u32_e32 v101, -1, v97
	v_fma_f32 v138, -v101, v97, v0
	v_cmp_ge_f32_e64 s[42:43], 0, v138
	v_add_u32_e32 v138, 1, v97
	s_nop 0
	v_cndmask_b32_e64 v101, v97, v101, s[42:43]
	v_fma_f32 v97, -v138, v97, v0
	v_cmp_lt_f32_e64 s[42:43], 0, v97
	s_nop 1
	v_cndmask_b32_e64 v97, v101, v138, s[42:43]
	v_mul_f32_e32 v101, 0x37800000, v97
	v_cndmask_b32_e32 v97, v97, v101, vcc
	v_cmp_class_f32_e32 vcc, v0, v180
	s_nop 1
	v_cndmask_b32_e32 v0, v97, v0, vcc
	v_div_scale_f32 v97, s[2:3], v0, v0, 1.0
	v_rcp_f32_e32 v101, v97
	s_ashr_i32 s2, s44, 12
	s_mul_hi_i32 s3, s2, 0x6000
	s_mulk_i32 s2, 0x6000
	v_fma_f32 v138, -v97, v101, 1.0
	v_fmac_f32_e32 v101, v138, v101
	v_div_scale_f32 v138, vcc, 1.0, v0, 1.0
	v_mul_f32_e32 v139, v138, v101
	v_fma_f32 v140, -v97, v139, v138
	v_fmac_f32_e32 v139, v140, v101
	s_add_u32 s26, s33, s2
	v_fma_f32 v97, -v97, v139, v138
	s_addc_u32 s27, s58, s3
	v_div_fmas_f32 v97, v97, v101, v139
	s_add_u32 s16, s26, 0x2000
	v_div_fixup_f32 v138, v97, v0, 1.0
	s_addc_u32 s17, s27, 0
	v_lshlrev_b32_e32 v0, 2, v78
	v_lshl_add_u64 v[140:141], s[26:27], 0, v[0:1]
	v_lshl_add_u64 v[150:151], s[16:17], 0, v[0:1]
	global_load_dwordx4 v[146:149], v[140:141], off
	v_pk_mul_f32 v[64:65], v[64:65], v[138:139] op_sel_hi:[1,0]
	global_load_dwordx4 v[150:153], v[150:151], off
	v_pk_mul_f32 v[62:63], v[62:63], v[138:139] op_sel_hi:[1,0]
	s_waitcnt vmcnt(0)
; __device__ __forceinline__ unsigned pk2(float lo, float hi) { unsigned r; asm("v_cvt_pk_bf16_f32 %0, %1, %2" : "=v"(r) : "v"(lo), "v"(hi)); return r; }
; __device__ __forceinline__ void phase_norm(const float* xin, const _Float16* xin_h, const bf16_t* dl, _Float16* xout, const float* g, const float* mod  , bf16_t* h) {
;     ...
; #pragma unroll
;             for (int j = 0; j < 8; ++j) { const int c = 4 * lane + 256 * j;
;                 const f32x4 gg = *(const f32x4*)(g + c), sh = *(const f32x4*)(mb + c), sc = *(const f32x4*)(mb + 2048 + c);
;                 const f32x4 y = v[q][j] * rstd * gg * (1.f + sc) + sh;
;                 u32x2 w; w.x = pk2(y.x, y.y); w.y = pk2(y.z, y.w); o8[64 * j] = w; } }
	v_pk_mul_f32 v[64:65], v[144:145], v[64:65]
	v_pk_mul_f32 v[62:63], v[142:143], v[62:63]
	v_pk_mul_f32 v[60:61], v[60:61], v[138:139] op_sel_hi:[1,0]
	v_pk_mul_f32 v[58:59], v[58:59], v[138:139] op_sel_hi:[1,0]
	v_pk_mul_f32 v[54:55], v[54:55], v[138:139] op_sel_hi:[1,0]
	v_pk_mul_f32 v[56:57], v[56:57], v[138:139] op_sel_hi:[1,0]
	v_pk_mul_f32 v[50:51], v[50:51], v[138:139] op_sel_hi:[1,0]
	v_pk_mul_f32 v[52:53], v[52:53], v[138:139] op_sel_hi:[1,0]
	v_pk_mul_f32 v[46:47], v[46:47], v[138:139] op_sel_hi:[1,0]
	v_pk_mul_f32 v[48:49], v[48:49], v[138:139] op_sel_hi:[1,0]
	v_pk_mul_f32 v[42:43], v[42:43], v[138:139] op_sel_hi:[1,0]
	v_pk_mul_f32 v[44:45], v[44:45], v[138:139] op_sel_hi:[1,0]
	v_pk_mul_f32 v[38:39], v[38:39], v[138:139] op_sel_hi:[1,0]
	v_pk_mul_f32 v[40:41], v[40:41], v[138:139] op_sel_hi:[1,0]
	v_pk_mul_f32 v[34:35], v[34:35], v[138:139] op_sel_hi:[1,0]
	v_pk_mul_f32 v[36:37], v[36:37], v[138:139] op_sel_hi:[1,0]
	s_cmpk_gt_i32 s12, 0x3fff
	s_waitcnt lgkmcnt(0)
	v_pk_add_f32 v[142:143], v[152:153], 1.0 op_sel_hi:[1,0]
	v_pk_add_f32 v[144:145], v[150:151], 1.0 op_sel_hi:[1,0]
	v_pk_fma_f32 v[64:65], v[142:143], v[64:65], v[148:149]
	v_pk_fma_f32 v[62:63], v[144:145], v[62:63], v[146:147]
	s_nop 0
	v_cvt_pk_bf16_f32 v62, v62, v63
	v_cvt_pk_bf16_f32 v63, v64, v65
	v_add_co_u32_e32 v64, vcc, s83, v154
	s_nop 1
	v_addc_co_u32_e32 v65, vcc, 0, v155, vcc
	global_store_dwordx2 v[64:65], v[62:63], off
	v_lshlrev_b32_e32 v62, 2, v82
	v_mov_b32_e32 v63, v1
	v_lshl_add_u64 v[150:151], s[16:17], 0, v[62:63]
	global_load_dwordx4 v[142:145], v[80:81], off offset:1024
	global_load_dwordx4 v[146:149], v[140:141], off offset:1024
	s_waitcnt vmcnt(0)
	v_pk_mul_f32 v[58:59], v[142:143], v[58:59]
	global_load_dwordx4 v[150:153], v[150:151], off
	v_pk_mul_f32 v[60:61], v[144:145], v[60:61]
	s_waitcnt vmcnt(0) lgkmcnt(0)
	v_pk_add_f32 v[144:145], v[150:151], 1.0 op_sel_hi:[1,0]
	v_pk_add_f32 v[142:143], v[152:153], 1.0 op_sel_hi:[1,0]
	v_pk_fma_f32 v[58:59], v[144:145], v[58:59], v[146:147]
	v_pk_fma_f32 v[60:61], v[142:143], v[60:61], v[148:149]
	v_cvt_pk_bf16_f32 v58, v58, v59
	s_nop 0
	v_cvt_pk_bf16_f32 v59, v60, v61
	global_store_dwordx2 v[64:65], v[58:59], off offset:512
	v_lshlrev_b32_e32 v58, 2, v84
	v_mov_b32_e32 v59, v1
	v_lshl_add_u64 v[60:61], s[16:17], 0, v[58:59]
	global_load_dwordx4 v[142:145], v[80:81], off offset:2048
	global_load_dwordx4 v[146:149], v[140:141], off offset:2048
	global_load_dwordx4 v[150:153], v[60:61], off
	s_waitcnt vmcnt(0)
	v_pk_mul_f32 v[54:55], v[142:143], v[54:55]
	v_pk_mul_f32 v[56:57], v[144:145], v[56:57]
	s_waitcnt lgkmcnt(0)
	v_pk_add_f32 v[142:143], v[150:151], 1.0 op_sel_hi:[1,0]
	v_pk_add_f32 v[60:61], v[152:153], 1.0 op_sel_hi:[1,0]
	v_pk_fma_f32 v[54:55], v[142:143], v[54:55], v[146:147]
	v_pk_fma_f32 v[56:57], v[60:61], v[56:57], v[148:149]
	v_cvt_pk_bf16_f32 v54, v54, v55
	s_nop 0
	v_cvt_pk_bf16_f32 v55, v56, v57
	global_store_dwordx2 v[64:65], v[54:55], off offset:1024
	v_lshlrev_b32_e32 v54, 2, v86
	v_mov_b32_e32 v55, v1
	v_lshl_add_u64 v[56:57], s[16:17], 0, v[54:55]
	global_load_dwordx4 v[142:145], v[80:81], off offset:3072
	global_load_dwordx4 v[146:149], v[140:141], off offset:3072
	global_load_dwordx4 v[150:153], v[56:57], off
	s_waitcnt vmcnt(0)
	v_pk_mul_f32 v[50:51], v[50:51], v[142:143]
	v_pk_mul_f32 v[52:53], v[52:53], v[144:145]
	s_waitcnt lgkmcnt(0)
	v_pk_add_f32 v[60:61], v[150:151], 1.0 op_sel_hi:[1,0]
	v_pk_add_f32 v[56:57], v[152:153], 1.0 op_sel_hi:[1,0]
	v_pk_fma_f32 v[50:51], v[50:51], v[60:61], v[146:147]
	v_pk_fma_f32 v[52:53], v[52:53], v[56:57], v[148:149]
	v_cvt_pk_bf16_f32 v50, v50, v51
	s_nop 0
	v_cvt_pk_bf16_f32 v51, v52, v53
	global_store_dwordx2 v[64:65], v[50:51], off offset:1536
	v_lshlrev_b32_e32 v50, 2, v88
	v_mov_b32_e32 v51, v1
	v_lshl_add_u64 v[52:53], s[26:27], 0, v[50:51]
	global_load_dwordx4 v[144:147], v[52:53], off
	v_lshl_add_u64 v[52:53], s[16:17], 0, v[50:51]
	global_load_dwordx4 v[140:143], v[90:91], off
	global_load_dwordx4 v[148:151], v[52:53], off
	s_waitcnt vmcnt(0)
	v_pk_mul_f32 v[46:47], v[46:47], v[140:141]
	s_waitcnt lgkmcnt(0)
	v_pk_add_f32 v[56:57], v[148:149], 1.0 op_sel_hi:[1,0]
	v_pk_mul_f32 v[48:49], v[48:49], v[142:143]
	v_pk_add_f32 v[52:53], v[150:151], 1.0 op_sel_hi:[1,0]
	v_pk_fma_f32 v[46:47], v[46:47], v[56:57], v[144:145]
	v_pk_fma_f32 v[48:49], v[48:49], v[52:53], v[146:147]
	v_cvt_pk_bf16_f32 v46, v46, v47
	s_nop 0
	v_cvt_pk_bf16_f32 v47, v48, v49
	global_store_dwordx2 v[64:65], v[46:47], off offset:2048
	v_lshlrev_b32_e32 v46, 2, v92
	v_mov_b32_e32 v47, v1
	v_lshl_add_u64 v[48:49], s[26:27], 0, v[46:47]
	global_load_dwordx4 v[144:147], v[48:49], off
	v_lshl_add_u64 v[48:49], s[16:17], 0, v[46:47]
	global_load_dwordx4 v[140:143], v[94:95], off
	global_load_dwordx4 v[148:151], v[48:49], off
	s_waitcnt vmcnt(0)
	v_pk_mul_f32 v[42:43], v[42:43], v[140:141]
	s_waitcnt lgkmcnt(0)
	v_pk_add_f32 v[52:53], v[148:149], 1.0 op_sel_hi:[1,0]
	v_pk_mul_f32 v[44:45], v[44:45], v[142:143]
	v_pk_add_f32 v[48:49], v[150:151], 1.0 op_sel_hi:[1,0]
	v_pk_fma_f32 v[42:43], v[42:43], v[52:53], v[144:145]
	v_pk_fma_f32 v[44:45], v[44:45], v[48:49], v[146:147]
	v_cvt_pk_bf16_f32 v42, v42, v43
	s_nop 0
	v_cvt_pk_bf16_f32 v43, v44, v45
	global_store_dwordx2 v[64:65], v[42:43], off offset:2560
	v_lshlrev_b32_e32 v42, 2, v96
	v_mov_b32_e32 v43, v1
	v_lshl_add_u64 v[44:45], s[26:27], 0, v[42:43]
	global_load_dwordx4 v[144:147], v[44:45], off
	v_lshl_add_u64 v[44:45], s[16:17], 0, v[42:43]
	global_load_dwordx4 v[140:143], v[98:99], off
	global_load_dwordx4 v[148:151], v[44:45], off
	s_waitcnt vmcnt(0)
	v_pk_mul_f32 v[38:39], v[38:39], v[140:141]
	s_waitcnt lgkmcnt(0)
	v_pk_add_f32 v[48:49], v[148:149], 1.0 op_sel_hi:[1,0]
	v_pk_mul_f32 v[40:41], v[40:41], v[142:143]
	v_pk_add_f32 v[44:45], v[150:151], 1.0 op_sel_hi:[1,0]
	v_pk_fma_f32 v[38:39], v[38:39], v[48:49], v[144:145]
	v_pk_fma_f32 v[40:41], v[40:41], v[44:45], v[146:147]
	v_cvt_pk_bf16_f32 v38, v38, v39
	s_nop 0
	v_cvt_pk_bf16_f32 v39, v40, v41
	global_store_dwordx2 v[64:65], v[38:39], off offset:3072
	v_lshlrev_b32_e32 v38, 2, v100
	v_mov_b32_e32 v39, v1
	v_lshl_add_u64 v[40:41], s[26:27], 0, v[38:39]
	global_load_dwordx4 v[144:147], v[40:41], off
	v_lshl_add_u64 v[40:41], s[16:17], 0, v[38:39]
	global_load_dwordx4 v[140:143], v[102:103], off
	global_load_dwordx4 v[148:151], v[40:41], off
	s_waitcnt vmcnt(0)
	v_pk_mul_f32 v[34:35], v[34:35], v[140:141]
	s_waitcnt lgkmcnt(0)
	v_pk_add_f32 v[44:45], v[148:149], 1.0 op_sel_hi:[1,0]
	v_pk_mul_f32 v[36:37], v[36:37], v[142:143]
	v_pk_add_f32 v[40:41], v[150:151], 1.0 op_sel_hi:[1,0]
	v_pk_fma_f32 v[34:35], v[34:35], v[44:45], v[144:145]
	v_pk_fma_f32 v[36:37], v[36:37], v[40:41], v[146:147]
	v_cvt_pk_bf16_f32 v34, v34, v35
	s_nop 0
	v_cvt_pk_bf16_f32 v35, v36, v37
	global_store_dwordx2 v[64:65], v[34:35], off offset:3584
	s_cbranch_scc1 .LBB0_274
; __device__ __forceinline__ float bf_lo(unsigned u) { return __uint_as_float(u << 16); }
; __device__ __forceinline__ float bf_hi(unsigned u) { return __uint_as_float(u & 0xffff0000u); }
; __device__ __forceinline__ void phase_norm(const float* xin, const _Float16* xin_h, const bf16_t* dl, _Float16* xout, const float* g, const float* mod  , bf16_t* h) {
;     ...
;             if (dl) {
; #pragma unroll
;                 for (int j = 0; j < 8; ++j) { v[q][j].x += bf_lo(d[q][j].x); v[q][j].y += bf_hi(d[q][j].x); v[q][j].z += bf_lo(d[q][j].y); v[q][j].w += bf_hi(d[q][j].y); } }
;             if (xout) { f16x4* xo = (f16x4*)(xout + (size_t)row * XH_PITCH) + lane;
; #pragma unroll
;                 for (int j = 0; j < 8; ++j) xo[64 * j] = (f16x4){(_Float16)v[q][j].x, (_Float16)v[q][j].y, (_Float16)v[q][j].z, (_Float16)v[q][j].w}; }
	s_and_b64 vcc, exec, s[40:41]
	s_cbranch_vccnz .LBB0_292
	v_lshlrev_b32_e32 v34, 16, v120
	v_and_b32_e32 v35, 0xffff0000, v120
	v_pk_add_f32 v[30:31], v[30:31], v[34:35]
	v_lshlrev_b32_e32 v34, 16, v121
	v_and_b32_e32 v35, 0xffff0000, v121
	v_pk_add_f32 v[32:33], v[32:33], v[34:35]
	v_lshlrev_b32_e32 v34, 16, v118
	v_and_b32_e32 v35, 0xffff0000, v118
	v_pk_add_f32 v[26:27], v[26:27], v[34:35]
	v_lshlrev_b32_e32 v34, 16, v119
	v_and_b32_e32 v35, 0xffff0000, v119
	v_pk_add_f32 v[28:29], v[28:29], v[34:35]
	v_lshlrev_b32_e32 v34, 16, v116
	v_and_b32_e32 v35, 0xffff0000, v116
	v_pk_add_f32 v[22:23], v[22:23], v[34:35]
	v_lshlrev_b32_e32 v34, 16, v117
	v_and_b32_e32 v35, 0xffff0000, v117
	v_pk_add_f32 v[24:25], v[24:25], v[34:35]
	v_lshlrev_b32_e32 v34, 16, v114
	v_and_b32_e32 v35, 0xffff0000, v114
	v_pk_add_f32 v[18:19], v[18:19], v[34:35]
	v_lshlrev_b32_e32 v34, 16, v115
	v_and_b32_e32 v35, 0xffff0000, v115
	v_pk_add_f32 v[20:21], v[20:21], v[34:35]
	v_lshlrev_b32_e32 v34, 16, v112
	v_and_b32_e32 v35, 0xffff0000, v112
	v_pk_add_f32 v[14:15], v[14:15], v[34:35]
	v_lshlrev_b32_e32 v34, 16, v113
	v_and_b32_e32 v35, 0xffff0000, v113
	v_pk_add_f32 v[16:17], v[16:17], v[34:35]
	v_lshlrev_b32_e32 v34, 16, v110
	v_and_b32_e32 v35, 0xffff0000, v110
	v_pk_add_f32 v[10:11], v[10:11], v[34:35]
	v_lshlrev_b32_e32 v34, 16, v111
	v_and_b32_e32 v35, 0xffff0000, v111
	v_pk_add_f32 v[12:13], v[12:13], v[34:35]
	v_lshlrev_b32_e32 v34, 16, v108
	v_and_b32_e32 v35, 0xffff0000, v108
	v_pk_add_f32 v[6:7], v[6:7], v[34:35]
	v_lshlrev_b32_e32 v34, 16, v109
	v_and_b32_e32 v35, 0xffff0000, v109
	v_pk_add_f32 v[8:9], v[8:9], v[34:35]
	v_lshlrev_b32_e32 v34, 16, v106
	v_and_b32_e32 v35, 0xffff0000, v106
	v_pk_add_f32 v[2:3], v[2:3], v[34:35]
	v_lshlrev_b32_e32 v34, 16, v107
	v_and_b32_e32 v35, 0xffff0000, v107
	v_pk_add_f32 v[4:5], v[4:5], v[34:35]
.LBB0_292:
	s_nop 0
	v_mov_b32_e32 v34, v5
	v_mov_b32_e32 v37, v10
	v_mov_b32_e32 v41, v11
	v_mov_b32_e32 v36, v12
	v_mov_b32_e32 v40, v13
	v_mov_b32_e32 v44, v17
	v_mov_b32_e32 v49, v22
	v_mov_b32_e32 v53, v23
	v_mov_b32_e32 v48, v24
	v_mov_b32_e32 v52, v25
	s_and_b64 vcc, exec, s[50:51]
	s_cbranch_vccz .LBB0_296
	s_ashr_i32 s13, s12, 31
	s_lshl_b64 s[2:3], s[12:13], 13
	v_lshl_add_u64 v[56:57], v[74:75], 0, s[2:3]
	v_cvt_pk_f16_f32 v61, v32, v33
	v_cvt_pk_f16_f32 v60, v30, v31
	global_store_dwordx2 v[56:57], v[60:61], off
	v_cvt_pk_f16_f32 v61, v28, v29
	v_cvt_pk_f16_f32 v60, v26, v27
	global_store_dwordx2 v[56:57], v[60:61], off offset:512
	v_cvt_pk_f16_f32 v61, v48, v52
	v_cvt_pk_f16_f32 v60, v49, v53
	global_store_dwordx2 v[56:57], v[60:61], off offset:1024
	v_cvt_pk_f16_f32 v61, v20, v21
	v_cvt_pk_f16_f32 v60, v18, v19
	global_store_dwordx2 v[56:57], v[60:61], off offset:1536
	v_cvt_pk_f16_f32 v61, v16, v44
	v_cvt_pk_f16_f32 v60, v14, v15
	global_store_dwordx2 v[56:57], v[60:61], off offset:2048
	v_cvt_pk_f16_f32 v61, v36, v40
	v_cvt_pk_f16_f32 v60, v37, v41
	global_store_dwordx2 v[56:57], v[60:61], off offset:2560
	v_cvt_pk_f16_f32 v61, v8, v9
	v_cvt_pk_f16_f32 v60, v6, v7
	global_store_dwordx2 v[56:57], v[60:61], off offset:3072
	v_cvt_pk_f16_f32 v61, v4, v34
	v_cvt_pk_f16_f32 v60, v2, v3
	global_store_dwordx2 v[56:57], v[60:61], off offset:3584
	v_mov_b32_e32 v56, v29
	v_mov_b32_e32 v57, v33
	v_mov_b32_e32 v60, v28
	v_mov_b32_e32 v61, v32
	v_mov_b32_e32 v64, v27
	v_mov_b32_e32 v65, v31
	v_mov_b32_e32 v138, v26
	v_mov_b32_e32 v139, v30
	s_cbranch_execnz .LBB0_273
	s_branch .LBB0_272

; __device__ __forceinline__ float gelu_f(float x) { const float u = 0.7978845608028654f * (x + 0.044715f * x * x * x); return x * frcp(1.f + fexp2(-2.885390081777927f * u)); }
;     __device__ __forceinline__ void operator()(const f32x4 (&acc)[2][2][4][2], const Unit& u, int wr, int wc, int fr, int fq) const {
;     ...
;             for (int ai = 0; ai < 2; ++ai)
; #pragma unroll
;                 for (int m = 0; m < 4; ++m) { const int row = row0 + ai * 128 + m * 16; float s1 = 0.f, s2 = 0.f;
; #pragma unroll
;                     for (int bj = 0; bj < 2; ++bj) { float o[8];
; #pragma unroll
;                         for (int j = 0; j < 4; ++j) { o[j] = gelu_f(acc[ai][bj][m][0][j]); o[4 + j] = gelu_f(acc[ai][bj][m][1][j]); }
; #pragma unroll
;                         for (int j = 0; j < 8; ++j) { s1 += o[j]; s2 += o[j] * o[j]; }
.LBB0_312:
	v_lshl_add_u32 v142, s4, 8, v150
	v_mul_f32_e32 v0, 0x3d372713, v126
	v_mul_f32_e32 v144, 0x3d372713, v122
	v_mul_f32_e32 v145, 0x3d372713, v127
	v_mul_f32_e32 v146, 0x3d372713, v123
	v_mul_f32_e32 v147, 0x3d372713, v128
	v_mul_f32_e32 v148, 0x3d372713, v124
	v_mul_f32_e32 v149, 0x3d372713, v129
	v_mul_f32_e32 v154, 0x3d372713, v125
	s_mov_b64 s[12:13], -1
	s_cmp_gt_i32 s89, 15
	v_ashrrev_i32_e32 v143, 31, v142
	v_mul_f32_e32 v161, v126, v0
	v_mul_f32_e32 v160, v122, v144
	v_mul_f32_e32 v159, v127, v145
	v_mul_f32_e32 v158, v123, v146
	v_mul_f32_e32 v157, v128, v147
	v_mul_f32_e32 v156, v124, v148
	v_mul_f32_e32 v155, v129, v149
	v_mul_f32_e32 v154, v125, v154
	s_cbranch_scc0 .LBB0_331
	v_fma_f32 v147, v127, v159, v127
	v_mul_f32_e32 v147, 0x3f4c422a, v147
	v_mul_f32_e32 v147, 0xc038aa3b, v147
	v_exp_f32_e32 v147, v147
	v_fma_f32 v146, v126, v161, v126
	v_mul_f32_e32 v146, 0x3f4c422a, v146
	v_mul_f32_e32 v146, 0xc038aa3b, v146
	v_add_f32_e32 v147, 1.0, v147
	v_rcp_f32_e32 v164, v147
	v_fma_f32 v147, v123, v158, v123
	v_mul_f32_e32 v147, 0x3f4c422a, v147
	v_mul_f32_e32 v147, 0xc038aa3b, v147
	v_exp_f32_e32 v147, v147
	v_exp_f32_e32 v146, v146
	v_mul_f32_e32 v167, v127, v164
	v_mul_f32_e32 v169, v167, v167
	v_add_f32_e32 v147, 1.0, v147
	v_rcp_f32_e32 v148, v147
	v_fma_f32 v147, v128, v157, v128
	v_mul_f32_e32 v147, 0x3f4c422a, v147
	v_mul_f32_e32 v147, 0xc038aa3b, v147
	v_exp_f32_e32 v147, v147
	v_add_f32_e32 v146, 1.0, v146
	v_rcp_f32_e32 v163, v146
	v_fma_f32 v146, v122, v160, v122
	v_add_f32_e32 v147, 1.0, v147
	v_rcp_f32_e32 v165, v147
	v_fma_f32 v147, v124, v156, v124
	v_mul_f32_e32 v147, 0x3f4c422a, v147
	v_mul_f32_e32 v147, 0xc038aa3b, v147
	v_exp_f32_e32 v147, v147
	v_mul_f32_e32 v146, 0x3f4c422a, v146
	v_mul_f32_e32 v146, 0xc038aa3b, v146
	v_exp_f32_e32 v146, v146
	v_add_f32_e32 v147, 1.0, v147
	v_rcp_f32_e32 v149, v147
	v_fma_f32 v147, v129, v155, v129
	v_mul_f32_e32 v147, 0x3f4c422a, v147
	v_mul_f32_e32 v147, 0xc038aa3b, v147
	v_exp_f32_e32 v147, v147
	v_add_f32_e32 v146, 1.0, v146
	v_rcp_f32_e32 v146, v146
	v_mul_f32_e32 v166, v126, v163
	v_add_f32_e32 v147, 1.0, v147
	v_rcp_f32_e32 v147, v147
	v_fma_f32 v163, v126, v163, 0
	v_fmac_f32_e32 v163, v127, v164
	v_mul_f32_e32 v168, v128, v165
	v_fmac_f32_e32 v163, v128, v165
	v_mov_b32_e32 v164, v122
	v_mov_b32_e32 v165, v129
	v_fmac_f32_e32 v169, v166, v166
	v_pk_mul_f32 v[164:165], v[164:165], v[146:147]
	v_fmac_f32_e32 v169, v168, v168
	v_pk_mul_f32 v[146:147], v[164:165], v[164:165]
	v_add_f32_e32 v163, v165, v163
	v_add_f32_e32 v147, v147, v169
	v_add_f32_e32 v169, v146, v147
	v_mov_b32_e32 v146, v123
	v_mov_b32_e32 v147, v124
	v_pk_mul_f32 v[148:149], v[146:147], v[148:149]
	v_add_f32_e32 v163, v164, v163
	v_pk_mul_f32 v[146:147], v[148:149], v[148:149]
	v_add_f32_e32 v163, v148, v163
	v_add_f32_e32 v146, v146, v169
	v_add_f32_e32 v175, v147, v146
	v_cvt_pk_bf16_f32 v147, v168, v165
	v_mul_f32_e32 v165, 0x3d372713, v119
	v_mul_f32_e32 v165, v119, v165
	v_fma_f32 v165, v119, v165, v119
	v_mul_f32_e32 v165, 0x3f4c422a, v165
	v_mul_f32_e32 v165, 0xc038aa3b, v165
	v_exp_f32_e32 v165, v165
	v_cvt_pk_bf16_f32 v146, v166, v167
	v_add_f32_e32 v174, v149, v163
	v_mul_f32_e32 v163, 0x3d372713, v118
	v_add_f32_e32 v165, 1.0, v165
	v_rcp_f32_e32 v166, v165
	v_mul_f32_e32 v165, 0x3d372713, v115
	v_mul_f32_e32 v165, v115, v165
	v_fma_f32 v165, v115, v165, v115
	v_mul_f32_e32 v165, 0x3f4c422a, v165
	v_mul_f32_e32 v165, 0xc038aa3b, v165
	v_exp_f32_e32 v165, v165
	v_mul_f32_e32 v163, v118, v163
	v_fma_f32 v162, v125, v154, v125
	v_fma_f32 v163, v118, v163, v118
	v_add_f32_e32 v165, 1.0, v165
	v_rcp_f32_e32 v168, v165
	v_mul_f32_e32 v165, 0x3d372713, v120
	v_mul_f32_e32 v165, v120, v165
	v_fma_f32 v165, v120, v165, v120
	v_mul_f32_e32 v165, 0x3f4c422a, v165
	v_mul_f32_e32 v165, 0xc038aa3b, v165
	v_exp_f32_e32 v165, v165
	v_mul_f32_e32 v162, 0x3f4c422a, v162
	v_mul_f32_e32 v163, 0x3f4c422a, v163
	v_mul_f32_e32 v162, 0xc038aa3b, v162
	v_add_f32_e32 v165, 1.0, v165
	v_rcp_f32_e32 v167, v165
	v_mul_f32_e32 v165, 0x3d372713, v116
	v_mul_f32_e32 v165, v116, v165
	v_fma_f32 v165, v116, v165, v116
	v_mul_f32_e32 v165, 0x3f4c422a, v165
	v_mul_f32_e32 v165, 0xc038aa3b, v165
	v_exp_f32_e32 v165, v165
	v_mul_f32_e32 v163, 0xc038aa3b, v163
	v_exp_f32_e32 v162, v162
	v_exp_f32_e32 v163, v163
	v_add_f32_e32 v165, 1.0, v165
	v_cvt_pk_bf16_f32 v148, v164, v148
	v_mul_f32_e32 v164, 0x3d372713, v114
	v_rcp_f32_e32 v170, v165
	v_mul_f32_e32 v165, 0x3d372713, v121
	v_mul_f32_e32 v164, v114, v164
	v_mul_f32_e32 v165, v121, v165
	v_fma_f32 v164, v114, v164, v114
	v_fma_f32 v165, v121, v165, v121
	v_add_f32_e32 v162, 1.0, v162
	v_add_f32_e32 v163, 1.0, v163
	v_mul_f32_e32 v164, 0x3f4c422a, v164
	v_mul_f32_e32 v165, 0x3f4c422a, v165
	v_mul_f32_e32 v171, 0x3d372713, v117
	v_rcp_f32_e32 v162, v162
	v_rcp_f32_e32 v163, v163
	v_mul_f32_e32 v164, 0xc038aa3b, v164
	v_mul_f32_e32 v165, 0xc038aa3b, v165
	v_mul_f32_e32 v171, v117, v171
	s_add_i32 s2, s89, -16
	v_exp_f32_e32 v164, v164
	v_exp_f32_e32 v165, v165
	v_fma_f32 v171, v117, v171, v117
	v_lshl_or_b32 v0, s2, 8, v152
	v_lshlrev_b64 v[144:145], 12, v[142:143]
	v_mul_f32_e32 v171, 0x3f4c422a, v171
	v_lshl_add_u64 v[144:145], s[46:47], 0, v[144:145]
	v_lshlrev_b32_e32 v0, 1, v0
	v_mul_f32_e32 v171, 0xc038aa3b, v171
	v_pk_mov_b32 v[172:173], v[124:125], v[118:119] op_sel:[1,0]
	v_lshl_add_u64 v[144:145], v[144:145], 0, v[0:1]
	v_exp_f32_e32 v171, v171
	v_pk_mul_f32 v[162:163], v[172:173], v[162:163]
	v_add_f32_e32 v164, 1.0, v164
	v_add_f32_e32 v165, 1.0, v165
	v_add_f32_e32 v174, v162, v174
	v_pk_mul_f32 v[172:173], v[162:163], v[162:163]
	v_cvt_pk_bf16_f32 v149, v149, v162
; __device__ __forceinline__ float gelu_f(float x) { const float u = 0.7978845608028654f * (x + 0.044715f * x * x * x); return x * frcp(1.f + fexp2(-2.885390081777927f * u)); }
; __device__ __forceinline__ void st8(bf16_t* p, const float (&v)[8]) { u32x4 w; w.x = pk2(v[0], v[1]); w.y = pk2(v[2], v[3]); w.z = pk2(v[4], v[5]); w.w = pk2(v[6], v[7]); *(u32x4*)p = w; }
;     __device__ __forceinline__ void operator()(const f32x4 (&acc)[2][2][4][2], const Unit& u, int wr, int wc, int fr, int fq) const {
;     ...
;                 for (int m = 0; m < 4; ++m) { const int row = row0 + ai * 128 + m * 16; float s1 = 0.f, s2 = 0.f;
; #pragma unroll
;                     for (int bj = 0; bj < 2; ++bj) { float o[8];
; #pragma unroll
;                         for (int j = 0; j < 4; ++j) { o[j] = gelu_f(acc[ai][bj][m][0][j]); o[4 + j] = gelu_f(acc[ai][bj][m][1][j]); }
; #pragma unroll
;                         for (int j = 0; j < 8; ++j) { s1 += o[j]; s2 += o[j] * o[j]; }
;                         st8(gv + (size_t)row * DM + colt + bj * 128, o); }
;                     s1 += __shfl_xor(s1, 16); s2 += __shfl_xor(s2, 16); s1 += __shfl_xor(s1, 32); s2 += __shfl_xor(s2, 32);
;                     if (fq == 0) { float2 w; w.x = s1; w.y = s2; *(float2*)(stats + ((size_t)row * 32 + (pn - 16) * 4 + wc) * 2) = w; }
	global_store_dwordx4 v[144:145], v[146:149], off
	v_rcp_f32_e32 v164, v164
	v_rcp_f32_e32 v165, v165
	v_mov_b32_e32 v146, v119
	v_mov_b32_e32 v147, v120
	v_add_f32_e32 v172, v172, v175
	v_add_f32_e32 v148, v174, v163
	v_pk_mul_f32 v[146:147], v[146:147], v[166:167]
	v_add_f32_e32 v162, v172, v173
	v_add_f32_e32 v166, v146, v148
	v_pk_mul_f32 v[148:149], v[146:147], v[146:147]
	v_add_f32_e32 v171, 1.0, v171
	v_add_f32_e32 v148, v148, v162
	v_rcp_f32_e32 v171, v171
	v_add_f32_e32 v162, v147, v166
	v_add_f32_e32 v166, v149, v148
	v_mov_b32_e32 v148, v114
	v_mov_b32_e32 v149, v121
	v_pk_mul_f32 v[148:149], v[148:149], v[164:165]
	v_mul_f32_e32 v169, v115, v168
	v_pk_mul_f32 v[164:165], v[148:149], v[148:149]
	v_add_f32_e32 v162, v149, v162
	v_add_f32_e32 v165, v165, v166
	v_add_f32_e32 v162, v148, v162
	v_add_f32_e32 v172, v164, v165
	v_pk_mul_f32 v[164:165], v[116:117], v[170:171]
	v_fmac_f32_e32 v162, v115, v168
	v_mov_b32_e32 v168, v164
	v_pk_mul_f32 v[166:167], v[168:169], v[168:169]
	v_cvt_pk_bf16_f32 v147, v147, v149
	v_cvt_pk_bf16_f32 v146, v163, v146
	v_cvt_pk_bf16_f32 v148, v148, v169
	v_mov_b32_e32 v163, v165
	v_add_f32_e32 v149, v167, v172
	v_add_f32_e32 v167, v166, v149
	v_cvt_pk_bf16_f32 v149, v164, v165
	global_store_dwordx4 v[144:145], v[146:149], off offset:256
	v_and_b32_e32 v145, 64, v182
	v_xor_b32_e32 v144, 16, v182
	v_add_u32_e32 v146, 64, v145
	v_pk_fma_f32 v[162:163], v[116:117], v[170:171], v[162:163]
	v_pk_mul_f32 v[168:169], v[164:165], v[164:165]
	v_cmp_lt_i32_e32 vcc, v144, v146
	v_mov_b32_e32 v163, v169
	v_mov_b32_e32 v166, v165
	v_cndmask_b32_e32 v144, v182, v144, vcc
	v_pk_add_f32 v[166:167], v[162:163], v[166:167]
	v_lshlrev_b32_e32 v162, 2, v144
	ds_bpermute_b32 v144, v162, v166
	ds_bpermute_b32 v145, v162, v167
	v_xor_b32_e32 v147, 32, v182
	v_cmp_lt_i32_e32 vcc, v147, v146
	s_lshl_b32 s2, s2, 2
	s_or_b32 s30, s2, s73
	v_cndmask_b32_e32 v146, v182, v147, vcc
	s_waitcnt lgkmcnt(0)
	v_pk_add_f32 v[144:145], v[166:167], v[144:145]
	v_lshlrev_b32_e32 v163, 2, v146
	ds_bpermute_b32 v146, v163, v144
	ds_bpermute_b32 v147, v163, v145
	s_and_saveexec_b64 s[12:13], s[40:41]
	s_cbranch_execz .LBB0_315
	v_lshlrev_b64 v[148:149], 8, v[142:143]
	v_lshl_add_u64 v[148:149], s[48:49], 0, v[148:149]
	v_lshl_add_u64 v[148:149], s[30:31], 3, v[148:149]
	s_waitcnt lgkmcnt(0)
	v_pk_add_f32 v[144:145], v[144:145], v[146:147]
	s_waitcnt vmcnt(0)
	global_store_dwordx2 v[148:149], v[144:145], off
.LBB0_315:
	s_or_b64 exec, exec, s[12:13]
	v_mul_f32_e32 v149, 0x3d372713, v111
	v_mul_f32_e32 v149, v111, v149
	v_fma_f32 v149, v111, v149, v111
	v_mul_f32_e32 v149, 0x3f4c422a, v149
	v_mul_f32_e32 v149, 0xc038aa3b, v149
	v_exp_f32_e32 v149, v149
	v_mul_f32_e32 v148, 0x3d372713, v110
	v_mul_f32_e32 v148, v110, v148
	v_fma_f32 v148, v110, v148, v110
	v_add_f32_e32 v149, 1.0, v149
	v_rcp_f32_e32 v167, v149
	v_mul_f32_e32 v149, 0x3d372713, v107
	v_mul_f32_e32 v149, v107, v149
	v_fma_f32 v149, v107, v149, v107
	v_mul_f32_e32 v149, 0x3f4c422a, v149
	v_mul_f32_e32 v149, 0xc038aa3b, v149
	v_exp_f32_e32 v149, v149
	v_mul_f32_e32 v148, 0x3f4c422a, v148
	v_mul_f32_e32 v148, 0xc038aa3b, v148
	v_exp_f32_e32 v148, v148
	v_add_f32_e32 v149, 1.0, v149
	v_rcp_f32_e32 v164, v149
	v_mul_f32_e32 v149, 0x3d372713, v112
	v_mul_f32_e32 v149, v112, v149
	v_fma_f32 v149, v112, v149, v112
	v_mul_f32_e32 v149, 0x3f4c422a, v149
	v_mul_f32_e32 v149, 0xc038aa3b, v149
	v_exp_f32_e32 v149, v149
	v_add_f32_e32 v148, 1.0, v148
	v_rcp_f32_e32 v166, v148
	v_mul_f32_e32 v148, 0x3d372713, v106
	v_add_f32_e32 v149, 1.0, v149
	v_rcp_f32_e32 v171, v149
	v_mul_f32_e32 v149, 0x3d372713, v108
	v_mul_f32_e32 v149, v108, v149
	v_fma_f32 v149, v108, v149, v108
	v_mul_f32_e32 v149, 0x3f4c422a, v149
	v_mul_f32_e32 v149, 0xc038aa3b, v149
	v_exp_f32_e32 v149, v149
	v_mul_f32_e32 v148, v106, v148
	v_fma_f32 v148, v106, v148, v106
	v_mul_f32_e32 v148, 0x3f4c422a, v148
	v_add_f32_e32 v149, 1.0, v149
	v_rcp_f32_e32 v165, v149
	v_mul_f32_e32 v149, 0x3d372713, v113
	v_mul_f32_e32 v149, v113, v149
	v_fma_f32 v149, v113, v149, v113
	v_mul_f32_e32 v149, 0x3f4c422a, v149
	v_mul_f32_e32 v148, 0xc038aa3b, v148
	v_mul_f32_e32 v149, 0xc038aa3b, v149
	v_exp_f32_e32 v148, v148
	v_exp_f32_e32 v149, v149
	v_mul_f32_e32 v170, v111, v167
	v_fma_f32 v173, v110, v166, 0
	v_add_f32_e32 v148, 1.0, v148
	v_add_f32_e32 v149, 1.0, v149
	v_rcp_f32_e32 v148, v148
	v_rcp_f32_e32 v149, v149
	v_mul_f32_e32 v169, v110, v166
	v_fmac_f32_e32 v173, v111, v167
	v_mul_f32_e32 v174, v170, v170
	v_mov_b32_e32 v166, v106
	v_mov_b32_e32 v167, v113
	v_mul_f32_e32 v172, v112, v171
	v_fmac_f32_e32 v174, v169, v169
	v_pk_mul_f32 v[148:149], v[166:167], v[148:149]
	v_fmac_f32_e32 v174, v172, v172
	v_pk_mul_f32 v[166:167], v[148:149], v[148:149]
	v_fmac_f32_e32 v173, v112, v171
	v_add_f32_e32 v167, v167, v174
	v_add_f32_e32 v171, v149, v173
	v_add_f32_e32 v173, v166, v167
	v_mov_b32_e32 v166, v107
	v_mov_b32_e32 v167, v108
	v_pk_mul_f32 v[166:167], v[166:167], v[164:165]
	v_add_f32_e32 v171, v148, v171
	v_pk_mul_f32 v[164:165], v[166:167], v[166:167]
	v_add_f32_e32 v171, v166, v171
	v_add_f32_e32 v164, v164, v173
	v_add_f32_e32 v186, v165, v164
	v_cvt_pk_bf16_f32 v165, v172, v149
	v_mul_f32_e32 v149, 0x3d372713, v103
	v_mul_f32_e32 v149, v103, v149
	v_fma_f32 v149, v103, v149, v103
	v_mul_f32_e32 v149, 0x3f4c422a, v149
	v_mul_f32_e32 v149, 0xc038aa3b, v149
	v_exp_f32_e32 v149, v149
	v_cvt_pk_bf16_f32 v164, v169, v170
	v_add_f32_e32 v185, v167, v171
	v_cvt_pk_bf16_f32 v166, v148, v166
	v_add_f32_e32 v149, 1.0, v149
	v_rcp_f32_e32 v170, v149
	v_mul_f32_e32 v149, 0x3d372713, v99
	v_mul_f32_e32 v149, v99, v149
	v_fma_f32 v149, v99, v149, v99
; __device__ __forceinline__ float gelu_f(float x) { const float u = 0.7978845608028654f * (x + 0.044715f * x * x * x); return x * frcp(1.f + fexp2(-2.885390081777927f * u)); }
; __device__ __forceinline__ void st8(bf16_t* p, const float (&v)[8]) { u32x4 w; w.x = pk2(v[0], v[1]); w.y = pk2(v[2], v[3]); w.z = pk2(v[4], v[5]); w.w = pk2(v[6], v[7]); *(u32x4*)p = w; }
;     __device__ __forceinline__ void operator()(const f32x4 (&acc)[2][2][4][2], const Unit& u, int wr, int wc, int fr, int fq) const {
;     ...
;                 for (int m = 0; m < 4; ++m) { const int row = row0 + ai * 128 + m * 16; float s1 = 0.f, s2 = 0.f;
; #pragma unroll
;                     for (int bj = 0; bj < 2; ++bj) { float o[8];
; #pragma unroll
;                         for (int j = 0; j < 4; ++j) { o[j] = gelu_f(acc[ai][bj][m][0][j]); o[4 + j] = gelu_f(acc[ai][bj][m][1][j]); }
; #pragma unroll
;                         for (int j = 0; j < 8; ++j) { s1 += o[j]; s2 += o[j] * o[j]; }
;                         st8(gv + (size_t)row * DM + colt + bj * 128, o); }
;                     s1 += __shfl_xor(s1, 16); s2 += __shfl_xor(s2, 16); s1 += __shfl_xor(s1, 32); s2 += __shfl_xor(s2, 32);
;                     if (fq == 0) { float2 w; w.x = s1; w.y = s2; *(float2*)(stats + ((size_t)row * 32 + (pn - 16) * 4 + wc) * 2) = w; }
	v_mul_f32_e32 v149, 0x3f4c422a, v149
	v_mul_f32_e32 v149, 0xc038aa3b, v149
	v_exp_f32_e32 v149, v149
	v_mul_f32_e32 v148, 0x3d372713, v102
	v_mul_f32_e32 v148, v102, v148
	v_fma_f32 v148, v102, v148, v102
	v_add_f32_e32 v149, 1.0, v149
	v_rcp_f32_e32 v172, v149
	v_mul_f32_e32 v149, 0x3d372713, v104
	v_mul_f32_e32 v149, v104, v149
	v_fma_f32 v149, v104, v149, v104
	v_mul_f32_e32 v149, 0x3f4c422a, v149
	v_mul_f32_e32 v149, 0xc038aa3b, v149
	v_exp_f32_e32 v149, v149
	v_mul_f32_e32 v148, 0x3f4c422a, v148
	v_mul_f32_e32 v168, 0x3d372713, v109
	v_mul_f32_e32 v148, 0xc038aa3b, v148
	v_add_f32_e32 v149, 1.0, v149
	v_rcp_f32_e32 v171, v149
	v_mul_f32_e32 v149, 0x3d372713, v100
	v_mul_f32_e32 v149, v100, v149
	v_fma_f32 v149, v100, v149, v100
	v_mul_f32_e32 v149, 0x3f4c422a, v149
	v_mul_f32_e32 v149, 0xc038aa3b, v149
	v_mul_f32_e32 v168, v109, v168
	v_exp_f32_e32 v148, v148
	v_exp_f32_e32 v149, v149
	v_fma_f32 v168, v109, v168, v109
	v_mul_f32_e32 v168, 0x3f4c422a, v168
	v_mul_f32_e32 v168, 0xc038aa3b, v168
	v_exp_f32_e32 v168, v168
	v_add_f32_e32 v148, 1.0, v148
	v_add_f32_e32 v149, 1.0, v149
	v_rcp_f32_e32 v169, v148
	v_mul_f32_e32 v148, 0x3d372713, v98
	v_rcp_f32_e32 v174, v149
	v_mul_f32_e32 v149, 0x3d372713, v105
	v_mul_f32_e32 v148, v98, v148
	v_mul_f32_e32 v149, v105, v149
	v_fma_f32 v148, v98, v148, v98
	v_fma_f32 v149, v105, v149, v105
	v_add_f32_e32 v168, 1.0, v168
	v_mul_f32_e32 v148, 0x3f4c422a, v148
	v_mul_f32_e32 v149, 0x3f4c422a, v149
	v_mul_f32_e32 v175, 0x3d372713, v101
	v_or_b32_e32 v144, 16, v142
	v_rcp_f32_e32 v168, v168
	v_mul_f32_e32 v148, 0xc038aa3b, v148
	v_mul_f32_e32 v149, 0xc038aa3b, v149
	v_mul_f32_e32 v175, v101, v175
	v_ashrrev_i32_e32 v145, 31, v144
	v_exp_f32_e32 v148, v148
	v_exp_f32_e32 v149, v149
	v_fma_f32 v175, v101, v175, v101
	s_waitcnt lgkmcnt(0)
	v_lshlrev_b64 v[146:147], 12, v[144:145]
	v_mul_f32_e32 v175, 0x3f4c422a, v175
	v_lshl_add_u64 v[146:147], s[46:47], 0, v[146:147]
	v_mul_f32_e32 v175, 0xc038aa3b, v175
	v_pk_mov_b32 v[176:177], v[108:109], v[102:103] op_sel:[1,0]
	v_lshl_add_u64 v[146:147], v[146:147], 0, v[0:1]
	v_exp_f32_e32 v175, v175
	v_pk_mul_f32 v[168:169], v[176:177], v[168:169]
	v_add_f32_e32 v148, 1.0, v148
	v_add_f32_e32 v149, 1.0, v149
	v_add_f32_e32 v185, v168, v185
	v_pk_mul_f32 v[176:177], v[168:169], v[168:169]
	v_cvt_pk_bf16_f32 v167, v167, v168
	global_store_dwordx4 v[146:147], v[164:167], off
	v_rcp_f32_e32 v148, v148
	v_rcp_f32_e32 v149, v149
	v_mov_b32_e32 v164, v103
	v_mov_b32_e32 v165, v104
	v_add_f32_e32 v176, v176, v186
	v_add_f32_e32 v166, v185, v169
	v_pk_mul_f32 v[164:165], v[164:165], v[170:171]
	v_add_f32_e32 v168, v176, v177
	v_add_f32_e32 v170, v164, v166
	v_pk_mul_f32 v[166:167], v[164:165], v[164:165]
	v_add_f32_e32 v175, 1.0, v175
	v_add_f32_e32 v166, v166, v168
	v_rcp_f32_e32 v175, v175
	v_add_f32_e32 v168, v165, v170
	v_add_f32_e32 v170, v167, v166
	v_mov_b32_e32 v166, v98
	v_mov_b32_e32 v167, v105
	v_pk_mul_f32 v[148:149], v[166:167], v[148:149]
	v_mul_f32_e32 v173, v99, v172
	v_pk_mul_f32 v[166:167], v[148:149], v[148:149]
	v_add_f32_e32 v168, v149, v168
	v_add_f32_e32 v167, v167, v170
	v_add_f32_e32 v168, v148, v168
	v_add_f32_e32 v167, v166, v167
	v_cvt_pk_bf16_f32 v165, v165, v149
	v_cvt_pk_bf16_f32 v166, v148, v173
	v_pk_mul_f32 v[148:149], v[100:101], v[174:175]
	v_fmac_f32_e32 v168, v99, v172
	v_mov_b32_e32 v172, v148
	v_cvt_pk_bf16_f32 v164, v169, v164
	v_pk_mul_f32 v[170:171], v[172:173], v[172:173]
	v_mov_b32_e32 v169, v149
	v_add_f32_e32 v167, v171, v167
	v_pk_fma_f32 v[168:169], v[100:101], v[174:175], v[168:169]
	v_pk_mul_f32 v[172:173], v[148:149], v[148:149]
	v_add_f32_e32 v171, v170, v167
	v_mov_b32_e32 v169, v173
	v_mov_b32_e32 v170, v149
	v_pk_add_f32 v[168:169], v[168:169], v[170:171]
	v_cvt_pk_bf16_f32 v167, v148, v149
	global_store_dwordx4 v[146:147], v[164:167], off offset:256
	ds_bpermute_b32 v146, v162, v168
	ds_bpermute_b32 v147, v162, v169
	s_waitcnt lgkmcnt(0)
	v_pk_add_f32 v[146:147], v[168:169], v[146:147]
	ds_bpermute_b32 v148, v163, v146
	ds_bpermute_b32 v149, v163, v147
	s_and_saveexec_b64 s[12:13], s[40:41]
	s_cbranch_execz .LBB0_317
	v_lshlrev_b64 v[144:145], 8, v[144:145]
	v_lshl_add_u64 v[144:145], s[48:49], 0, v[144:145]
	v_lshl_add_u64 v[144:145], s[30:31], 3, v[144:145]
	s_waitcnt lgkmcnt(0)
	v_pk_add_f32 v[146:147], v[146:147], v[148:149]
	s_waitcnt vmcnt(0)
	global_store_dwordx2 v[144:145], v[146:147], off
; __device__ __forceinline__ float gelu_f(float x) { const float u = 0.7978845608028654f * (x + 0.044715f * x * x * x); return x * frcp(1.f + fexp2(-2.885390081777927f * u)); }
;     __device__ __forceinline__ void operator()(const f32x4 (&acc)[2][2][4][2], const Unit& u, int wr, int wc, int fr, int fq) const {
;     ...
;                 for (int m = 0; m < 4; ++m) { const int row = row0 + ai * 128 + m * 16; float s1 = 0.f, s2 = 0.f;
; #pragma unroll
;                     for (int bj = 0; bj < 2; ++bj) { float o[8];
; #pragma unroll
;                         for (int j = 0; j < 4; ++j) { o[j] = gelu_f(acc[ai][bj][m][0][j]); o[4 + j] = gelu_f(acc[ai][bj][m][1][j]); }
.LBB0_317:
	s_or_b64 exec, exec, s[12:13]
	s_waitcnt lgkmcnt(0)
	v_mul_f32_e32 v149, 0x3d372713, v95
	v_mul_f32_e32 v149, v95, v149
	v_fma_f32 v149, v95, v149, v95
	v_mul_f32_e32 v149, 0x3f4c422a, v149
	v_mul_f32_e32 v149, 0xc038aa3b, v149
	v_exp_f32_e32 v149, v149
	v_mul_f32_e32 v148, 0x3d372713, v94
	v_mul_f32_e32 v148, v94, v148
	v_fma_f32 v148, v94, v148, v94
	v_add_f32_e32 v149, 1.0, v149
	v_rcp_f32_e32 v167, v149
	v_mul_f32_e32 v149, 0x3d372713, v91
	v_mul_f32_e32 v149, v91, v149
	v_fma_f32 v149, v91, v149, v91
	v_mul_f32_e32 v149, 0x3f4c422a, v149
	v_mul_f32_e32 v149, 0xc038aa3b, v149
	v_exp_f32_e32 v149, v149
	v_mul_f32_e32 v148, 0x3f4c422a, v148
	v_mul_f32_e32 v148, 0xc038aa3b, v148
	v_exp_f32_e32 v148, v148
	v_add_f32_e32 v149, 1.0, v149
	v_rcp_f32_e32 v164, v149
	v_mul_f32_e32 v149, 0x3d372713, v96
	v_mul_f32_e32 v149, v96, v149
	v_fma_f32 v149, v96, v149, v96
	v_mul_f32_e32 v149, 0x3f4c422a, v149
	v_mul_f32_e32 v149, 0xc038aa3b, v149
	v_exp_f32_e32 v149, v149
	v_add_f32_e32 v148, 1.0, v148
	v_rcp_f32_e32 v166, v148
	v_mul_f32_e32 v148, 0x3d372713, v90
	v_add_f32_e32 v149, 1.0, v149
	v_rcp_f32_e32 v171, v149
	v_mul_f32_e32 v149, 0x3d372713, v92
	v_mul_f32_e32 v149, v92, v149
	v_fma_f32 v149, v92, v149, v92
	v_mul_f32_e32 v149, 0x3f4c422a, v149
	v_mul_f32_e32 v149, 0xc038aa3b, v149
	v_exp_f32_e32 v149, v149
	v_mul_f32_e32 v148, v90, v148
	v_fma_f32 v148, v90, v148, v90
	v_mul_f32_e32 v148, 0x3f4c422a, v148
	v_add_f32_e32 v149, 1.0, v149
	v_rcp_f32_e32 v165, v149
	v_mul_f32_e32 v149, 0x3d372713, v97
	v_mul_f32_e32 v149, v97, v149
	v_fma_f32 v149, v97, v149, v97
	v_mul_f32_e32 v149, 0x3f4c422a, v149
	v_mul_f32_e32 v148, 0xc038aa3b, v148
	v_mul_f32_e32 v149, 0xc038aa3b, v149
	v_exp_f32_e32 v148, v148
	v_exp_f32_e32 v149, v149
	v_mul_f32_e32 v170, v95, v167
	v_fma_f32 v173, v94, v166, 0
	v_add_f32_e32 v148, 1.0, v148
	v_add_f32_e32 v149, 1.0, v149
	v_rcp_f32_e32 v148, v148
	v_rcp_f32_e32 v149, v149
	v_mul_f32_e32 v169, v94, v166
	v_fmac_f32_e32 v173, v95, v167
	v_mul_f32_e32 v174, v170, v170
	v_mov_b32_e32 v166, v90
	v_mov_b32_e32 v167, v97
	v_mul_f32_e32 v172, v96, v171
	v_fmac_f32_e32 v174, v169, v169
	v_pk_mul_f32 v[148:149], v[166:167], v[148:149]
	v_fmac_f32_e32 v174, v172, v172
	v_pk_mul_f32 v[166:167], v[148:149], v[148:149]
	v_fmac_f32_e32 v173, v96, v171
	v_add_f32_e32 v167, v167, v174
	v_add_f32_e32 v171, v149, v173
	v_add_f32_e32 v173, v166, v167
	v_mov_b32_e32 v166, v91
	v_mov_b32_e32 v167, v92
	v_pk_mul_f32 v[166:167], v[166:167], v[164:165]
	v_add_f32_e32 v171, v148, v171
	v_pk_mul_f32 v[164:165], v[166:167], v[166:167]
	v_add_f32_e32 v171, v166, v171
	v_add_f32_e32 v164, v164, v173
	v_add_f32_e32 v186, v165, v164
	v_cvt_pk_bf16_f32 v165, v172, v149
	v_mul_f32_e32 v149, 0x3d372713, v87
	v_mul_f32_e32 v149, v87, v149
	v_fma_f32 v149, v87, v149, v87
	v_mul_f32_e32 v149, 0x3f4c422a, v149
	v_mul_f32_e32 v149, 0xc038aa3b, v149
	v_exp_f32_e32 v149, v149
	v_cvt_pk_bf16_f32 v164, v169, v170
	v_add_f32_e32 v185, v167, v171
	v_cvt_pk_bf16_f32 v166, v148, v166
	v_add_f32_e32 v149, 1.0, v149
	v_rcp_f32_e32 v170, v149
	v_mul_f32_e32 v149, 0x3d372713, v83
	v_mul_f32_e32 v149, v83, v149
	v_fma_f32 v149, v83, v149, v83
	v_mul_f32_e32 v149, 0x3f4c422a, v149
	v_mul_f32_e32 v149, 0xc038aa3b, v149
	v_exp_f32_e32 v149, v149
	v_mul_f32_e32 v148, 0x3d372713, v86
	v_mul_f32_e32 v148, v86, v148
	v_fma_f32 v148, v86, v148, v86
	v_add_f32_e32 v149, 1.0, v149
	v_rcp_f32_e32 v172, v149
	v_mul_f32_e32 v149, 0x3d372713, v88
	v_mul_f32_e32 v149, v88, v149
	v_fma_f32 v149, v88, v149, v88
	v_mul_f32_e32 v149, 0x3f4c422a, v149
	v_mul_f32_e32 v149, 0xc038aa3b, v149
	v_exp_f32_e32 v149, v149
	v_mul_f32_e32 v148, 0x3f4c422a, v148
	v_mul_f32_e32 v168, 0x3d372713, v93
	v_mul_f32_e32 v148, 0xc038aa3b, v148
	v_add_f32_e32 v149, 1.0, v149
	v_rcp_f32_e32 v171, v149
	v_mul_f32_e32 v149, 0x3d372713, v84
	v_mul_f32_e32 v149, v84, v149
	v_fma_f32 v149, v84, v149, v84
	v_mul_f32_e32 v149, 0x3f4c422a, v149
	v_mul_f32_e32 v149, 0xc038aa3b, v149
	v_mul_f32_e32 v168, v93, v168
	v_exp_f32_e32 v148, v148
	v_exp_f32_e32 v149, v149
	v_fma_f32 v168, v93, v168, v93
	v_mul_f32_e32 v168, 0x3f4c422a, v168
	v_mul_f32_e32 v168, 0xc038aa3b, v168
	v_exp_f32_e32 v168, v168
	v_add_f32_e32 v148, 1.0, v148
	v_add_f32_e32 v149, 1.0, v149
	v_rcp_f32_e32 v169, v148
	v_mul_f32_e32 v148, 0x3d372713, v82
	v_rcp_f32_e32 v174, v149
	v_mul_f32_e32 v149, 0x3d372713, v89
	v_mul_f32_e32 v148, v82, v148
	v_mul_f32_e32 v149, v89, v149
	v_fma_f32 v148, v82, v148, v82
	v_fma_f32 v149, v89, v149, v89
	v_add_f32_e32 v168, 1.0, v168
	v_mul_f32_e32 v148, 0x3f4c422a, v148
	v_mul_f32_e32 v149, 0x3f4c422a, v149
	v_mul_f32_e32 v175, 0x3d372713, v85
	v_or_b32_e32 v144, 32, v142
	v_rcp_f32_e32 v168, v168
	v_mul_f32_e32 v148, 0xc038aa3b, v148
	v_mul_f32_e32 v149, 0xc038aa3b, v149
	v_mul_f32_e32 v175, v85, v175
	v_ashrrev_i32_e32 v145, 31, v144
	v_exp_f32_e32 v148, v148
	v_exp_f32_e32 v149, v149
	v_fma_f32 v175, v85, v175, v85
	v_lshlrev_b64 v[146:147], 12, v[144:145]
	v_mul_f32_e32 v175, 0x3f4c422a, v175
	v_lshl_add_u64 v[146:147], s[46:47], 0, v[146:147]
	v_mul_f32_e32 v175, 0xc038aa3b, v175
	v_pk_mov_b32 v[176:177], v[92:93], v[86:87] op_sel:[1,0]
	v_lshl_add_u64 v[146:147], v[146:147], 0, v[0:1]
	v_exp_f32_e32 v175, v175
	v_pk_mul_f32 v[168:169], v[176:177], v[168:169]
	v_add_f32_e32 v148, 1.0, v148
	v_add_f32_e32 v149, 1.0, v149
	v_add_f32_e32 v185, v168, v185
	v_pk_mul_f32 v[176:177], v[168:169], v[168:169]
	v_cvt_pk_bf16_f32 v167, v167, v168
	global_store_dwordx4 v[146:147], v[164:167], off
	v_rcp_f32_e32 v148, v148
	v_rcp_f32_e32 v149, v149
	v_mov_b32_e32 v164, v87
	v_mov_b32_e32 v165, v88
; __device__ __forceinline__ float gelu_f(float x) { const float u = 0.7978845608028654f * (x + 0.044715f * x * x * x); return x * frcp(1.f + fexp2(-2.885390081777927f * u)); }
; __device__ __forceinline__ void st8(bf16_t* p, const float (&v)[8]) { u32x4 w; w.x = pk2(v[0], v[1]); w.y = pk2(v[2], v[3]); w.z = pk2(v[4], v[5]); w.w = pk2(v[6], v[7]); *(u32x4*)p = w; }
;     __device__ __forceinline__ void operator()(const f32x4 (&acc)[2][2][4][2], const Unit& u, int wr, int wc, int fr, int fq) const {
;     ...
;                     for (int bj = 0; bj < 2; ++bj) { float o[8];
; #pragma unroll
;                         for (int j = 0; j < 4; ++j) { o[j] = gelu_f(acc[ai][bj][m][0][j]); o[4 + j] = gelu_f(acc[ai][bj][m][1][j]); }
; #pragma unroll
;                         for (int j = 0; j < 8; ++j) { s1 += o[j]; s2 += o[j] * o[j]; }
;                         st8(gv + (size_t)row * DM + colt + bj * 128, o); }
;                     s1 += __shfl_xor(s1, 16); s2 += __shfl_xor(s2, 16); s1 += __shfl_xor(s1, 32); s2 += __shfl_xor(s2, 32);
;                     if (fq == 0) { float2 w; w.x = s1; w.y = s2; *(float2*)(stats + ((size_t)row * 32 + (pn - 16) * 4 + wc) * 2) = w; }
	v_add_f32_e32 v176, v176, v186
	v_add_f32_e32 v166, v185, v169
	v_pk_mul_f32 v[164:165], v[164:165], v[170:171]
	v_add_f32_e32 v168, v176, v177
	v_add_f32_e32 v170, v164, v166
	v_pk_mul_f32 v[166:167], v[164:165], v[164:165]
	v_add_f32_e32 v175, 1.0, v175
	v_add_f32_e32 v166, v166, v168
	v_rcp_f32_e32 v175, v175
	v_add_f32_e32 v168, v165, v170
	v_add_f32_e32 v170, v167, v166
	v_mov_b32_e32 v166, v82
	v_mov_b32_e32 v167, v89
	v_pk_mul_f32 v[148:149], v[166:167], v[148:149]
	v_mul_f32_e32 v173, v83, v172
	v_pk_mul_f32 v[166:167], v[148:149], v[148:149]
	v_add_f32_e32 v168, v149, v168
	v_add_f32_e32 v167, v167, v170
	v_add_f32_e32 v168, v148, v168
	v_add_f32_e32 v167, v166, v167
	v_cvt_pk_bf16_f32 v165, v165, v149
	v_cvt_pk_bf16_f32 v166, v148, v173
	v_pk_mul_f32 v[148:149], v[84:85], v[174:175]
	v_fmac_f32_e32 v168, v83, v172
	v_mov_b32_e32 v172, v148
	v_cvt_pk_bf16_f32 v164, v169, v164
	v_pk_mul_f32 v[170:171], v[172:173], v[172:173]
	v_mov_b32_e32 v169, v149
	v_add_f32_e32 v167, v171, v167
	v_pk_fma_f32 v[168:169], v[84:85], v[174:175], v[168:169]
	v_pk_mul_f32 v[172:173], v[148:149], v[148:149]
	v_add_f32_e32 v171, v170, v167
	v_mov_b32_e32 v169, v173
	v_mov_b32_e32 v170, v149
	v_pk_add_f32 v[168:169], v[168:169], v[170:171]
	v_cvt_pk_bf16_f32 v167, v148, v149
	global_store_dwordx4 v[146:147], v[164:167], off offset:256
	ds_bpermute_b32 v146, v162, v168
	ds_bpermute_b32 v147, v162, v169
	s_waitcnt lgkmcnt(0)
	v_pk_add_f32 v[146:147], v[168:169], v[146:147]
	ds_bpermute_b32 v148, v163, v146
	ds_bpermute_b32 v149, v163, v147
	s_and_saveexec_b64 s[12:13], s[40:41]
	s_cbranch_execz .LBB0_319
	v_lshlrev_b64 v[144:145], 8, v[144:145]
	v_lshl_add_u64 v[144:145], s[48:49], 0, v[144:145]
	v_lshl_add_u64 v[144:145], s[30:31], 3, v[144:145]
	s_waitcnt lgkmcnt(0)
	v_pk_add_f32 v[146:147], v[146:147], v[148:149]
	s_waitcnt vmcnt(0)
	global_store_dwordx2 v[144:145], v[146:147], off
.LBB0_319:
	s_or_b64 exec, exec, s[12:13]
	s_waitcnt lgkmcnt(0)
	v_mul_f32_e32 v149, 0x3d372713, v79
	v_mul_f32_e32 v149, v79, v149
	v_fma_f32 v149, v79, v149, v79
	v_mul_f32_e32 v149, 0x3f4c422a, v149
	v_mul_f32_e32 v149, 0xc038aa3b, v149
	v_exp_f32_e32 v149, v149
	v_mul_f32_e32 v148, 0x3d372713, v78
	v_mul_f32_e32 v148, v78, v148
	v_fma_f32 v148, v78, v148, v78
	v_add_f32_e32 v149, 1.0, v149
	v_rcp_f32_e32 v167, v149
	v_mul_f32_e32 v149, 0x3d372713, v75
	v_mul_f32_e32 v149, v75, v149
	v_fma_f32 v149, v75, v149, v75
	v_mul_f32_e32 v149, 0x3f4c422a, v149
	v_mul_f32_e32 v149, 0xc038aa3b, v149
	v_exp_f32_e32 v149, v149
	v_mul_f32_e32 v148, 0x3f4c422a, v148
	v_mul_f32_e32 v148, 0xc038aa3b, v148
	v_exp_f32_e32 v148, v148
	v_add_f32_e32 v149, 1.0, v149
	v_rcp_f32_e32 v164, v149
	v_mul_f32_e32 v149, 0x3d372713, v80
	v_mul_f32_e32 v149, v80, v149
	v_fma_f32 v149, v80, v149, v80
	v_mul_f32_e32 v149, 0x3f4c422a, v149
	v_mul_f32_e32 v149, 0xc038aa3b, v149
	v_exp_f32_e32 v149, v149
	v_add_f32_e32 v148, 1.0, v148
	v_rcp_f32_e32 v166, v148
	v_mul_f32_e32 v148, 0x3d372713, v74
	v_add_f32_e32 v149, 1.0, v149
	v_rcp_f32_e32 v171, v149
	v_mul_f32_e32 v149, 0x3d372713, v76
	v_mul_f32_e32 v149, v76, v149
	v_fma_f32 v149, v76, v149, v76
	v_mul_f32_e32 v149, 0x3f4c422a, v149
	v_mul_f32_e32 v149, 0xc038aa3b, v149
	v_exp_f32_e32 v149, v149
	v_mul_f32_e32 v148, v74, v148
	v_fma_f32 v148, v74, v148, v74
	v_mul_f32_e32 v148, 0x3f4c422a, v148
	v_add_f32_e32 v149, 1.0, v149
	v_rcp_f32_e32 v165, v149
	v_mul_f32_e32 v149, 0x3d372713, v81
	v_mul_f32_e32 v149, v81, v149
	v_fma_f32 v149, v81, v149, v81
	v_mul_f32_e32 v149, 0x3f4c422a, v149
	v_mul_f32_e32 v148, 0xc038aa3b, v148
	v_mul_f32_e32 v149, 0xc038aa3b, v149
	v_exp_f32_e32 v148, v148
	v_exp_f32_e32 v149, v149
	v_mul_f32_e32 v170, v79, v167
	v_fma_f32 v173, v78, v166, 0
	v_add_f32_e32 v148, 1.0, v148
	v_add_f32_e32 v149, 1.0, v149
	v_rcp_f32_e32 v148, v148
	v_rcp_f32_e32 v149, v149
	v_mul_f32_e32 v169, v78, v166
	v_fmac_f32_e32 v173, v79, v167
	v_mul_f32_e32 v174, v170, v170
	v_mov_b32_e32 v166, v74
	v_mov_b32_e32 v167, v81
	v_mul_f32_e32 v172, v80, v171
	v_fmac_f32_e32 v174, v169, v169
	v_pk_mul_f32 v[148:149], v[166:167], v[148:149]
	v_fmac_f32_e32 v174, v172, v172
	v_pk_mul_f32 v[166:167], v[148:149], v[148:149]
	v_fmac_f32_e32 v173, v80, v171
	v_add_f32_e32 v167, v167, v174
	v_add_f32_e32 v171, v149, v173
	v_add_f32_e32 v173, v166, v167
	v_mov_b32_e32 v166, v75
	v_mov_b32_e32 v167, v76
	v_pk_mul_f32 v[166:167], v[166:167], v[164:165]
	v_add_f32_e32 v171, v148, v171
	v_pk_mul_f32 v[164:165], v[166:167], v[166:167]
	v_add_f32_e32 v171, v166, v171
	v_add_f32_e32 v164, v164, v173
	v_add_f32_e32 v186, v165, v164
	v_cvt_pk_bf16_f32 v165, v172, v149
	v_mul_f32_e32 v149, 0x3d372713, v71
	v_mul_f32_e32 v149, v71, v149
	v_fma_f32 v149, v71, v149, v71
	v_mul_f32_e32 v149, 0x3f4c422a, v149
	v_mul_f32_e32 v149, 0xc038aa3b, v149
	v_exp_f32_e32 v149, v149
	v_cvt_pk_bf16_f32 v164, v169, v170
	v_add_f32_e32 v185, v167, v171
	v_cvt_pk_bf16_f32 v166, v148, v166
	v_add_f32_e32 v149, 1.0, v149
	v_rcp_f32_e32 v170, v149
	v_mul_f32_e32 v149, 0x3d372713, v67
	v_mul_f32_e32 v149, v67, v149
	v_fma_f32 v149, v67, v149, v67
	v_mul_f32_e32 v149, 0x3f4c422a, v149
	v_mul_f32_e32 v149, 0xc038aa3b, v149
	v_exp_f32_e32 v149, v149
	v_mul_f32_e32 v148, 0x3d372713, v70
	v_mul_f32_e32 v148, v70, v148
	v_fma_f32 v148, v70, v148, v70
	v_add_f32_e32 v149, 1.0, v149
	v_rcp_f32_e32 v172, v149
	v_mul_f32_e32 v149, 0x3d372713, v72
	v_mul_f32_e32 v149, v72, v149
	v_fma_f32 v149, v72, v149, v72
	v_mul_f32_e32 v149, 0x3f4c422a, v149
	v_mul_f32_e32 v149, 0xc038aa3b, v149
	v_exp_f32_e32 v149, v149
	v_mul_f32_e32 v148, 0x3f4c422a, v148
	v_mul_f32_e32 v168, 0x3d372713, v77
	v_mul_f32_e32 v148, 0xc038aa3b, v148
; __device__ __forceinline__ float gelu_f(float x) { const float u = 0.7978845608028654f * (x + 0.044715f * x * x * x); return x * frcp(1.f + fexp2(-2.885390081777927f * u)); }
; __device__ __forceinline__ void st8(bf16_t* p, const float (&v)[8]) { u32x4 w; w.x = pk2(v[0], v[1]); w.y = pk2(v[2], v[3]); w.z = pk2(v[4], v[5]); w.w = pk2(v[6], v[7]); *(u32x4*)p = w; }
;     __device__ __forceinline__ void operator()(const f32x4 (&acc)[2][2][4][2], const Unit& u, int wr, int wc, int fr, int fq) const {
;     ...
;                 for (int m = 0; m < 4; ++m) { const int row = row0 + ai * 128 + m * 16; float s1 = 0.f, s2 = 0.f;
; #pragma unroll
;                     for (int bj = 0; bj < 2; ++bj) { float o[8];
; #pragma unroll
;                         for (int j = 0; j < 4; ++j) { o[j] = gelu_f(acc[ai][bj][m][0][j]); o[4 + j] = gelu_f(acc[ai][bj][m][1][j]); }
; #pragma unroll
;                         for (int j = 0; j < 8; ++j) { s1 += o[j]; s2 += o[j] * o[j]; }
;                         st8(gv + (size_t)row * DM + colt + bj * 128, o); }
;                     s1 += __shfl_xor(s1, 16); s2 += __shfl_xor(s2, 16); s1 += __shfl_xor(s1, 32); s2 += __shfl_xor(s2, 32);
;                     if (fq == 0) { float2 w; w.x = s1; w.y = s2; *(float2*)(stats + ((size_t)row * 32 + (pn - 16) * 4 + wc) * 2) = w; }
	v_add_f32_e32 v149, 1.0, v149
	v_rcp_f32_e32 v171, v149
	v_mul_f32_e32 v149, 0x3d372713, v68
	v_mul_f32_e32 v149, v68, v149
	v_fma_f32 v149, v68, v149, v68
	v_mul_f32_e32 v149, 0x3f4c422a, v149
	v_mul_f32_e32 v149, 0xc038aa3b, v149
	v_mul_f32_e32 v168, v77, v168
	v_exp_f32_e32 v148, v148
	v_exp_f32_e32 v149, v149
	v_fma_f32 v168, v77, v168, v77
	v_mul_f32_e32 v168, 0x3f4c422a, v168
	v_mul_f32_e32 v168, 0xc038aa3b, v168
	v_exp_f32_e32 v168, v168
	v_add_f32_e32 v148, 1.0, v148
	v_add_f32_e32 v149, 1.0, v149
	v_rcp_f32_e32 v169, v148
	v_mul_f32_e32 v148, 0x3d372713, v66
	v_rcp_f32_e32 v174, v149
	v_mul_f32_e32 v149, 0x3d372713, v73
	v_mul_f32_e32 v148, v66, v148
	v_mul_f32_e32 v149, v73, v149
	v_fma_f32 v148, v66, v148, v66
	v_fma_f32 v149, v73, v149, v73
	v_add_f32_e32 v168, 1.0, v168
	v_mul_f32_e32 v148, 0x3f4c422a, v148
	v_mul_f32_e32 v149, 0x3f4c422a, v149
	v_mul_f32_e32 v175, 0x3d372713, v69
	v_or_b32_e32 v144, 48, v142
	v_rcp_f32_e32 v168, v168
	v_mul_f32_e32 v148, 0xc038aa3b, v148
	v_mul_f32_e32 v149, 0xc038aa3b, v149
	v_mul_f32_e32 v175, v69, v175
	v_ashrrev_i32_e32 v145, 31, v144
	v_exp_f32_e32 v148, v148
	v_exp_f32_e32 v149, v149
	v_fma_f32 v175, v69, v175, v69
	v_lshlrev_b64 v[146:147], 12, v[144:145]
	v_mul_f32_e32 v175, 0x3f4c422a, v175
	v_lshl_add_u64 v[146:147], s[46:47], 0, v[146:147]
	v_mul_f32_e32 v175, 0xc038aa3b, v175
	v_pk_mov_b32 v[176:177], v[76:77], v[70:71] op_sel:[1,0]
	v_lshl_add_u64 v[146:147], v[146:147], 0, v[0:1]
	v_exp_f32_e32 v175, v175
	v_pk_mul_f32 v[168:169], v[176:177], v[168:169]
	v_add_f32_e32 v148, 1.0, v148
	v_add_f32_e32 v149, 1.0, v149
	v_add_f32_e32 v185, v168, v185
	v_pk_mul_f32 v[176:177], v[168:169], v[168:169]
	v_cvt_pk_bf16_f32 v167, v167, v168
	global_store_dwordx4 v[146:147], v[164:167], off
	v_rcp_f32_e32 v148, v148
	v_rcp_f32_e32 v149, v149
	v_mov_b32_e32 v164, v71
	v_mov_b32_e32 v165, v72
	v_add_f32_e32 v176, v176, v186
	v_add_f32_e32 v166, v185, v169
	v_pk_mul_f32 v[164:165], v[164:165], v[170:171]
	v_add_f32_e32 v168, v176, v177
	v_add_f32_e32 v170, v164, v166
	v_pk_mul_f32 v[166:167], v[164:165], v[164:165]
	v_add_f32_e32 v175, 1.0, v175
	v_add_f32_e32 v166, v166, v168
	v_rcp_f32_e32 v175, v175
	v_add_f32_e32 v168, v165, v170
	v_add_f32_e32 v170, v167, v166
	v_mov_b32_e32 v166, v66
	v_mov_b32_e32 v167, v73
	v_pk_mul_f32 v[148:149], v[166:167], v[148:149]
	v_mul_f32_e32 v173, v67, v172
	v_pk_mul_f32 v[166:167], v[148:149], v[148:149]
	v_add_f32_e32 v168, v149, v168
	v_add_f32_e32 v167, v167, v170
	v_add_f32_e32 v168, v148, v168
	v_add_f32_e32 v167, v166, v167
	v_cvt_pk_bf16_f32 v165, v165, v149
	v_cvt_pk_bf16_f32 v166, v148, v173
	v_pk_mul_f32 v[148:149], v[68:69], v[174:175]
	v_fmac_f32_e32 v168, v67, v172
	v_mov_b32_e32 v172, v148
	v_cvt_pk_bf16_f32 v164, v169, v164
	v_pk_mul_f32 v[170:171], v[172:173], v[172:173]
	v_mov_b32_e32 v169, v149
	v_add_f32_e32 v167, v171, v167
	v_pk_fma_f32 v[168:169], v[68:69], v[174:175], v[168:169]
	v_pk_mul_f32 v[172:173], v[148:149], v[148:149]
	v_add_f32_e32 v171, v170, v167
	v_mov_b32_e32 v169, v173
	v_mov_b32_e32 v170, v149
	v_pk_add_f32 v[168:169], v[168:169], v[170:171]
	v_cvt_pk_bf16_f32 v167, v148, v149
	global_store_dwordx4 v[146:147], v[164:167], off offset:256
	ds_bpermute_b32 v146, v162, v168
	ds_bpermute_b32 v147, v162, v169
	s_waitcnt lgkmcnt(0)
	v_pk_add_f32 v[146:147], v[168:169], v[146:147]
	ds_bpermute_b32 v148, v163, v146
	ds_bpermute_b32 v149, v163, v147
	s_and_saveexec_b64 s[12:13], s[40:41]
	s_cbranch_execz .LBB0_321
	v_lshlrev_b64 v[144:145], 8, v[144:145]
	v_lshl_add_u64 v[144:145], s[48:49], 0, v[144:145]
	v_lshl_add_u64 v[144:145], s[30:31], 3, v[144:145]
	s_waitcnt lgkmcnt(0)
	v_pk_add_f32 v[146:147], v[146:147], v[148:149]
	s_waitcnt vmcnt(0)
	global_store_dwordx2 v[144:145], v[146:147], off
.LBB0_321:
	s_or_b64 exec, exec, s[12:13]
	s_waitcnt lgkmcnt(0)
	v_mul_f32_e32 v149, 0x3d372713, v63
	v_mul_f32_e32 v149, v63, v149
	v_fma_f32 v149, v63, v149, v63
	v_mul_f32_e32 v149, 0x3f4c422a, v149
	v_mul_f32_e32 v149, 0xc038aa3b, v149
	v_exp_f32_e32 v149, v149
	v_mul_f32_e32 v148, 0x3d372713, v62
	v_mul_f32_e32 v148, v62, v148
	v_fma_f32 v148, v62, v148, v62
	v_add_f32_e32 v149, 1.0, v149
	v_rcp_f32_e32 v167, v149
	v_mul_f32_e32 v149, 0x3d372713, v59
	v_mul_f32_e32 v149, v59, v149
	v_fma_f32 v149, v59, v149, v59
	v_mul_f32_e32 v149, 0x3f4c422a, v149
	v_mul_f32_e32 v149, 0xc038aa3b, v149
	v_exp_f32_e32 v149, v149
	v_mul_f32_e32 v148, 0x3f4c422a, v148
	v_mul_f32_e32 v148, 0xc038aa3b, v148
	v_exp_f32_e32 v148, v148
	v_add_f32_e32 v149, 1.0, v149
	v_rcp_f32_e32 v164, v149
	v_mul_f32_e32 v149, 0x3d372713, v64
	v_mul_f32_e32 v149, v64, v149
	v_fma_f32 v149, v64, v149, v64
	v_mul_f32_e32 v149, 0x3f4c422a, v149
	v_mul_f32_e32 v149, 0xc038aa3b, v149
	v_exp_f32_e32 v149, v149
	v_add_f32_e32 v148, 1.0, v148
	v_rcp_f32_e32 v166, v148
	v_mul_f32_e32 v148, 0x3d372713, v58
	v_add_f32_e32 v149, 1.0, v149
	v_rcp_f32_e32 v171, v149
	v_mul_f32_e32 v149, 0x3d372713, v60
	v_mul_f32_e32 v149, v60, v149
	v_fma_f32 v149, v60, v149, v60
	v_mul_f32_e32 v149, 0x3f4c422a, v149
	v_mul_f32_e32 v149, 0xc038aa3b, v149
	v_exp_f32_e32 v149, v149
	v_mul_f32_e32 v148, v58, v148
	v_fma_f32 v148, v58, v148, v58
	v_mul_f32_e32 v148, 0x3f4c422a, v148
	v_add_f32_e32 v149, 1.0, v149
	v_rcp_f32_e32 v165, v149
	v_mul_f32_e32 v149, 0x3d372713, v65
	v_mul_f32_e32 v149, v65, v149
	v_fma_f32 v149, v65, v149, v65
	v_mul_f32_e32 v149, 0x3f4c422a, v149
	v_mul_f32_e32 v148, 0xc038aa3b, v148
	v_mul_f32_e32 v149, 0xc038aa3b, v149
	v_exp_f32_e32 v148, v148
	v_exp_f32_e32 v149, v149
	v_mul_f32_e32 v170, v63, v167
	v_fma_f32 v173, v62, v166, 0
	v_add_f32_e32 v148, 1.0, v148
; __device__ __forceinline__ float gelu_f(float x) { const float u = 0.7978845608028654f * (x + 0.044715f * x * x * x); return x * frcp(1.f + fexp2(-2.885390081777927f * u)); }
; __device__ __forceinline__ void st8(bf16_t* p, const float (&v)[8]) { u32x4 w; w.x = pk2(v[0], v[1]); w.y = pk2(v[2], v[3]); w.z = pk2(v[4], v[5]); w.w = pk2(v[6], v[7]); *(u32x4*)p = w; }
;     __device__ __forceinline__ void operator()(const f32x4 (&acc)[2][2][4][2], const Unit& u, int wr, int wc, int fr, int fq) const {
;     ...
; #pragma unroll
;             for (int ai = 0; ai < 2; ++ai)
; #pragma unroll
;                 for (int m = 0; m < 4; ++m) { const int row = row0 + ai * 128 + m * 16; float s1 = 0.f, s2 = 0.f;
; #pragma unroll
;                     for (int bj = 0; bj < 2; ++bj) { float o[8];
; #pragma unroll
;                         for (int j = 0; j < 4; ++j) { o[j] = gelu_f(acc[ai][bj][m][0][j]); o[4 + j] = gelu_f(acc[ai][bj][m][1][j]); }
; #pragma unroll
;                         for (int j = 0; j < 8; ++j) { s1 += o[j]; s2 += o[j] * o[j]; }
;                         st8(gv + (size_t)row * DM + colt + bj * 128, o); }
;                     s1 += __shfl_xor(s1, 16); s2 += __shfl_xor(s2, 16); s1 += __shfl_xor(s1, 32); s2 += __shfl_xor(s2, 32);
;                     if (fq == 0) { float2 w; w.x = s1; w.y = s2; *(float2*)(stats + ((size_t)row * 32 + (pn - 16) * 4 + wc) * 2) = w; }
	v_add_f32_e32 v149, 1.0, v149
	v_rcp_f32_e32 v148, v148
	v_rcp_f32_e32 v149, v149
	v_mul_f32_e32 v169, v62, v166
	v_fmac_f32_e32 v173, v63, v167
	v_mul_f32_e32 v174, v170, v170
	v_mov_b32_e32 v166, v58
	v_mov_b32_e32 v167, v65
	v_mul_f32_e32 v172, v64, v171
	v_fmac_f32_e32 v174, v169, v169
	v_pk_mul_f32 v[148:149], v[166:167], v[148:149]
	v_fmac_f32_e32 v174, v172, v172
	v_pk_mul_f32 v[166:167], v[148:149], v[148:149]
	v_fmac_f32_e32 v173, v64, v171
	v_add_f32_e32 v167, v167, v174
	v_add_f32_e32 v171, v149, v173
	v_add_f32_e32 v173, v166, v167
	v_mov_b32_e32 v166, v59
	v_mov_b32_e32 v167, v60
	v_pk_mul_f32 v[166:167], v[166:167], v[164:165]
	v_add_f32_e32 v171, v148, v171
	v_pk_mul_f32 v[164:165], v[166:167], v[166:167]
	v_add_f32_e32 v171, v166, v171
	v_add_f32_e32 v164, v164, v173
	v_add_f32_e32 v186, v165, v164
	v_cvt_pk_bf16_f32 v165, v172, v149
	v_mul_f32_e32 v149, 0x3d372713, v55
	v_mul_f32_e32 v149, v55, v149
	v_fma_f32 v149, v55, v149, v55
	v_mul_f32_e32 v149, 0x3f4c422a, v149
	v_mul_f32_e32 v149, 0xc038aa3b, v149
	v_exp_f32_e32 v149, v149
	v_cvt_pk_bf16_f32 v164, v169, v170
	v_add_f32_e32 v185, v167, v171
	v_cvt_pk_bf16_f32 v166, v148, v166
	v_add_f32_e32 v149, 1.0, v149
	v_rcp_f32_e32 v170, v149
	v_mul_f32_e32 v149, 0x3d372713, v51
	v_mul_f32_e32 v149, v51, v149
	v_fma_f32 v149, v51, v149, v51
	v_mul_f32_e32 v149, 0x3f4c422a, v149
	v_mul_f32_e32 v149, 0xc038aa3b, v149
	v_exp_f32_e32 v149, v149
	v_mul_f32_e32 v148, 0x3d372713, v54
	v_mul_f32_e32 v148, v54, v148
	v_fma_f32 v148, v54, v148, v54
	v_add_f32_e32 v149, 1.0, v149
	v_rcp_f32_e32 v172, v149
	v_mul_f32_e32 v149, 0x3d372713, v56
	v_mul_f32_e32 v149, v56, v149
	v_fma_f32 v149, v56, v149, v56
	v_mul_f32_e32 v149, 0x3f4c422a, v149
	v_mul_f32_e32 v149, 0xc038aa3b, v149
	v_exp_f32_e32 v149, v149
	v_mul_f32_e32 v148, 0x3f4c422a, v148
	v_mul_f32_e32 v168, 0x3d372713, v61
	v_mul_f32_e32 v148, 0xc038aa3b, v148
	v_add_f32_e32 v149, 1.0, v149
	v_rcp_f32_e32 v171, v149
	v_mul_f32_e32 v149, 0x3d372713, v52
	v_mul_f32_e32 v149, v52, v149
	v_fma_f32 v149, v52, v149, v52
	v_mul_f32_e32 v149, 0x3f4c422a, v149
	v_mul_f32_e32 v149, 0xc038aa3b, v149
	v_mul_f32_e32 v168, v61, v168
	v_exp_f32_e32 v148, v148
	v_exp_f32_e32 v149, v149
	v_fma_f32 v168, v61, v168, v61
	v_mul_f32_e32 v168, 0x3f4c422a, v168
	v_mul_f32_e32 v168, 0xc038aa3b, v168
	v_exp_f32_e32 v168, v168
	v_add_f32_e32 v148, 1.0, v148
	v_add_f32_e32 v149, 1.0, v149
	v_rcp_f32_e32 v169, v148
	v_mul_f32_e32 v148, 0x3d372713, v50
	v_rcp_f32_e32 v174, v149
	v_mul_f32_e32 v149, 0x3d372713, v57
	v_mul_f32_e32 v148, v50, v148
	v_mul_f32_e32 v149, v57, v149
	v_fma_f32 v148, v50, v148, v50
	v_fma_f32 v149, v57, v149, v57
	v_add_f32_e32 v168, 1.0, v168
	v_mul_f32_e32 v148, 0x3f4c422a, v148
	v_mul_f32_e32 v149, 0x3f4c422a, v149
	v_mul_f32_e32 v175, 0x3d372713, v53
	v_add_u32_e32 v144, 0x80, v142
	v_rcp_f32_e32 v168, v168
	v_mul_f32_e32 v148, 0xc038aa3b, v148
	v_mul_f32_e32 v149, 0xc038aa3b, v149
	v_mul_f32_e32 v175, v53, v175
	v_ashrrev_i32_e32 v145, 31, v144
	v_exp_f32_e32 v148, v148
	v_exp_f32_e32 v149, v149
	v_fma_f32 v175, v53, v175, v53
	v_lshlrev_b64 v[146:147], 12, v[144:145]
	v_mul_f32_e32 v175, 0x3f4c422a, v175
	v_lshl_add_u64 v[146:147], s[46:47], 0, v[146:147]
	v_mul_f32_e32 v175, 0xc038aa3b, v175
	v_pk_mov_b32 v[176:177], v[60:61], v[54:55] op_sel:[1,0]
	v_lshl_add_u64 v[146:147], v[146:147], 0, v[0:1]
	v_exp_f32_e32 v175, v175
	v_pk_mul_f32 v[168:169], v[176:177], v[168:169]
	v_add_f32_e32 v148, 1.0, v148
	v_add_f32_e32 v149, 1.0, v149
	v_add_f32_e32 v185, v168, v185
	v_pk_mul_f32 v[176:177], v[168:169], v[168:169]
	v_cvt_pk_bf16_f32 v167, v167, v168
	global_store_dwordx4 v[146:147], v[164:167], off
	v_rcp_f32_e32 v148, v148
	v_rcp_f32_e32 v149, v149
	v_mov_b32_e32 v164, v55
	v_mov_b32_e32 v165, v56
	v_add_f32_e32 v176, v176, v186
	v_add_f32_e32 v166, v185, v169
	v_pk_mul_f32 v[164:165], v[164:165], v[170:171]
	v_add_f32_e32 v168, v176, v177
	v_add_f32_e32 v170, v164, v166
	v_pk_mul_f32 v[166:167], v[164:165], v[164:165]
	v_add_f32_e32 v175, 1.0, v175
	v_add_f32_e32 v166, v166, v168
	v_rcp_f32_e32 v175, v175
	v_add_f32_e32 v168, v165, v170
	v_add_f32_e32 v170, v167, v166
	v_mov_b32_e32 v166, v50
	v_mov_b32_e32 v167, v57
	v_pk_mul_f32 v[148:149], v[166:167], v[148:149]
	v_mul_f32_e32 v173, v51, v172
	v_pk_mul_f32 v[166:167], v[148:149], v[148:149]
	v_add_f32_e32 v168, v149, v168
	v_add_f32_e32 v167, v167, v170
	v_add_f32_e32 v168, v148, v168
	v_add_f32_e32 v167, v166, v167
	v_cvt_pk_bf16_f32 v165, v165, v149
	v_cvt_pk_bf16_f32 v166, v148, v173
	v_pk_mul_f32 v[148:149], v[52:53], v[174:175]
	v_fmac_f32_e32 v168, v51, v172
	v_mov_b32_e32 v172, v148
	v_cvt_pk_bf16_f32 v164, v169, v164
	v_pk_mul_f32 v[170:171], v[172:173], v[172:173]
	v_mov_b32_e32 v169, v149
	v_add_f32_e32 v167, v171, v167
	v_pk_fma_f32 v[168:169], v[52:53], v[174:175], v[168:169]
	v_pk_mul_f32 v[172:173], v[148:149], v[148:149]
	v_add_f32_e32 v171, v170, v167
	v_mov_b32_e32 v169, v173
	v_mov_b32_e32 v170, v149
	v_pk_add_f32 v[168:169], v[168:169], v[170:171]
	v_cvt_pk_bf16_f32 v167, v148, v149
	global_store_dwordx4 v[146:147], v[164:167], off offset:256
	ds_bpermute_b32 v146, v162, v168
	ds_bpermute_b32 v147, v162, v169
	s_waitcnt lgkmcnt(0)
	v_pk_add_f32 v[146:147], v[168:169], v[146:147]
	ds_bpermute_b32 v148, v163, v146
	ds_bpermute_b32 v149, v163, v147
	s_and_saveexec_b64 s[12:13], s[40:41]
	s_cbranch_execz .LBB0_323
	v_lshlrev_b64 v[144:145], 8, v[144:145]
	v_lshl_add_u64 v[144:145], s[48:49], 0, v[144:145]
	v_lshl_add_u64 v[144:145], s[30:31], 3, v[144:145]
	s_waitcnt lgkmcnt(0)
	v_pk_add_f32 v[146:147], v[146:147], v[148:149]
	s_waitcnt vmcnt(0)
	global_store_dwordx2 v[144:145], v[146:147], off
; __device__ __forceinline__ float gelu_f(float x) { const float u = 0.7978845608028654f * (x + 0.044715f * x * x * x); return x * frcp(1.f + fexp2(-2.885390081777927f * u)); }
; __device__ __forceinline__ void st8(bf16_t* p, const float (&v)[8]) { u32x4 w; w.x = pk2(v[0], v[1]); w.y = pk2(v[2], v[3]); w.z = pk2(v[4], v[5]); w.w = pk2(v[6], v[7]); *(u32x4*)p = w; }
;     __device__ __forceinline__ void operator()(const f32x4 (&acc)[2][2][4][2], const Unit& u, int wr, int wc, int fr, int fq) const {
;     ...
; #pragma unroll
;             for (int ai = 0; ai < 2; ++ai)
; #pragma unroll
;                 for (int m = 0; m < 4; ++m) { const int row = row0 + ai * 128 + m * 16; float s1 = 0.f, s2 = 0.f;
; #pragma unroll
;                     for (int bj = 0; bj < 2; ++bj) { float o[8];
; #pragma unroll
;                         for (int j = 0; j < 4; ++j) { o[j] = gelu_f(acc[ai][bj][m][0][j]); o[4 + j] = gelu_f(acc[ai][bj][m][1][j]); }
; #pragma unroll
;                         for (int j = 0; j < 8; ++j) { s1 += o[j]; s2 += o[j] * o[j]; }
;                         st8(gv + (size_t)row * DM + colt + bj * 128, o); }
;                     s1 += __shfl_xor(s1, 16); s2 += __shfl_xor(s2, 16); s1 += __shfl_xor(s1, 32); s2 += __shfl_xor(s2, 32);
;                     if (fq == 0) { float2 w; w.x = s1; w.y = s2; *(float2*)(stats + ((size_t)row * 32 + (pn - 16) * 4 + wc) * 2) = w; }
.LBB0_323:
	s_or_b64 exec, exec, s[12:13]
	s_waitcnt lgkmcnt(0)
	v_mul_f32_e32 v149, 0x3d372713, v47
	v_mul_f32_e32 v149, v47, v149
	v_fma_f32 v149, v47, v149, v47
	v_mul_f32_e32 v149, 0x3f4c422a, v149
	v_mul_f32_e32 v149, 0xc038aa3b, v149
	v_exp_f32_e32 v149, v149
	v_mul_f32_e32 v148, 0x3d372713, v46
	v_mul_f32_e32 v148, v46, v148
	v_fma_f32 v148, v46, v148, v46
	v_add_f32_e32 v149, 1.0, v149
	v_rcp_f32_e32 v167, v149
	v_mul_f32_e32 v149, 0x3d372713, v43
	v_mul_f32_e32 v149, v43, v149
	v_fma_f32 v149, v43, v149, v43
	v_mul_f32_e32 v149, 0x3f4c422a, v149
	v_mul_f32_e32 v149, 0xc038aa3b, v149
	v_exp_f32_e32 v149, v149
	v_mul_f32_e32 v148, 0x3f4c422a, v148
	v_mul_f32_e32 v148, 0xc038aa3b, v148
	v_exp_f32_e32 v148, v148
	v_add_f32_e32 v149, 1.0, v149
	v_rcp_f32_e32 v164, v149
	v_mul_f32_e32 v149, 0x3d372713, v48
	v_mul_f32_e32 v149, v48, v149
	v_fma_f32 v149, v48, v149, v48
	v_mul_f32_e32 v149, 0x3f4c422a, v149
	v_mul_f32_e32 v149, 0xc038aa3b, v149
	v_exp_f32_e32 v149, v149
	v_add_f32_e32 v148, 1.0, v148
	v_rcp_f32_e32 v166, v148
	v_mul_f32_e32 v148, 0x3d372713, v42
	v_add_f32_e32 v149, 1.0, v149
	v_rcp_f32_e32 v171, v149
	v_mul_f32_e32 v149, 0x3d372713, v44
	v_mul_f32_e32 v149, v44, v149
	v_fma_f32 v149, v44, v149, v44
	v_mul_f32_e32 v149, 0x3f4c422a, v149
	v_mul_f32_e32 v149, 0xc038aa3b, v149
	v_exp_f32_e32 v149, v149
	v_mul_f32_e32 v148, v42, v148
	v_fma_f32 v148, v42, v148, v42
	v_mul_f32_e32 v148, 0x3f4c422a, v148
	v_add_f32_e32 v149, 1.0, v149
	v_rcp_f32_e32 v165, v149
	v_mul_f32_e32 v149, 0x3d372713, v49
	v_mul_f32_e32 v149, v49, v149
	v_fma_f32 v149, v49, v149, v49
	v_mul_f32_e32 v149, 0x3f4c422a, v149
	v_mul_f32_e32 v148, 0xc038aa3b, v148
	v_mul_f32_e32 v149, 0xc038aa3b, v149
	v_exp_f32_e32 v148, v148
	v_exp_f32_e32 v149, v149
	v_mul_f32_e32 v170, v47, v167
	v_fma_f32 v173, v46, v166, 0
	v_add_f32_e32 v148, 1.0, v148
	v_add_f32_e32 v149, 1.0, v149
	v_rcp_f32_e32 v148, v148
	v_rcp_f32_e32 v149, v149
	v_mul_f32_e32 v169, v46, v166
	v_fmac_f32_e32 v173, v47, v167
	v_mul_f32_e32 v174, v170, v170
	v_mov_b32_e32 v166, v42
	v_mov_b32_e32 v167, v49
	v_mul_f32_e32 v172, v48, v171
	v_fmac_f32_e32 v174, v169, v169
	v_pk_mul_f32 v[148:149], v[166:167], v[148:149]
	v_fmac_f32_e32 v174, v172, v172
	v_pk_mul_f32 v[166:167], v[148:149], v[148:149]
	v_fmac_f32_e32 v173, v48, v171
	v_add_f32_e32 v167, v167, v174
	v_add_f32_e32 v171, v149, v173
	v_add_f32_e32 v173, v166, v167
	v_mov_b32_e32 v166, v43
	v_mov_b32_e32 v167, v44
	v_pk_mul_f32 v[166:167], v[166:167], v[164:165]
	v_add_f32_e32 v171, v148, v171
	v_pk_mul_f32 v[164:165], v[166:167], v[166:167]
	v_add_f32_e32 v171, v166, v171
	v_add_f32_e32 v164, v164, v173
	v_add_f32_e32 v186, v165, v164
	v_cvt_pk_bf16_f32 v165, v172, v149
	v_mul_f32_e32 v149, 0x3d372713, v39
	v_mul_f32_e32 v149, v39, v149
	v_fma_f32 v149, v39, v149, v39
	v_mul_f32_e32 v149, 0x3f4c422a, v149
	v_mul_f32_e32 v149, 0xc038aa3b, v149
	v_exp_f32_e32 v149, v149
	v_cvt_pk_bf16_f32 v164, v169, v170
	v_add_f32_e32 v185, v167, v171
	v_cvt_pk_bf16_f32 v166, v148, v166
	v_add_f32_e32 v149, 1.0, v149
	v_rcp_f32_e32 v170, v149
	v_mul_f32_e32 v149, 0x3d372713, v35
	v_mul_f32_e32 v149, v35, v149
	v_fma_f32 v149, v35, v149, v35
	v_mul_f32_e32 v149, 0x3f4c422a, v149
	v_mul_f32_e32 v149, 0xc038aa3b, v149
	v_exp_f32_e32 v149, v149
	v_mul_f32_e32 v148, 0x3d372713, v38
	v_mul_f32_e32 v148, v38, v148
	v_fma_f32 v148, v38, v148, v38
	v_add_f32_e32 v149, 1.0, v149
	v_rcp_f32_e32 v172, v149
	v_mul_f32_e32 v149, 0x3d372713, v40
	v_mul_f32_e32 v149, v40, v149
	v_fma_f32 v149, v40, v149, v40
	v_mul_f32_e32 v149, 0x3f4c422a, v149
	v_mul_f32_e32 v149, 0xc038aa3b, v149
	v_exp_f32_e32 v149, v149
	v_mul_f32_e32 v148, 0x3f4c422a, v148
	v_mul_f32_e32 v168, 0x3d372713, v45
	v_mul_f32_e32 v148, 0xc038aa3b, v148
	v_add_f32_e32 v149, 1.0, v149
	v_rcp_f32_e32 v171, v149
	v_mul_f32_e32 v149, 0x3d372713, v36
	v_mul_f32_e32 v149, v36, v149
	v_fma_f32 v149, v36, v149, v36
	v_mul_f32_e32 v149, 0x3f4c422a, v149
	v_mul_f32_e32 v149, 0xc038aa3b, v149
	v_mul_f32_e32 v168, v45, v168
	v_exp_f32_e32 v148, v148
	v_exp_f32_e32 v149, v149
	v_fma_f32 v168, v45, v168, v45
	v_mul_f32_e32 v168, 0x3f4c422a, v168
	v_mul_f32_e32 v168, 0xc038aa3b, v168
	v_exp_f32_e32 v168, v168
	v_add_f32_e32 v148, 1.0, v148
	v_add_f32_e32 v149, 1.0, v149
	v_rcp_f32_e32 v169, v148
	v_mul_f32_e32 v148, 0x3d372713, v34
	v_rcp_f32_e32 v174, v149
	v_mul_f32_e32 v149, 0x3d372713, v41
	v_mul_f32_e32 v148, v34, v148
	v_mul_f32_e32 v149, v41, v149
	v_fma_f32 v148, v34, v148, v34
	v_fma_f32 v149, v41, v149, v41
	v_add_f32_e32 v168, 1.0, v168
	v_mul_f32_e32 v148, 0x3f4c422a, v148
	v_mul_f32_e32 v149, 0x3f4c422a, v149
	v_mul_f32_e32 v175, 0x3d372713, v37
	v_add_u32_e32 v144, 0x90, v142
	v_rcp_f32_e32 v168, v168
	v_mul_f32_e32 v148, 0xc038aa3b, v148
	v_mul_f32_e32 v149, 0xc038aa3b, v149
	v_mul_f32_e32 v175, v37, v175
	v_ashrrev_i32_e32 v145, 31, v144
	v_exp_f32_e32 v148, v148
	v_exp_f32_e32 v149, v149
	v_fma_f32 v175, v37, v175, v37
	v_lshlrev_b64 v[146:147], 12, v[144:145]
	v_mul_f32_e32 v175, 0x3f4c422a, v175
	v_lshl_add_u64 v[146:147], s[46:47], 0, v[146:147]
	v_mul_f32_e32 v175, 0xc038aa3b, v175
	v_pk_mov_b32 v[176:177], v[44:45], v[38:39] op_sel:[1,0]
	v_lshl_add_u64 v[146:147], v[146:147], 0, v[0:1]
	v_exp_f32_e32 v175, v175
	v_pk_mul_f32 v[168:169], v[176:177], v[168:169]
	v_add_f32_e32 v148, 1.0, v148
	v_add_f32_e32 v149, 1.0, v149
	v_add_f32_e32 v185, v168, v185
	v_pk_mul_f32 v[176:177], v[168:169], v[168:169]
	v_cvt_pk_bf16_f32 v167, v167, v168
	global_store_dwordx4 v[146:147], v[164:167], off
	v_rcp_f32_e32 v148, v148
	v_rcp_f32_e32 v149, v149
	v_mov_b32_e32 v164, v39
	v_mov_b32_e32 v165, v40
; __device__ __forceinline__ float gelu_f(float x) { const float u = 0.7978845608028654f * (x + 0.044715f * x * x * x); return x * frcp(1.f + fexp2(-2.885390081777927f * u)); }
; __device__ __forceinline__ void st8(bf16_t* p, const float (&v)[8]) { u32x4 w; w.x = pk2(v[0], v[1]); w.y = pk2(v[2], v[3]); w.z = pk2(v[4], v[5]); w.w = pk2(v[6], v[7]); *(u32x4*)p = w; }
;     __device__ __forceinline__ void operator()(const f32x4 (&acc)[2][2][4][2], const Unit& u, int wr, int wc, int fr, int fq) const {
;     ...
; #pragma unroll
;             for (int ai = 0; ai < 2; ++ai)
; #pragma unroll
;                 for (int m = 0; m < 4; ++m) { const int row = row0 + ai * 128 + m * 16; float s1 = 0.f, s2 = 0.f;
; #pragma unroll
;                     for (int bj = 0; bj < 2; ++bj) { float o[8];
; #pragma unroll
;                         for (int j = 0; j < 4; ++j) { o[j] = gelu_f(acc[ai][bj][m][0][j]); o[4 + j] = gelu_f(acc[ai][bj][m][1][j]); }
; #pragma unroll
;                         for (int j = 0; j < 8; ++j) { s1 += o[j]; s2 += o[j] * o[j]; }
;                         st8(gv + (size_t)row * DM + colt + bj * 128, o); }
;                     s1 += __shfl_xor(s1, 16); s2 += __shfl_xor(s2, 16); s1 += __shfl_xor(s1, 32); s2 += __shfl_xor(s2, 32);
;                     if (fq == 0) { float2 w; w.x = s1; w.y = s2; *(float2*)(stats + ((size_t)row * 32 + (pn - 16) * 4 + wc) * 2) = w; }
	v_add_f32_e32 v176, v176, v186
	v_add_f32_e32 v166, v185, v169
	v_pk_mul_f32 v[164:165], v[164:165], v[170:171]
	v_add_f32_e32 v168, v176, v177
	v_add_f32_e32 v170, v164, v166
	v_pk_mul_f32 v[166:167], v[164:165], v[164:165]
	v_add_f32_e32 v175, 1.0, v175
	v_add_f32_e32 v166, v166, v168
	v_rcp_f32_e32 v175, v175
	v_add_f32_e32 v168, v165, v170
	v_add_f32_e32 v170, v167, v166
	v_mov_b32_e32 v166, v34
	v_mov_b32_e32 v167, v41
	v_pk_mul_f32 v[148:149], v[166:167], v[148:149]
	v_mul_f32_e32 v173, v35, v172
	v_pk_mul_f32 v[166:167], v[148:149], v[148:149]
	v_add_f32_e32 v168, v149, v168
	v_add_f32_e32 v167, v167, v170
	v_add_f32_e32 v168, v148, v168
	v_add_f32_e32 v167, v166, v167
	v_cvt_pk_bf16_f32 v165, v165, v149
	v_cvt_pk_bf16_f32 v166, v148, v173
	v_pk_mul_f32 v[148:149], v[36:37], v[174:175]
	v_fmac_f32_e32 v168, v35, v172
	v_mov_b32_e32 v172, v148
	v_cvt_pk_bf16_f32 v164, v169, v164
	v_pk_mul_f32 v[170:171], v[172:173], v[172:173]
	v_mov_b32_e32 v169, v149
	v_add_f32_e32 v167, v171, v167
	v_pk_fma_f32 v[168:169], v[36:37], v[174:175], v[168:169]
	v_pk_mul_f32 v[172:173], v[148:149], v[148:149]
	v_add_f32_e32 v171, v170, v167
	v_mov_b32_e32 v169, v173
	v_mov_b32_e32 v170, v149
	v_pk_add_f32 v[168:169], v[168:169], v[170:171]
	v_cvt_pk_bf16_f32 v167, v148, v149
	global_store_dwordx4 v[146:147], v[164:167], off offset:256
	ds_bpermute_b32 v146, v162, v168
	ds_bpermute_b32 v147, v162, v169
	s_waitcnt lgkmcnt(0)
	v_pk_add_f32 v[146:147], v[168:169], v[146:147]
	ds_bpermute_b32 v148, v163, v146
	ds_bpermute_b32 v149, v163, v147
	s_and_saveexec_b64 s[12:13], s[40:41]
	s_cbranch_execz .LBB0_325
	v_lshlrev_b64 v[144:145], 8, v[144:145]
	v_lshl_add_u64 v[144:145], s[48:49], 0, v[144:145]
	v_lshl_add_u64 v[144:145], s[30:31], 3, v[144:145]
	s_waitcnt lgkmcnt(0)
	v_pk_add_f32 v[146:147], v[146:147], v[148:149]
	s_waitcnt vmcnt(0)
	global_store_dwordx2 v[144:145], v[146:147], off
.LBB0_325:
	s_or_b64 exec, exec, s[12:13]
	s_waitcnt lgkmcnt(0)
	v_mul_f32_e32 v149, 0x3d372713, v31
	v_mul_f32_e32 v149, v31, v149
	v_fma_f32 v149, v31, v149, v31
	v_mul_f32_e32 v149, 0x3f4c422a, v149
	v_mul_f32_e32 v149, 0xc038aa3b, v149
	v_exp_f32_e32 v149, v149
	v_mul_f32_e32 v148, 0x3d372713, v30
	v_mul_f32_e32 v148, v30, v148
	v_fma_f32 v148, v30, v148, v30
	v_add_f32_e32 v149, 1.0, v149
	v_rcp_f32_e32 v167, v149
	v_mul_f32_e32 v149, 0x3d372713, v27
	v_mul_f32_e32 v149, v27, v149
	v_fma_f32 v149, v27, v149, v27
	v_mul_f32_e32 v149, 0x3f4c422a, v149
	v_mul_f32_e32 v149, 0xc038aa3b, v149
	v_exp_f32_e32 v149, v149
	v_mul_f32_e32 v148, 0x3f4c422a, v148
	v_mul_f32_e32 v148, 0xc038aa3b, v148
	v_exp_f32_e32 v148, v148
	v_add_f32_e32 v149, 1.0, v149
	v_rcp_f32_e32 v164, v149
	v_mul_f32_e32 v149, 0x3d372713, v32
	v_mul_f32_e32 v149, v32, v149
	v_fma_f32 v149, v32, v149, v32
	v_mul_f32_e32 v149, 0x3f4c422a, v149
	v_mul_f32_e32 v149, 0xc038aa3b, v149
	v_exp_f32_e32 v149, v149
	v_add_f32_e32 v148, 1.0, v148
	v_rcp_f32_e32 v166, v148
	v_mul_f32_e32 v148, 0x3d372713, v26
	v_add_f32_e32 v149, 1.0, v149
	v_rcp_f32_e32 v171, v149
	v_mul_f32_e32 v149, 0x3d372713, v28
	v_mul_f32_e32 v149, v28, v149
	v_fma_f32 v149, v28, v149, v28
	v_mul_f32_e32 v149, 0x3f4c422a, v149
	v_mul_f32_e32 v149, 0xc038aa3b, v149
	v_exp_f32_e32 v149, v149
	v_mul_f32_e32 v148, v26, v148
	v_fma_f32 v148, v26, v148, v26
	v_mul_f32_e32 v148, 0x3f4c422a, v148
	v_add_f32_e32 v149, 1.0, v149
	v_rcp_f32_e32 v165, v149
	v_mul_f32_e32 v149, 0x3d372713, v33
	v_mul_f32_e32 v149, v33, v149
	v_fma_f32 v149, v33, v149, v33
	v_mul_f32_e32 v149, 0x3f4c422a, v149
	v_mul_f32_e32 v148, 0xc038aa3b, v148
	v_mul_f32_e32 v149, 0xc038aa3b, v149
	v_exp_f32_e32 v148, v148
	v_exp_f32_e32 v149, v149
	v_mul_f32_e32 v170, v31, v167
	v_fma_f32 v173, v30, v166, 0
	v_add_f32_e32 v148, 1.0, v148
	v_add_f32_e32 v149, 1.0, v149
	v_rcp_f32_e32 v148, v148
	v_rcp_f32_e32 v149, v149
	v_mul_f32_e32 v169, v30, v166
	v_fmac_f32_e32 v173, v31, v167
	v_mul_f32_e32 v174, v170, v170
	v_mov_b32_e32 v166, v26
	v_mov_b32_e32 v167, v33
	v_mul_f32_e32 v172, v32, v171
	v_fmac_f32_e32 v174, v169, v169
	v_pk_mul_f32 v[148:149], v[166:167], v[148:149]
	v_fmac_f32_e32 v174, v172, v172
	v_pk_mul_f32 v[166:167], v[148:149], v[148:149]
	v_fmac_f32_e32 v173, v32, v171
	v_add_f32_e32 v167, v167, v174
	v_add_f32_e32 v171, v149, v173
	v_add_f32_e32 v173, v166, v167
	v_mov_b32_e32 v166, v27
	v_mov_b32_e32 v167, v28
	v_pk_mul_f32 v[166:167], v[166:167], v[164:165]
	v_add_f32_e32 v171, v148, v171
	v_pk_mul_f32 v[164:165], v[166:167], v[166:167]
	v_add_f32_e32 v171, v166, v171
	v_add_f32_e32 v164, v164, v173
	v_add_f32_e32 v186, v165, v164
	v_cvt_pk_bf16_f32 v165, v172, v149
	v_mul_f32_e32 v149, 0x3d372713, v23
	v_mul_f32_e32 v149, v23, v149
	v_fma_f32 v149, v23, v149, v23
	v_mul_f32_e32 v149, 0x3f4c422a, v149
	v_mul_f32_e32 v149, 0xc038aa3b, v149
	v_exp_f32_e32 v149, v149
	v_cvt_pk_bf16_f32 v164, v169, v170
	v_add_f32_e32 v185, v167, v171
	v_cvt_pk_bf16_f32 v166, v148, v166
	v_add_f32_e32 v149, 1.0, v149
	v_rcp_f32_e32 v170, v149
	v_mul_f32_e32 v149, 0x3d372713, v19
	v_mul_f32_e32 v149, v19, v149
	v_fma_f32 v149, v19, v149, v19
	v_mul_f32_e32 v149, 0x3f4c422a, v149
	v_mul_f32_e32 v149, 0xc038aa3b, v149
	v_exp_f32_e32 v149, v149
	v_mul_f32_e32 v148, 0x3d372713, v22
	v_mul_f32_e32 v148, v22, v148
	v_fma_f32 v148, v22, v148, v22
	v_add_f32_e32 v149, 1.0, v149
	v_rcp_f32_e32 v172, v149
	v_mul_f32_e32 v149, 0x3d372713, v24
	v_mul_f32_e32 v149, v24, v149
	v_fma_f32 v149, v24, v149, v24
	v_mul_f32_e32 v149, 0x3f4c422a, v149
	v_mul_f32_e32 v149, 0xc038aa3b, v149
	v_exp_f32_e32 v149, v149
	v_mul_f32_e32 v148, 0x3f4c422a, v148
	v_mul_f32_e32 v168, 0x3d372713, v29
	v_mul_f32_e32 v148, 0xc038aa3b, v148
; __device__ __forceinline__ float gelu_f(float x) { const float u = 0.7978845608028654f * (x + 0.044715f * x * x * x); return x * frcp(1.f + fexp2(-2.885390081777927f * u)); }
; __device__ __forceinline__ void st8(bf16_t* p, const float (&v)[8]) { u32x4 w; w.x = pk2(v[0], v[1]); w.y = pk2(v[2], v[3]); w.z = pk2(v[4], v[5]); w.w = pk2(v[6], v[7]); *(u32x4*)p = w; }
;     __device__ __forceinline__ void operator()(const f32x4 (&acc)[2][2][4][2], const Unit& u, int wr, int wc, int fr, int fq) const {
;     ...
; #pragma unroll
;             for (int ai = 0; ai < 2; ++ai)
; #pragma unroll
;                 for (int m = 0; m < 4; ++m) { const int row = row0 + ai * 128 + m * 16; float s1 = 0.f, s2 = 0.f;
; #pragma unroll
;                     for (int bj = 0; bj < 2; ++bj) { float o[8];
; #pragma unroll
;                         for (int j = 0; j < 4; ++j) { o[j] = gelu_f(acc[ai][bj][m][0][j]); o[4 + j] = gelu_f(acc[ai][bj][m][1][j]); }
; #pragma unroll
;                         for (int j = 0; j < 8; ++j) { s1 += o[j]; s2 += o[j] * o[j]; }
;                         st8(gv + (size_t)row * DM + colt + bj * 128, o); }
;                     s1 += __shfl_xor(s1, 16); s2 += __shfl_xor(s2, 16); s1 += __shfl_xor(s1, 32); s2 += __shfl_xor(s2, 32);
;                     if (fq == 0) { float2 w; w.x = s1; w.y = s2; *(float2*)(stats + ((size_t)row * 32 + (pn - 16) * 4 + wc) * 2) = w; }
	v_add_f32_e32 v149, 1.0, v149
	v_rcp_f32_e32 v171, v149
	v_mul_f32_e32 v149, 0x3d372713, v20
	v_mul_f32_e32 v149, v20, v149
	v_fma_f32 v149, v20, v149, v20
	v_mul_f32_e32 v149, 0x3f4c422a, v149
	v_mul_f32_e32 v149, 0xc038aa3b, v149
	v_mul_f32_e32 v168, v29, v168
	v_exp_f32_e32 v148, v148
	v_exp_f32_e32 v149, v149
	v_fma_f32 v168, v29, v168, v29
	v_mul_f32_e32 v168, 0x3f4c422a, v168
	v_mul_f32_e32 v168, 0xc038aa3b, v168
	v_exp_f32_e32 v168, v168
	v_add_f32_e32 v148, 1.0, v148
	v_add_f32_e32 v149, 1.0, v149
	v_rcp_f32_e32 v169, v148
	v_mul_f32_e32 v148, 0x3d372713, v18
	v_rcp_f32_e32 v174, v149
	v_mul_f32_e32 v149, 0x3d372713, v25
	v_mul_f32_e32 v148, v18, v148
	v_mul_f32_e32 v149, v25, v149
	v_fma_f32 v148, v18, v148, v18
	v_fma_f32 v149, v25, v149, v25
	v_add_f32_e32 v168, 1.0, v168
	v_mul_f32_e32 v148, 0x3f4c422a, v148
	v_mul_f32_e32 v149, 0x3f4c422a, v149
	v_mul_f32_e32 v175, 0x3d372713, v21
	v_add_u32_e32 v144, 0xa0, v142
	v_rcp_f32_e32 v168, v168
	v_mul_f32_e32 v148, 0xc038aa3b, v148
	v_mul_f32_e32 v149, 0xc038aa3b, v149
	v_mul_f32_e32 v175, v21, v175
	v_ashrrev_i32_e32 v145, 31, v144
	v_exp_f32_e32 v148, v148
	v_exp_f32_e32 v149, v149
	v_fma_f32 v175, v21, v175, v21
	v_lshlrev_b64 v[146:147], 12, v[144:145]
	v_mul_f32_e32 v175, 0x3f4c422a, v175
	v_lshl_add_u64 v[146:147], s[46:47], 0, v[146:147]
	v_mul_f32_e32 v175, 0xc038aa3b, v175
	v_pk_mov_b32 v[176:177], v[28:29], v[22:23] op_sel:[1,0]
	v_lshl_add_u64 v[146:147], v[146:147], 0, v[0:1]
	v_exp_f32_e32 v175, v175
	v_pk_mul_f32 v[168:169], v[176:177], v[168:169]
	v_add_f32_e32 v148, 1.0, v148
	v_add_f32_e32 v149, 1.0, v149
	v_add_f32_e32 v185, v168, v185
	v_pk_mul_f32 v[176:177], v[168:169], v[168:169]
	v_cvt_pk_bf16_f32 v167, v167, v168
	global_store_dwordx4 v[146:147], v[164:167], off
	v_rcp_f32_e32 v148, v148
	v_rcp_f32_e32 v149, v149
	v_mov_b32_e32 v164, v23
	v_mov_b32_e32 v165, v24
	v_add_f32_e32 v176, v176, v186
	v_add_f32_e32 v166, v185, v169
	v_pk_mul_f32 v[164:165], v[164:165], v[170:171]
	v_add_f32_e32 v168, v176, v177
	v_add_f32_e32 v170, v164, v166
	v_pk_mul_f32 v[166:167], v[164:165], v[164:165]
	v_add_f32_e32 v175, 1.0, v175
	v_add_f32_e32 v166, v166, v168
	v_rcp_f32_e32 v175, v175
	v_add_f32_e32 v168, v165, v170
	v_add_f32_e32 v170, v167, v166
	v_mov_b32_e32 v166, v18
	v_mov_b32_e32 v167, v25
	v_pk_mul_f32 v[148:149], v[166:167], v[148:149]
	v_mul_f32_e32 v173, v19, v172
	v_pk_mul_f32 v[166:167], v[148:149], v[148:149]
	v_add_f32_e32 v168, v149, v168
	v_add_f32_e32 v167, v167, v170
	v_add_f32_e32 v168, v148, v168
	v_add_f32_e32 v167, v166, v167
	v_cvt_pk_bf16_f32 v165, v165, v149
	v_cvt_pk_bf16_f32 v166, v148, v173
	v_pk_mul_f32 v[148:149], v[20:21], v[174:175]
	v_fmac_f32_e32 v168, v19, v172
	v_mov_b32_e32 v172, v148
	v_cvt_pk_bf16_f32 v164, v169, v164
	v_pk_mul_f32 v[170:171], v[172:173], v[172:173]
	v_mov_b32_e32 v169, v149
	v_add_f32_e32 v167, v171, v167
	v_pk_fma_f32 v[168:169], v[20:21], v[174:175], v[168:169]
	v_pk_mul_f32 v[172:173], v[148:149], v[148:149]
	v_add_f32_e32 v171, v170, v167
	v_mov_b32_e32 v169, v173
	v_mov_b32_e32 v170, v149
	v_pk_add_f32 v[168:169], v[168:169], v[170:171]
	v_cvt_pk_bf16_f32 v167, v148, v149
	global_store_dwordx4 v[146:147], v[164:167], off offset:256
	ds_bpermute_b32 v146, v162, v168
	ds_bpermute_b32 v147, v162, v169
	s_waitcnt lgkmcnt(0)
	v_pk_add_f32 v[146:147], v[168:169], v[146:147]
	ds_bpermute_b32 v148, v163, v146
	ds_bpermute_b32 v149, v163, v147
	s_and_saveexec_b64 s[12:13], s[40:41]
	s_cbranch_execz .LBB0_327
	v_lshlrev_b64 v[144:145], 8, v[144:145]
	v_lshl_add_u64 v[144:145], s[48:49], 0, v[144:145]
	v_lshl_add_u64 v[144:145], s[30:31], 3, v[144:145]
	s_waitcnt lgkmcnt(0)
	v_pk_add_f32 v[146:147], v[146:147], v[148:149]
	s_waitcnt vmcnt(0)
	global_store_dwordx2 v[144:145], v[146:147], off
.LBB0_327:
	s_or_b64 exec, exec, s[12:13]
	s_waitcnt lgkmcnt(0)
	v_mul_f32_e32 v149, 0x3d372713, v15
	v_mul_f32_e32 v149, v15, v149
	v_fma_f32 v149, v15, v149, v15
	v_mul_f32_e32 v149, 0x3f4c422a, v149
	v_mul_f32_e32 v149, 0xc038aa3b, v149
	v_exp_f32_e32 v149, v149
	v_mul_f32_e32 v148, 0x3d372713, v14
	v_mul_f32_e32 v148, v14, v148
	v_fma_f32 v148, v14, v148, v14
	v_add_f32_e32 v149, 1.0, v149
	v_rcp_f32_e32 v167, v149
	v_mul_f32_e32 v149, 0x3d372713, v11
	v_mul_f32_e32 v149, v11, v149
	v_fma_f32 v149, v11, v149, v11
	v_mul_f32_e32 v149, 0x3f4c422a, v149
	v_mul_f32_e32 v149, 0xc038aa3b, v149
	v_exp_f32_e32 v149, v149
	v_mul_f32_e32 v148, 0x3f4c422a, v148
	v_mul_f32_e32 v148, 0xc038aa3b, v148
	v_exp_f32_e32 v148, v148
	v_add_f32_e32 v149, 1.0, v149
	v_rcp_f32_e32 v164, v149
	v_mul_f32_e32 v149, 0x3d372713, v16
	v_mul_f32_e32 v149, v16, v149
	v_fma_f32 v149, v16, v149, v16
	v_mul_f32_e32 v149, 0x3f4c422a, v149
	v_mul_f32_e32 v149, 0xc038aa3b, v149
	v_exp_f32_e32 v149, v149
	v_add_f32_e32 v148, 1.0, v148
	v_rcp_f32_e32 v166, v148
	v_mul_f32_e32 v148, 0x3d372713, v10
	v_add_f32_e32 v149, 1.0, v149
	v_rcp_f32_e32 v171, v149
	v_mul_f32_e32 v149, 0x3d372713, v12
	v_mul_f32_e32 v149, v12, v149
	v_fma_f32 v149, v12, v149, v12
	v_mul_f32_e32 v149, 0x3f4c422a, v149
	v_mul_f32_e32 v149, 0xc038aa3b, v149
	v_exp_f32_e32 v149, v149
	v_mul_f32_e32 v148, v10, v148
	v_fma_f32 v148, v10, v148, v10
	v_mul_f32_e32 v148, 0x3f4c422a, v148
	v_add_f32_e32 v149, 1.0, v149
	v_rcp_f32_e32 v165, v149
	v_mul_f32_e32 v149, 0x3d372713, v17
	v_mul_f32_e32 v149, v17, v149
	v_fma_f32 v149, v17, v149, v17
	v_mul_f32_e32 v149, 0x3f4c422a, v149
	v_mul_f32_e32 v148, 0xc038aa3b, v148
	v_mul_f32_e32 v149, 0xc038aa3b, v149
	v_exp_f32_e32 v148, v148
	v_exp_f32_e32 v149, v149
	v_add_u32_e32 v144, 0xb0, v142
; __device__ __forceinline__ float gelu_f(float x) { const float u = 0.7978845608028654f * (x + 0.044715f * x * x * x); return x * frcp(1.f + fexp2(-2.885390081777927f * u)); }
; __device__ __forceinline__ void st8(bf16_t* p, const float (&v)[8]) { u32x4 w; w.x = pk2(v[0], v[1]); w.y = pk2(v[2], v[3]); w.z = pk2(v[4], v[5]); w.w = pk2(v[6], v[7]); *(u32x4*)p = w; }
;     __device__ __forceinline__ void operator()(const f32x4 (&acc)[2][2][4][2], const Unit& u, int wr, int wc, int fr, int fq) const {
;     ...
; #pragma unroll
;             for (int ai = 0; ai < 2; ++ai)
; #pragma unroll
;                 for (int m = 0; m < 4; ++m) { const int row = row0 + ai * 128 + m * 16; float s1 = 0.f, s2 = 0.f;
; #pragma unroll
;                     for (int bj = 0; bj < 2; ++bj) { float o[8];
; #pragma unroll
;                         for (int j = 0; j < 4; ++j) { o[j] = gelu_f(acc[ai][bj][m][0][j]); o[4 + j] = gelu_f(acc[ai][bj][m][1][j]); }
; #pragma unroll
;                         for (int j = 0; j < 8; ++j) { s1 += o[j]; s2 += o[j] * o[j]; }
;                         st8(gv + (size_t)row * DM + colt + bj * 128, o); }
;                     s1 += __shfl_xor(s1, 16); s2 += __shfl_xor(s2, 16); s1 += __shfl_xor(s1, 32); s2 += __shfl_xor(s2, 32);
;                     if (fq == 0) { float2 w; w.x = s1; w.y = s2; *(float2*)(stats + ((size_t)row * 32 + (pn - 16) * 4 + wc) * 2) = w; }
	v_ashrrev_i32_e32 v145, 31, v144
	v_add_f32_e32 v148, 1.0, v148
	v_add_f32_e32 v149, 1.0, v149
	v_rcp_f32_e32 v148, v148
	v_rcp_f32_e32 v149, v149
	v_lshlrev_b64 v[146:147], 12, v[144:145]
	v_mul_f32_e32 v170, v15, v167
	v_fma_f32 v173, v14, v166, 0
	v_mul_f32_e32 v169, v14, v166
	v_fmac_f32_e32 v173, v15, v167
	v_mul_f32_e32 v174, v170, v170
	v_mov_b32_e32 v166, v10
	v_mov_b32_e32 v167, v17
	v_lshl_add_u64 v[146:147], s[46:47], 0, v[146:147]
	v_mul_f32_e32 v172, v16, v171
	v_fmac_f32_e32 v174, v169, v169
	v_pk_mul_f32 v[148:149], v[166:167], v[148:149]
	v_lshl_add_u64 v[146:147], v[146:147], 0, v[0:1]
	v_mul_f32_e32 v0, 0x3d372713, v6
	v_fmac_f32_e32 v174, v172, v172
	v_pk_mul_f32 v[166:167], v[148:149], v[148:149]
	v_mul_f32_e32 v0, v6, v0
	v_fmac_f32_e32 v173, v16, v171
	v_add_f32_e32 v167, v167, v174
	v_fma_f32 v0, v6, v0, v6
	v_add_f32_e32 v171, v149, v173
	v_add_f32_e32 v173, v166, v167
	v_mov_b32_e32 v166, v11
	v_mov_b32_e32 v167, v12
	v_mul_f32_e32 v0, 0x3f4c422a, v0
	v_pk_mul_f32 v[166:167], v[166:167], v[164:165]
	v_mul_f32_e32 v0, 0xc038aa3b, v0
	v_pk_mul_f32 v[164:165], v[166:167], v[166:167]
	v_exp_f32_e32 v0, v0
	v_add_f32_e32 v164, v164, v173
	v_add_f32_e32 v186, v165, v164
	v_cvt_pk_bf16_f32 v165, v172, v149
	v_mul_f32_e32 v149, 0x3d372713, v8
	v_mul_f32_e32 v149, v8, v149
	v_add_f32_e32 v0, 1.0, v0
	v_fma_f32 v149, v8, v149, v8
	v_cvt_pk_bf16_f32 v164, v169, v170
	v_rcp_f32_e32 v169, v0
	v_mul_f32_e32 v0, 0x3d372713, v2
	v_mul_f32_e32 v149, 0x3f4c422a, v149
	v_mul_f32_e32 v0, v2, v0
	v_mul_f32_e32 v149, 0xc038aa3b, v149
	v_fma_f32 v0, v2, v0, v2
	v_exp_f32_e32 v149, v149
	v_mul_f32_e32 v0, 0x3f4c422a, v0
	v_mul_f32_e32 v0, 0xc038aa3b, v0
	v_add_f32_e32 v171, v148, v171
	v_exp_f32_e32 v0, v0
	v_add_f32_e32 v171, v166, v171
	v_add_f32_e32 v149, 1.0, v149
	v_add_f32_e32 v185, v167, v171
	v_rcp_f32_e32 v171, v149
	v_mul_f32_e32 v149, 0x3d372713, v4
	v_mul_f32_e32 v149, v4, v149
	v_add_f32_e32 v0, 1.0, v0
	v_fma_f32 v149, v4, v149, v4
	v_cvt_pk_bf16_f32 v166, v148, v166
	v_rcp_f32_e32 v148, v0
	v_mul_f32_e32 v0, 0x3d372713, v7
	v_mul_f32_e32 v149, 0x3f4c422a, v149
	v_mul_f32_e32 v168, 0x3d372713, v13
	v_mul_f32_e32 v0, v7, v0
	v_mul_f32_e32 v149, 0xc038aa3b, v149
	v_mul_f32_e32 v168, v13, v168
	v_fma_f32 v0, v7, v0, v7
	v_exp_f32_e32 v149, v149
	v_fma_f32 v168, v13, v168, v13
	v_mul_f32_e32 v0, 0x3f4c422a, v0
	v_mul_f32_e32 v168, 0x3f4c422a, v168
	v_mul_f32_e32 v0, 0xc038aa3b, v0
	v_mul_f32_e32 v168, 0xc038aa3b, v168
	v_exp_f32_e32 v0, v0
	v_exp_f32_e32 v168, v168
	v_add_f32_e32 v149, 1.0, v149
	v_mul_f32_e32 v172, 0x3d372713, v5
	v_rcp_f32_e32 v174, v149
	v_mul_f32_e32 v149, 0x3d372713, v9
	v_mul_f32_e32 v172, v5, v172
	v_mul_f32_e32 v149, v9, v149
	v_fma_f32 v172, v5, v172, v5
	v_add_f32_e32 v0, 1.0, v0
	v_fma_f32 v149, v9, v149, v9
	v_mul_f32_e32 v172, 0x3f4c422a, v172
	v_add_f32_e32 v168, 1.0, v168
	v_rcp_f32_e32 v170, v0
	v_mul_f32_e32 v0, 0x3d372713, v3
	v_mul_f32_e32 v149, 0x3f4c422a, v149
	v_mul_f32_e32 v172, 0xc038aa3b, v172
	v_rcp_f32_e32 v168, v168
	v_mul_f32_e32 v0, v3, v0
	v_mul_f32_e32 v149, 0xc038aa3b, v149
	v_exp_f32_e32 v172, v172
	v_fma_f32 v0, v3, v0, v3
	v_exp_f32_e32 v149, v149
	v_mul_f32_e32 v0, 0x3f4c422a, v0
	v_mul_f32_e32 v0, 0xc038aa3b, v0
	v_pk_mov_b32 v[176:177], v[12:13], v[6:7] op_sel:[1,0]
	v_exp_f32_e32 v0, v0
	v_add_f32_e32 v172, 1.0, v172
	v_pk_mul_f32 v[168:169], v[176:177], v[168:169]
	v_add_f32_e32 v149, 1.0, v149
	v_rcp_f32_e32 v175, v172
	v_add_f32_e32 v172, v168, v185
	v_pk_mul_f32 v[176:177], v[168:169], v[168:169]
	v_cvt_pk_bf16_f32 v167, v167, v168
	global_store_dwordx4 v[146:147], v[164:167], off
	v_rcp_f32_e32 v149, v149
	v_add_f32_e32 v176, v176, v186
	v_mov_b32_e32 v164, v7
	v_mov_b32_e32 v165, v8
	v_add_f32_e32 v166, v172, v169
	v_pk_mul_f32 v[164:165], v[164:165], v[170:171]
	v_add_f32_e32 v168, v176, v177
	v_add_f32_e32 v170, v164, v166
	v_pk_mul_f32 v[166:167], v[164:165], v[164:165]
	v_add_f32_e32 v0, 1.0, v0
	v_add_f32_e32 v166, v166, v168
	v_rcp_f32_e32 v0, v0
	v_add_f32_e32 v168, v165, v170
	v_add_f32_e32 v170, v167, v166
	v_mov_b32_e32 v166, v2
	v_mov_b32_e32 v167, v9
	v_pk_mul_f32 v[148:149], v[166:167], v[148:149]
	v_mul_f32_e32 v173, v3, v0
	v_pk_mul_f32 v[166:167], v[148:149], v[148:149]
	v_add_f32_e32 v168, v149, v168
	v_add_f32_e32 v167, v167, v170
	v_add_f32_e32 v168, v148, v168
	v_add_f32_e32 v167, v166, v167
	v_cvt_pk_bf16_f32 v165, v165, v149
	v_cvt_pk_bf16_f32 v166, v148, v173
	v_pk_mul_f32 v[148:149], v[4:5], v[174:175]
	v_fmac_f32_e32 v168, v3, v0
	v_mov_b32_e32 v172, v148
	v_cvt_pk_bf16_f32 v164, v169, v164
	v_pk_mul_f32 v[170:171], v[172:173], v[172:173]
	v_mov_b32_e32 v169, v149
	v_add_f32_e32 v0, v171, v167
	v_pk_fma_f32 v[168:169], v[4:5], v[174:175], v[168:169]
	v_pk_mul_f32 v[172:173], v[148:149], v[148:149]
	v_add_f32_e32 v171, v170, v0
	v_mov_b32_e32 v169, v173
	v_mov_b32_e32 v170, v149
	v_pk_add_f32 v[168:169], v[168:169], v[170:171]
	v_cvt_pk_bf16_f32 v167, v148, v149
	global_store_dwordx4 v[146:147], v[164:167], off offset:256
	ds_bpermute_b32 v146, v162, v168
	ds_bpermute_b32 v147, v162, v169
	s_waitcnt lgkmcnt(0)
	v_pk_add_f32 v[146:147], v[168:169], v[146:147]
	ds_bpermute_b32 v148, v163, v146
	ds_bpermute_b32 v149, v163, v147
	s_and_saveexec_b64 s[12:13], s[40:41]
	s_cbranch_execz .LBB0_329
	v_lshlrev_b64 v[144:145], 8, v[144:145]
	v_lshl_add_u64 v[144:145], s[48:49], 0, v[144:145]
	v_lshl_add_u64 v[144:145], s[30:31], 3, v[144:145]
	s_waitcnt lgkmcnt(0)
	v_pk_add_f32 v[146:147], v[146:147], v[148:149]
	s_waitcnt vmcnt(0)
	global_store_dwordx2 v[144:145], v[146:147], off

; __device__ __forceinline__ float gelu_silu_f(float u, float z) { const float t = 0.7978845608028654f * (u + 0.044715f * u * u * u); return u * z * frcp((1.f + fexp2(-2.885390081777927f * t)) * (1.f + fexp2(-1.4426950408889634f * z))); }
; __device__ __forceinline__ void st8(bf16_t* p, const float (&v)[8]) { u32x4 w; w.x = pk2(v[0], v[1]); w.y = pk2(v[2], v[3]); w.z = pk2(v[4], v[5]); w.w = pk2(v[6], v[7]); *(u32x4*)p = w; }
;     __device__ __forceinline__ void operator()(const f32x4 (&acc)[2][2][4][2], const Unit& u, int wr, int wc, int fr, int fq) const {
;     ...
;             const int colt = pn * 128 + wc * 32 + 8 * fq;
; #pragma unroll
;             for (int ai = 0; ai < 2; ++ai)
; #pragma unroll
;                 for (int m = 0; m < 4; ++m) { float o[8];
; #pragma unroll
;                     for (int j = 0; j < 4; ++j) { o[j] = gelu_silu_f(acc[ai][0][m][0][j], acc[ai][1][m][0][j]); o[4 + j] = gelu_silu_f(acc[ai][0][m][1][j], acc[ai][1][m][1][j]); }
;                     st8(uz + (size_t)(row0 + ai * 128 + m * 16) * DM + colt, o); }
.LBB0_331:
	s_and_b64 vcc, exec, s[12:13]
	s_cbranch_vccz .LBB0_330
	v_fma_f32 v0, v126, v161, v126
	v_mul_f32_e32 v0, 0x3f4c422a, v0
	v_mul_f32_e32 v0, 0xc038aa3b, v0
	v_exp_f32_e32 v146, v0
	v_mul_f32_e32 v0, 0xbfb8aa3b, v118
	v_exp_f32_e32 v147, v0
	v_mul_f32_e32 v126, v126, v118
	v_fma_f32 v118, v122, v160, v122
	v_mul_f32_e32 v118, 0x3f4c422a, v118
	v_pk_add_f32 v[146:147], v[146:147], 1.0 op_sel_hi:[1,0]
	v_mul_f32_e32 v122, v122, v114
	v_mul_f32_e32 v118, 0xc038aa3b, v118
	v_mul_f32_e32 v114, 0xbfb8aa3b, v114
	v_mul_f32_e32 v0, v146, v147
	v_exp_f32_e32 v146, v118
	v_exp_f32_e32 v147, v114
	v_rcp_f32_e32 v0, v0
	v_lshl_or_b32 v144, s89, 7, v152
	v_ashrrev_i32_e32 v145, 31, v144
	v_pk_add_f32 v[146:147], v[146:147], 1.0 op_sel_hi:[1,0]
	v_mul_f32_e32 v0, v126, v0
	v_mul_f32_e32 v114, v146, v147
	v_rcp_f32_e32 v114, v114
	v_mul_f32_e32 v126, v127, v119
	s_mov_b32 s2, 0x80000
	v_mul_f32_e32 v122, v122, v114
	v_fma_f32 v114, v127, v159, v127
	v_mul_f32_e32 v114, 0x3f4c422a, v114
	v_mul_f32_e32 v114, 0xc038aa3b, v114
	v_exp_f32_e32 v118, v114
	v_mul_f32_e32 v114, 0xbfb8aa3b, v119
	v_exp_f32_e32 v119, v114
	s_nop 0
	v_pk_add_f32 v[118:119], v[118:119], 1.0 op_sel_hi:[1,0]
	s_nop 0
	v_mul_f32_e32 v114, v118, v119
	v_rcp_f32_e32 v114, v114
	v_mul_f32_e32 v119, v123, v115
	v_mul_f32_e32 v115, 0xbfb8aa3b, v115
	v_exp_f32_e32 v115, v115
	v_mul_f32_e32 v118, v126, v114
	v_fma_f32 v114, v123, v158, v123
	v_mul_f32_e32 v114, 0x3f4c422a, v114
	v_mul_f32_e32 v114, 0xc038aa3b, v114
	v_exp_f32_e32 v114, v114
	v_cvt_pk_bf16_f32 v118, v0, v118
	v_mul_f32_e32 v0, 0x3d372713, v110
	v_mul_f32_e32 v0, v110, v0
	v_pk_add_f32 v[114:115], v[114:115], 1.0 op_sel_hi:[1,0]
	v_fma_f32 v0, v110, v0, v110
	v_mul_f32_e32 v114, v114, v115
	v_rcp_f32_e32 v114, v114
	v_mul_f32_e32 v115, 0xbfb8aa3b, v120
	v_exp_f32_e32 v115, v115
	v_mul_f32_e32 v0, 0x3f4c422a, v0
	v_mul_f32_e32 v123, v119, v114
	v_fma_f32 v114, v128, v157, v128
	v_mul_f32_e32 v114, 0x3f4c422a, v114
	v_mul_f32_e32 v114, 0xc038aa3b, v114
	v_exp_f32_e32 v114, v114
	v_mul_f32_e32 v119, v128, v120
	v_mul_f32_e32 v120, v124, v116
	v_mul_f32_e32 v0, 0xc038aa3b, v0
	v_pk_add_f32 v[114:115], v[114:115], 1.0 op_sel_hi:[1,0]
	v_mul_f32_e32 v110, v110, v102
	v_mul_f32_e32 v114, v114, v115
	v_rcp_f32_e32 v114, v114
	v_mul_f32_e32 v115, 0xbfb8aa3b, v116
	v_exp_f32_e32 v115, v115
	v_mul_f32_e32 v116, v129, v121
	v_mul_f32_e32 v119, v119, v114
	v_fma_f32 v114, v124, v156, v124
	v_mul_f32_e32 v114, 0x3f4c422a, v114
	v_mul_f32_e32 v114, 0xc038aa3b, v114
	v_exp_f32_e32 v114, v114
	s_nop 0
	v_pk_add_f32 v[114:115], v[114:115], 1.0 op_sel_hi:[1,0]
	s_nop 0
	v_mul_f32_e32 v114, v114, v115
	v_rcp_f32_e32 v114, v114
	v_mul_f32_e32 v115, 0xbfb8aa3b, v121
	v_exp_f32_e32 v115, v115
	v_mul_f32_e32 v124, v120, v114
	v_fma_f32 v114, v129, v155, v129
	v_mul_f32_e32 v114, 0x3f4c422a, v114
	v_mul_f32_e32 v114, 0xc038aa3b, v114
	v_exp_f32_e32 v114, v114
	s_nop 0
	v_pk_add_f32 v[114:115], v[114:115], 1.0 op_sel_hi:[1,0]
	s_nop 0
	v_mul_f32_e32 v114, v114, v115
	v_rcp_f32_e32 v114, v114
	v_mul_f32_e32 v115, 0xbfb8aa3b, v117
	v_exp_f32_e32 v115, v115
	v_mul_f32_e32 v120, v116, v114
	v_fma_f32 v114, v125, v154, v125
	v_mul_f32_e32 v114, 0x3f4c422a, v114
	v_mul_f32_e32 v114, 0xc038aa3b, v114
	v_exp_f32_e32 v114, v114
	v_mul_f32_e32 v116, v125, v117
	v_cvt_pk_bf16_f32 v119, v119, v120
	v_cvt_pk_bf16_f32 v120, v122, v123
	v_pk_add_f32 v[114:115], v[114:115], 1.0 op_sel_hi:[1,0]
	s_nop 0
	v_mul_f32_e32 v114, v114, v115
	v_rcp_f32_e32 v114, v114
	s_nop 0
	v_mul_f32_e32 v121, v116, v114
	v_lshlrev_b64 v[114:115], 12, v[142:143]
	v_lshl_add_u64 v[114:115], s[44:45], 0, v[114:115]
	v_lshlrev_b64 v[116:117], 1, v[144:145]
	v_lshl_add_u64 v[114:115], v[114:115], 0, v[116:117]
	v_cvt_pk_bf16_f32 v121, v124, v121
	global_store_dwordx4 v[114:115], v[118:121], off
	s_nop 1
	v_exp_f32_e32 v118, v0
	v_mul_f32_e32 v0, 0xbfb8aa3b, v102
	v_exp_f32_e32 v119, v0
	v_mul_f32_e32 v102, 0x3d372713, v106
	v_mul_f32_e32 v102, v106, v102
	v_fma_f32 v102, v106, v102, v106
	v_mul_f32_e32 v102, 0x3f4c422a, v102
	v_pk_add_f32 v[118:119], v[118:119], 1.0 op_sel_hi:[1,0]
	v_mul_f32_e32 v106, v106, v98
	v_mul_f32_e32 v102, 0xc038aa3b, v102
	v_mul_f32_e32 v98, 0xbfb8aa3b, v98
	v_mul_f32_e32 v0, v118, v119
	v_exp_f32_e32 v118, v102
	v_exp_f32_e32 v119, v98
	v_rcp_f32_e32 v0, v0
	v_pk_add_f32 v[118:119], v[118:119], 1.0 op_sel_hi:[1,0]
	s_nop 0
	v_mul_f32_e32 v98, v118, v119
	v_rcp_f32_e32 v98, v98
	v_mul_f32_e32 v0, v110, v0
	v_mul_f32_e32 v110, v111, v103
	v_mul_f32_e32 v106, v106, v98
	v_mul_f32_e32 v98, 0x3d372713, v111
	v_mul_f32_e32 v98, v111, v98
	v_fma_f32 v98, v111, v98, v111
	v_mul_f32_e32 v98, 0x3f4c422a, v98
	v_mul_f32_e32 v98, 0xc038aa3b, v98
	v_exp_f32_e32 v102, v98
	v_mul_f32_e32 v98, 0xbfb8aa3b, v103
	v_exp_f32_e32 v103, v98
	s_nop 0
	v_pk_add_f32 v[102:103], v[102:103], 1.0 op_sel_hi:[1,0]
	s_nop 0
	v_mul_f32_e32 v98, v102, v103
	v_rcp_f32_e32 v98, v98
	v_mul_f32_e32 v102, v107, v99
	v_mul_f32_e32 v99, 0xbfb8aa3b, v99
	v_exp_f32_e32 v99, v99
	v_mul_f32_e32 v110, v110, v98
	v_mul_f32_e32 v98, 0x3d372713, v107
	v_mul_f32_e32 v98, v107, v98
	v_fma_f32 v98, v107, v98, v107
	v_mul_f32_e32 v98, 0x3f4c422a, v98
	v_mul_f32_e32 v98, 0xc038aa3b, v98
	v_exp_f32_e32 v98, v98
	s_nop 0
	v_pk_add_f32 v[98:99], v[98:99], 1.0 op_sel_hi:[1,0]
	s_nop 0
	v_mul_f32_e32 v98, v98, v99
	v_rcp_f32_e32 v98, v98
	v_mul_f32_e32 v99, 0xbfb8aa3b, v104
	v_exp_f32_e32 v99, v99
	v_mul_f32_e32 v107, v102, v98
	v_mul_f32_e32 v98, 0x3d372713, v112
	v_mul_f32_e32 v98, v112, v98
	v_fma_f32 v98, v112, v98, v112
	v_mul_f32_e32 v98, 0x3f4c422a, v98
	v_mul_f32_e32 v98, 0xc038aa3b, v98
; __device__ __forceinline__ float gelu_silu_f(float u, float z) { const float t = 0.7978845608028654f * (u + 0.044715f * u * u * u); return u * z * frcp((1.f + fexp2(-2.885390081777927f * t)) * (1.f + fexp2(-1.4426950408889634f * z))); }
; __device__ __forceinline__ void st8(bf16_t* p, const float (&v)[8]) { u32x4 w; w.x = pk2(v[0], v[1]); w.y = pk2(v[2], v[3]); w.z = pk2(v[4], v[5]); w.w = pk2(v[6], v[7]); *(u32x4*)p = w; }
;     __device__ __forceinline__ void operator()(const f32x4 (&acc)[2][2][4][2], const Unit& u, int wr, int wc, int fr, int fq) const {
;     ...
;             const int colt = pn * 128 + wc * 32 + 8 * fq;
; #pragma unroll
;             for (int ai = 0; ai < 2; ++ai)
; #pragma unroll
;                 for (int m = 0; m < 4; ++m) { float o[8];
; #pragma unroll
;                     for (int j = 0; j < 4; ++j) { o[j] = gelu_silu_f(acc[ai][0][m][0][j], acc[ai][1][m][0][j]); o[4 + j] = gelu_silu_f(acc[ai][0][m][1][j], acc[ai][1][m][1][j]); }
;                     st8(uz + (size_t)(row0 + ai * 128 + m * 16) * DM + colt, o); }
	v_exp_f32_e32 v98, v98
	v_mul_f32_e32 v102, v112, v104
	v_pk_add_f32 v[98:99], v[98:99], 1.0 op_sel_hi:[1,0]
	s_nop 0
	v_mul_f32_e32 v98, v98, v99
	v_rcp_f32_e32 v98, v98
	v_mul_f32_e32 v99, 0xbfb8aa3b, v100
	v_exp_f32_e32 v99, v99
	v_mul_f32_e32 v104, v102, v98
	v_mul_f32_e32 v98, 0x3d372713, v108
	v_mul_f32_e32 v98, v108, v98
	v_fma_f32 v98, v108, v98, v108
	v_mul_f32_e32 v98, 0x3f4c422a, v98
	v_mul_f32_e32 v98, 0xc038aa3b, v98
	v_exp_f32_e32 v98, v98
	v_mul_f32_e32 v102, v108, v100
	v_mul_f32_e32 v100, v113, v105
	v_pk_add_f32 v[98:99], v[98:99], 1.0 op_sel_hi:[1,0]
	s_nop 0
	v_mul_f32_e32 v98, v98, v99
	v_rcp_f32_e32 v98, v98
	v_mul_f32_e32 v99, 0xbfb8aa3b, v105
	v_exp_f32_e32 v99, v99
	v_mul_f32_e32 v108, v102, v98
	v_mul_f32_e32 v98, 0x3d372713, v113
	v_mul_f32_e32 v98, v113, v98
	v_fma_f32 v98, v113, v98, v113
	v_mul_f32_e32 v98, 0x3f4c422a, v98
	v_mul_f32_e32 v98, 0xc038aa3b, v98
	v_exp_f32_e32 v98, v98
	v_mul_f32_e32 v102, v109, v101
	v_pk_add_f32 v[98:99], v[98:99], 1.0 op_sel_hi:[1,0]
	s_nop 0
	v_mul_f32_e32 v98, v98, v99
	v_rcp_f32_e32 v98, v98
	v_mul_f32_e32 v99, 0xbfb8aa3b, v101
	v_exp_f32_e32 v99, v99
	v_mul_f32_e32 v100, v100, v98
	v_mul_f32_e32 v98, 0x3d372713, v109
	v_mul_f32_e32 v98, v109, v98
	v_fma_f32 v98, v109, v98, v109
	v_mul_f32_e32 v98, 0x3f4c422a, v98
	v_mul_f32_e32 v98, 0xc038aa3b, v98
	v_exp_f32_e32 v98, v98
	s_nop 0
	v_pk_add_f32 v[98:99], v[98:99], 1.0 op_sel_hi:[1,0]
	s_nop 0
	v_mul_f32_e32 v98, v98, v99
	v_rcp_f32_e32 v98, v98
	s_nop 0
	v_mul_f32_e32 v101, v102, v98
	v_or_b32_e32 v98, 16, v142
	v_ashrrev_i32_e32 v99, 31, v98
	v_lshlrev_b64 v[98:99], 12, v[98:99]
	v_lshl_add_u64 v[98:99], s[44:45], 0, v[98:99]
	v_lshl_add_u64 v[102:103], v[98:99], 0, v[116:117]
	v_cvt_pk_bf16_f32 v98, v0, v110
	v_mul_f32_e32 v0, 0x3d372713, v94
	v_mul_f32_e32 v0, v94, v0
	v_fma_f32 v0, v94, v0, v94
	v_mul_f32_e32 v0, 0x3f4c422a, v0
	v_mul_f32_e32 v0, 0xc038aa3b, v0
	v_cvt_pk_bf16_f32 v99, v104, v100
	v_cvt_pk_bf16_f32 v100, v106, v107
	v_cvt_pk_bf16_f32 v101, v108, v101
	global_store_dwordx4 v[102:103], v[98:101], off
	v_mul_f32_e32 v94, v94, v86
	s_nop 0
	v_exp_f32_e32 v98, v0
	v_mul_f32_e32 v0, 0xbfb8aa3b, v86
	v_exp_f32_e32 v99, v0
	v_mul_f32_e32 v86, 0x3d372713, v90
	v_mul_f32_e32 v86, v90, v86
	v_fma_f32 v86, v90, v86, v90
	v_mul_f32_e32 v86, 0x3f4c422a, v86
	v_pk_add_f32 v[98:99], v[98:99], 1.0 op_sel_hi:[1,0]
	v_mul_f32_e32 v90, v90, v82
	v_mul_f32_e32 v86, 0xc038aa3b, v86
	v_mul_f32_e32 v82, 0xbfb8aa3b, v82
	v_mul_f32_e32 v0, v98, v99
	v_exp_f32_e32 v98, v86
	v_exp_f32_e32 v99, v82
	v_rcp_f32_e32 v0, v0
	v_pk_add_f32 v[98:99], v[98:99], 1.0 op_sel_hi:[1,0]
	s_nop 0
	v_mul_f32_e32 v82, v98, v99
	v_rcp_f32_e32 v82, v82
	v_mul_f32_e32 v0, v94, v0
	v_mul_f32_e32 v94, v95, v87
	v_mul_f32_e32 v90, v90, v82
	v_mul_f32_e32 v82, 0x3d372713, v95
	v_mul_f32_e32 v82, v95, v82
	v_fma_f32 v82, v95, v82, v95
	v_mul_f32_e32 v82, 0x3f4c422a, v82
	v_mul_f32_e32 v82, 0xc038aa3b, v82
	v_exp_f32_e32 v86, v82
	v_mul_f32_e32 v82, 0xbfb8aa3b, v87
	v_exp_f32_e32 v87, v82
	s_nop 0
	v_pk_add_f32 v[86:87], v[86:87], 1.0 op_sel_hi:[1,0]
	s_nop 0
	v_mul_f32_e32 v82, v86, v87
	v_rcp_f32_e32 v82, v82
	v_mul_f32_e32 v86, v91, v83
	v_mul_f32_e32 v83, 0xbfb8aa3b, v83
	v_exp_f32_e32 v83, v83
	v_mul_f32_e32 v94, v94, v82
	v_mul_f32_e32 v82, 0x3d372713, v91
	v_mul_f32_e32 v82, v91, v82
	v_fma_f32 v82, v91, v82, v91
	v_mul_f32_e32 v82, 0x3f4c422a, v82
	v_mul_f32_e32 v82, 0xc038aa3b, v82
	v_exp_f32_e32 v82, v82
	s_nop 0
	v_pk_add_f32 v[82:83], v[82:83], 1.0 op_sel_hi:[1,0]
	s_nop 0
	v_mul_f32_e32 v82, v82, v83
	v_rcp_f32_e32 v82, v82
	v_mul_f32_e32 v83, 0xbfb8aa3b, v88
	v_exp_f32_e32 v83, v83
	v_mul_f32_e32 v91, v86, v82
	v_mul_f32_e32 v82, 0x3d372713, v96
	v_mul_f32_e32 v82, v96, v82
	v_fma_f32 v82, v96, v82, v96
	v_mul_f32_e32 v82, 0x3f4c422a, v82
	v_mul_f32_e32 v82, 0xc038aa3b, v82
	v_exp_f32_e32 v82, v82
	v_mul_f32_e32 v86, v96, v88
	v_pk_add_f32 v[82:83], v[82:83], 1.0 op_sel_hi:[1,0]
	s_nop 0
	v_mul_f32_e32 v82, v82, v83
	v_rcp_f32_e32 v82, v82
	v_mul_f32_e32 v83, 0xbfb8aa3b, v84
	v_exp_f32_e32 v83, v83
	v_mul_f32_e32 v88, v86, v82
	v_mul_f32_e32 v82, 0x3d372713, v92
	v_mul_f32_e32 v82, v92, v82
	v_fma_f32 v82, v92, v82, v92
	v_mul_f32_e32 v82, 0x3f4c422a, v82
	v_mul_f32_e32 v82, 0xc038aa3b, v82
	v_exp_f32_e32 v82, v82
	v_mul_f32_e32 v86, v92, v84
	v_mul_f32_e32 v84, v97, v89
	v_pk_add_f32 v[82:83], v[82:83], 1.0 op_sel_hi:[1,0]
	s_nop 0
	v_mul_f32_e32 v82, v82, v83
	v_rcp_f32_e32 v82, v82
	v_mul_f32_e32 v83, 0xbfb8aa3b, v89
	v_exp_f32_e32 v83, v83
	v_mul_f32_e32 v92, v86, v82
	v_mul_f32_e32 v82, 0x3d372713, v97
	v_mul_f32_e32 v82, v97, v82
	v_fma_f32 v82, v97, v82, v97
	v_mul_f32_e32 v82, 0x3f4c422a, v82
	v_mul_f32_e32 v82, 0xc038aa3b, v82
	v_exp_f32_e32 v82, v82
	v_mul_f32_e32 v86, v93, v85
	v_pk_add_f32 v[82:83], v[82:83], 1.0 op_sel_hi:[1,0]
	s_nop 0
	v_mul_f32_e32 v82, v82, v83
	v_rcp_f32_e32 v82, v82
	v_mul_f32_e32 v83, 0xbfb8aa3b, v85
	v_exp_f32_e32 v83, v83
	v_mul_f32_e32 v84, v84, v82
	v_mul_f32_e32 v82, 0x3d372713, v93
	v_mul_f32_e32 v82, v93, v82
	v_fma_f32 v82, v93, v82, v93
	v_mul_f32_e32 v82, 0x3f4c422a, v82
	v_mul_f32_e32 v82, 0xc038aa3b, v82
	v_exp_f32_e32 v82, v82
	s_nop 0
	v_pk_add_f32 v[82:83], v[82:83], 1.0 op_sel_hi:[1,0]
	s_nop 0
	v_mul_f32_e32 v82, v82, v83
	v_rcp_f32_e32 v82, v82
	s_nop 0
	v_mul_f32_e32 v85, v86, v82
	v_or_b32_e32 v82, 32, v142
	v_ashrrev_i32_e32 v83, 31, v82
	v_lshlrev_b64 v[82:83], 12, v[82:83]
	v_lshl_add_u64 v[82:83], s[44:45], 0, v[82:83]
	v_lshl_add_u64 v[86:87], v[82:83], 0, v[116:117]
	v_cvt_pk_bf16_f32 v82, v0, v94
	v_mul_f32_e32 v0, 0x3d372713, v78
	v_mul_f32_e32 v0, v78, v0
	v_fma_f32 v0, v78, v0, v78
; __device__ __forceinline__ float gelu_silu_f(float u, float z) { const float t = 0.7978845608028654f * (u + 0.044715f * u * u * u); return u * z * frcp((1.f + fexp2(-2.885390081777927f * t)) * (1.f + fexp2(-1.4426950408889634f * z))); }
; __device__ __forceinline__ void st8(bf16_t* p, const float (&v)[8]) { u32x4 w; w.x = pk2(v[0], v[1]); w.y = pk2(v[2], v[3]); w.z = pk2(v[4], v[5]); w.w = pk2(v[6], v[7]); *(u32x4*)p = w; }
;     __device__ __forceinline__ void operator()(const f32x4 (&acc)[2][2][4][2], const Unit& u, int wr, int wc, int fr, int fq) const {
;     ...
;             const int colt = pn * 128 + wc * 32 + 8 * fq;
; #pragma unroll
;             for (int ai = 0; ai < 2; ++ai)
; #pragma unroll
;                 for (int m = 0; m < 4; ++m) { float o[8];
; #pragma unroll
;                     for (int j = 0; j < 4; ++j) { o[j] = gelu_silu_f(acc[ai][0][m][0][j], acc[ai][1][m][0][j]); o[4 + j] = gelu_silu_f(acc[ai][0][m][1][j], acc[ai][1][m][1][j]); }
;                     st8(uz + (size_t)(row0 + ai * 128 + m * 16) * DM + colt, o); }
	v_mul_f32_e32 v0, 0x3f4c422a, v0
	v_mul_f32_e32 v0, 0xc038aa3b, v0
	v_cvt_pk_bf16_f32 v83, v88, v84
	v_cvt_pk_bf16_f32 v84, v90, v91
	v_cvt_pk_bf16_f32 v85, v92, v85
	global_store_dwordx4 v[86:87], v[82:85], off
	v_mul_f32_e32 v78, v78, v70
	s_nop 0
	v_exp_f32_e32 v82, v0
	v_mul_f32_e32 v0, 0xbfb8aa3b, v70
	v_exp_f32_e32 v83, v0
	v_mul_f32_e32 v70, 0x3d372713, v74
	v_mul_f32_e32 v70, v74, v70
	v_fma_f32 v70, v74, v70, v74
	v_mul_f32_e32 v70, 0x3f4c422a, v70
	v_pk_add_f32 v[82:83], v[82:83], 1.0 op_sel_hi:[1,0]
	v_mul_f32_e32 v74, v74, v66
	v_mul_f32_e32 v70, 0xc038aa3b, v70
	v_mul_f32_e32 v66, 0xbfb8aa3b, v66
	v_mul_f32_e32 v0, v82, v83
	v_exp_f32_e32 v82, v70
	v_exp_f32_e32 v83, v66
	v_rcp_f32_e32 v0, v0
	v_pk_add_f32 v[82:83], v[82:83], 1.0 op_sel_hi:[1,0]
	s_nop 0
	v_mul_f32_e32 v66, v82, v83
	v_rcp_f32_e32 v66, v66
	v_mul_f32_e32 v0, v78, v0
	v_mul_f32_e32 v78, v79, v71
	v_mul_f32_e32 v74, v74, v66
	v_mul_f32_e32 v66, 0x3d372713, v79
	v_mul_f32_e32 v66, v79, v66
	v_fma_f32 v66, v79, v66, v79
	v_mul_f32_e32 v66, 0x3f4c422a, v66
	v_mul_f32_e32 v66, 0xc038aa3b, v66
	v_exp_f32_e32 v70, v66
	v_mul_f32_e32 v66, 0xbfb8aa3b, v71
	v_exp_f32_e32 v71, v66
	s_nop 0
	v_pk_add_f32 v[70:71], v[70:71], 1.0 op_sel_hi:[1,0]
	s_nop 0
	v_mul_f32_e32 v66, v70, v71
	v_rcp_f32_e32 v66, v66
	v_mul_f32_e32 v70, v75, v67
	v_mul_f32_e32 v67, 0xbfb8aa3b, v67
	v_exp_f32_e32 v67, v67
	v_mul_f32_e32 v78, v78, v66
	v_mul_f32_e32 v66, 0x3d372713, v75
	v_mul_f32_e32 v66, v75, v66
	v_fma_f32 v66, v75, v66, v75
	v_mul_f32_e32 v66, 0x3f4c422a, v66
	v_mul_f32_e32 v66, 0xc038aa3b, v66
	v_exp_f32_e32 v66, v66
	s_nop 0
	v_pk_add_f32 v[66:67], v[66:67], 1.0 op_sel_hi:[1,0]
	s_nop 0
	v_mul_f32_e32 v66, v66, v67
	v_rcp_f32_e32 v66, v66
	v_mul_f32_e32 v67, 0xbfb8aa3b, v72
	v_exp_f32_e32 v67, v67
	v_mul_f32_e32 v75, v70, v66
	v_mul_f32_e32 v66, 0x3d372713, v80
	v_mul_f32_e32 v66, v80, v66
	v_fma_f32 v66, v80, v66, v80
	v_mul_f32_e32 v66, 0x3f4c422a, v66
	v_mul_f32_e32 v66, 0xc038aa3b, v66
	v_exp_f32_e32 v66, v66
	v_mul_f32_e32 v70, v80, v72
	v_pk_add_f32 v[66:67], v[66:67], 1.0 op_sel_hi:[1,0]
	s_nop 0
	v_mul_f32_e32 v66, v66, v67
	v_rcp_f32_e32 v66, v66
	v_mul_f32_e32 v67, 0xbfb8aa3b, v68
	v_exp_f32_e32 v67, v67
	v_mul_f32_e32 v72, v70, v66
	v_mul_f32_e32 v66, 0x3d372713, v76
	v_mul_f32_e32 v66, v76, v66
	v_fma_f32 v66, v76, v66, v76
	v_mul_f32_e32 v66, 0x3f4c422a, v66
	v_mul_f32_e32 v66, 0xc038aa3b, v66
	v_exp_f32_e32 v66, v66
	v_mul_f32_e32 v70, v76, v68
	v_mul_f32_e32 v68, v81, v73
	v_pk_add_f32 v[66:67], v[66:67], 1.0 op_sel_hi:[1,0]
	s_nop 0
	v_mul_f32_e32 v66, v66, v67
	v_rcp_f32_e32 v66, v66
	v_mul_f32_e32 v67, 0xbfb8aa3b, v73
	v_exp_f32_e32 v67, v67
	v_mul_f32_e32 v76, v70, v66
	v_mul_f32_e32 v66, 0x3d372713, v81
	v_mul_f32_e32 v66, v81, v66
	v_fma_f32 v66, v81, v66, v81
	v_mul_f32_e32 v66, 0x3f4c422a, v66
	v_mul_f32_e32 v66, 0xc038aa3b, v66
	v_exp_f32_e32 v66, v66
	v_mul_f32_e32 v70, v77, v69
	v_pk_add_f32 v[66:67], v[66:67], 1.0 op_sel_hi:[1,0]
	s_nop 0
	v_mul_f32_e32 v66, v66, v67
	v_rcp_f32_e32 v66, v66
	v_mul_f32_e32 v67, 0xbfb8aa3b, v69
	v_exp_f32_e32 v67, v67
	v_mul_f32_e32 v68, v68, v66
	v_mul_f32_e32 v66, 0x3d372713, v77
	v_mul_f32_e32 v66, v77, v66
	v_fma_f32 v66, v77, v66, v77
	v_mul_f32_e32 v66, 0x3f4c422a, v66
	v_mul_f32_e32 v66, 0xc038aa3b, v66
	v_exp_f32_e32 v66, v66
	s_nop 0
	v_pk_add_f32 v[66:67], v[66:67], 1.0 op_sel_hi:[1,0]
	s_nop 0
	v_mul_f32_e32 v66, v66, v67
	v_rcp_f32_e32 v66, v66
	s_nop 0
	v_mul_f32_e32 v69, v70, v66
	v_or_b32_e32 v66, 48, v142
	v_ashrrev_i32_e32 v67, 31, v66
	v_lshlrev_b64 v[66:67], 12, v[66:67]
	v_lshl_add_u64 v[66:67], s[44:45], 0, v[66:67]
	v_lshl_add_u64 v[70:71], v[66:67], 0, v[116:117]
	v_cvt_pk_bf16_f32 v66, v0, v78
	v_mul_f32_e32 v0, 0x3d372713, v62
	v_mul_f32_e32 v0, v62, v0
	v_fma_f32 v0, v62, v0, v62
	v_mul_f32_e32 v0, 0x3f4c422a, v0
	v_mul_f32_e32 v0, 0xc038aa3b, v0
	v_cvt_pk_bf16_f32 v67, v72, v68
	v_cvt_pk_bf16_f32 v68, v74, v75
	v_cvt_pk_bf16_f32 v69, v76, v69
	global_store_dwordx4 v[70:71], v[66:69], off
	v_mul_f32_e32 v62, v62, v54
	s_nop 0
	v_exp_f32_e32 v66, v0
	v_mul_f32_e32 v0, 0xbfb8aa3b, v54
	v_exp_f32_e32 v67, v0
	v_mul_f32_e32 v54, 0x3d372713, v58
	v_mul_f32_e32 v54, v58, v54
	v_fma_f32 v54, v58, v54, v58
	v_mul_f32_e32 v54, 0x3f4c422a, v54
	v_pk_add_f32 v[66:67], v[66:67], 1.0 op_sel_hi:[1,0]
	v_mul_f32_e32 v58, v58, v50
	v_mul_f32_e32 v54, 0xc038aa3b, v54
	v_mul_f32_e32 v50, 0xbfb8aa3b, v50
	v_mul_f32_e32 v0, v66, v67
	v_exp_f32_e32 v66, v54
	v_exp_f32_e32 v67, v50
	v_rcp_f32_e32 v0, v0
	v_pk_add_f32 v[66:67], v[66:67], 1.0 op_sel_hi:[1,0]
	s_nop 0
	v_mul_f32_e32 v50, v66, v67
	v_rcp_f32_e32 v50, v50
	v_mul_f32_e32 v0, v62, v0
	v_mul_f32_e32 v62, v63, v55
	v_mul_f32_e32 v58, v58, v50
	v_mul_f32_e32 v50, 0x3d372713, v63
	v_mul_f32_e32 v50, v63, v50
	v_fma_f32 v50, v63, v50, v63
	v_mul_f32_e32 v50, 0x3f4c422a, v50
	v_mul_f32_e32 v50, 0xc038aa3b, v50
	v_exp_f32_e32 v54, v50
	v_mul_f32_e32 v50, 0xbfb8aa3b, v55
	v_exp_f32_e32 v55, v50
	s_nop 0
	v_pk_add_f32 v[54:55], v[54:55], 1.0 op_sel_hi:[1,0]
	s_nop 0
	v_mul_f32_e32 v50, v54, v55
	v_rcp_f32_e32 v50, v50
	v_mul_f32_e32 v55, v59, v51
	v_mul_f32_e32 v51, 0xbfb8aa3b, v51
	v_exp_f32_e32 v51, v51
	v_mul_f32_e32 v54, v62, v50
	v_mul_f32_e32 v50, 0x3d372713, v59
	v_mul_f32_e32 v50, v59, v50
	v_fma_f32 v50, v59, v50, v59
	v_mul_f32_e32 v50, 0x3f4c422a, v50
	v_mul_f32_e32 v50, 0xc038aa3b, v50
	v_exp_f32_e32 v50, v50
	v_mul_f32_e32 v59, v64, v56
	v_pk_add_f32 v[50:51], v[50:51], 1.0 op_sel_hi:[1,0]
	s_nop 0
	v_mul_f32_e32 v50, v50, v51
	v_rcp_f32_e32 v50, v50
	v_mul_f32_e32 v51, 0xbfb8aa3b, v56
	v_exp_f32_e32 v51, v51
	v_mul_f32_e32 v55, v55, v50
; __device__ __forceinline__ float gelu_silu_f(float u, float z) { const float t = 0.7978845608028654f * (u + 0.044715f * u * u * u); return u * z * frcp((1.f + fexp2(-2.885390081777927f * t)) * (1.f + fexp2(-1.4426950408889634f * z))); }
; __device__ __forceinline__ void st8(bf16_t* p, const float (&v)[8]) { u32x4 w; w.x = pk2(v[0], v[1]); w.y = pk2(v[2], v[3]); w.z = pk2(v[4], v[5]); w.w = pk2(v[6], v[7]); *(u32x4*)p = w; }
;     __device__ __forceinline__ void operator()(const f32x4 (&acc)[2][2][4][2], const Unit& u, int wr, int wc, int fr, int fq) const {
;     ...
;             const int colt = pn * 128 + wc * 32 + 8 * fq;
; #pragma unroll
;             for (int ai = 0; ai < 2; ++ai)
; #pragma unroll
;                 for (int m = 0; m < 4; ++m) { float o[8];
; #pragma unroll
;                     for (int j = 0; j < 4; ++j) { o[j] = gelu_silu_f(acc[ai][0][m][0][j], acc[ai][1][m][0][j]); o[4 + j] = gelu_silu_f(acc[ai][0][m][1][j], acc[ai][1][m][1][j]); }
;                     st8(uz + (size_t)(row0 + ai * 128 + m * 16) * DM + colt, o); }
	v_mul_f32_e32 v50, 0x3d372713, v64
	v_mul_f32_e32 v50, v64, v50
	v_fma_f32 v50, v64, v50, v64
	v_mul_f32_e32 v50, 0x3f4c422a, v50
	v_mul_f32_e32 v50, 0xc038aa3b, v50
	v_exp_f32_e32 v50, v50
	s_nop 0
	v_pk_add_f32 v[50:51], v[50:51], 1.0 op_sel_hi:[1,0]
	s_nop 0
	v_mul_f32_e32 v50, v50, v51
	v_rcp_f32_e32 v50, v50
	v_mul_f32_e32 v51, 0xbfb8aa3b, v52
	v_exp_f32_e32 v51, v51
	v_mul_f32_e32 v56, v59, v50
	v_mul_f32_e32 v50, 0x3d372713, v60
	v_mul_f32_e32 v50, v60, v50
	v_fma_f32 v50, v60, v50, v60
	v_mul_f32_e32 v50, 0x3f4c422a, v50
	v_mul_f32_e32 v50, 0xc038aa3b, v50
	v_exp_f32_e32 v50, v50
	v_mul_f32_e32 v59, v60, v52
	v_mul_f32_e32 v52, v65, v57
	v_pk_add_f32 v[50:51], v[50:51], 1.0 op_sel_hi:[1,0]
	s_nop 0
	v_mul_f32_e32 v50, v50, v51
	v_rcp_f32_e32 v50, v50
	v_mul_f32_e32 v51, 0xbfb8aa3b, v57
	v_exp_f32_e32 v51, v51
	v_mul_f32_e32 v57, v61, v53
	v_mul_f32_e32 v59, v59, v50
	v_mul_f32_e32 v50, 0x3d372713, v65
	v_mul_f32_e32 v50, v65, v50
	v_fma_f32 v50, v65, v50, v65
	v_mul_f32_e32 v50, 0x3f4c422a, v50
	v_mul_f32_e32 v50, 0xc038aa3b, v50
	v_exp_f32_e32 v50, v50
	s_nop 0
	v_pk_add_f32 v[50:51], v[50:51], 1.0 op_sel_hi:[1,0]
	s_nop 0
	v_mul_f32_e32 v50, v50, v51
	v_rcp_f32_e32 v50, v50
	v_mul_f32_e32 v51, 0xbfb8aa3b, v53
	v_exp_f32_e32 v51, v51
	v_mul_f32_e32 v52, v52, v50
	v_mul_f32_e32 v50, 0x3d372713, v61
	v_mul_f32_e32 v50, v61, v50
	v_fma_f32 v50, v61, v50, v61
	v_mul_f32_e32 v50, 0x3f4c422a, v50
	v_mul_f32_e32 v50, 0xc038aa3b, v50
	v_exp_f32_e32 v50, v50
	s_nop 0
	v_pk_add_f32 v[50:51], v[50:51], 1.0 op_sel_hi:[1,0]
	s_nop 0
	v_mul_f32_e32 v50, v50, v51
	v_rcp_f32_e32 v50, v50
	v_cvt_pk_bf16_f32 v51, v56, v52
	v_cvt_pk_bf16_f32 v52, v58, v55
	s_nop 0
	v_mul_f32_e32 v53, v57, v50
	v_cvt_pk_bf16_f32 v50, v0, v54
	v_mul_f32_e32 v0, 0x3d372713, v46
	v_mul_f32_e32 v0, v46, v0
	v_fma_f32 v0, v46, v0, v46
	v_add_co_u32_e32 v54, vcc, s2, v114
	v_mul_f32_e32 v0, 0x3f4c422a, v0
	s_nop 0
	v_addc_co_u32_e32 v55, vcc, 0, v115, vcc
	v_mul_f32_e32 v0, 0xc038aa3b, v0
	v_cvt_pk_bf16_f32 v53, v59, v53
	global_store_dwordx4 v[54:55], v[50:53], off
	v_mul_f32_e32 v46, v46, v38
	s_mov_b32 s2, 0xa0000
	v_exp_f32_e32 v50, v0
	v_mul_f32_e32 v0, 0xbfb8aa3b, v38
	v_exp_f32_e32 v51, v0
	v_mul_f32_e32 v38, 0x3d372713, v42
	v_mul_f32_e32 v38, v42, v38
	v_fma_f32 v38, v42, v38, v42
	v_mul_f32_e32 v38, 0x3f4c422a, v38
	v_pk_add_f32 v[50:51], v[50:51], 1.0 op_sel_hi:[1,0]
	v_mul_f32_e32 v42, v42, v34
	v_mul_f32_e32 v38, 0xc038aa3b, v38
	v_mul_f32_e32 v34, 0xbfb8aa3b, v34
	v_mul_f32_e32 v0, v50, v51
	v_exp_f32_e32 v50, v38
	v_exp_f32_e32 v51, v34
	v_rcp_f32_e32 v0, v0
	v_pk_add_f32 v[50:51], v[50:51], 1.0 op_sel_hi:[1,0]
	s_nop 0
	v_mul_f32_e32 v34, v50, v51
	v_rcp_f32_e32 v34, v34
	v_mul_f32_e32 v0, v46, v0
	v_mul_f32_e32 v46, v47, v39
	v_mul_f32_e32 v42, v42, v34
	v_mul_f32_e32 v34, 0x3d372713, v47
	v_mul_f32_e32 v34, v47, v34
	v_fma_f32 v34, v47, v34, v47
	v_mul_f32_e32 v34, 0x3f4c422a, v34
	v_mul_f32_e32 v34, 0xc038aa3b, v34
	v_exp_f32_e32 v38, v34
	v_mul_f32_e32 v34, 0xbfb8aa3b, v39
	v_exp_f32_e32 v39, v34
	s_nop 0
	v_pk_add_f32 v[38:39], v[38:39], 1.0 op_sel_hi:[1,0]
	s_nop 0
	v_mul_f32_e32 v34, v38, v39
	v_rcp_f32_e32 v34, v34
	v_mul_f32_e32 v39, v43, v35
	v_mul_f32_e32 v35, 0xbfb8aa3b, v35
	v_exp_f32_e32 v35, v35
	v_mul_f32_e32 v38, v46, v34
	v_mul_f32_e32 v34, 0x3d372713, v43
	v_mul_f32_e32 v34, v43, v34
	v_fma_f32 v34, v43, v34, v43
	v_mul_f32_e32 v34, 0x3f4c422a, v34
	v_mul_f32_e32 v34, 0xc038aa3b, v34
	v_exp_f32_e32 v34, v34
	v_mul_f32_e32 v43, v48, v40
	v_pk_add_f32 v[34:35], v[34:35], 1.0 op_sel_hi:[1,0]
	s_nop 0
	v_mul_f32_e32 v34, v34, v35
	v_rcp_f32_e32 v34, v34
	v_mul_f32_e32 v35, 0xbfb8aa3b, v40
	v_exp_f32_e32 v35, v35
	v_mul_f32_e32 v39, v39, v34
	v_mul_f32_e32 v34, 0x3d372713, v48
	v_mul_f32_e32 v34, v48, v34
	v_fma_f32 v34, v48, v34, v48
	v_mul_f32_e32 v34, 0x3f4c422a, v34
	v_mul_f32_e32 v34, 0xc038aa3b, v34
	v_exp_f32_e32 v34, v34
	s_nop 0
	v_pk_add_f32 v[34:35], v[34:35], 1.0 op_sel_hi:[1,0]
	s_nop 0
	v_mul_f32_e32 v34, v34, v35
	v_rcp_f32_e32 v34, v34
	v_mul_f32_e32 v35, 0xbfb8aa3b, v36
	v_exp_f32_e32 v35, v35
	v_mul_f32_e32 v40, v43, v34
	v_mul_f32_e32 v34, 0x3d372713, v44
	v_mul_f32_e32 v34, v44, v34
	v_fma_f32 v34, v44, v34, v44
	v_mul_f32_e32 v34, 0x3f4c422a, v34
	v_mul_f32_e32 v34, 0xc038aa3b, v34
	v_exp_f32_e32 v34, v34
	v_mul_f32_e32 v43, v44, v36
	v_mul_f32_e32 v36, v49, v41
	v_pk_add_f32 v[34:35], v[34:35], 1.0 op_sel_hi:[1,0]
	s_nop 0
	v_mul_f32_e32 v34, v34, v35
	v_rcp_f32_e32 v34, v34
	v_mul_f32_e32 v35, 0xbfb8aa3b, v41
	v_exp_f32_e32 v35, v35
	v_mul_f32_e32 v41, v45, v37
	v_mul_f32_e32 v43, v43, v34
	v_mul_f32_e32 v34, 0x3d372713, v49
	v_mul_f32_e32 v34, v49, v34
	v_fma_f32 v34, v49, v34, v49
	v_mul_f32_e32 v34, 0x3f4c422a, v34
	v_mul_f32_e32 v34, 0xc038aa3b, v34
	v_exp_f32_e32 v34, v34
	s_nop 0
	v_pk_add_f32 v[34:35], v[34:35], 1.0 op_sel_hi:[1,0]
	s_nop 0
	v_mul_f32_e32 v34, v34, v35
	v_rcp_f32_e32 v34, v34
	v_mul_f32_e32 v35, 0xbfb8aa3b, v37
	v_exp_f32_e32 v35, v35
	v_mul_f32_e32 v36, v36, v34
	v_mul_f32_e32 v34, 0x3d372713, v45
	v_mul_f32_e32 v34, v45, v34
	v_fma_f32 v34, v45, v34, v45
	v_mul_f32_e32 v34, 0x3f4c422a, v34
	v_mul_f32_e32 v34, 0xc038aa3b, v34
	v_exp_f32_e32 v34, v34
	s_nop 0
	v_pk_add_f32 v[34:35], v[34:35], 1.0 op_sel_hi:[1,0]
	s_nop 0
	v_mul_f32_e32 v34, v34, v35
	v_rcp_f32_e32 v34, v34
	v_cvt_pk_bf16_f32 v35, v40, v36
	v_cvt_pk_bf16_f32 v36, v42, v39
	s_nop 0
	v_mul_f32_e32 v37, v41, v34
	v_cvt_pk_bf16_f32 v34, v0, v38
	v_mul_f32_e32 v0, 0x3d372713, v30
	v_mul_f32_e32 v0, v30, v0
	v_fma_f32 v0, v30, v0, v30
	v_add_co_u32_e32 v38, vcc, s76, v114
	v_mul_f32_e32 v0, 0x3f4c422a, v0
	s_nop 0
; __device__ __forceinline__ float gelu_silu_f(float u, float z) { const float t = 0.7978845608028654f * (u + 0.044715f * u * u * u); return u * z * frcp((1.f + fexp2(-2.885390081777927f * t)) * (1.f + fexp2(-1.4426950408889634f * z))); }
; __device__ __forceinline__ void st8(bf16_t* p, const float (&v)[8]) { u32x4 w; w.x = pk2(v[0], v[1]); w.y = pk2(v[2], v[3]); w.z = pk2(v[4], v[5]); w.w = pk2(v[6], v[7]); *(u32x4*)p = w; }
;     __device__ __forceinline__ void operator()(const f32x4 (&acc)[2][2][4][2], const Unit& u, int wr, int wc, int fr, int fq) const {
;     ...
;             const int colt = pn * 128 + wc * 32 + 8 * fq;
; #pragma unroll
;             for (int ai = 0; ai < 2; ++ai)
; #pragma unroll
;                 for (int m = 0; m < 4; ++m) { float o[8];
; #pragma unroll
;                     for (int j = 0; j < 4; ++j) { o[j] = gelu_silu_f(acc[ai][0][m][0][j], acc[ai][1][m][0][j]); o[4 + j] = gelu_silu_f(acc[ai][0][m][1][j], acc[ai][1][m][1][j]); }
;                     st8(uz + (size_t)(row0 + ai * 128 + m * 16) * DM + colt, o); }
	v_addc_co_u32_e32 v39, vcc, 0, v115, vcc
	v_mul_f32_e32 v0, 0xc038aa3b, v0
	v_cvt_pk_bf16_f32 v37, v43, v37
	global_store_dwordx4 v[38:39], v[34:37], off
	v_mul_f32_e32 v30, v30, v22
	s_nop 0
	v_exp_f32_e32 v34, v0
	v_mul_f32_e32 v0, 0xbfb8aa3b, v22
	v_exp_f32_e32 v35, v0
	v_mul_f32_e32 v22, 0x3d372713, v26
	v_mul_f32_e32 v22, v26, v22
	v_fma_f32 v22, v26, v22, v26
	v_mul_f32_e32 v22, 0x3f4c422a, v22
	v_pk_add_f32 v[34:35], v[34:35], 1.0 op_sel_hi:[1,0]
	v_mul_f32_e32 v26, v26, v18
	v_mul_f32_e32 v22, 0xc038aa3b, v22
	v_mul_f32_e32 v18, 0xbfb8aa3b, v18
	v_mul_f32_e32 v0, v34, v35
	v_exp_f32_e32 v34, v22
	v_exp_f32_e32 v35, v18
	v_rcp_f32_e32 v0, v0
	v_pk_add_f32 v[34:35], v[34:35], 1.0 op_sel_hi:[1,0]
	s_nop 0
	v_mul_f32_e32 v18, v34, v35
	v_rcp_f32_e32 v18, v18
	v_mul_f32_e32 v0, v30, v0
	v_mul_f32_e32 v30, v31, v23
	v_mul_f32_e32 v26, v26, v18
	v_mul_f32_e32 v18, 0x3d372713, v31
	v_mul_f32_e32 v18, v31, v18
	v_fma_f32 v18, v31, v18, v31
	v_mul_f32_e32 v18, 0x3f4c422a, v18
	v_mul_f32_e32 v18, 0xc038aa3b, v18
	v_exp_f32_e32 v22, v18
	v_mul_f32_e32 v18, 0xbfb8aa3b, v23
	v_exp_f32_e32 v23, v18
	s_nop 0
	v_pk_add_f32 v[22:23], v[22:23], 1.0 op_sel_hi:[1,0]
	s_nop 0
	v_mul_f32_e32 v18, v22, v23
	v_rcp_f32_e32 v18, v18
	v_mul_f32_e32 v23, v27, v19
	v_mul_f32_e32 v19, 0xbfb8aa3b, v19
	v_exp_f32_e32 v19, v19
	v_mul_f32_e32 v22, v30, v18
	v_mul_f32_e32 v18, 0x3d372713, v27
	v_mul_f32_e32 v18, v27, v18
	v_fma_f32 v18, v27, v18, v27
	v_mul_f32_e32 v18, 0x3f4c422a, v18
	v_mul_f32_e32 v18, 0xc038aa3b, v18
	v_exp_f32_e32 v18, v18
	v_mul_f32_e32 v27, v32, v24
	v_pk_add_f32 v[18:19], v[18:19], 1.0 op_sel_hi:[1,0]
	s_nop 0
	v_mul_f32_e32 v18, v18, v19
	v_rcp_f32_e32 v18, v18
	v_mul_f32_e32 v19, 0xbfb8aa3b, v24
	v_exp_f32_e32 v19, v19
	v_mul_f32_e32 v23, v23, v18
	v_mul_f32_e32 v18, 0x3d372713, v32
	v_mul_f32_e32 v18, v32, v18
	v_fma_f32 v18, v32, v18, v32
	v_mul_f32_e32 v18, 0x3f4c422a, v18
	v_mul_f32_e32 v18, 0xc038aa3b, v18
	v_exp_f32_e32 v18, v18
	s_nop 0
	v_pk_add_f32 v[18:19], v[18:19], 1.0 op_sel_hi:[1,0]
	s_nop 0
	v_mul_f32_e32 v18, v18, v19
	v_rcp_f32_e32 v18, v18
	v_mul_f32_e32 v19, 0xbfb8aa3b, v20
	v_exp_f32_e32 v19, v19
	v_mul_f32_e32 v24, v27, v18
	v_mul_f32_e32 v18, 0x3d372713, v28
	v_mul_f32_e32 v18, v28, v18
	v_fma_f32 v18, v28, v18, v28
	v_mul_f32_e32 v18, 0x3f4c422a, v18
	v_mul_f32_e32 v18, 0xc038aa3b, v18
	v_exp_f32_e32 v18, v18
	v_mul_f32_e32 v27, v28, v20
	v_mul_f32_e32 v20, v33, v25
	v_pk_add_f32 v[18:19], v[18:19], 1.0 op_sel_hi:[1,0]
	s_nop 0
	v_mul_f32_e32 v18, v18, v19
	v_rcp_f32_e32 v18, v18
	v_mul_f32_e32 v19, 0xbfb8aa3b, v25
	v_exp_f32_e32 v19, v19
	v_mul_f32_e32 v25, v29, v21
	v_mul_f32_e32 v27, v27, v18
	v_mul_f32_e32 v18, 0x3d372713, v33
	v_mul_f32_e32 v18, v33, v18
	v_fma_f32 v18, v33, v18, v33
	v_mul_f32_e32 v18, 0x3f4c422a, v18
	v_mul_f32_e32 v18, 0xc038aa3b, v18
	v_exp_f32_e32 v18, v18
	s_nop 0
	v_pk_add_f32 v[18:19], v[18:19], 1.0 op_sel_hi:[1,0]
	s_nop 0
	v_mul_f32_e32 v18, v18, v19
	v_rcp_f32_e32 v18, v18
	v_mul_f32_e32 v19, 0xbfb8aa3b, v21
	v_exp_f32_e32 v19, v19
	v_mul_f32_e32 v20, v20, v18
	v_mul_f32_e32 v18, 0x3d372713, v29
	v_mul_f32_e32 v18, v29, v18
	v_fma_f32 v18, v29, v18, v29
	v_mul_f32_e32 v18, 0x3f4c422a, v18
	v_mul_f32_e32 v18, 0xc038aa3b, v18
	v_exp_f32_e32 v18, v18
	s_nop 0
	v_pk_add_f32 v[18:19], v[18:19], 1.0 op_sel_hi:[1,0]
	s_nop 0
	v_mul_f32_e32 v18, v18, v19
	v_rcp_f32_e32 v18, v18
	v_cvt_pk_bf16_f32 v19, v24, v20
	v_cvt_pk_bf16_f32 v20, v26, v23
	s_nop 0
	v_mul_f32_e32 v21, v25, v18
	v_cvt_pk_bf16_f32 v18, v0, v22
	v_mul_f32_e32 v0, 0x3d372713, v14
	v_mul_f32_e32 v0, v14, v0
	v_fma_f32 v0, v14, v0, v14
	v_add_co_u32_e32 v22, vcc, s2, v114
; __device__ __forceinline__ float gelu_silu_f(float u, float z) { const float t = 0.7978845608028654f * (u + 0.044715f * u * u * u); return u * z * frcp((1.f + fexp2(-2.885390081777927f * t)) * (1.f + fexp2(-1.4426950408889634f * z))); }
; __device__ __forceinline__ void st8(bf16_t* p, const float (&v)[8]) { u32x4 w; w.x = pk2(v[0], v[1]); w.y = pk2(v[2], v[3]); w.z = pk2(v[4], v[5]); w.w = pk2(v[6], v[7]); *(u32x4*)p = w; }
;     __device__ __forceinline__ void operator()(const f32x4 (&acc)[2][2][4][2], const Unit& u, int wr, int wc, int fr, int fq) const {
;     ...
;             const int colt = pn * 128 + wc * 32 + 8 * fq;
; #pragma unroll
;             for (int ai = 0; ai < 2; ++ai)
; #pragma unroll
;                 for (int m = 0; m < 4; ++m) { float o[8];
; #pragma unroll
;                     for (int j = 0; j < 4; ++j) { o[j] = gelu_silu_f(acc[ai][0][m][0][j], acc[ai][1][m][0][j]); o[4 + j] = gelu_silu_f(acc[ai][0][m][1][j], acc[ai][1][m][1][j]); }
;                     st8(uz + (size_t)(row0 + ai * 128 + m * 16) * DM + colt, o); }
	v_mul_f32_e32 v0, 0x3f4c422a, v0
	s_nop 0
	v_addc_co_u32_e32 v23, vcc, 0, v115, vcc
	v_mul_f32_e32 v0, 0xc038aa3b, v0
	v_cvt_pk_bf16_f32 v21, v27, v21
	global_store_dwordx4 v[22:23], v[18:21], off
	v_mul_f32_e32 v14, v14, v6
	s_nop 0
	v_exp_f32_e32 v18, v0
	v_mul_f32_e32 v0, 0xbfb8aa3b, v6
	v_exp_f32_e32 v19, v0
	v_mul_f32_e32 v6, 0x3d372713, v10
	v_mul_f32_e32 v6, v10, v6
	v_fma_f32 v6, v10, v6, v10
	v_mul_f32_e32 v6, 0x3f4c422a, v6
	v_pk_add_f32 v[18:19], v[18:19], 1.0 op_sel_hi:[1,0]
	v_mul_f32_e32 v10, v10, v2
	v_mul_f32_e32 v6, 0xc038aa3b, v6
	v_mul_f32_e32 v2, 0xbfb8aa3b, v2
	v_mul_f32_e32 v0, v18, v19
	v_exp_f32_e32 v18, v6
	v_exp_f32_e32 v19, v2
	v_rcp_f32_e32 v0, v0
	v_pk_add_f32 v[18:19], v[18:19], 1.0 op_sel_hi:[1,0]
	s_nop 0
	v_mul_f32_e32 v2, v18, v19
	v_rcp_f32_e32 v2, v2
	v_mul_f32_e32 v0, v14, v0
	v_mul_f32_e32 v14, v15, v7
	v_mul_f32_e32 v10, v10, v2
	v_mul_f32_e32 v2, 0x3d372713, v15
	v_mul_f32_e32 v2, v15, v2
	v_fma_f32 v2, v15, v2, v15
	v_mul_f32_e32 v2, 0x3f4c422a, v2
	v_mul_f32_e32 v2, 0xc038aa3b, v2
	v_exp_f32_e32 v6, v2
	v_mul_f32_e32 v2, 0xbfb8aa3b, v7
	v_exp_f32_e32 v7, v2
	s_nop 0
	v_pk_add_f32 v[6:7], v[6:7], 1.0 op_sel_hi:[1,0]
	s_nop 0
	v_mul_f32_e32 v2, v6, v7
	v_rcp_f32_e32 v2, v2
	v_mul_f32_e32 v7, v11, v3
	v_mul_f32_e32 v3, 0xbfb8aa3b, v3
	v_exp_f32_e32 v3, v3
	v_mul_f32_e32 v6, v14, v2
	v_mul_f32_e32 v2, 0x3d372713, v11
	v_mul_f32_e32 v2, v11, v2
	v_fma_f32 v2, v11, v2, v11
	v_mul_f32_e32 v2, 0x3f4c422a, v2
	v_mul_f32_e32 v2, 0xc038aa3b, v2
	v_exp_f32_e32 v2, v2
	v_mul_f32_e32 v11, v16, v8
	v_pk_add_f32 v[2:3], v[2:3], 1.0 op_sel_hi:[1,0]
	s_nop 0
	v_mul_f32_e32 v2, v2, v3
	v_rcp_f32_e32 v2, v2
	v_mul_f32_e32 v3, 0xbfb8aa3b, v8
	v_exp_f32_e32 v3, v3
	v_mul_f32_e32 v7, v7, v2
	v_mul_f32_e32 v2, 0x3d372713, v16
	v_mul_f32_e32 v2, v16, v2
	v_fma_f32 v2, v16, v2, v16
	v_mul_f32_e32 v2, 0x3f4c422a, v2
	v_mul_f32_e32 v2, 0xc038aa3b, v2
	v_exp_f32_e32 v2, v2
	s_nop 0
	v_pk_add_f32 v[2:3], v[2:3], 1.0 op_sel_hi:[1,0]
	s_nop 0
	v_mul_f32_e32 v2, v2, v3
	v_rcp_f32_e32 v2, v2
	v_mul_f32_e32 v3, 0xbfb8aa3b, v4
	v_exp_f32_e32 v3, v3
	v_mul_f32_e32 v8, v11, v2
	v_mul_f32_e32 v2, 0x3d372713, v12
	v_mul_f32_e32 v2, v12, v2
	v_fma_f32 v2, v12, v2, v12
	v_mul_f32_e32 v2, 0x3f4c422a, v2
	v_mul_f32_e32 v2, 0xc038aa3b, v2
	v_exp_f32_e32 v2, v2
	v_mul_f32_e32 v11, v12, v4
	v_mul_f32_e32 v4, v17, v9
	v_pk_add_f32 v[2:3], v[2:3], 1.0 op_sel_hi:[1,0]
	s_nop 0
	v_mul_f32_e32 v2, v2, v3
	v_rcp_f32_e32 v2, v2
	v_mul_f32_e32 v3, 0xbfb8aa3b, v9
	v_exp_f32_e32 v3, v3
	v_mul_f32_e32 v9, v13, v5
	v_mul_f32_e32 v11, v11, v2
	v_mul_f32_e32 v2, 0x3d372713, v17
	v_mul_f32_e32 v2, v17, v2
	v_fma_f32 v2, v17, v2, v17
	v_mul_f32_e32 v2, 0x3f4c422a, v2
	v_mul_f32_e32 v2, 0xc038aa3b, v2
	v_exp_f32_e32 v2, v2
	s_nop 0
	v_pk_add_f32 v[2:3], v[2:3], 1.0 op_sel_hi:[1,0]
	s_nop 0
	v_mul_f32_e32 v2, v2, v3
	v_rcp_f32_e32 v2, v2
	v_mul_f32_e32 v3, 0xbfb8aa3b, v5
	v_exp_f32_e32 v3, v3
	v_mul_f32_e32 v4, v4, v2
	v_mul_f32_e32 v2, 0x3d372713, v13
	v_mul_f32_e32 v2, v13, v2
	v_fma_f32 v2, v13, v2, v13
	v_mul_f32_e32 v2, 0x3f4c422a, v2
	v_mul_f32_e32 v2, 0xc038aa3b, v2
	v_exp_f32_e32 v2, v2
	s_nop 0
	v_pk_add_f32 v[2:3], v[2:3], 1.0 op_sel_hi:[1,0]
	s_nop 0
	v_mul_f32_e32 v2, v2, v3
	v_rcp_f32_e32 v2, v2
	v_cvt_pk_bf16_f32 v3, v8, v4
	v_cvt_pk_bf16_f32 v4, v10, v7
	s_nop 0
	v_mul_f32_e32 v5, v9, v2
	v_cvt_pk_bf16_f32 v2, v0, v6
	v_add_co_u32_e32 v6, vcc, 0xb0000, v114
	v_cvt_pk_bf16_f32 v5, v11, v5
	s_nop 1
	v_addc_co_u32_e32 v7, vcc, 0, v115, vcc
	global_store_dwordx4 v[6:7], v[2:5], off
	s_andn2_b64 vcc, exec, s[42:43]
	s_mov_b64 s[12:13], -1
	s_cbranch_vccnz .LBB0_305

; __device__ __forceinline__ void st8(bf16_t* p, const float (&v)[8]) { u32x4 w; w.x = pk2(v[0], v[1]); w.y = pk2(v[2], v[3]); w.z = pk2(v[4], v[5]); w.w = pk2(v[6], v[7]); *(u32x4*)p = w; }
;     __device__ __forceinline__ void operator()(const f32x4 (&acc)[2][2][4][2], const Unit& u, int wr, int wc, int fr, int fq) const {
;     ...
;             bf16_t* dst = pn < 4 ? q : k; const float sc = pn < 4 ? QSCALE : 1.f;
;             const int head = (pn & 3) * 2 + (wc >> 1), i0 = 32 * (wc & 1) + 8 * fq;
; #pragma unroll
;             for (int ai = 0; ai < 2; ++ai)
; #pragma unroll
;                 for (int m = 0; m < 4; ++m) {
;                     const int row = row0 + ai * 128 + m * 16, pos = row & (SEQ - 1);
;                     const f32x4* cp = (const f32x4*)(cosT + pos * 64 + i0); const f32x4* sp = (const f32x4*)(sinT + pos * 64 + i0);
;                     const f32x4 c0 = cp[0], c1 = cp[1], s0 = sp[0], s1 = sp[1];
;                     float o1[8], o2[8];
; #pragma unroll
;                     for (int j = 0; j < 4; ++j) {
;                         const float a0 = acc[ai][0][m][0][j], b0 = acc[ai][1][m][0][j], a1 = acc[ai][0][m][1][j], b1 = acc[ai][1][m][1][j];
;                         o1[j] = (a0 * c0[j] - b0 * s0[j]) * sc; o2[j] = (b0 * c0[j] + a0 * s0[j]) * sc;
;                         o1[4 + j] = (a1 * c1[j] - b1 * s1[j]) * sc; o2[4 + j] = (b1 * c1[j] + a1 * s1[j]) * sc;
;                     }
;                     bf16_t* rp = dst + (size_t)row * AW + head * 128 + i0;
;                     st8(rp, o1); st8(rp + 64, o2);
.LBB0_355:
	s_cmp_lt_i32 s72, 4
	s_cselect_b64 vcc, -1, 0
	v_mov_b32_e32 v0, 0x3e0293ee
	v_cndmask_b32_e32 v173, 1.0, v0, vcc
	v_lshlrev_b32_e32 v0, 8, v164
	v_and_b32_e32 v0, 0xfcf00, v0
	v_lshl_add_u64 v[2:3], v[154:155], 0, v[0:1]
	v_lshl_add_u64 v[6:7], v[156:157], 0, v[0:1]
	global_load_dwordx4 v[142:145], v[2:3], off
	s_nop 0
	global_load_dwordx4 v[2:5], v[2:3], off offset:16
	s_nop 0
	global_load_dwordx4 v[138:141], v[6:7], off
	s_nop 0
	global_load_dwordx4 v[6:9], v[6:7], off offset:16
	s_and_b64 s[2:3], vcc, exec
	s_mov_b32 s2, 0xd6e4000
	s_cselect_b32 s2, s2, 0xf6e4000
	s_add_u32 s2, s22, s2
	v_mov_b32_e32 v174, v134
	v_mov_b32_e32 v175, v126
	s_addc_u32 s3, s23, 0
	s_lshl_b32 s4, s72, 1
	s_and_b32 s4, s4, 6
	s_or_b32 s4, s4, s66
	s_lshl_b32 s4, s4, 8
	s_add_u32 s2, s2, s4
	s_addc_u32 s3, s3, 0
	v_mov_b32_e32 v163, v1
	v_lshl_add_u64 v[166:167], s[2:3], 0, v[162:163]
	v_ashrrev_i32_e32 v165, 31, v164
	s_waitcnt vmcnt(0) lgkmcnt(0)
	v_mov_b32_e32 v176, v142
	v_mov_b32_e32 v177, v138
	v_pk_mul_f32 v[174:175], v[174:175], v[176:177]
	v_mov_b32_e32 v138, v143
	v_sub_f32_e32 v0, v174, v175
	v_mov_b32_e32 v174, v126
	v_mov_b32_e32 v175, v134
	v_pk_mul_f32 v[174:175], v[174:175], v[176:177]
	v_mov_b32_e32 v176, v2
	v_add_f32_e32 v126, v174, v175
	v_mov_b32_e32 v174, v130
	v_mov_b32_e32 v175, v122
	v_mov_b32_e32 v177, v6
	v_pk_mul_f32 v[174:175], v[174:175], v[176:177]
	v_mul_f32_e32 v163, v173, v126
	v_sub_f32_e32 v2, v174, v175
	v_mov_b32_e32 v174, v122
	v_mov_b32_e32 v175, v130
	v_pk_mul_f32 v[174:175], v[174:175], v[176:177]
	v_mov_b32_e32 v126, v135
	v_mul_f32_e32 v185, v173, v2
	v_add_f32_e32 v2, v174, v175
	v_pk_mul_f32 v[142:143], v[126:127], v[138:139]
	v_mov_b32_e32 v134, v127
	v_mul_f32_e32 v174, v173, v2
	v_sub_f32_e32 v2, v142, v143
	v_pk_mul_f32 v[126:127], v[134:135], v[138:139]
	v_mul_f32_e32 v142, v173, v2
	v_add_f32_e32 v2, v126, v127
	v_mov_b32_e32 v122, v131
	v_mov_b32_e32 v6, v3
	v_mul_f32_e32 v126, v173, v2
	v_pk_mul_f32 v[2:3], v[122:123], v[6:7]
	v_mov_b32_e32 v130, v123
	v_sub_f32_e32 v2, v2, v3
	v_mul_f32_e32 v122, v173, v2
	v_pk_mul_f32 v[2:3], v[130:131], v[6:7]
	v_mov_b32_e32 v6, v144
	v_add_f32_e32 v2, v2, v3
	v_mul_f32_e32 v123, v173, v2
	v_mov_b32_e32 v2, v136
	v_mov_b32_e32 v3, v128
	v_mov_b32_e32 v7, v140
	v_pk_mul_f32 v[2:3], v[2:3], v[6:7]
	v_mov_b32_e32 v140, v145
	v_sub_f32_e32 v2, v2, v3
	v_mul_f32_e32 v127, v173, v2
	v_mov_b32_e32 v2, v128
	v_mov_b32_e32 v3, v136
	v_pk_mul_f32 v[2:3], v[2:3], v[6:7]
	v_mov_b32_e32 v6, v4
	v_add_f32_e32 v2, v2, v3
	v_mul_f32_e32 v130, v173, v2
	v_mov_b32_e32 v2, v132
	v_mov_b32_e32 v3, v124
	v_mov_b32_e32 v7, v8
	v_pk_mul_f32 v[2:3], v[2:3], v[6:7]
	v_mov_b32_e32 v128, v137
	v_sub_f32_e32 v2, v2, v3
	v_mul_f32_e32 v131, v173, v2
	v_mov_b32_e32 v2, v124
	v_mov_b32_e32 v3, v132
	v_pk_mul_f32 v[2:3], v[2:3], v[6:7]
	v_mov_b32_e32 v136, v129
	v_add_f32_e32 v2, v2, v3
	v_mul_f32_e32 v134, v173, v2
	v_pk_mul_f32 v[2:3], v[128:129], v[140:141]
	v_mov_b32_e32 v124, v133
	v_sub_f32_e32 v2, v2, v3
	v_mul_f32_e32 v4, v173, v2
	v_pk_mul_f32 v[2:3], v[136:137], v[140:141]
	v_mov_b32_e32 v8, v5
	v_add_f32_e32 v2, v2, v3
	v_mul_f32_e32 v128, v173, v2
	v_pk_mul_f32 v[2:3], v[124:125], v[8:9]
	v_mov_b32_e32 v132, v125
	v_sub_f32_e32 v2, v2, v3
	v_mul_f32_e32 v5, v173, v2
	v_pk_mul_f32 v[2:3], v[132:133], v[8:9]
	v_mul_f32_e32 v0, v173, v0
	v_add_f32_e32 v2, v2, v3
	v_mul_f32_e32 v8, v173, v2
	v_lshlrev_b64 v[2:3], 11, v[164:165]
	v_lshl_add_u64 v[6:7], v[166:167], 0, v[2:3]
	v_cvt_pk_bf16_f32 v3, v127, v4
	v_cvt_pk_bf16_f32 v2, v0, v142
	v_cvt_pk_bf16_f32 v4, v185, v122
	v_cvt_pk_bf16_f32 v5, v131, v5
	global_store_dwordx4 v[6:7], v[2:5], off
	v_mov_b32_e32 v132, v118
	v_mov_b32_e32 v133, v110
	v_cvt_pk_bf16_f32 v3, v130, v128
	v_or_b32_e32 v130, 16, v164
	v_lshlrev_b32_e32 v0, 8, v130
	v_cvt_pk_bf16_f32 v2, v163, v126
	v_and_b32_e32 v0, 0xfdf00, v0
	v_cvt_pk_bf16_f32 v4, v174, v123
	v_cvt_pk_bf16_f32 v5, v134, v8
	global_store_dwordx4 v[6:7], v[2:5], off offset:128
	v_lshl_add_u64 v[6:7], v[156:157], 0, v[0:1]
	v_ashrrev_i32_e32 v131, 31, v130
	v_lshl_add_u64 v[2:3], v[154:155], 0, v[0:1]
	global_load_dwordx4 v[126:129], v[2:3], off
	s_nop 0
	global_load_dwordx4 v[2:5], v[2:3], off offset:16
	s_nop 0
	global_load_dwordx4 v[122:125], v[6:7], off
	s_nop 0
	global_load_dwordx4 v[6:9], v[6:7], off offset:16
	s_waitcnt vmcnt(0) lgkmcnt(0)
; __device__ __forceinline__ void st8(bf16_t* p, const float (&v)[8]) { u32x4 w; w.x = pk2(v[0], v[1]); w.y = pk2(v[2], v[3]); w.z = pk2(v[4], v[5]); w.w = pk2(v[6], v[7]); *(u32x4*)p = w; }
;     __device__ __forceinline__ void operator()(const f32x4 (&acc)[2][2][4][2], const Unit& u, int wr, int wc, int fr, int fq) const {
;     ...
;             bf16_t* dst = pn < 4 ? q : k; const float sc = pn < 4 ? QSCALE : 1.f;
;             const int head = (pn & 3) * 2 + (wc >> 1), i0 = 32 * (wc & 1) + 8 * fq;
; #pragma unroll
;             for (int ai = 0; ai < 2; ++ai)
; #pragma unroll
;                 for (int m = 0; m < 4; ++m) {
;                     const int row = row0 + ai * 128 + m * 16, pos = row & (SEQ - 1);
;                     const f32x4* cp = (const f32x4*)(cosT + pos * 64 + i0); const f32x4* sp = (const f32x4*)(sinT + pos * 64 + i0);
;                     const f32x4 c0 = cp[0], c1 = cp[1], s0 = sp[0], s1 = sp[1];
;                     float o1[8], o2[8];
; #pragma unroll
;                     for (int j = 0; j < 4; ++j) {
;                         const float a0 = acc[ai][0][m][0][j], b0 = acc[ai][1][m][0][j], a1 = acc[ai][0][m][1][j], b1 = acc[ai][1][m][1][j];
;                         o1[j] = (a0 * c0[j] - b0 * s0[j]) * sc; o2[j] = (b0 * c0[j] + a0 * s0[j]) * sc;
;                         o1[4 + j] = (a1 * c1[j] - b1 * s1[j]) * sc; o2[4 + j] = (b1 * c1[j] + a1 * s1[j]) * sc;
;                     }
;                     bf16_t* rp = dst + (size_t)row * AW + head * 128 + i0;
;                     st8(rp, o1); st8(rp + 64, o2);
	v_mov_b32_e32 v134, v126
	v_mov_b32_e32 v135, v122
	v_pk_mul_f32 v[132:133], v[132:133], v[134:135]
	v_mov_b32_e32 v122, v127
	v_sub_f32_e32 v0, v132, v133
	v_mov_b32_e32 v132, v110
	v_mov_b32_e32 v133, v118
	v_pk_mul_f32 v[132:133], v[132:133], v[134:135]
	v_mov_b32_e32 v134, v2
	v_add_f32_e32 v110, v132, v133
	v_mov_b32_e32 v132, v114
	v_mov_b32_e32 v133, v106
	v_mov_b32_e32 v135, v6
	v_pk_mul_f32 v[132:133], v[132:133], v[134:135]
	v_mul_f32_e32 v136, v173, v110
	v_sub_f32_e32 v2, v132, v133
	v_mov_b32_e32 v132, v106
	v_mov_b32_e32 v133, v114
	v_pk_mul_f32 v[132:133], v[132:133], v[134:135]
	v_mov_b32_e32 v110, v119
	v_mul_f32_e32 v137, v173, v2
	v_add_f32_e32 v2, v132, v133
	v_pk_mul_f32 v[126:127], v[110:111], v[122:123]
	v_mov_b32_e32 v118, v111
	v_mul_f32_e32 v132, v173, v2
	v_sub_f32_e32 v2, v126, v127
	v_pk_mul_f32 v[110:111], v[118:119], v[122:123]
	v_mul_f32_e32 v126, v173, v2
	v_add_f32_e32 v2, v110, v111
	v_mov_b32_e32 v106, v115
	v_mov_b32_e32 v6, v3
	v_mul_f32_e32 v110, v173, v2
	v_pk_mul_f32 v[2:3], v[106:107], v[6:7]
	v_mov_b32_e32 v114, v107
	v_sub_f32_e32 v2, v2, v3
	v_mul_f32_e32 v106, v173, v2
	v_pk_mul_f32 v[2:3], v[114:115], v[6:7]
	v_mov_b32_e32 v6, v128
	v_add_f32_e32 v2, v2, v3
	v_mul_f32_e32 v107, v173, v2
	v_mov_b32_e32 v2, v120
	v_mov_b32_e32 v3, v112
	v_mov_b32_e32 v7, v124
	v_pk_mul_f32 v[2:3], v[2:3], v[6:7]
	v_mov_b32_e32 v124, v129
	v_sub_f32_e32 v2, v2, v3
	v_mul_f32_e32 v111, v173, v2
	v_mov_b32_e32 v2, v112
	v_mov_b32_e32 v3, v120
	v_pk_mul_f32 v[2:3], v[2:3], v[6:7]
	v_mov_b32_e32 v6, v4
	v_add_f32_e32 v2, v2, v3
	v_mul_f32_e32 v114, v173, v2
	v_mov_b32_e32 v2, v116
	v_mov_b32_e32 v3, v108
	v_mov_b32_e32 v7, v8
	v_pk_mul_f32 v[2:3], v[2:3], v[6:7]
	v_mov_b32_e32 v112, v121
	v_sub_f32_e32 v2, v2, v3
	v_mul_f32_e32 v115, v173, v2
	v_mov_b32_e32 v2, v108
	v_mov_b32_e32 v3, v116
	v_pk_mul_f32 v[2:3], v[2:3], v[6:7]
	v_mov_b32_e32 v120, v113
	v_add_f32_e32 v2, v2, v3
	v_mul_f32_e32 v118, v173, v2
	v_pk_mul_f32 v[2:3], v[112:113], v[124:125]
	v_mov_b32_e32 v108, v117
	v_sub_f32_e32 v2, v2, v3
	v_mul_f32_e32 v4, v173, v2
	v_pk_mul_f32 v[2:3], v[120:121], v[124:125]
	v_mov_b32_e32 v8, v5
	v_add_f32_e32 v2, v2, v3
	v_mul_f32_e32 v112, v173, v2
	v_pk_mul_f32 v[2:3], v[108:109], v[8:9]
	v_mov_b32_e32 v116, v109
	v_sub_f32_e32 v2, v2, v3
	v_mul_f32_e32 v5, v173, v2
	v_pk_mul_f32 v[2:3], v[116:117], v[8:9]
	v_mul_f32_e32 v0, v173, v0
	v_add_f32_e32 v2, v2, v3
	v_mul_f32_e32 v8, v173, v2
	v_lshlrev_b64 v[2:3], 11, v[130:131]
	v_lshl_add_u64 v[6:7], v[166:167], 0, v[2:3]
	v_cvt_pk_bf16_f32 v3, v111, v4
	v_cvt_pk_bf16_f32 v2, v0, v126
	v_cvt_pk_bf16_f32 v4, v137, v106
	v_cvt_pk_bf16_f32 v5, v115, v5
	global_store_dwordx4 v[6:7], v[2:5], off
	v_mov_b32_e32 v116, v102
	v_mov_b32_e32 v117, v94
	v_cvt_pk_bf16_f32 v3, v114, v112
	v_or_b32_e32 v114, 32, v164
	v_lshlrev_b32_e32 v0, 8, v114
	v_and_b32_e32 v0, 0xfef00, v0
	v_cvt_pk_bf16_f32 v2, v136, v110
	v_cvt_pk_bf16_f32 v4, v132, v107
	v_cvt_pk_bf16_f32 v5, v118, v8
	global_store_dwordx4 v[6:7], v[2:5], off offset:128
	v_lshl_add_u64 v[6:7], v[154:155], 0, v[0:1]
	v_lshl_add_u64 v[110:111], v[156:157], 0, v[0:1]
	global_load_dwordx4 v[2:5], v[6:7], off
	s_nop 0
	global_load_dwordx4 v[6:9], v[6:7], off offset:16
	s_nop 0
	global_load_dwordx4 v[106:109], v[110:111], off
	s_nop 0
	global_load_dwordx4 v[110:113], v[110:111], off offset:16
	v_ashrrev_i32_e32 v115, 31, v114
	s_waitcnt vmcnt(0) lgkmcnt(0)
	v_mov_b32_e32 v118, v2
	v_mov_b32_e32 v119, v106
	v_pk_mul_f32 v[116:117], v[116:117], v[118:119]
	v_mov_b32_e32 v106, v3
	v_sub_f32_e32 v0, v116, v117
	v_mov_b32_e32 v116, v94
	v_mov_b32_e32 v117, v102
	v_pk_mul_f32 v[116:117], v[116:117], v[118:119]
	v_mov_b32_e32 v118, v6
	v_add_f32_e32 v2, v116, v117
	v_mov_b32_e32 v116, v98
	v_mov_b32_e32 v117, v90
	v_mov_b32_e32 v119, v110
	v_pk_mul_f32 v[116:117], v[116:117], v[118:119]
	v_mul_f32_e32 v120, v173, v2
	v_sub_f32_e32 v2, v116, v117
	v_mov_b32_e32 v116, v90
	v_mov_b32_e32 v117, v98
	v_pk_mul_f32 v[116:117], v[116:117], v[118:119]
	v_mul_f32_e32 v121, v173, v2
	v_add_f32_e32 v2, v116, v117
	v_mov_b32_e32 v94, v103
	v_mul_f32_e32 v116, v173, v2
	v_pk_mul_f32 v[2:3], v[94:95], v[106:107]
	v_mov_b32_e32 v102, v95
	v_sub_f32_e32 v2, v2, v3
	v_mul_f32_e32 v94, v173, v2
	v_pk_mul_f32 v[2:3], v[102:103], v[106:107]
	v_mov_b32_e32 v90, v99
	v_add_f32_e32 v2, v2, v3
	v_mov_b32_e32 v110, v7
	v_mul_f32_e32 v95, v173, v2
	v_pk_mul_f32 v[2:3], v[90:91], v[110:111]
	v_mov_b32_e32 v98, v91
	v_sub_f32_e32 v2, v2, v3
	v_mul_f32_e32 v90, v173, v2
	v_pk_mul_f32 v[2:3], v[98:99], v[110:111]
	v_mov_b32_e32 v6, v4
	v_add_f32_e32 v2, v2, v3
	v_mul_f32_e32 v91, v173, v2
	v_mov_b32_e32 v2, v104
	v_mov_b32_e32 v3, v96
	v_mov_b32_e32 v7, v108
	v_pk_mul_f32 v[2:3], v[2:3], v[6:7]
	v_mov_b32_e32 v108, v5
	v_sub_f32_e32 v2, v2, v3
	v_mul_f32_e32 v4, v173, v2
	v_mov_b32_e32 v2, v96
	v_mov_b32_e32 v3, v104
	v_pk_mul_f32 v[2:3], v[2:3], v[6:7]
	v_mov_b32_e32 v6, v8
	v_add_f32_e32 v2, v2, v3
	v_mul_f32_e32 v98, v173, v2
	v_mov_b32_e32 v2, v100
	v_mov_b32_e32 v3, v92
	v_mov_b32_e32 v7, v112
	v_pk_mul_f32 v[2:3], v[2:3], v[6:7]
	v_mov_b32_e32 v96, v105
	v_sub_f32_e32 v2, v2, v3
	v_mul_f32_e32 v8, v173, v2
	v_mov_b32_e32 v2, v92
	v_mov_b32_e32 v3, v100
	v_pk_mul_f32 v[2:3], v[2:3], v[6:7]
	v_mov_b32_e32 v104, v97
	v_add_f32_e32 v2, v2, v3
	v_mul_f32_e32 v99, v173, v2
	v_pk_mul_f32 v[2:3], v[96:97], v[108:109]
	v_mov_b32_e32 v92, v101
	v_sub_f32_e32 v2, v2, v3
	v_mul_f32_e32 v5, v173, v2
	v_pk_mul_f32 v[2:3], v[104:105], v[108:109]
	v_mov_b32_e32 v112, v9
	v_add_f32_e32 v2, v2, v3
	v_mul_f32_e32 v96, v173, v2
	v_pk_mul_f32 v[2:3], v[92:93], v[112:113]
	v_mov_b32_e32 v100, v93
	v_sub_f32_e32 v2, v2, v3
	v_mul_f32_e32 v9, v173, v2
	v_pk_mul_f32 v[2:3], v[100:101], v[112:113]
	v_mul_f32_e32 v0, v173, v0
	v_add_f32_e32 v2, v2, v3
	v_mul_f32_e32 v92, v173, v2
	v_lshlrev_b64 v[2:3], 11, v[114:115]
	v_lshl_add_u64 v[6:7], v[166:167], 0, v[2:3]
	v_cvt_pk_bf16_f32 v3, v4, v5
	v_cvt_pk_bf16_f32 v2, v0, v94
	v_cvt_pk_bf16_f32 v4, v121, v90
	v_cvt_pk_bf16_f32 v5, v8, v9
	global_store_dwordx4 v[6:7], v[2:5], off
	v_mov_b32_e32 v100, v86
	v_mov_b32_e32 v101, v78
	v_cvt_pk_bf16_f32 v3, v98, v96
	v_or_b32_e32 v98, 48, v164
	v_lshlrev_b32_e32 v0, 8, v98
	v_and_b32_e32 v0, 0xfff00, v0
	v_cvt_pk_bf16_f32 v2, v120, v95
	v_cvt_pk_bf16_f32 v4, v116, v91
	v_cvt_pk_bf16_f32 v5, v99, v92
	global_store_dwordx4 v[6:7], v[2:5], off offset:128
	v_lshl_add_u64 v[6:7], v[154:155], 0, v[0:1]
	v_lshl_add_u64 v[94:95], v[156:157], 0, v[0:1]
	global_load_dwordx4 v[2:5], v[6:7], off
	s_nop 0
	global_load_dwordx4 v[6:9], v[6:7], off offset:16
	s_nop 0
	global_load_dwordx4 v[90:93], v[94:95], off
	s_nop 0
	global_load_dwordx4 v[94:97], v[94:95], off offset:16
	v_ashrrev_i32_e32 v99, 31, v98
	s_waitcnt vmcnt(0) lgkmcnt(0)
; __device__ __forceinline__ void st8(bf16_t* p, const float (&v)[8]) { u32x4 w; w.x = pk2(v[0], v[1]); w.y = pk2(v[2], v[3]); w.z = pk2(v[4], v[5]); w.w = pk2(v[6], v[7]); *(u32x4*)p = w; }
;     __device__ __forceinline__ void operator()(const f32x4 (&acc)[2][2][4][2], const Unit& u, int wr, int wc, int fr, int fq) const {
;     ...
;             bf16_t* dst = pn < 4 ? q : k; const float sc = pn < 4 ? QSCALE : 1.f;
;             const int head = (pn & 3) * 2 + (wc >> 1), i0 = 32 * (wc & 1) + 8 * fq;
; #pragma unroll
;             for (int ai = 0; ai < 2; ++ai)
; #pragma unroll
;                 for (int m = 0; m < 4; ++m) {
;                     const int row = row0 + ai * 128 + m * 16, pos = row & (SEQ - 1);
;                     const f32x4* cp = (const f32x4*)(cosT + pos * 64 + i0); const f32x4* sp = (const f32x4*)(sinT + pos * 64 + i0);
;                     const f32x4 c0 = cp[0], c1 = cp[1], s0 = sp[0], s1 = sp[1];
;                     float o1[8], o2[8];
; #pragma unroll
;                     for (int j = 0; j < 4; ++j) {
;                         const float a0 = acc[ai][0][m][0][j], b0 = acc[ai][1][m][0][j], a1 = acc[ai][0][m][1][j], b1 = acc[ai][1][m][1][j];
;                         o1[j] = (a0 * c0[j] - b0 * s0[j]) * sc; o2[j] = (b0 * c0[j] + a0 * s0[j]) * sc;
;                         o1[4 + j] = (a1 * c1[j] - b1 * s1[j]) * sc; o2[4 + j] = (b1 * c1[j] + a1 * s1[j]) * sc;
;                     }
;                     bf16_t* rp = dst + (size_t)row * AW + head * 128 + i0;
;                     st8(rp, o1); st8(rp + 64, o2);
	v_mov_b32_e32 v102, v2
	v_mov_b32_e32 v103, v90
	v_pk_mul_f32 v[100:101], v[100:101], v[102:103]
	v_mov_b32_e32 v90, v3
	v_sub_f32_e32 v0, v100, v101
	v_mov_b32_e32 v100, v78
	v_mov_b32_e32 v101, v86
	v_pk_mul_f32 v[100:101], v[100:101], v[102:103]
	v_mov_b32_e32 v102, v6
	v_add_f32_e32 v2, v100, v101
	v_mov_b32_e32 v100, v82
	v_mov_b32_e32 v101, v74
	v_mov_b32_e32 v103, v94
	v_pk_mul_f32 v[100:101], v[100:101], v[102:103]
	v_mul_f32_e32 v104, v173, v2
	v_sub_f32_e32 v2, v100, v101
	v_mov_b32_e32 v100, v74
	v_mov_b32_e32 v101, v82
	v_pk_mul_f32 v[100:101], v[100:101], v[102:103]
	v_mul_f32_e32 v105, v173, v2
	v_add_f32_e32 v2, v100, v101
	v_mov_b32_e32 v78, v87
	v_mul_f32_e32 v100, v173, v2
	v_pk_mul_f32 v[2:3], v[78:79], v[90:91]
	v_mov_b32_e32 v86, v79
	v_sub_f32_e32 v2, v2, v3
	v_mul_f32_e32 v78, v173, v2
	v_pk_mul_f32 v[2:3], v[86:87], v[90:91]
	v_mov_b32_e32 v74, v83
	v_add_f32_e32 v2, v2, v3
	v_mov_b32_e32 v94, v7
	v_mul_f32_e32 v79, v173, v2
	v_pk_mul_f32 v[2:3], v[74:75], v[94:95]
	v_mov_b32_e32 v82, v75
	v_sub_f32_e32 v2, v2, v3
	v_mul_f32_e32 v74, v173, v2
	v_pk_mul_f32 v[2:3], v[82:83], v[94:95]
	v_mov_b32_e32 v6, v4
	v_add_f32_e32 v2, v2, v3
	v_mul_f32_e32 v75, v173, v2
	v_mov_b32_e32 v2, v88
	v_mov_b32_e32 v3, v80
	v_mov_b32_e32 v7, v92
	v_pk_mul_f32 v[2:3], v[2:3], v[6:7]
	v_mov_b32_e32 v92, v5
	v_sub_f32_e32 v2, v2, v3
	v_mul_f32_e32 v4, v173, v2
	v_mov_b32_e32 v2, v80
	v_mov_b32_e32 v3, v88
	v_pk_mul_f32 v[2:3], v[2:3], v[6:7]
	v_mov_b32_e32 v6, v8
	v_add_f32_e32 v2, v2, v3
	v_mul_f32_e32 v82, v173, v2
	v_mov_b32_e32 v2, v84
	v_mov_b32_e32 v3, v76
	v_mov_b32_e32 v7, v96
	v_pk_mul_f32 v[2:3], v[2:3], v[6:7]
	v_mov_b32_e32 v80, v89
	v_sub_f32_e32 v2, v2, v3
	v_mul_f32_e32 v8, v173, v2
	v_mov_b32_e32 v2, v76
	v_mov_b32_e32 v3, v84
	v_pk_mul_f32 v[2:3], v[2:3], v[6:7]
	v_mov_b32_e32 v88, v81
	v_add_f32_e32 v2, v2, v3
	v_mul_f32_e32 v83, v173, v2
	v_pk_mul_f32 v[2:3], v[80:81], v[92:93]
	v_mov_b32_e32 v76, v85
	v_sub_f32_e32 v2, v2, v3
	v_mul_f32_e32 v5, v173, v2
	v_pk_mul_f32 v[2:3], v[88:89], v[92:93]
	v_mov_b32_e32 v96, v9
	v_add_f32_e32 v2, v2, v3
	v_mul_f32_e32 v80, v173, v2
	v_pk_mul_f32 v[2:3], v[76:77], v[96:97]
	v_mov_b32_e32 v84, v77
	v_sub_f32_e32 v2, v2, v3
	v_mul_f32_e32 v9, v173, v2
	v_pk_mul_f32 v[2:3], v[84:85], v[96:97]
	v_mul_f32_e32 v0, v173, v0
	v_add_f32_e32 v2, v2, v3
	v_mul_f32_e32 v76, v173, v2
	v_lshlrev_b64 v[2:3], 11, v[98:99]
	v_lshl_add_u64 v[6:7], v[166:167], 0, v[2:3]
	v_cvt_pk_bf16_f32 v3, v4, v5
	v_cvt_pk_bf16_f32 v2, v0, v78
	v_cvt_pk_bf16_f32 v4, v105, v74
	v_cvt_pk_bf16_f32 v5, v8, v9
	global_store_dwordx4 v[6:7], v[2:5], off
	v_mov_b32_e32 v84, v70
	v_mov_b32_e32 v85, v62
	v_cvt_pk_bf16_f32 v3, v82, v80
	v_add_u32_e32 v82, 0x80, v164
	v_lshlrev_b32_e32 v0, 8, v82
	v_and_b32_e32 v0, 0xfcf00, v0
	v_cvt_pk_bf16_f32 v2, v104, v79
	v_cvt_pk_bf16_f32 v4, v100, v75
	v_cvt_pk_bf16_f32 v5, v83, v76
	global_store_dwordx4 v[6:7], v[2:5], off offset:128
	v_lshl_add_u64 v[6:7], v[154:155], 0, v[0:1]
	v_lshl_add_u64 v[78:79], v[156:157], 0, v[0:1]
	global_load_dwordx4 v[2:5], v[6:7], off
	s_nop 0
	global_load_dwordx4 v[6:9], v[6:7], off offset:16
	s_nop 0
	global_load_dwordx4 v[74:77], v[78:79], off
	s_nop 0
	global_load_dwordx4 v[78:81], v[78:79], off offset:16
	v_ashrrev_i32_e32 v83, 31, v82
	s_waitcnt vmcnt(0) lgkmcnt(0)
	v_mov_b32_e32 v86, v2
	v_mov_b32_e32 v87, v74
	v_pk_mul_f32 v[84:85], v[84:85], v[86:87]
	v_mov_b32_e32 v74, v3
	v_sub_f32_e32 v0, v84, v85
	v_mov_b32_e32 v84, v62
	v_mov_b32_e32 v85, v70
	v_pk_mul_f32 v[84:85], v[84:85], v[86:87]
	v_mov_b32_e32 v86, v6
	v_add_f32_e32 v2, v84, v85
	v_mov_b32_e32 v84, v66
	v_mov_b32_e32 v85, v58
	v_mov_b32_e32 v87, v78
	v_pk_mul_f32 v[84:85], v[84:85], v[86:87]
	v_mul_f32_e32 v88, v173, v2
	v_sub_f32_e32 v2, v84, v85
	v_mov_b32_e32 v84, v58
	v_mov_b32_e32 v85, v66
	v_pk_mul_f32 v[84:85], v[84:85], v[86:87]
	v_mul_f32_e32 v89, v173, v2
	v_add_f32_e32 v2, v84, v85
	v_mov_b32_e32 v62, v71
	v_mul_f32_e32 v84, v173, v2
	v_pk_mul_f32 v[2:3], v[62:63], v[74:75]
	v_mov_b32_e32 v70, v63
	v_sub_f32_e32 v2, v2, v3
	v_mul_f32_e32 v62, v173, v2
	v_pk_mul_f32 v[2:3], v[70:71], v[74:75]
	v_mov_b32_e32 v58, v67
	v_add_f32_e32 v2, v2, v3
	v_mov_b32_e32 v78, v7
	v_mul_f32_e32 v63, v173, v2
	v_pk_mul_f32 v[2:3], v[58:59], v[78:79]
	v_mov_b32_e32 v66, v59
	v_sub_f32_e32 v2, v2, v3
	v_mul_f32_e32 v58, v173, v2
	v_pk_mul_f32 v[2:3], v[66:67], v[78:79]
	v_mov_b32_e32 v6, v4
	v_add_f32_e32 v2, v2, v3
	v_mul_f32_e32 v59, v173, v2
	v_mov_b32_e32 v2, v72
	v_mov_b32_e32 v3, v64
	v_mov_b32_e32 v7, v76
	v_pk_mul_f32 v[2:3], v[2:3], v[6:7]
	v_mov_b32_e32 v76, v5
	v_sub_f32_e32 v2, v2, v3
	v_mul_f32_e32 v4, v173, v2
	v_mov_b32_e32 v2, v64
	v_mov_b32_e32 v3, v72
	v_pk_mul_f32 v[2:3], v[2:3], v[6:7]
	v_mov_b32_e32 v6, v8
	v_add_f32_e32 v2, v2, v3
	v_mul_f32_e32 v66, v173, v2
	v_mov_b32_e32 v2, v68
	v_mov_b32_e32 v3, v60
	v_mov_b32_e32 v7, v80
	v_pk_mul_f32 v[2:3], v[2:3], v[6:7]
	v_mov_b32_e32 v64, v73
	v_sub_f32_e32 v2, v2, v3
	v_mul_f32_e32 v8, v173, v2
	v_mov_b32_e32 v2, v60
	v_mov_b32_e32 v3, v68
	v_pk_mul_f32 v[2:3], v[2:3], v[6:7]
	v_mov_b32_e32 v72, v65
	v_add_f32_e32 v2, v2, v3
	v_mul_f32_e32 v67, v173, v2
	v_pk_mul_f32 v[2:3], v[64:65], v[76:77]
	v_mov_b32_e32 v60, v69
	v_sub_f32_e32 v2, v2, v3
	v_mul_f32_e32 v5, v173, v2
	v_pk_mul_f32 v[2:3], v[72:73], v[76:77]
	v_mov_b32_e32 v80, v9
	v_add_f32_e32 v2, v2, v3
	v_mul_f32_e32 v64, v173, v2
	v_pk_mul_f32 v[2:3], v[60:61], v[80:81]
	v_mov_b32_e32 v68, v61
	v_sub_f32_e32 v2, v2, v3
	v_mul_f32_e32 v9, v173, v2
	v_pk_mul_f32 v[2:3], v[68:69], v[80:81]
	v_mul_f32_e32 v0, v173, v0
	v_add_f32_e32 v2, v2, v3
	v_mul_f32_e32 v60, v173, v2
	v_lshlrev_b64 v[2:3], 11, v[82:83]
	v_lshl_add_u64 v[6:7], v[166:167], 0, v[2:3]
	v_cvt_pk_bf16_f32 v3, v4, v5
	v_cvt_pk_bf16_f32 v2, v0, v62
	v_cvt_pk_bf16_f32 v4, v89, v58
	v_cvt_pk_bf16_f32 v5, v8, v9
	global_store_dwordx4 v[6:7], v[2:5], off
	v_mov_b32_e32 v68, v54
	v_mov_b32_e32 v69, v46
	v_cvt_pk_bf16_f32 v3, v66, v64
	v_add_u32_e32 v66, 0x90, v164
	v_lshlrev_b32_e32 v0, 8, v66
	v_and_b32_e32 v0, 0xfdf00, v0
	v_cvt_pk_bf16_f32 v2, v88, v63
	v_cvt_pk_bf16_f32 v4, v84, v59
	v_cvt_pk_bf16_f32 v5, v67, v60
	global_store_dwordx4 v[6:7], v[2:5], off offset:128
	v_lshl_add_u64 v[6:7], v[154:155], 0, v[0:1]
	v_lshl_add_u64 v[62:63], v[156:157], 0, v[0:1]
	global_load_dwordx4 v[2:5], v[6:7], off
	s_nop 0
	global_load_dwordx4 v[6:9], v[6:7], off offset:16
	s_nop 0
	global_load_dwordx4 v[58:61], v[62:63], off
	s_nop 0
	global_load_dwordx4 v[62:65], v[62:63], off offset:16
	v_ashrrev_i32_e32 v67, 31, v66
	s_waitcnt vmcnt(0) lgkmcnt(0)
; __device__ __forceinline__ void st8(bf16_t* p, const float (&v)[8]) { u32x4 w; w.x = pk2(v[0], v[1]); w.y = pk2(v[2], v[3]); w.z = pk2(v[4], v[5]); w.w = pk2(v[6], v[7]); *(u32x4*)p = w; }
;     __device__ __forceinline__ void operator()(const f32x4 (&acc)[2][2][4][2], const Unit& u, int wr, int wc, int fr, int fq) const {
;     ...
;             bf16_t* dst = pn < 4 ? q : k; const float sc = pn < 4 ? QSCALE : 1.f;
;             const int head = (pn & 3) * 2 + (wc >> 1), i0 = 32 * (wc & 1) + 8 * fq;
; #pragma unroll
;             for (int ai = 0; ai < 2; ++ai)
; #pragma unroll
;                 for (int m = 0; m < 4; ++m) {
;                     const int row = row0 + ai * 128 + m * 16, pos = row & (SEQ - 1);
;                     const f32x4* cp = (const f32x4*)(cosT + pos * 64 + i0); const f32x4* sp = (const f32x4*)(sinT + pos * 64 + i0);
;                     const f32x4 c0 = cp[0], c1 = cp[1], s0 = sp[0], s1 = sp[1];
;                     float o1[8], o2[8];
; #pragma unroll
;                     for (int j = 0; j < 4; ++j) {
;                         const float a0 = acc[ai][0][m][0][j], b0 = acc[ai][1][m][0][j], a1 = acc[ai][0][m][1][j], b1 = acc[ai][1][m][1][j];
;                         o1[j] = (a0 * c0[j] - b0 * s0[j]) * sc; o2[j] = (b0 * c0[j] + a0 * s0[j]) * sc;
;                         o1[4 + j] = (a1 * c1[j] - b1 * s1[j]) * sc; o2[4 + j] = (b1 * c1[j] + a1 * s1[j]) * sc;
;                     }
;                     bf16_t* rp = dst + (size_t)row * AW + head * 128 + i0;
;                     st8(rp, o1); st8(rp + 64, o2);
	v_mov_b32_e32 v70, v2
	v_mov_b32_e32 v71, v58
	v_pk_mul_f32 v[68:69], v[68:69], v[70:71]
	v_mov_b32_e32 v58, v3
	v_sub_f32_e32 v0, v68, v69
	v_mov_b32_e32 v68, v46
	v_mov_b32_e32 v69, v54
	v_pk_mul_f32 v[68:69], v[68:69], v[70:71]
	v_mov_b32_e32 v70, v6
	v_add_f32_e32 v2, v68, v69
	v_mov_b32_e32 v68, v50
	v_mov_b32_e32 v69, v42
	v_mov_b32_e32 v71, v62
	v_pk_mul_f32 v[68:69], v[68:69], v[70:71]
	v_mul_f32_e32 v72, v173, v2
	v_sub_f32_e32 v2, v68, v69
	v_mov_b32_e32 v68, v42
	v_mov_b32_e32 v69, v50
	v_pk_mul_f32 v[68:69], v[68:69], v[70:71]
	v_mul_f32_e32 v73, v173, v2
	v_add_f32_e32 v2, v68, v69
	v_mov_b32_e32 v46, v55
	v_mul_f32_e32 v68, v173, v2
	v_pk_mul_f32 v[2:3], v[46:47], v[58:59]
	v_mov_b32_e32 v54, v47
	v_sub_f32_e32 v2, v2, v3
	v_mul_f32_e32 v46, v173, v2
	v_pk_mul_f32 v[2:3], v[54:55], v[58:59]
	v_mov_b32_e32 v42, v51
	v_add_f32_e32 v2, v2, v3
	v_mov_b32_e32 v62, v7
	v_mul_f32_e32 v47, v173, v2
	v_pk_mul_f32 v[2:3], v[42:43], v[62:63]
	v_mov_b32_e32 v50, v43
	v_sub_f32_e32 v2, v2, v3
	v_mul_f32_e32 v42, v173, v2
	v_pk_mul_f32 v[2:3], v[50:51], v[62:63]
	v_mov_b32_e32 v6, v4
	v_add_f32_e32 v2, v2, v3
	v_mul_f32_e32 v43, v173, v2
	v_mov_b32_e32 v2, v56
	v_mov_b32_e32 v3, v48
	v_mov_b32_e32 v7, v60
	v_pk_mul_f32 v[2:3], v[2:3], v[6:7]
	v_mov_b32_e32 v60, v5
	v_sub_f32_e32 v2, v2, v3
	v_mul_f32_e32 v4, v173, v2
	v_mov_b32_e32 v2, v48
	v_mov_b32_e32 v3, v56
	v_pk_mul_f32 v[2:3], v[2:3], v[6:7]
	v_mov_b32_e32 v6, v8
	v_add_f32_e32 v2, v2, v3
	v_mul_f32_e32 v50, v173, v2
	v_mov_b32_e32 v2, v52
	v_mov_b32_e32 v3, v44
	v_mov_b32_e32 v7, v64
	v_pk_mul_f32 v[2:3], v[2:3], v[6:7]
	v_mov_b32_e32 v48, v57
	v_sub_f32_e32 v2, v2, v3
	v_mul_f32_e32 v8, v173, v2
	v_mov_b32_e32 v2, v44
	v_mov_b32_e32 v3, v52
	v_pk_mul_f32 v[2:3], v[2:3], v[6:7]
	v_mov_b32_e32 v56, v49
	v_add_f32_e32 v2, v2, v3
	v_mul_f32_e32 v51, v173, v2
	v_pk_mul_f32 v[2:3], v[48:49], v[60:61]
	v_mov_b32_e32 v44, v53
	v_sub_f32_e32 v2, v2, v3
	v_mul_f32_e32 v5, v173, v2
	v_pk_mul_f32 v[2:3], v[56:57], v[60:61]
	v_mov_b32_e32 v64, v9
	v_add_f32_e32 v2, v2, v3
	v_mul_f32_e32 v48, v173, v2
	v_pk_mul_f32 v[2:3], v[44:45], v[64:65]
	v_mov_b32_e32 v52, v45
	v_sub_f32_e32 v2, v2, v3
	v_mul_f32_e32 v9, v173, v2
	v_pk_mul_f32 v[2:3], v[52:53], v[64:65]
	v_mul_f32_e32 v0, v173, v0
	v_add_f32_e32 v2, v2, v3
	v_mul_f32_e32 v44, v173, v2
	v_lshlrev_b64 v[2:3], 11, v[66:67]
	v_lshl_add_u64 v[6:7], v[166:167], 0, v[2:3]
	v_cvt_pk_bf16_f32 v3, v4, v5
	v_cvt_pk_bf16_f32 v2, v0, v46
	v_cvt_pk_bf16_f32 v4, v73, v42
	v_cvt_pk_bf16_f32 v5, v8, v9
	global_store_dwordx4 v[6:7], v[2:5], off
	v_mov_b32_e32 v52, v38
	v_mov_b32_e32 v53, v30
	v_cvt_pk_bf16_f32 v3, v50, v48
	v_add_u32_e32 v50, 0xa0, v164
	v_lshlrev_b32_e32 v0, 8, v50
	v_and_b32_e32 v0, 0xfef00, v0
	v_cvt_pk_bf16_f32 v2, v72, v47
	v_cvt_pk_bf16_f32 v4, v68, v43
	v_cvt_pk_bf16_f32 v5, v51, v44
	global_store_dwordx4 v[6:7], v[2:5], off offset:128
	v_lshl_add_u64 v[6:7], v[154:155], 0, v[0:1]
	v_lshl_add_u64 v[46:47], v[156:157], 0, v[0:1]
	global_load_dwordx4 v[2:5], v[6:7], off
	s_nop 0
	global_load_dwordx4 v[6:9], v[6:7], off offset:16
	s_nop 0
	global_load_dwordx4 v[42:45], v[46:47], off
	s_nop 0
	global_load_dwordx4 v[46:49], v[46:47], off offset:16
	v_ashrrev_i32_e32 v51, 31, v50
	s_waitcnt vmcnt(0) lgkmcnt(0)
; __device__ __forceinline__ void st8(bf16_t* p, const float (&v)[8]) { u32x4 w; w.x = pk2(v[0], v[1]); w.y = pk2(v[2], v[3]); w.z = pk2(v[4], v[5]); w.w = pk2(v[6], v[7]); *(u32x4*)p = w; }
;     __device__ __forceinline__ void operator()(const f32x4 (&acc)[2][2][4][2], const Unit& u, int wr, int wc, int fr, int fq) const {
;     ...
;             bf16_t* dst = pn < 4 ? q : k; const float sc = pn < 4 ? QSCALE : 1.f;
;             const int head = (pn & 3) * 2 + (wc >> 1), i0 = 32 * (wc & 1) + 8 * fq;
; #pragma unroll
;             for (int ai = 0; ai < 2; ++ai)
; #pragma unroll
;                 for (int m = 0; m < 4; ++m) {
;                     const int row = row0 + ai * 128 + m * 16, pos = row & (SEQ - 1);
;                     const f32x4* cp = (const f32x4*)(cosT + pos * 64 + i0); const f32x4* sp = (const f32x4*)(sinT + pos * 64 + i0);
;                     const f32x4 c0 = cp[0], c1 = cp[1], s0 = sp[0], s1 = sp[1];
;                     float o1[8], o2[8];
; #pragma unroll
;                     for (int j = 0; j < 4; ++j) {
;                         const float a0 = acc[ai][0][m][0][j], b0 = acc[ai][1][m][0][j], a1 = acc[ai][0][m][1][j], b1 = acc[ai][1][m][1][j];
;                         o1[j] = (a0 * c0[j] - b0 * s0[j]) * sc; o2[j] = (b0 * c0[j] + a0 * s0[j]) * sc;
;                         o1[4 + j] = (a1 * c1[j] - b1 * s1[j]) * sc; o2[4 + j] = (b1 * c1[j] + a1 * s1[j]) * sc;
;                     }
;                     bf16_t* rp = dst + (size_t)row * AW + head * 128 + i0;
;                     st8(rp, o1); st8(rp + 64, o2);
	v_mov_b32_e32 v54, v2
	v_mov_b32_e32 v55, v42
	v_pk_mul_f32 v[52:53], v[52:53], v[54:55]
	v_mov_b32_e32 v42, v3
	v_sub_f32_e32 v0, v52, v53
	v_mov_b32_e32 v52, v30
	v_mov_b32_e32 v53, v38
	v_pk_mul_f32 v[52:53], v[52:53], v[54:55]
	v_mov_b32_e32 v54, v6
	v_add_f32_e32 v2, v52, v53
	v_mov_b32_e32 v52, v34
	v_mov_b32_e32 v53, v26
	v_mov_b32_e32 v55, v46
	v_pk_mul_f32 v[52:53], v[52:53], v[54:55]
	v_mul_f32_e32 v56, v173, v2
	v_sub_f32_e32 v2, v52, v53
	v_mov_b32_e32 v52, v26
	v_mov_b32_e32 v53, v34
	v_pk_mul_f32 v[52:53], v[52:53], v[54:55]
	v_mul_f32_e32 v57, v173, v2
	v_add_f32_e32 v2, v52, v53
	v_mov_b32_e32 v30, v39
	v_mul_f32_e32 v52, v173, v2
	v_pk_mul_f32 v[2:3], v[30:31], v[42:43]
	v_mov_b32_e32 v38, v31
	v_sub_f32_e32 v2, v2, v3
	v_mul_f32_e32 v30, v173, v2
	v_pk_mul_f32 v[2:3], v[38:39], v[42:43]
	v_mov_b32_e32 v26, v35
	v_add_f32_e32 v2, v2, v3
	v_mov_b32_e32 v46, v7
	v_mul_f32_e32 v31, v173, v2
	v_pk_mul_f32 v[2:3], v[26:27], v[46:47]
	v_mov_b32_e32 v34, v27
	v_sub_f32_e32 v2, v2, v3
	v_mul_f32_e32 v26, v173, v2
	v_pk_mul_f32 v[2:3], v[34:35], v[46:47]
	v_mov_b32_e32 v6, v4
	v_add_f32_e32 v2, v2, v3
	v_mul_f32_e32 v27, v173, v2
	v_mov_b32_e32 v2, v40
	v_mov_b32_e32 v3, v32
	v_mov_b32_e32 v7, v44
	v_pk_mul_f32 v[2:3], v[2:3], v[6:7]
	v_mov_b32_e32 v44, v5
	v_sub_f32_e32 v2, v2, v3
	v_mul_f32_e32 v4, v173, v2
	v_mov_b32_e32 v2, v32
	v_mov_b32_e32 v3, v40
	v_pk_mul_f32 v[2:3], v[2:3], v[6:7]
	v_mov_b32_e32 v6, v8
	v_add_f32_e32 v2, v2, v3
	v_mul_f32_e32 v34, v173, v2
	v_mov_b32_e32 v2, v36
	v_mov_b32_e32 v3, v28
	v_mov_b32_e32 v7, v48
	v_pk_mul_f32 v[2:3], v[2:3], v[6:7]
	v_mov_b32_e32 v32, v41
	v_sub_f32_e32 v2, v2, v3
	v_mul_f32_e32 v8, v173, v2
	v_mov_b32_e32 v2, v28
	v_mov_b32_e32 v3, v36
	v_pk_mul_f32 v[2:3], v[2:3], v[6:7]
	v_mov_b32_e32 v40, v33
	v_add_f32_e32 v2, v2, v3
	v_mul_f32_e32 v35, v173, v2
	v_pk_mul_f32 v[2:3], v[32:33], v[44:45]
	v_mov_b32_e32 v28, v37
	v_sub_f32_e32 v2, v2, v3
	v_mul_f32_e32 v5, v173, v2
	v_pk_mul_f32 v[2:3], v[40:41], v[44:45]
	v_mov_b32_e32 v48, v9
	v_add_f32_e32 v2, v2, v3
	v_mul_f32_e32 v32, v173, v2
	v_pk_mul_f32 v[2:3], v[28:29], v[48:49]
	v_mov_b32_e32 v36, v29
	v_sub_f32_e32 v2, v2, v3
	v_mul_f32_e32 v9, v173, v2
	v_pk_mul_f32 v[2:3], v[36:37], v[48:49]
	v_mul_f32_e32 v0, v173, v0
	v_add_f32_e32 v2, v2, v3
	v_mul_f32_e32 v28, v173, v2
	v_lshlrev_b64 v[2:3], 11, v[50:51]
	v_lshl_add_u64 v[6:7], v[166:167], 0, v[2:3]
	v_cvt_pk_bf16_f32 v3, v4, v5
	v_cvt_pk_bf16_f32 v2, v0, v30
	v_cvt_pk_bf16_f32 v4, v57, v26
	v_cvt_pk_bf16_f32 v5, v8, v9
	global_store_dwordx4 v[6:7], v[2:5], off
	v_mov_b32_e32 v36, v22
	v_mov_b32_e32 v37, v14
	v_cvt_pk_bf16_f32 v3, v34, v32
	v_add_u32_e32 v34, 0xb0, v164
	v_lshlrev_b32_e32 v0, 8, v34
	v_and_b32_e32 v0, 0xfff00, v0
	v_cvt_pk_bf16_f32 v2, v56, v31
	v_cvt_pk_bf16_f32 v4, v52, v27
	v_cvt_pk_bf16_f32 v5, v35, v28
	global_store_dwordx4 v[6:7], v[2:5], off offset:128
	v_lshl_add_u64 v[6:7], v[154:155], 0, v[0:1]
	v_lshl_add_u64 v[30:31], v[156:157], 0, v[0:1]
	global_load_dwordx4 v[2:5], v[6:7], off
	s_nop 0
	global_load_dwordx4 v[6:9], v[6:7], off offset:16
	s_nop 0
	global_load_dwordx4 v[26:29], v[30:31], off
	s_nop 0
	global_load_dwordx4 v[30:33], v[30:31], off offset:16
	v_ashrrev_i32_e32 v35, 31, v34
	s_waitcnt vmcnt(0) lgkmcnt(0)
	v_mov_b32_e32 v38, v2
	v_mov_b32_e32 v39, v26
	v_pk_mul_f32 v[36:37], v[36:37], v[38:39]
	v_mov_b32_e32 v26, v3
	v_sub_f32_e32 v0, v36, v37
	v_mov_b32_e32 v36, v14
	v_mov_b32_e32 v37, v22
	v_pk_mul_f32 v[36:37], v[36:37], v[38:39]
	v_mov_b32_e32 v38, v6
	v_add_f32_e32 v2, v36, v37
	v_mov_b32_e32 v36, v18
	v_mov_b32_e32 v37, v10
	v_mov_b32_e32 v39, v30
	v_pk_mul_f32 v[36:37], v[36:37], v[38:39]
	v_mul_f32_e32 v40, v173, v2
	v_sub_f32_e32 v2, v36, v37
	v_mov_b32_e32 v36, v10
	v_mov_b32_e32 v37, v18
	v_pk_mul_f32 v[36:37], v[36:37], v[38:39]
	v_mul_f32_e32 v41, v173, v2
	v_add_f32_e32 v2, v36, v37
	v_mov_b32_e32 v14, v23
	v_mul_f32_e32 v36, v173, v2
	v_pk_mul_f32 v[2:3], v[14:15], v[26:27]
	v_mov_b32_e32 v22, v15
	v_sub_f32_e32 v2, v2, v3
	v_mul_f32_e32 v14, v173, v2
	v_pk_mul_f32 v[2:3], v[22:23], v[26:27]
	v_mov_b32_e32 v10, v19
	v_add_f32_e32 v2, v2, v3
	v_mov_b32_e32 v30, v7
	v_mul_f32_e32 v15, v173, v2
	v_pk_mul_f32 v[2:3], v[10:11], v[30:31]
	v_mov_b32_e32 v18, v11
	v_sub_f32_e32 v2, v2, v3
	v_mul_f32_e32 v10, v173, v2
	v_pk_mul_f32 v[2:3], v[18:19], v[30:31]
	v_mov_b32_e32 v6, v4
	v_add_f32_e32 v2, v2, v3
	v_mul_f32_e32 v11, v173, v2
	v_mov_b32_e32 v2, v24
	v_mov_b32_e32 v3, v16
	v_mov_b32_e32 v7, v28
	v_pk_mul_f32 v[2:3], v[2:3], v[6:7]
	v_mov_b32_e32 v28, v5
	v_sub_f32_e32 v2, v2, v3
	v_mul_f32_e32 v4, v173, v2
	v_mov_b32_e32 v2, v16
	v_mov_b32_e32 v3, v24
	v_pk_mul_f32 v[2:3], v[2:3], v[6:7]
	v_mov_b32_e32 v6, v8
	v_add_f32_e32 v2, v2, v3
	v_mul_f32_e32 v18, v173, v2
	v_mov_b32_e32 v2, v20
	v_mov_b32_e32 v3, v12
	v_mov_b32_e32 v7, v32
	v_pk_mul_f32 v[2:3], v[2:3], v[6:7]
	v_mov_b32_e32 v16, v25
	v_sub_f32_e32 v2, v2, v3
	v_mul_f32_e32 v8, v173, v2
	v_mov_b32_e32 v2, v12
	v_mov_b32_e32 v3, v20
	v_pk_mul_f32 v[2:3], v[2:3], v[6:7]
	v_mov_b32_e32 v24, v17
	v_add_f32_e32 v2, v2, v3
	v_mul_f32_e32 v19, v173, v2
	v_pk_mul_f32 v[2:3], v[16:17], v[28:29]
	v_mov_b32_e32 v12, v21
	v_sub_f32_e32 v2, v2, v3
	v_mul_f32_e32 v5, v173, v2
	v_pk_mul_f32 v[2:3], v[24:25], v[28:29]
	v_mov_b32_e32 v32, v9
	v_add_f32_e32 v2, v2, v3
	v_mul_f32_e32 v16, v173, v2
	v_pk_mul_f32 v[2:3], v[12:13], v[32:33]
	v_mov_b32_e32 v20, v13
	v_sub_f32_e32 v2, v2, v3
	v_mul_f32_e32 v9, v173, v2
	v_pk_mul_f32 v[2:3], v[20:21], v[32:33]
	v_mul_f32_e32 v0, v173, v0
	v_add_f32_e32 v2, v2, v3
	v_mul_f32_e32 v12, v173, v2
	v_lshlrev_b64 v[2:3], 11, v[34:35]
	v_lshl_add_u64 v[6:7], v[166:167], 0, v[2:3]
	v_cvt_pk_bf16_f32 v2, v0, v14
	v_cvt_pk_bf16_f32 v3, v4, v5
	v_cvt_pk_bf16_f32 v4, v41, v10
	v_cvt_pk_bf16_f32 v5, v8, v9
	global_store_dwordx4 v[6:7], v[2:5], off
	s_nop 1
	v_cvt_pk_bf16_f32 v2, v40, v15
	v_cvt_pk_bf16_f32 v3, v18, v16
	v_cvt_pk_bf16_f32 v4, v36, v11
	v_cvt_pk_bf16_f32 v5, v19, v12
	global_store_dwordx4 v[6:7], v[2:5], off offset:128
	s_andn2_b64 vcc, exec, s[40:41]
	s_mov_b64 s[12:13], -1
	s_cbranch_vccnz .LBB0_343
	s_branch .LBB0_747

; __device__ __forceinline__ float fexp2(float x) { return __builtin_amdgcn_exp2f(x); }
; __device__ __forceinline__ float frcp(float x) { return __builtin_amdgcn_rcpf(x); }
; __device__ __forceinline__ void st8(bf16_t* p, const float (&v)[8]) { u32x4 w; w.x = pk2(v[0], v[1]); w.y = pk2(v[2], v[3]); w.z = pk2(v[4], v[5]); w.w = pk2(v[6], v[7]); *(u32x4*)p = w; }
; __device__ __forceinline__ float silu_f(float x) { return x * frcp(1.f + fexp2(-1.4426950408889634f * x)); }
;     __device__ __forceinline__ void operator()(const f32x4 (&acc)[2][2][4][2], const Unit& u, int wr, int wc, int fr, int fq) const {
;     ...
;             const bool isp = wc < 2; bf16_t* dst = isp ? pp : gz; const int colt = (pn - 16) * 64 + (wc & 1) * 32 + 8 * fq;
; #pragma unroll
;             for (int ai = 0; ai < 2; ++ai)
; #pragma unroll
;                 for (int m = 0; m < 4; ++m) { float o[8];
; #pragma unroll
;                     for (int j = 0; j < 4; ++j) { const float a0 = acc[ai][0][m][0][j], b0 = acc[ai][1][m][0][j], a1 = acc[ai][0][m][1][j], b1 = acc[ai][1][m][1][j];
;                         o[j] = isp ? a0 * b0 : a0 * silu_f(b0); o[4 + j] = isp ? a1 * b1 : a1 * silu_f(b1); }
;                     st8(dst + (size_t)(row0 + ai * 128 + m * 16) * AW + colt, o); }
.LBB0_374:
	v_lshl_add_u32 v0, s72, 6, v170
	v_ashrrev_i32_e32 v165, 31, v164
	v_lshl_add_u64 v[138:139], v[0:1], 1, s[46:47]
	v_lshlrev_b64 v[140:141], 11, v[164:165]
	v_mul_f32_e32 v0, v133, v9
	v_lshl_add_u64 v[140:141], v[138:139], 0, v[140:141]
	v_cvt_pk_bf16_f32 v2, v2, v3
	v_cvt_pk_bf16_f32 v3, v6, v5
	v_cvt_pk_bf16_f32 v4, v4, v7
	v_cvt_pk_bf16_f32 v5, v8, v0
	s_and_b64 vcc, exec, s[42:43]
	s_mov_b64 s[12:13], -1
	global_store_dwordx4 v[140:141], v[2:5], off
	s_cbranch_vccnz .LBB0_376
	v_mul_f32_e32 v0, 0xbfb8aa3b, v110
	v_exp_f32_e32 v0, v0
	v_mul_f32_e32 v2, 0xbfb8aa3b, v106
	v_exp_f32_e32 v2, v2
	v_add_f32_e32 v0, 1.0, v0
	v_rcp_f32_e32 v0, v0
	v_add_f32_e32 v2, 1.0, v2
	v_rcp_f32_e32 v2, v2
	v_mul_f32_e32 v3, v110, v0
	v_mul_f32_e32 v0, v106, v2
	v_mul_f32_e32 v2, v118, v3
	s_cbranch_execnz .LBB0_378
	s_branch .LBB0_377

; __device__ __forceinline__ float fexp2(float x) { return __builtin_amdgcn_exp2f(x); }
; __device__ __forceinline__ float frcp(float x) { return __builtin_amdgcn_rcpf(x); }
; __device__ __forceinline__ void st8(bf16_t* p, const float (&v)[8]) { u32x4 w; w.x = pk2(v[0], v[1]); w.y = pk2(v[2], v[3]); w.z = pk2(v[4], v[5]); w.w = pk2(v[6], v[7]); *(u32x4*)p = w; }
; __device__ __forceinline__ float silu_f(float x) { return x * frcp(1.f + fexp2(-1.4426950408889634f * x)); }
;     __device__ __forceinline__ void operator()(const f32x4 (&acc)[2][2][4][2], const Unit& u, int wr, int wc, int fr, int fq) const {
;     ...
;             const bool isp = wc < 2; bf16_t* dst = isp ? pp : gz; const int colt = (pn - 16) * 64 + (wc & 1) * 32 + 8 * fq;
; #pragma unroll
;             for (int ai = 0; ai < 2; ++ai)
; #pragma unroll
;                 for (int m = 0; m < 4; ++m) { float o[8];
; #pragma unroll
;                     for (int j = 0; j < 4; ++j) { const float a0 = acc[ai][0][m][0][j], b0 = acc[ai][1][m][0][j], a1 = acc[ai][0][m][1][j], b1 = acc[ai][1][m][1][j];
;                         o[j] = isp ? a0 * b0 : a0 * silu_f(b0); o[4 + j] = isp ? a1 * b1 : a1 * silu_f(b1); }
;                     st8(dst + (size_t)(row0 + ai * 128 + m * 16) * AW + colt, o); }
.LBB0_390:
	v_or_b32_e32 v140, 16, v164
	v_ashrrev_i32_e32 v141, 31, v140
	v_lshlrev_b64 v[140:141], 11, v[140:141]
	v_mul_f32_e32 v0, v117, v0
	v_lshl_add_u64 v[140:141], v[138:139], 0, v[140:141]
	v_cvt_pk_bf16_f32 v2, v2, v3
	v_cvt_pk_bf16_f32 v3, v4, v5
	v_cvt_pk_bf16_f32 v4, v6, v7
	v_cvt_pk_bf16_f32 v5, v8, v0
	s_and_b64 vcc, exec, s[42:43]
	s_mov_b64 s[12:13], -1
	global_store_dwordx4 v[140:141], v[2:5], off
	s_cbranch_vccnz .LBB0_392
	v_mul_f32_e32 v0, 0xbfb8aa3b, v94
	v_exp_f32_e32 v0, v0
	v_mul_f32_e32 v2, 0xbfb8aa3b, v90
	v_exp_f32_e32 v2, v2
	v_add_f32_e32 v0, 1.0, v0
	v_rcp_f32_e32 v0, v0
	v_add_f32_e32 v2, 1.0, v2
	v_rcp_f32_e32 v2, v2
	v_mul_f32_e32 v3, v94, v0
	v_mul_f32_e32 v0, v90, v2
	v_mul_f32_e32 v2, v102, v3
	s_cbranch_execnz .LBB0_394
	s_branch .LBB0_393

; __device__ __forceinline__ float fexp2(float x) { return __builtin_amdgcn_exp2f(x); }
; __device__ __forceinline__ float frcp(float x) { return __builtin_amdgcn_rcpf(x); }
; __device__ __forceinline__ void st8(bf16_t* p, const float (&v)[8]) { u32x4 w; w.x = pk2(v[0], v[1]); w.y = pk2(v[2], v[3]); w.z = pk2(v[4], v[5]); w.w = pk2(v[6], v[7]); *(u32x4*)p = w; }
; __device__ __forceinline__ float silu_f(float x) { return x * frcp(1.f + fexp2(-1.4426950408889634f * x)); }
;     __device__ __forceinline__ void operator()(const f32x4 (&acc)[2][2][4][2], const Unit& u, int wr, int wc, int fr, int fq) const {
;     ...
;             const bool isp = wc < 2; bf16_t* dst = isp ? pp : gz; const int colt = (pn - 16) * 64 + (wc & 1) * 32 + 8 * fq;
; #pragma unroll
;             for (int ai = 0; ai < 2; ++ai)
; #pragma unroll
;                 for (int m = 0; m < 4; ++m) { float o[8];
; #pragma unroll
;                     for (int j = 0; j < 4; ++j) { const float a0 = acc[ai][0][m][0][j], b0 = acc[ai][1][m][0][j], a1 = acc[ai][0][m][1][j], b1 = acc[ai][1][m][1][j];
;                         o[j] = isp ? a0 * b0 : a0 * silu_f(b0); o[4 + j] = isp ? a1 * b1 : a1 * silu_f(b1); }
;                     st8(dst + (size_t)(row0 + ai * 128 + m * 16) * AW + colt, o); }
.LBB0_406:
	v_or_b32_e32 v140, 32, v164
	v_ashrrev_i32_e32 v141, 31, v140
	v_lshlrev_b64 v[140:141], 11, v[140:141]
	v_mul_f32_e32 v0, v101, v0
	v_lshl_add_u64 v[140:141], v[138:139], 0, v[140:141]
	v_cvt_pk_bf16_f32 v2, v2, v3
	v_cvt_pk_bf16_f32 v3, v4, v5
	v_cvt_pk_bf16_f32 v4, v6, v7
	v_cvt_pk_bf16_f32 v5, v8, v0
	s_and_b64 vcc, exec, s[42:43]
	s_mov_b64 s[12:13], -1
	global_store_dwordx4 v[140:141], v[2:5], off
	s_cbranch_vccnz .LBB0_408
	v_mul_f32_e32 v0, 0xbfb8aa3b, v78
	v_exp_f32_e32 v0, v0
	v_mul_f32_e32 v2, 0xbfb8aa3b, v74
	v_exp_f32_e32 v2, v2
	v_add_f32_e32 v0, 1.0, v0
	v_rcp_f32_e32 v0, v0
	v_add_f32_e32 v2, 1.0, v2
	v_rcp_f32_e32 v2, v2
	v_mul_f32_e32 v3, v78, v0
	v_mul_f32_e32 v0, v74, v2
	v_mul_f32_e32 v2, v86, v3
	s_cbranch_execnz .LBB0_410
	s_branch .LBB0_409

; __device__ __forceinline__ float fexp2(float x) { return __builtin_amdgcn_exp2f(x); }
; __device__ __forceinline__ float frcp(float x) { return __builtin_amdgcn_rcpf(x); }
; __device__ __forceinline__ void st8(bf16_t* p, const float (&v)[8]) { u32x4 w; w.x = pk2(v[0], v[1]); w.y = pk2(v[2], v[3]); w.z = pk2(v[4], v[5]); w.w = pk2(v[6], v[7]); *(u32x4*)p = w; }
; __device__ __forceinline__ float silu_f(float x) { return x * frcp(1.f + fexp2(-1.4426950408889634f * x)); }
;     __device__ __forceinline__ void operator()(const f32x4 (&acc)[2][2][4][2], const Unit& u, int wr, int wc, int fr, int fq) const {
;     ...
;             const bool isp = wc < 2; bf16_t* dst = isp ? pp : gz; const int colt = (pn - 16) * 64 + (wc & 1) * 32 + 8 * fq;
; #pragma unroll
;             for (int ai = 0; ai < 2; ++ai)
; #pragma unroll
;                 for (int m = 0; m < 4; ++m) { float o[8];
; #pragma unroll
;                     for (int j = 0; j < 4; ++j) { const float a0 = acc[ai][0][m][0][j], b0 = acc[ai][1][m][0][j], a1 = acc[ai][0][m][1][j], b1 = acc[ai][1][m][1][j];
;                         o[j] = isp ? a0 * b0 : a0 * silu_f(b0); o[4 + j] = isp ? a1 * b1 : a1 * silu_f(b1); }
;                     st8(dst + (size_t)(row0 + ai * 128 + m * 16) * AW + colt, o); }
.LBB0_422:
	v_or_b32_e32 v140, 48, v164
	v_ashrrev_i32_e32 v141, 31, v140
	v_lshlrev_b64 v[140:141], 11, v[140:141]
	v_mul_f32_e32 v0, v85, v0
	v_lshl_add_u64 v[140:141], v[138:139], 0, v[140:141]
	v_cvt_pk_bf16_f32 v2, v2, v3
	v_cvt_pk_bf16_f32 v3, v4, v5
	v_cvt_pk_bf16_f32 v4, v6, v7
	v_cvt_pk_bf16_f32 v5, v8, v0
	s_and_b64 vcc, exec, s[42:43]
	s_mov_b64 s[12:13], -1
	global_store_dwordx4 v[140:141], v[2:5], off
	s_cbranch_vccnz .LBB0_424
	v_mul_f32_e32 v0, 0xbfb8aa3b, v62
	v_exp_f32_e32 v0, v0
	v_mul_f32_e32 v2, 0xbfb8aa3b, v58
	v_exp_f32_e32 v2, v2
	v_add_f32_e32 v0, 1.0, v0
	v_rcp_f32_e32 v0, v0
	v_add_f32_e32 v2, 1.0, v2
	v_rcp_f32_e32 v2, v2
	v_mul_f32_e32 v3, v62, v0
	v_mul_f32_e32 v0, v58, v2
	v_mul_f32_e32 v2, v70, v3
	s_cbranch_execnz .LBB0_426
	s_branch .LBB0_425

; __device__ __forceinline__ float fexp2(float x) { return __builtin_amdgcn_exp2f(x); }
; __device__ __forceinline__ float frcp(float x) { return __builtin_amdgcn_rcpf(x); }
; __device__ __forceinline__ void st8(bf16_t* p, const float (&v)[8]) { u32x4 w; w.x = pk2(v[0], v[1]); w.y = pk2(v[2], v[3]); w.z = pk2(v[4], v[5]); w.w = pk2(v[6], v[7]); *(u32x4*)p = w; }
; __device__ __forceinline__ float silu_f(float x) { return x * frcp(1.f + fexp2(-1.4426950408889634f * x)); }
;     __device__ __forceinline__ void operator()(const f32x4 (&acc)[2][2][4][2], const Unit& u, int wr, int wc, int fr, int fq) const {
;     ...
;             const bool isp = wc < 2; bf16_t* dst = isp ? pp : gz; const int colt = (pn - 16) * 64 + (wc & 1) * 32 + 8 * fq;
; #pragma unroll
;             for (int ai = 0; ai < 2; ++ai)
; #pragma unroll
;                 for (int m = 0; m < 4; ++m) { float o[8];
; #pragma unroll
;                     for (int j = 0; j < 4; ++j) { const float a0 = acc[ai][0][m][0][j], b0 = acc[ai][1][m][0][j], a1 = acc[ai][0][m][1][j], b1 = acc[ai][1][m][1][j];
;                         o[j] = isp ? a0 * b0 : a0 * silu_f(b0); o[4 + j] = isp ? a1 * b1 : a1 * silu_f(b1); }
;                     st8(dst + (size_t)(row0 + ai * 128 + m * 16) * AW + colt, o); }
.LBB0_438:
	v_lshlrev_b64 v[140:141], 11, v[164:165]
	v_lshl_add_u64 v[140:141], v[138:139], 0, v[140:141]
	v_cvt_pk_bf16_f32 v2, v2, v3
	v_cvt_pk_bf16_f32 v3, v4, v5
	v_cvt_pk_bf16_f32 v4, v6, v7
	v_add_co_u32_e32 v6, vcc, 0x40000, v140
	v_mul_f32_e32 v0, v69, v0
	s_nop 0
	v_addc_co_u32_e32 v7, vcc, 0, v141, vcc
	v_cvt_pk_bf16_f32 v5, v8, v0
	s_and_b64 vcc, exec, s[42:43]
	s_mov_b64 s[12:13], -1
	global_store_dwordx4 v[6:7], v[2:5], off
	s_cbranch_vccnz .LBB0_440
	v_mul_f32_e32 v0, 0xbfb8aa3b, v46
	v_exp_f32_e32 v0, v0
	v_mul_f32_e32 v2, 0xbfb8aa3b, v42
	v_exp_f32_e32 v2, v2
	v_add_f32_e32 v0, 1.0, v0
	v_rcp_f32_e32 v0, v0
	v_add_f32_e32 v2, 1.0, v2
	v_rcp_f32_e32 v2, v2
	v_mul_f32_e32 v3, v46, v0
	v_mul_f32_e32 v0, v42, v2
	v_mul_f32_e32 v2, v54, v3
	s_cbranch_execnz .LBB0_442
	s_branch .LBB0_441

; __device__ __forceinline__ float fexp2(float x) { return __builtin_amdgcn_exp2f(x); }
; __device__ __forceinline__ float frcp(float x) { return __builtin_amdgcn_rcpf(x); }
; __device__ __forceinline__ void st8(bf16_t* p, const float (&v)[8]) { u32x4 w; w.x = pk2(v[0], v[1]); w.y = pk2(v[2], v[3]); w.z = pk2(v[4], v[5]); w.w = pk2(v[6], v[7]); *(u32x4*)p = w; }
; __device__ __forceinline__ float silu_f(float x) { return x * frcp(1.f + fexp2(-1.4426950408889634f * x)); }
;     __device__ __forceinline__ void operator()(const f32x4 (&acc)[2][2][4][2], const Unit& u, int wr, int wc, int fr, int fq) const {
;     ...
;             const bool isp = wc < 2; bf16_t* dst = isp ? pp : gz; const int colt = (pn - 16) * 64 + (wc & 1) * 32 + 8 * fq;
; #pragma unroll
;             for (int ai = 0; ai < 2; ++ai)
; #pragma unroll
;                 for (int m = 0; m < 4; ++m) { float o[8];
; #pragma unroll
;                     for (int j = 0; j < 4; ++j) { const float a0 = acc[ai][0][m][0][j], b0 = acc[ai][1][m][0][j], a1 = acc[ai][0][m][1][j], b1 = acc[ai][1][m][1][j];
;                         o[j] = isp ? a0 * b0 : a0 * silu_f(b0); o[4 + j] = isp ? a1 * b1 : a1 * silu_f(b1); }
;                     st8(dst + (size_t)(row0 + ai * 128 + m * 16) * AW + colt, o); }
.LBB0_454:
	v_lshlrev_b64 v[140:141], 11, v[164:165]
	v_lshl_add_u64 v[140:141], v[138:139], 0, v[140:141]
	v_cvt_pk_bf16_f32 v2, v2, v3
	v_cvt_pk_bf16_f32 v3, v4, v5
	v_cvt_pk_bf16_f32 v4, v6, v7
	v_add_co_u32_e32 v6, vcc, 0x48000, v140
	v_mul_f32_e32 v0, v53, v0
	s_nop 0
	v_addc_co_u32_e32 v7, vcc, 0, v141, vcc
	v_cvt_pk_bf16_f32 v5, v8, v0
	s_and_b64 vcc, exec, s[42:43]
	s_mov_b64 s[12:13], -1
	global_store_dwordx4 v[6:7], v[2:5], off
	s_cbranch_vccnz .LBB0_456
	v_mul_f32_e32 v0, 0xbfb8aa3b, v30
	v_exp_f32_e32 v0, v0
	v_mul_f32_e32 v2, 0xbfb8aa3b, v26
	v_exp_f32_e32 v2, v2
	v_add_f32_e32 v0, 1.0, v0
	v_rcp_f32_e32 v0, v0
	v_add_f32_e32 v2, 1.0, v2
	v_rcp_f32_e32 v2, v2
	v_mul_f32_e32 v3, v30, v0
	v_mul_f32_e32 v0, v26, v2
	v_mul_f32_e32 v2, v38, v3
	s_cbranch_execnz .LBB0_458
	s_branch .LBB0_457

; __device__ __forceinline__ float fexp2(float x) { return __builtin_amdgcn_exp2f(x); }
; __device__ __forceinline__ float frcp(float x) { return __builtin_amdgcn_rcpf(x); }
; __device__ __forceinline__ void st8(bf16_t* p, const float (&v)[8]) { u32x4 w; w.x = pk2(v[0], v[1]); w.y = pk2(v[2], v[3]); w.z = pk2(v[4], v[5]); w.w = pk2(v[6], v[7]); *(u32x4*)p = w; }
; __device__ __forceinline__ float silu_f(float x) { return x * frcp(1.f + fexp2(-1.4426950408889634f * x)); }
;     __device__ __forceinline__ void operator()(const f32x4 (&acc)[2][2][4][2], const Unit& u, int wr, int wc, int fr, int fq) const {
;     ...
;             const bool isp = wc < 2; bf16_t* dst = isp ? pp : gz; const int colt = (pn - 16) * 64 + (wc & 1) * 32 + 8 * fq;
; #pragma unroll
;             for (int ai = 0; ai < 2; ++ai)
; #pragma unroll
;                 for (int m = 0; m < 4; ++m) { float o[8];
; #pragma unroll
;                     for (int j = 0; j < 4; ++j) { const float a0 = acc[ai][0][m][0][j], b0 = acc[ai][1][m][0][j], a1 = acc[ai][0][m][1][j], b1 = acc[ai][1][m][1][j];
;                         o[j] = isp ? a0 * b0 : a0 * silu_f(b0); o[4 + j] = isp ? a1 * b1 : a1 * silu_f(b1); }
;                     st8(dst + (size_t)(row0 + ai * 128 + m * 16) * AW + colt, o); }
.LBB0_470:
	v_lshlrev_b64 v[140:141], 11, v[164:165]
	v_lshl_add_u64 v[140:141], v[138:139], 0, v[140:141]
	v_cvt_pk_bf16_f32 v2, v2, v3
	v_cvt_pk_bf16_f32 v3, v4, v5
	v_cvt_pk_bf16_f32 v4, v6, v7
	v_add_co_u32_e32 v6, vcc, 0x50000, v140
	v_mul_f32_e32 v0, v37, v0
	s_nop 0
	v_addc_co_u32_e32 v7, vcc, 0, v141, vcc
	v_cvt_pk_bf16_f32 v5, v8, v0
	s_and_b64 vcc, exec, s[42:43]
	s_mov_b64 s[12:13], -1
	global_store_dwordx4 v[6:7], v[2:5], off
	s_cbranch_vccnz .LBB0_472
	v_mul_f32_e32 v0, 0xbfb8aa3b, v14
	v_exp_f32_e32 v0, v0
	v_mul_f32_e32 v2, 0xbfb8aa3b, v10
	v_exp_f32_e32 v2, v2
	v_add_f32_e32 v0, 1.0, v0
	v_rcp_f32_e32 v0, v0
	v_add_f32_e32 v2, 1.0, v2
	v_rcp_f32_e32 v2, v2
	v_mul_f32_e32 v3, v14, v0
	v_mul_f32_e32 v0, v10, v2
	v_mul_f32_e32 v2, v22, v3
	s_cbranch_execnz .LBB0_474
	s_branch .LBB0_473

; __device__ __forceinline__ float fexp2(float x) { return __builtin_amdgcn_exp2f(x); }
; __device__ __forceinline__ float frcp(float x) { return __builtin_amdgcn_rcpf(x); }
; __device__ __forceinline__ void st8(bf16_t* p, const float (&v)[8]) { u32x4 w; w.x = pk2(v[0], v[1]); w.y = pk2(v[2], v[3]); w.z = pk2(v[4], v[5]); w.w = pk2(v[6], v[7]); *(u32x4*)p = w; }
; __device__ __forceinline__ float silu_f(float x) { return x * frcp(1.f + fexp2(-1.4426950408889634f * x)); }
;     __device__ __forceinline__ void operator()(const f32x4 (&acc)[2][2][4][2], const Unit& u, int wr, int wc, int fr, int fq) const {
;     ...
;             const bool isp = wc < 2; bf16_t* dst = isp ? pp : gz; const int colt = (pn - 16) * 64 + (wc & 1) * 32 + 8 * fq;
; #pragma unroll
;             for (int ai = 0; ai < 2; ++ai)
; #pragma unroll
;                 for (int m = 0; m < 4; ++m) { float o[8];
; #pragma unroll
;                     for (int j = 0; j < 4; ++j) { const float a0 = acc[ai][0][m][0][j], b0 = acc[ai][1][m][0][j], a1 = acc[ai][0][m][1][j], b1 = acc[ai][1][m][1][j];
;                         o[j] = isp ? a0 * b0 : a0 * silu_f(b0); o[4 + j] = isp ? a1 * b1 : a1 * silu_f(b1); }
;                     st8(dst + (size_t)(row0 + ai * 128 + m * 16) * AW + colt, o); }
.LBB0_486:
	v_lshlrev_b64 v[140:141], 11, v[164:165]
	v_lshl_add_u64 v[138:139], v[138:139], 0, v[140:141]
	v_cvt_pk_bf16_f32 v2, v2, v3
	v_cvt_pk_bf16_f32 v3, v4, v5
	v_cvt_pk_bf16_f32 v4, v6, v7
	v_add_co_u32_e32 v6, vcc, 0x58000, v138
	v_mul_f32_e32 v0, v21, v0
	s_nop 0
	v_addc_co_u32_e32 v7, vcc, 0, v139, vcc
	v_cvt_pk_bf16_f32 v5, v8, v0
	global_store_dwordx4 v[6:7], v[2:5], off
	s_mov_b64 s[12:13], 0

; __device__ __forceinline__ float fexp2(float x) { return __builtin_amdgcn_exp2f(x); }
; __device__ __forceinline__ float frcp(float x) { return __builtin_amdgcn_rcpf(x); }
; __device__ __forceinline__ void st8(bf16_t* p, const float (&v)[8]) { u32x4 w; w.x = pk2(v[0], v[1]); w.y = pk2(v[2], v[3]); w.z = pk2(v[4], v[5]); w.w = pk2(v[6], v[7]); *(u32x4*)p = w; }
; __device__ __forceinline__ float silu_f(float x) { return x * frcp(1.f + fexp2(-1.4426950408889634f * x)); }
;     __device__ __forceinline__ void operator()(const f32x4 (&acc)[2][2][4][2], const Unit& u, int wr, int wc, int fr, int fq) const {
;     ...
;             const bool isv = pn < 12; bf16_t* dst = isv ? v : sza; const int colt = (pn & 3) * 256 + wc * 32 + 8 * fq;
; #pragma unroll
;             for (int ai = 0; ai < 2; ++ai)
; #pragma unroll
;                 for (int m = 0; m < 4; ++m) {
;                     bf16_t* rp = dst + (size_t)(row0 + ai * 128 + m * 16) * AW + colt;
; #pragma unroll
;                     for (int bj = 0; bj < 2; ++bj) { float o[8];
; #pragma unroll
;                         for (int j = 0; j < 4; ++j) { const float a = acc[ai][bj][m][0][j], b = acc[ai][bj][m][1][j]; o[j] = isv ? a : silu_f(a); o[4 + j] = isv ? b : silu_f(b); }
;                         st8(rp + bj * 128, o); }
.LBB0_504:
	s_and_b64 s[2:3], exec, s[12:13]
	s_mov_b32 s2, 0x116e4000
	s_cselect_b32 s2, s2, 0x136e4000
	s_add_u32 s2, s22, s2
	s_addc_u32 s3, s23, 0
	s_lshl_b32 s4, s72, 8
	s_and_b32 s4, s4, 0x300
	v_or_b32_e32 v0, s4, v171
	v_lshlrev_b32_e32 v0, 1, v0
	v_ashrrev_i32_e32 v165, 31, v164
	v_lshl_add_u64 v[2:3], s[2:3], 0, v[0:1]
	v_lshlrev_b64 v[4:5], 11, v[164:165]
	v_lshl_add_u64 v[4:5], v[2:3], 0, v[4:5]
	s_and_b64 vcc, exec, s[42:43]
	s_mov_b64 s[12:13], -1
	v_cvt_pk_bf16_f32 v142, v7, v9
	v_cvt_pk_bf16_f32 v143, v139, v141
	v_cvt_pk_bf16_f32 v144, v6, v8
	v_cvt_pk_bf16_f32 v145, v138, v140
	global_store_dwordx4 v[4:5], v[142:145], off
	s_cbranch_vccnz .LBB0_506
	v_mul_f32_e32 v0, 0xbfb8aa3b, v126
	v_mul_f32_e32 v6, 0xbfb8aa3b, v122
	v_exp_f32_e32 v0, v0
	v_exp_f32_e32 v6, v6
	v_add_f32_e32 v0, 1.0, v0
	v_add_f32_e32 v6, 1.0, v6
	v_rcp_f32_e32 v0, v0
	v_rcp_f32_e32 v7, v6
	v_mul_f32_e32 v6, v126, v0
	v_mul_f32_e32 v0, v122, v7
	s_cbranch_execnz .LBB0_508
	s_branch .LBB0_507

; __device__ __forceinline__ float fexp2(float x) { return __builtin_amdgcn_exp2f(x); }
; __device__ __forceinline__ float frcp(float x) { return __builtin_amdgcn_rcpf(x); }
; __device__ __forceinline__ void st8(bf16_t* p, const float (&v)[8]) { u32x4 w; w.x = pk2(v[0], v[1]); w.y = pk2(v[2], v[3]); w.z = pk2(v[4], v[5]); w.w = pk2(v[6], v[7]); *(u32x4*)p = w; }
; __device__ __forceinline__ float silu_f(float x) { return x * frcp(1.f + fexp2(-1.4426950408889634f * x)); }
;     __device__ __forceinline__ void operator()(const f32x4 (&acc)[2][2][4][2], const Unit& u, int wr, int wc, int fr, int fq) const {
;     ...
;             const bool isv = pn < 12; bf16_t* dst = isv ? v : sza; const int colt = (pn & 3) * 256 + wc * 32 + 8 * fq;
; #pragma unroll
;             for (int ai = 0; ai < 2; ++ai)
; #pragma unroll
;                 for (int m = 0; m < 4; ++m) {
;                     bf16_t* rp = dst + (size_t)(row0 + ai * 128 + m * 16) * AW + colt;
; #pragma unroll
;                     for (int bj = 0; bj < 2; ++bj) { float o[8];
; #pragma unroll
;                         for (int j = 0; j < 4; ++j) { const float a = acc[ai][bj][m][0][j], b = acc[ai][bj][m][1][j]; o[j] = isv ? a : silu_f(a); o[4 + j] = isv ? b : silu_f(b); }
;                         st8(rp + bj * 128, o); }
.LBB0_520:
	s_and_b64 vcc, exec, s[42:43]
	s_mov_b64 s[12:13], -1
	v_cvt_pk_bf16_f32 v142, v6, v8
	v_cvt_pk_bf16_f32 v143, v138, v140
	v_cvt_pk_bf16_f32 v144, v0, v7
	v_cvt_pk_bf16_f32 v145, v9, v139
	global_store_dwordx4 v[4:5], v[142:145], off offset:256
	s_cbranch_vccnz .LBB0_522
	v_mul_f32_e32 v0, 0xbfb8aa3b, v118
	v_mul_f32_e32 v4, 0xbfb8aa3b, v114
	v_exp_f32_e32 v0, v0
	v_exp_f32_e32 v4, v4
	v_add_f32_e32 v0, 1.0, v0
	v_add_f32_e32 v4, 1.0, v4
	v_rcp_f32_e32 v0, v0
	v_rcp_f32_e32 v4, v4
	v_mul_f32_e32 v6, v118, v0
	v_mul_f32_e32 v0, v114, v4
	s_cbranch_execnz .LBB0_524
	s_branch .LBB0_523

; __device__ __forceinline__ float fexp2(float x) { return __builtin_amdgcn_exp2f(x); }
; __device__ __forceinline__ float frcp(float x) { return __builtin_amdgcn_rcpf(x); }
; __device__ __forceinline__ void st8(bf16_t* p, const float (&v)[8]) { u32x4 w; w.x = pk2(v[0], v[1]); w.y = pk2(v[2], v[3]); w.z = pk2(v[4], v[5]); w.w = pk2(v[6], v[7]); *(u32x4*)p = w; }
; __device__ __forceinline__ float silu_f(float x) { return x * frcp(1.f + fexp2(-1.4426950408889634f * x)); }
;     __device__ __forceinline__ void operator()(const f32x4 (&acc)[2][2][4][2], const Unit& u, int wr, int wc, int fr, int fq) const {
;     ...
;             const bool isv = pn < 12; bf16_t* dst = isv ? v : sza; const int colt = (pn & 3) * 256 + wc * 32 + 8 * fq;
; #pragma unroll
;             for (int ai = 0; ai < 2; ++ai)
; #pragma unroll
;                 for (int m = 0; m < 4; ++m) {
;                     bf16_t* rp = dst + (size_t)(row0 + ai * 128 + m * 16) * AW + colt;
; #pragma unroll
;                     for (int bj = 0; bj < 2; ++bj) { float o[8];
; #pragma unroll
;                         for (int j = 0; j < 4; ++j) { const float a = acc[ai][bj][m][0][j], b = acc[ai][bj][m][1][j]; o[j] = isv ? a : silu_f(a); o[4 + j] = isv ? b : silu_f(b); }
;                         st8(rp + bj * 128, o); }
.LBB0_536:
	v_or_b32_e32 v4, 16, v164
	v_ashrrev_i32_e32 v5, 31, v4
	v_lshlrev_b64 v[4:5], 11, v[4:5]
	v_lshl_add_u64 v[4:5], v[2:3], 0, v[4:5]
	s_and_b64 vcc, exec, s[42:43]
	s_mov_b64 s[12:13], -1
	v_cvt_pk_bf16_f32 v142, v6, v8
	v_cvt_pk_bf16_f32 v143, v138, v140
	v_cvt_pk_bf16_f32 v144, v0, v7
	v_cvt_pk_bf16_f32 v145, v9, v139
	global_store_dwordx4 v[4:5], v[142:145], off
	s_cbranch_vccnz .LBB0_538
	v_mul_f32_e32 v0, 0xbfb8aa3b, v110
	v_mul_f32_e32 v6, 0xbfb8aa3b, v106
	v_exp_f32_e32 v0, v0
	v_exp_f32_e32 v6, v6
	v_add_f32_e32 v0, 1.0, v0
	v_add_f32_e32 v6, 1.0, v6
	v_rcp_f32_e32 v0, v0
	v_rcp_f32_e32 v7, v6
	v_mul_f32_e32 v6, v110, v0
	v_mul_f32_e32 v0, v106, v7
	s_cbranch_execnz .LBB0_540
	s_branch .LBB0_539

; __device__ __forceinline__ float fexp2(float x) { return __builtin_amdgcn_exp2f(x); }
; __device__ __forceinline__ float frcp(float x) { return __builtin_amdgcn_rcpf(x); }
; __device__ __forceinline__ void st8(bf16_t* p, const float (&v)[8]) { u32x4 w; w.x = pk2(v[0], v[1]); w.y = pk2(v[2], v[3]); w.z = pk2(v[4], v[5]); w.w = pk2(v[6], v[7]); *(u32x4*)p = w; }
; __device__ __forceinline__ float silu_f(float x) { return x * frcp(1.f + fexp2(-1.4426950408889634f * x)); }
;     __device__ __forceinline__ void operator()(const f32x4 (&acc)[2][2][4][2], const Unit& u, int wr, int wc, int fr, int fq) const {
;     ...
;             const bool isv = pn < 12; bf16_t* dst = isv ? v : sza; const int colt = (pn & 3) * 256 + wc * 32 + 8 * fq;
; #pragma unroll
;             for (int ai = 0; ai < 2; ++ai)
; #pragma unroll
;                 for (int m = 0; m < 4; ++m) {
;                     bf16_t* rp = dst + (size_t)(row0 + ai * 128 + m * 16) * AW + colt;
; #pragma unroll
;                     for (int bj = 0; bj < 2; ++bj) { float o[8];
; #pragma unroll
;                         for (int j = 0; j < 4; ++j) { const float a = acc[ai][bj][m][0][j], b = acc[ai][bj][m][1][j]; o[j] = isv ? a : silu_f(a); o[4 + j] = isv ? b : silu_f(b); }
;                         st8(rp + bj * 128, o); }
.LBB0_552:
	s_and_b64 vcc, exec, s[42:43]
	s_mov_b64 s[12:13], -1
	v_cvt_pk_bf16_f32 v142, v6, v8
	v_cvt_pk_bf16_f32 v143, v138, v140
	v_cvt_pk_bf16_f32 v144, v0, v7
	v_cvt_pk_bf16_f32 v145, v9, v139
	global_store_dwordx4 v[4:5], v[142:145], off offset:256
	s_cbranch_vccnz .LBB0_554
	v_mul_f32_e32 v0, 0xbfb8aa3b, v102
	v_mul_f32_e32 v4, 0xbfb8aa3b, v98
	v_exp_f32_e32 v0, v0
	v_exp_f32_e32 v4, v4
	v_add_f32_e32 v0, 1.0, v0
	v_add_f32_e32 v4, 1.0, v4
	v_rcp_f32_e32 v0, v0
	v_rcp_f32_e32 v4, v4
	v_mul_f32_e32 v6, v102, v0
	v_mul_f32_e32 v0, v98, v4
	s_cbranch_execnz .LBB0_556
	s_branch .LBB0_555

; __device__ __forceinline__ float fexp2(float x) { return __builtin_amdgcn_exp2f(x); }
; __device__ __forceinline__ float frcp(float x) { return __builtin_amdgcn_rcpf(x); }
; __device__ __forceinline__ void st8(bf16_t* p, const float (&v)[8]) { u32x4 w; w.x = pk2(v[0], v[1]); w.y = pk2(v[2], v[3]); w.z = pk2(v[4], v[5]); w.w = pk2(v[6], v[7]); *(u32x4*)p = w; }
; __device__ __forceinline__ float silu_f(float x) { return x * frcp(1.f + fexp2(-1.4426950408889634f * x)); }
;     __device__ __forceinline__ void operator()(const f32x4 (&acc)[2][2][4][2], const Unit& u, int wr, int wc, int fr, int fq) const {
;     ...
;             const bool isv = pn < 12; bf16_t* dst = isv ? v : sza; const int colt = (pn & 3) * 256 + wc * 32 + 8 * fq;
; #pragma unroll
;             for (int ai = 0; ai < 2; ++ai)
; #pragma unroll
;                 for (int m = 0; m < 4; ++m) {
;                     bf16_t* rp = dst + (size_t)(row0 + ai * 128 + m * 16) * AW + colt;
; #pragma unroll
;                     for (int bj = 0; bj < 2; ++bj) { float o[8];
; #pragma unroll
;                         for (int j = 0; j < 4; ++j) { const float a = acc[ai][bj][m][0][j], b = acc[ai][bj][m][1][j]; o[j] = isv ? a : silu_f(a); o[4 + j] = isv ? b : silu_f(b); }
;                         st8(rp + bj * 128, o); }
.LBB0_568:
	v_or_b32_e32 v4, 32, v164
	v_ashrrev_i32_e32 v5, 31, v4
	v_lshlrev_b64 v[4:5], 11, v[4:5]
	v_lshl_add_u64 v[4:5], v[2:3], 0, v[4:5]
	s_and_b64 vcc, exec, s[42:43]
	s_mov_b64 s[12:13], -1
	v_cvt_pk_bf16_f32 v142, v6, v8
	v_cvt_pk_bf16_f32 v143, v138, v140
	v_cvt_pk_bf16_f32 v144, v0, v7
	v_cvt_pk_bf16_f32 v145, v9, v139
	global_store_dwordx4 v[4:5], v[142:145], off
	s_cbranch_vccnz .LBB0_570
	v_mul_f32_e32 v0, 0xbfb8aa3b, v94
	v_mul_f32_e32 v6, 0xbfb8aa3b, v90
	v_exp_f32_e32 v0, v0
	v_exp_f32_e32 v6, v6
	v_add_f32_e32 v0, 1.0, v0
	v_add_f32_e32 v6, 1.0, v6
	v_rcp_f32_e32 v0, v0
	v_rcp_f32_e32 v7, v6
	v_mul_f32_e32 v6, v94, v0
	v_mul_f32_e32 v0, v90, v7
	s_cbranch_execnz .LBB0_572
	s_branch .LBB0_571

; __device__ __forceinline__ float fexp2(float x) { return __builtin_amdgcn_exp2f(x); }
; __device__ __forceinline__ float frcp(float x) { return __builtin_amdgcn_rcpf(x); }
; __device__ __forceinline__ void st8(bf16_t* p, const float (&v)[8]) { u32x4 w; w.x = pk2(v[0], v[1]); w.y = pk2(v[2], v[3]); w.z = pk2(v[4], v[5]); w.w = pk2(v[6], v[7]); *(u32x4*)p = w; }
; __device__ __forceinline__ float silu_f(float x) { return x * frcp(1.f + fexp2(-1.4426950408889634f * x)); }
;     __device__ __forceinline__ void operator()(const f32x4 (&acc)[2][2][4][2], const Unit& u, int wr, int wc, int fr, int fq) const {
;     ...
;             const bool isv = pn < 12; bf16_t* dst = isv ? v : sza; const int colt = (pn & 3) * 256 + wc * 32 + 8 * fq;
; #pragma unroll
;             for (int ai = 0; ai < 2; ++ai)
; #pragma unroll
;                 for (int m = 0; m < 4; ++m) {
;                     bf16_t* rp = dst + (size_t)(row0 + ai * 128 + m * 16) * AW + colt;
; #pragma unroll
;                     for (int bj = 0; bj < 2; ++bj) { float o[8];
; #pragma unroll
;                         for (int j = 0; j < 4; ++j) { const float a = acc[ai][bj][m][0][j], b = acc[ai][bj][m][1][j]; o[j] = isv ? a : silu_f(a); o[4 + j] = isv ? b : silu_f(b); }
;                         st8(rp + bj * 128, o); }
.LBB0_584:
	s_and_b64 vcc, exec, s[42:43]
	s_mov_b64 s[12:13], -1
	v_cvt_pk_bf16_f32 v142, v6, v8
	v_cvt_pk_bf16_f32 v143, v138, v140
	v_cvt_pk_bf16_f32 v144, v0, v7
	v_cvt_pk_bf16_f32 v145, v9, v139
	global_store_dwordx4 v[4:5], v[142:145], off offset:256
	s_cbranch_vccnz .LBB0_586
	v_mul_f32_e32 v0, 0xbfb8aa3b, v86
	v_mul_f32_e32 v4, 0xbfb8aa3b, v82
	v_exp_f32_e32 v0, v0
	v_exp_f32_e32 v4, v4
	v_add_f32_e32 v0, 1.0, v0
	v_add_f32_e32 v4, 1.0, v4
	v_rcp_f32_e32 v0, v0
	v_rcp_f32_e32 v4, v4
	v_mul_f32_e32 v6, v86, v0
	v_mul_f32_e32 v0, v82, v4
	s_cbranch_execnz .LBB0_588
	s_branch .LBB0_587

; __device__ __forceinline__ float fexp2(float x) { return __builtin_amdgcn_exp2f(x); }
; __device__ __forceinline__ float frcp(float x) { return __builtin_amdgcn_rcpf(x); }
; __device__ __forceinline__ void st8(bf16_t* p, const float (&v)[8]) { u32x4 w; w.x = pk2(v[0], v[1]); w.y = pk2(v[2], v[3]); w.z = pk2(v[4], v[5]); w.w = pk2(v[6], v[7]); *(u32x4*)p = w; }
; __device__ __forceinline__ float silu_f(float x) { return x * frcp(1.f + fexp2(-1.4426950408889634f * x)); }
;     __device__ __forceinline__ void operator()(const f32x4 (&acc)[2][2][4][2], const Unit& u, int wr, int wc, int fr, int fq) const {
;     ...
;             const bool isv = pn < 12; bf16_t* dst = isv ? v : sza; const int colt = (pn & 3) * 256 + wc * 32 + 8 * fq;
; #pragma unroll
;             for (int ai = 0; ai < 2; ++ai)
; #pragma unroll
;                 for (int m = 0; m < 4; ++m) {
;                     bf16_t* rp = dst + (size_t)(row0 + ai * 128 + m * 16) * AW + colt;
; #pragma unroll
;                     for (int bj = 0; bj < 2; ++bj) { float o[8];
; #pragma unroll
;                         for (int j = 0; j < 4; ++j) { const float a = acc[ai][bj][m][0][j], b = acc[ai][bj][m][1][j]; o[j] = isv ? a : silu_f(a); o[4 + j] = isv ? b : silu_f(b); }
;                         st8(rp + bj * 128, o); }
.LBB0_600:
	v_or_b32_e32 v4, 48, v164
	v_ashrrev_i32_e32 v5, 31, v4
	v_lshlrev_b64 v[4:5], 11, v[4:5]
	v_lshl_add_u64 v[4:5], v[2:3], 0, v[4:5]
	s_and_b64 vcc, exec, s[42:43]
	s_mov_b64 s[12:13], -1
	v_cvt_pk_bf16_f32 v142, v6, v8
	v_cvt_pk_bf16_f32 v143, v138, v140
	v_cvt_pk_bf16_f32 v144, v0, v7
	v_cvt_pk_bf16_f32 v145, v9, v139
	global_store_dwordx4 v[4:5], v[142:145], off
	s_cbranch_vccnz .LBB0_602
	v_mul_f32_e32 v0, 0xbfb8aa3b, v78
	v_mul_f32_e32 v6, 0xbfb8aa3b, v74
	v_exp_f32_e32 v0, v0
	v_exp_f32_e32 v6, v6
	v_add_f32_e32 v0, 1.0, v0
	v_add_f32_e32 v6, 1.0, v6
	v_rcp_f32_e32 v0, v0
	v_rcp_f32_e32 v7, v6
	v_mul_f32_e32 v6, v78, v0
	v_mul_f32_e32 v0, v74, v7
	s_cbranch_execnz .LBB0_604
	s_branch .LBB0_603

; __device__ __forceinline__ float fexp2(float x) { return __builtin_amdgcn_exp2f(x); }
; __device__ __forceinline__ float frcp(float x) { return __builtin_amdgcn_rcpf(x); }
; __device__ __forceinline__ void st8(bf16_t* p, const float (&v)[8]) { u32x4 w; w.x = pk2(v[0], v[1]); w.y = pk2(v[2], v[3]); w.z = pk2(v[4], v[5]); w.w = pk2(v[6], v[7]); *(u32x4*)p = w; }
; __device__ __forceinline__ float silu_f(float x) { return x * frcp(1.f + fexp2(-1.4426950408889634f * x)); }
;     __device__ __forceinline__ void operator()(const f32x4 (&acc)[2][2][4][2], const Unit& u, int wr, int wc, int fr, int fq) const {
;     ...
;             const bool isv = pn < 12; bf16_t* dst = isv ? v : sza; const int colt = (pn & 3) * 256 + wc * 32 + 8 * fq;
; #pragma unroll
;             for (int ai = 0; ai < 2; ++ai)
; #pragma unroll
;                 for (int m = 0; m < 4; ++m) {
;                     bf16_t* rp = dst + (size_t)(row0 + ai * 128 + m * 16) * AW + colt;
; #pragma unroll
;                     for (int bj = 0; bj < 2; ++bj) { float o[8];
; #pragma unroll
;                         for (int j = 0; j < 4; ++j) { const float a = acc[ai][bj][m][0][j], b = acc[ai][bj][m][1][j]; o[j] = isv ? a : silu_f(a); o[4 + j] = isv ? b : silu_f(b); }
;                         st8(rp + bj * 128, o); }
.LBB0_616:
	s_and_b64 vcc, exec, s[42:43]
	s_mov_b64 s[12:13], -1
	v_cvt_pk_bf16_f32 v142, v6, v8
	v_cvt_pk_bf16_f32 v143, v138, v140
	v_cvt_pk_bf16_f32 v144, v0, v7
	v_cvt_pk_bf16_f32 v145, v9, v139
	global_store_dwordx4 v[4:5], v[142:145], off offset:256
	s_cbranch_vccnz .LBB0_618
	v_mul_f32_e32 v0, 0xbfb8aa3b, v70
	v_mul_f32_e32 v4, 0xbfb8aa3b, v66
	v_exp_f32_e32 v0, v0
	v_exp_f32_e32 v4, v4
	v_add_f32_e32 v0, 1.0, v0
	v_add_f32_e32 v4, 1.0, v4
	v_rcp_f32_e32 v0, v0
	v_rcp_f32_e32 v4, v4
	v_mul_f32_e32 v6, v70, v0
	v_mul_f32_e32 v0, v66, v4
	s_cbranch_execnz .LBB0_620
	s_branch .LBB0_619

; __device__ __forceinline__ float fexp2(float x) { return __builtin_amdgcn_exp2f(x); }
; __device__ __forceinline__ float frcp(float x) { return __builtin_amdgcn_rcpf(x); }
; __device__ __forceinline__ void st8(bf16_t* p, const float (&v)[8]) { u32x4 w; w.x = pk2(v[0], v[1]); w.y = pk2(v[2], v[3]); w.z = pk2(v[4], v[5]); w.w = pk2(v[6], v[7]); *(u32x4*)p = w; }
; __device__ __forceinline__ float silu_f(float x) { return x * frcp(1.f + fexp2(-1.4426950408889634f * x)); }
;     __device__ __forceinline__ void operator()(const f32x4 (&acc)[2][2][4][2], const Unit& u, int wr, int wc, int fr, int fq) const {
;     ...
;             const bool isv = pn < 12; bf16_t* dst = isv ? v : sza; const int colt = (pn & 3) * 256 + wc * 32 + 8 * fq;
; #pragma unroll
;             for (int ai = 0; ai < 2; ++ai)
; #pragma unroll
;                 for (int m = 0; m < 4; ++m) {
;                     bf16_t* rp = dst + (size_t)(row0 + ai * 128 + m * 16) * AW + colt;
; #pragma unroll
;                     for (int bj = 0; bj < 2; ++bj) { float o[8];
; #pragma unroll
;                         for (int j = 0; j < 4; ++j) { const float a = acc[ai][bj][m][0][j], b = acc[ai][bj][m][1][j]; o[j] = isv ? a : silu_f(a); o[4 + j] = isv ? b : silu_f(b); }
;                         st8(rp + bj * 128, o); }
.LBB0_632:
	v_lshlrev_b64 v[4:5], 11, v[164:165]
	v_lshl_add_u64 v[4:5], v[2:3], 0, v[4:5]
	v_cvt_pk_bf16_f32 v142, v6, v8
	v_add_co_u32_e32 v6, vcc, 0x40000, v4
	v_cvt_pk_bf16_f32 v144, v0, v7
	s_mov_b64 s[12:13], -1
	s_nop 0
	v_addc_co_u32_e32 v7, vcc, 0, v5, vcc
	s_and_b64 vcc, exec, s[42:43]
	v_cvt_pk_bf16_f32 v143, v138, v140
	v_cvt_pk_bf16_f32 v145, v9, v139
	global_store_dwordx4 v[6:7], v[142:145], off
	s_cbranch_vccnz .LBB0_634
	v_mul_f32_e32 v0, 0xbfb8aa3b, v62
	v_mul_f32_e32 v6, 0xbfb8aa3b, v58
	v_exp_f32_e32 v0, v0
	v_exp_f32_e32 v6, v6
	v_add_f32_e32 v0, 1.0, v0
	v_add_f32_e32 v6, 1.0, v6
	v_rcp_f32_e32 v0, v0
	v_rcp_f32_e32 v7, v6
	v_mul_f32_e32 v6, v62, v0
	v_mul_f32_e32 v0, v58, v7
	s_cbranch_execnz .LBB0_636
	s_branch .LBB0_635

; __device__ __forceinline__ float fexp2(float x) { return __builtin_amdgcn_exp2f(x); }
; __device__ __forceinline__ float frcp(float x) { return __builtin_amdgcn_rcpf(x); }
; __device__ __forceinline__ void st8(bf16_t* p, const float (&v)[8]) { u32x4 w; w.x = pk2(v[0], v[1]); w.y = pk2(v[2], v[3]); w.z = pk2(v[4], v[5]); w.w = pk2(v[6], v[7]); *(u32x4*)p = w; }
; __device__ __forceinline__ float silu_f(float x) { return x * frcp(1.f + fexp2(-1.4426950408889634f * x)); }
;     __device__ __forceinline__ void operator()(const f32x4 (&acc)[2][2][4][2], const Unit& u, int wr, int wc, int fr, int fq) const {
;     ...
;             const bool isv = pn < 12; bf16_t* dst = isv ? v : sza; const int colt = (pn & 3) * 256 + wc * 32 + 8 * fq;
; #pragma unroll
;             for (int ai = 0; ai < 2; ++ai)
; #pragma unroll
;                 for (int m = 0; m < 4; ++m) {
;                     bf16_t* rp = dst + (size_t)(row0 + ai * 128 + m * 16) * AW + colt;
; #pragma unroll
;                     for (int bj = 0; bj < 2; ++bj) { float o[8];
; #pragma unroll
;                         for (int j = 0; j < 4; ++j) { const float a = acc[ai][bj][m][0][j], b = acc[ai][bj][m][1][j]; o[j] = isv ? a : silu_f(a); o[4 + j] = isv ? b : silu_f(b); }
;                         st8(rp + bj * 128, o); }
.LBB0_648:
	v_lshl_add_u64 v[142:143], v[4:5], 0, s[28:29]
	v_cvt_pk_bf16_f32 v4, v6, v8
	v_cvt_pk_bf16_f32 v6, v0, v7
	s_and_b64 vcc, exec, s[42:43]
	s_mov_b64 s[12:13], -1
	v_cvt_pk_bf16_f32 v5, v138, v140
	v_cvt_pk_bf16_f32 v7, v9, v139
	global_store_dwordx4 v[142:143], v[4:7], off offset:256
	s_cbranch_vccnz .LBB0_650
	v_mul_f32_e32 v0, 0xbfb8aa3b, v54
	v_mul_f32_e32 v4, 0xbfb8aa3b, v50
	v_exp_f32_e32 v0, v0
	v_exp_f32_e32 v4, v4
	v_add_f32_e32 v0, 1.0, v0
	v_add_f32_e32 v4, 1.0, v4
	v_rcp_f32_e32 v0, v0
	v_rcp_f32_e32 v4, v4
	v_mul_f32_e32 v6, v54, v0
	v_mul_f32_e32 v0, v50, v4
	s_cbranch_execnz .LBB0_652
	s_branch .LBB0_651

; __device__ __forceinline__ float fexp2(float x) { return __builtin_amdgcn_exp2f(x); }
; __device__ __forceinline__ float frcp(float x) { return __builtin_amdgcn_rcpf(x); }
; __device__ __forceinline__ void st8(bf16_t* p, const float (&v)[8]) { u32x4 w; w.x = pk2(v[0], v[1]); w.y = pk2(v[2], v[3]); w.z = pk2(v[4], v[5]); w.w = pk2(v[6], v[7]); *(u32x4*)p = w; }
; __device__ __forceinline__ float silu_f(float x) { return x * frcp(1.f + fexp2(-1.4426950408889634f * x)); }
;     __device__ __forceinline__ void operator()(const f32x4 (&acc)[2][2][4][2], const Unit& u, int wr, int wc, int fr, int fq) const {
;     ...
;             const bool isv = pn < 12; bf16_t* dst = isv ? v : sza; const int colt = (pn & 3) * 256 + wc * 32 + 8 * fq;
; #pragma unroll
;             for (int ai = 0; ai < 2; ++ai)
; #pragma unroll
;                 for (int m = 0; m < 4; ++m) {
;                     bf16_t* rp = dst + (size_t)(row0 + ai * 128 + m * 16) * AW + colt;
; #pragma unroll
;                     for (int bj = 0; bj < 2; ++bj) { float o[8];
; #pragma unroll
;                         for (int j = 0; j < 4; ++j) { const float a = acc[ai][bj][m][0][j], b = acc[ai][bj][m][1][j]; o[j] = isv ? a : silu_f(a); o[4 + j] = isv ? b : silu_f(b); }
;                         st8(rp + bj * 128, o); }
.LBB0_664:
	v_lshlrev_b64 v[4:5], 11, v[164:165]
	v_lshl_add_u64 v[4:5], v[2:3], 0, v[4:5]
	v_cvt_pk_bf16_f32 v142, v6, v8
	v_add_co_u32_e32 v6, vcc, 0x48000, v4
	v_cvt_pk_bf16_f32 v144, v0, v7
	s_mov_b64 s[12:13], -1
	s_nop 0
	v_addc_co_u32_e32 v7, vcc, 0, v5, vcc
	s_and_b64 vcc, exec, s[42:43]
	v_cvt_pk_bf16_f32 v143, v138, v140
	v_cvt_pk_bf16_f32 v145, v9, v139
	global_store_dwordx4 v[6:7], v[142:145], off
	s_cbranch_vccnz .LBB0_666
	v_mul_f32_e32 v0, 0xbfb8aa3b, v46
	v_mul_f32_e32 v6, 0xbfb8aa3b, v42
	v_exp_f32_e32 v0, v0
	v_exp_f32_e32 v6, v6
	v_add_f32_e32 v0, 1.0, v0
	v_add_f32_e32 v6, 1.0, v6
	v_rcp_f32_e32 v0, v0
	v_rcp_f32_e32 v7, v6
	v_mul_f32_e32 v6, v46, v0
	v_mul_f32_e32 v0, v42, v7
	s_cbranch_execnz .LBB0_668
	s_branch .LBB0_667

; __device__ __forceinline__ float fexp2(float x) { return __builtin_amdgcn_exp2f(x); }
; __device__ __forceinline__ float frcp(float x) { return __builtin_amdgcn_rcpf(x); }
; __device__ __forceinline__ void st8(bf16_t* p, const float (&v)[8]) { u32x4 w; w.x = pk2(v[0], v[1]); w.y = pk2(v[2], v[3]); w.z = pk2(v[4], v[5]); w.w = pk2(v[6], v[7]); *(u32x4*)p = w; }
; __device__ __forceinline__ float silu_f(float x) { return x * frcp(1.f + fexp2(-1.4426950408889634f * x)); }
;     __device__ __forceinline__ void operator()(const f32x4 (&acc)[2][2][4][2], const Unit& u, int wr, int wc, int fr, int fq) const {
;     ...
;             const bool isv = pn < 12; bf16_t* dst = isv ? v : sza; const int colt = (pn & 3) * 256 + wc * 32 + 8 * fq;
; #pragma unroll
;             for (int ai = 0; ai < 2; ++ai)
; #pragma unroll
;                 for (int m = 0; m < 4; ++m) {
;                     bf16_t* rp = dst + (size_t)(row0 + ai * 128 + m * 16) * AW + colt;
; #pragma unroll
;                     for (int bj = 0; bj < 2; ++bj) { float o[8];
; #pragma unroll
;                         for (int j = 0; j < 4; ++j) { const float a = acc[ai][bj][m][0][j], b = acc[ai][bj][m][1][j]; o[j] = isv ? a : silu_f(a); o[4 + j] = isv ? b : silu_f(b); }
;                         st8(rp + bj * 128, o); }
.LBB0_680:
	s_mov_b64 s[2:3], 0x48000
	v_lshl_add_u64 v[142:143], v[4:5], 0, s[2:3]
	v_cvt_pk_bf16_f32 v4, v6, v8
	v_cvt_pk_bf16_f32 v6, v0, v7
	s_and_b64 vcc, exec, s[42:43]
	s_mov_b64 s[12:13], -1
	v_cvt_pk_bf16_f32 v5, v138, v140
	v_cvt_pk_bf16_f32 v7, v9, v139
	global_store_dwordx4 v[142:143], v[4:7], off offset:256
	s_cbranch_vccnz .LBB0_682
	v_mul_f32_e32 v0, 0xbfb8aa3b, v38
	v_mul_f32_e32 v4, 0xbfb8aa3b, v34
	v_exp_f32_e32 v0, v0
	v_exp_f32_e32 v4, v4
	v_add_f32_e32 v0, 1.0, v0
	v_add_f32_e32 v4, 1.0, v4
	v_rcp_f32_e32 v0, v0
	v_rcp_f32_e32 v4, v4
	v_mul_f32_e32 v6, v38, v0
	v_mul_f32_e32 v0, v34, v4
	s_cbranch_execnz .LBB0_684
	s_branch .LBB0_683

; __device__ __forceinline__ float fexp2(float x) { return __builtin_amdgcn_exp2f(x); }
; __device__ __forceinline__ float frcp(float x) { return __builtin_amdgcn_rcpf(x); }
; __device__ __forceinline__ void st8(bf16_t* p, const float (&v)[8]) { u32x4 w; w.x = pk2(v[0], v[1]); w.y = pk2(v[2], v[3]); w.z = pk2(v[4], v[5]); w.w = pk2(v[6], v[7]); *(u32x4*)p = w; }
; __device__ __forceinline__ float silu_f(float x) { return x * frcp(1.f + fexp2(-1.4426950408889634f * x)); }
;     __device__ __forceinline__ void operator()(const f32x4 (&acc)[2][2][4][2], const Unit& u, int wr, int wc, int fr, int fq) const {
;     ...
;             const bool isv = pn < 12; bf16_t* dst = isv ? v : sza; const int colt = (pn & 3) * 256 + wc * 32 + 8 * fq;
; #pragma unroll
;             for (int ai = 0; ai < 2; ++ai)
; #pragma unroll
;                 for (int m = 0; m < 4; ++m) {
;                     bf16_t* rp = dst + (size_t)(row0 + ai * 128 + m * 16) * AW + colt;
; #pragma unroll
;                     for (int bj = 0; bj < 2; ++bj) { float o[8];
; #pragma unroll
;                         for (int j = 0; j < 4; ++j) { const float a = acc[ai][bj][m][0][j], b = acc[ai][bj][m][1][j]; o[j] = isv ? a : silu_f(a); o[4 + j] = isv ? b : silu_f(b); }
;                         st8(rp + bj * 128, o); }
.LBB0_696:
	v_lshlrev_b64 v[4:5], 11, v[164:165]
	v_lshl_add_u64 v[4:5], v[2:3], 0, v[4:5]
	v_cvt_pk_bf16_f32 v142, v6, v8
	v_add_co_u32_e32 v6, vcc, 0x50000, v4
	v_cvt_pk_bf16_f32 v144, v0, v7
	s_mov_b64 s[12:13], -1
	s_nop 0
	v_addc_co_u32_e32 v7, vcc, 0, v5, vcc
	s_and_b64 vcc, exec, s[42:43]
	v_cvt_pk_bf16_f32 v143, v138, v140
	v_cvt_pk_bf16_f32 v145, v9, v139
	global_store_dwordx4 v[6:7], v[142:145], off
	s_cbranch_vccnz .LBB0_698
	v_mul_f32_e32 v0, 0xbfb8aa3b, v30
	v_mul_f32_e32 v6, 0xbfb8aa3b, v26
	v_exp_f32_e32 v0, v0
	v_exp_f32_e32 v6, v6
	v_add_f32_e32 v0, 1.0, v0
	v_add_f32_e32 v6, 1.0, v6
	v_rcp_f32_e32 v0, v0
	v_rcp_f32_e32 v7, v6
	v_mul_f32_e32 v6, v30, v0
	v_mul_f32_e32 v0, v26, v7
	s_cbranch_execnz .LBB0_700
	s_branch .LBB0_699

; __device__ __forceinline__ float fexp2(float x) { return __builtin_amdgcn_exp2f(x); }
; __device__ __forceinline__ float frcp(float x) { return __builtin_amdgcn_rcpf(x); }
; __device__ __forceinline__ void st8(bf16_t* p, const float (&v)[8]) { u32x4 w; w.x = pk2(v[0], v[1]); w.y = pk2(v[2], v[3]); w.z = pk2(v[4], v[5]); w.w = pk2(v[6], v[7]); *(u32x4*)p = w; }
; __device__ __forceinline__ float silu_f(float x) { return x * frcp(1.f + fexp2(-1.4426950408889634f * x)); }
;     __device__ __forceinline__ void operator()(const f32x4 (&acc)[2][2][4][2], const Unit& u, int wr, int wc, int fr, int fq) const {
;     ...
;             const bool isv = pn < 12; bf16_t* dst = isv ? v : sza; const int colt = (pn & 3) * 256 + wc * 32 + 8 * fq;
; #pragma unroll
;             for (int ai = 0; ai < 2; ++ai)
; #pragma unroll
;                 for (int m = 0; m < 4; ++m) {
;                     bf16_t* rp = dst + (size_t)(row0 + ai * 128 + m * 16) * AW + colt;
; #pragma unroll
;                     for (int bj = 0; bj < 2; ++bj) { float o[8];
; #pragma unroll
;                         for (int j = 0; j < 4; ++j) { const float a = acc[ai][bj][m][0][j], b = acc[ai][bj][m][1][j]; o[j] = isv ? a : silu_f(a); o[4 + j] = isv ? b : silu_f(b); }
;                         st8(rp + bj * 128, o); }
.LBB0_712:
	s_mov_b64 s[2:3], 0x50000
	v_lshl_add_u64 v[142:143], v[4:5], 0, s[2:3]
	v_cvt_pk_bf16_f32 v4, v6, v8
	s_and_b64 vcc, exec, s[42:43]
	s_mov_b64 s[12:13], -1
	v_cvt_pk_bf16_f32 v5, v138, v140
	v_cvt_pk_bf16_f32 v6, v0, v7
	v_cvt_pk_bf16_f32 v7, v9, v139
	global_store_dwordx4 v[142:143], v[4:7], off offset:256
	s_cbranch_vccnz .LBB0_714
	v_mul_f32_e32 v0, 0xbfb8aa3b, v22
	v_mul_f32_e32 v4, 0xbfb8aa3b, v18
	v_exp_f32_e32 v0, v0
	v_exp_f32_e32 v4, v4
	v_add_f32_e32 v0, 1.0, v0
	v_add_f32_e32 v4, 1.0, v4
	v_rcp_f32_e32 v0, v0
	v_rcp_f32_e32 v5, v4
	v_mul_f32_e32 v4, v22, v0
	v_mul_f32_e32 v0, v18, v5
	s_cbranch_execnz .LBB0_716
	s_branch .LBB0_715

; __device__ __forceinline__ float fexp2(float x) { return __builtin_amdgcn_exp2f(x); }
; __device__ __forceinline__ float frcp(float x) { return __builtin_amdgcn_rcpf(x); }
; __device__ __forceinline__ void st8(bf16_t* p, const float (&v)[8]) { u32x4 w; w.x = pk2(v[0], v[1]); w.y = pk2(v[2], v[3]); w.z = pk2(v[4], v[5]); w.w = pk2(v[6], v[7]); *(u32x4*)p = w; }
; __device__ __forceinline__ float silu_f(float x) { return x * frcp(1.f + fexp2(-1.4426950408889634f * x)); }
;     __device__ __forceinline__ void operator()(const f32x4 (&acc)[2][2][4][2], const Unit& u, int wr, int wc, int fr, int fq) const {
;     ...
;             const bool isv = pn < 12; bf16_t* dst = isv ? v : sza; const int colt = (pn & 3) * 256 + wc * 32 + 8 * fq;
; #pragma unroll
;             for (int ai = 0; ai < 2; ++ai)
; #pragma unroll
;                 for (int m = 0; m < 4; ++m) {
;                     bf16_t* rp = dst + (size_t)(row0 + ai * 128 + m * 16) * AW + colt;
; #pragma unroll
;                     for (int bj = 0; bj < 2; ++bj) { float o[8];
; #pragma unroll
;                         for (int j = 0; j < 4; ++j) { const float a = acc[ai][bj][m][0][j], b = acc[ai][bj][m][1][j]; o[j] = isv ? a : silu_f(a); o[4 + j] = isv ? b : silu_f(b); }
;                         st8(rp + bj * 128, o); }
.LBB0_728:
	v_lshlrev_b64 v[140:141], 11, v[164:165]
	v_lshl_add_u64 v[2:3], v[2:3], 0, v[140:141]
	v_cvt_pk_bf16_f32 v140, v4, v6
	v_add_co_u32_e32 v4, vcc, 0x58000, v2
	v_cvt_pk_bf16_f32 v142, v0, v5
	s_mov_b64 s[12:13], -1
	s_nop 0
	v_addc_co_u32_e32 v5, vcc, 0, v3, vcc
	s_and_b64 vcc, exec, s[42:43]
	v_cvt_pk_bf16_f32 v141, v8, v138
	v_cvt_pk_bf16_f32 v143, v7, v9
	global_store_dwordx4 v[4:5], v[140:143], off
	s_cbranch_vccnz .LBB0_730
	v_mul_f32_e32 v0, 0xbfb8aa3b, v14
	v_mul_f32_e32 v4, 0xbfb8aa3b, v10
	v_exp_f32_e32 v0, v0
	v_exp_f32_e32 v4, v4
	v_add_f32_e32 v0, 1.0, v0
	v_add_f32_e32 v4, 1.0, v4
	v_rcp_f32_e32 v0, v0
	v_rcp_f32_e32 v5, v4
	v_mul_f32_e32 v4, v14, v0
	v_mul_f32_e32 v0, v10, v5
	s_cbranch_execnz .LBB0_732
	s_branch .LBB0_731

; __device__ __forceinline__ float fexp2(float x) { return __builtin_amdgcn_exp2f(x); }
; __device__ __forceinline__ float frcp(float x) { return __builtin_amdgcn_rcpf(x); }
; __device__ __forceinline__ void st8(bf16_t* p, const float (&v)[8]) { u32x4 w; w.x = pk2(v[0], v[1]); w.y = pk2(v[2], v[3]); w.z = pk2(v[4], v[5]); w.w = pk2(v[6], v[7]); *(u32x4*)p = w; }
; __device__ __forceinline__ float silu_f(float x) { return x * frcp(1.f + fexp2(-1.4426950408889634f * x)); }
;     __device__ __forceinline__ void operator()(const f32x4 (&acc)[2][2][4][2], const Unit& u, int wr, int wc, int fr, int fq) const {
;     ...
;             const bool isv = pn < 12; bf16_t* dst = isv ? v : sza; const int colt = (pn & 3) * 256 + wc * 32 + 8 * fq;
; #pragma unroll
;             for (int ai = 0; ai < 2; ++ai)
; #pragma unroll
;                 for (int m = 0; m < 4; ++m) {
;                     bf16_t* rp = dst + (size_t)(row0 + ai * 128 + m * 16) * AW + colt;
; #pragma unroll
;                     for (int bj = 0; bj < 2; ++bj) { float o[8];
; #pragma unroll
;                         for (int j = 0; j < 4; ++j) { const float a = acc[ai][bj][m][0][j], b = acc[ai][bj][m][1][j]; o[j] = isv ? a : silu_f(a); o[4 + j] = isv ? b : silu_f(b); }
;                         st8(rp + bj * 128, o); }
.LBB0_744:
	s_mov_b64 s[2:3], 0x58000
	v_lshl_add_u64 v[140:141], v[2:3], 0, s[2:3]
	v_cvt_pk_bf16_f32 v2, v4, v6
	v_cvt_pk_bf16_f32 v3, v8, v138
	v_cvt_pk_bf16_f32 v4, v0, v5
	v_cvt_pk_bf16_f32 v5, v7, v9
	global_store_dwordx4 v[140:141], v[2:5], off offset:256

; __device__ __forceinline__ float bf_lo(unsigned u) { return __uint_as_float(u << 16); }
; __device__ __forceinline__ float bf_hi(unsigned u) { return __uint_as_float(u & 0xffff0000u); }
; __device__ __forceinline__ void phase_final(const _Float16* xin_h, const bf16_t* dl, const float* g, float* out) {
;     ...
;     for (int row0 = blockIdx.x * NWAVES + wave; row0 < MTOK; row0 += 2 * NW) {
;         f32x4 v[2][8]; u32x2 d[2][8];
; #pragma unroll
;         for (int q = 0; q < 2; ++q) { const int row = min(row0 + q * NW, MTOK - 1); const f16x4* xr = (const f16x4*)(xin_h + (size_t)row * XH_PITCH) + lane; const u32x2* dr = (const u32x2*)(dl + (size_t)row * DM) + lane;
; #pragma unroll
;             for (int j = 0; j < 8; ++j) { const f16x4 t = xr[64 * j]; v[q][j] = (f32x4){(float)t.x, (float)t.y, (float)t.z, (float)t.w}; d[q][j] = dr[64 * j]; } }
;         asm volatile("s_waitcnt vmcnt(0)" ::: "memory");
; #pragma unroll
;         for (int q = 0; q < 2; ++q) { const int row = row0 + q * NW; float s = 0.f;
;             if (row >= MTOK) break;
; #pragma unroll
;             for (int j = 0; j < 8; ++j) { v[q][j].x += bf_lo(d[q][j].x); v[q][j].y += bf_hi(d[q][j].x); v[q][j].z += bf_lo(d[q][j].y); v[q][j].w += bf_hi(d[q][j].y);
;                 s += (v[q][j].x * v[q][j].x + v[q][j].y * v[q][j].y) + (v[q][j].z * v[q][j].z + v[q][j].w * v[q][j].w); }
.LBB0_755:
	s_ashr_i32 s13, s12, 31
	s_lshl_b64 s[16:17], s[12:13], 13
	v_lshl_add_u64 v[18:19], v[2:3], 0, s[16:17]
	global_load_dwordx2 v[42:43], v[18:19], off
	s_lshl_b64 s[2:3], s[12:13], 12
	v_lshl_add_u64 v[20:21], v[4:5], 0, s[2:3]
	global_load_dwordx2 v[44:45], v[20:21], off
	global_load_dwordx2 v[46:47], v[18:19], off offset:512
	global_load_dwordx2 v[48:49], v[20:21], off offset:512
	global_load_dwordx2 v[50:51], v[18:19], off offset:1024
	global_load_dwordx2 v[52:53], v[20:21], off offset:1024
	global_load_dwordx2 v[54:55], v[18:19], off offset:1536
	global_load_dwordx2 v[56:57], v[20:21], off offset:1536
	global_load_dwordx2 v[64:65], v[18:19], off offset:2048
	global_load_dwordx2 v[70:71], v[18:19], off offset:2560
	global_load_dwordx2 v[74:75], v[18:19], off offset:3072
	global_load_dwordx2 v[40:41], v[18:19], off offset:3584
	global_load_dwordx2 v[72:73], v[20:21], off offset:2048
	global_load_dwordx2 v[76:77], v[20:21], off offset:2560
	global_load_dwordx2 v[78:79], v[20:21], off offset:3072
	global_load_dwordx2 v[38:39], v[20:21], off offset:3584
	s_add_i32 s12, s12, s21
	s_min_i32 s2, s12, 0x3fff
	s_ashr_i32 s3, s2, 31
	s_lshl_b64 s[4:5], s[2:3], 13
	s_lshl_b64 s[2:3], s[2:3], 12
	v_lshl_add_u64 v[34:35], v[2:3], 0, s[4:5]
	v_lshl_add_u64 v[36:37], v[4:5], 0, s[2:3]
	global_load_dwordx2 v[30:31], v[34:35], off
	global_load_dwordx2 v[26:27], v[34:35], off offset:512
	global_load_dwordx2 v[22:23], v[34:35], off offset:1024
	global_load_dwordx2 v[20:21], v[34:35], off offset:1536
	global_load_dwordx2 v[32:33], v[36:37], off
	global_load_dwordx2 v[28:29], v[36:37], off offset:512
	global_load_dwordx2 v[24:25], v[36:37], off offset:1024
	global_load_dwordx2 v[18:19], v[36:37], off offset:1536
	s_cmpk_gt_i32 s12, 0x3fff
	s_waitcnt vmcnt(0) lgkmcnt(0)
	v_lshlrev_b32_e32 v60, 16, v44
	v_cvt_f32_f16_e32 v62, v46
	v_cvt_f32_f16_sdwa v63, v46 dst_sel:DWORD dst_unused:UNUSED_PAD src0_sel:WORD_1
	v_cvt_f32_f16_e32 v58, v42
	v_cvt_f32_f16_sdwa v59, v42 dst_sel:DWORD dst_unused:UNUSED_PAD src0_sel:WORD_1
	v_cvt_f32_f16_e32 v42, v43
	v_cvt_f32_f16_sdwa v43, v43 dst_sel:DWORD dst_unused:UNUSED_PAD src0_sel:WORD_1
	v_cvt_f32_f16_e32 v46, v47
	v_cvt_f32_f16_sdwa v47, v47 dst_sel:DWORD dst_unused:UNUSED_PAD src0_sel:WORD_1
	v_cvt_f32_f16_e32 v82, v50
	v_cvt_f32_f16_sdwa v83, v50 dst_sel:DWORD dst_unused:UNUSED_PAD src0_sel:WORD_1
	v_cvt_f32_f16_e32 v86, v51
	v_cvt_f32_f16_sdwa v87, v51 dst_sel:DWORD dst_unused:UNUSED_PAD src0_sel:WORD_1
	v_and_b32_e32 v61, 0xffff0000, v44
	v_lshlrev_b32_e32 v44, 16, v45
	v_and_b32_e32 v45, 0xffff0000, v45
	v_lshlrev_b32_e32 v80, 16, v48
	v_and_b32_e32 v81, 0xffff0000, v48
	v_lshlrev_b32_e32 v48, 16, v49
	v_and_b32_e32 v49, 0xffff0000, v49
	v_lshlrev_b32_e32 v84, 16, v52
	v_and_b32_e32 v85, 0xffff0000, v52
	v_lshlrev_b32_e32 v52, 16, v53
	v_and_b32_e32 v53, 0xffff0000, v53
	v_pk_add_f32 v[66:67], v[58:59], v[60:61]
	v_pk_add_f32 v[68:69], v[42:43], v[44:45]
	v_pk_add_f32 v[58:59], v[62:63], v[80:81]
	v_pk_add_f32 v[60:61], v[46:47], v[48:49]
	v_pk_add_f32 v[50:51], v[82:83], v[84:85]
	v_pk_add_f32 v[52:53], v[86:87], v[52:53]
	v_mov_b32_e32 v44, v67
	v_mov_b32_e32 v45, v59
	v_mov_b32_e32 v48, v69
	v_mov_b32_e32 v49, v61
	v_mov_b32_e32 v62, v51
	v_mov_b32_e32 v63, v53
	v_cvt_f32_f16_e32 v88, v54
	v_cvt_f32_f16_sdwa v89, v54 dst_sel:DWORD dst_unused:UNUSED_PAD src0_sel:WORD_1
	v_cvt_f32_f16_e32 v92, v55
	v_cvt_f32_f16_sdwa v93, v55 dst_sel:DWORD dst_unused:UNUSED_PAD src0_sel:WORD_1
	v_mov_b32_e32 v42, v66
	v_mov_b32_e32 v43, v58
	v_mov_b32_e32 v46, v68
	v_mov_b32_e32 v47, v60
	v_mov_b32_e32 v54, v50
	v_mov_b32_e32 v55, v52
	v_pk_mul_f32 v[44:45], v[44:45], v[44:45]
	v_pk_mul_f32 v[48:49], v[48:49], v[48:49]
	v_pk_mul_f32 v[62:63], v[62:63], v[62:63]
	v_pk_fma_f32 v[42:43], v[42:43], v[42:43], v[44:45]
	v_pk_fma_f32 v[44:45], v[46:47], v[46:47], v[48:49]
	v_pk_fma_f32 v[46:47], v[54:55], v[54:55], v[62:63]
	v_lshlrev_b32_e32 v90, 16, v56
	v_and_b32_e32 v91, 0xffff0000, v56
	v_pk_add_f32 v[42:43], v[42:43], v[44:45]
	v_pk_add_f32 v[44:45], v[46:47], v[46:47] op_sel:[0,1] op_sel_hi:[1,0]
	v_lshlrev_b32_e32 v46, 16, v57
	v_and_b32_e32 v47, 0xffff0000, v57
	v_cvt_f32_f16_e32 v56, v64
	v_cvt_f32_f16_sdwa v57, v64 dst_sel:DWORD dst_unused:UNUSED_PAD src0_sel:WORD_1
	v_cvt_f32_f16_e32 v64, v65
	v_cvt_f32_f16_sdwa v65, v65 dst_sel:DWORD dst_unused:UNUSED_PAD src0_sel:WORD_1
	v_pk_add_f32 v[54:55], v[88:89], v[90:91]
	v_pk_add_f32 v[62:63], v[92:93], v[46:47]
	v_mul_f32_e32 v0, v55, v55
	v_lshlrev_b32_e32 v80, 16, v72
	v_and_b32_e32 v81, 0xffff0000, v72
	v_lshlrev_b32_e32 v72, 16, v73
	v_and_b32_e32 v73, 0xffff0000, v73
	v_pk_fma_f32 v[46:47], v[54:55], v[54:55], v[0:1] op_sel_hi:[1,1,0]
	v_mul_f32_e32 v0, v63, v63
	v_pk_add_f32 v[56:57], v[56:57], v[80:81]
	v_pk_add_f32 v[64:65], v[64:65], v[72:73]
	v_pk_add_f32 v[42:43], v[42:43], v[42:43] op_sel:[0,1] op_sel_hi:[1,0]
	v_pk_fma_f32 v[48:49], v[62:63], v[62:63], v[0:1] op_sel_hi:[1,1,0]
	v_pk_mul_f32 v[72:73], v[56:57], v[56:57]
	v_pk_mul_f32 v[80:81], v[64:65], v[64:65]
	v_mov_b32_e32 v43, v72
	v_mov_b32_e32 v45, v73
	v_mov_b32_e32 v47, v80
	v_mov_b32_e32 v49, v81
	v_pk_add_f32 v[42:43], v[42:43], v[44:45]
	v_pk_add_f32 v[44:45], v[46:47], v[48:49]
	v_cvt_f32_f16_e32 v48, v71
	v_pk_add_f32 v[42:43], v[42:43], v[44:45]
	v_cvt_f32_f16_e32 v44, v70
	v_cvt_f32_f16_sdwa v45, v70 dst_sel:DWORD dst_unused:UNUSED_PAD src0_sel:WORD_1
	v_cvt_f32_f16_sdwa v49, v71 dst_sel:DWORD dst_unused:UNUSED_PAD src0_sel:WORD_1
	v_lshlrev_b32_e32 v46, 16, v76
	v_and_b32_e32 v47, 0xffff0000, v76
	v_pk_add_f32 v[70:71], v[44:45], v[46:47]
	v_lshlrev_b32_e32 v44, 16, v77
; __device__ __forceinline__ float bf_lo(unsigned u) { return __uint_as_float(u << 16); }
; __device__ __forceinline__ float bf_hi(unsigned u) { return __uint_as_float(u & 0xffff0000u); }
; __device__ __forceinline__ float wave_sum(float v) {
; #pragma unroll
;     for (int o = 1; o < 64; o <<= 1) v += __shfl_xor(v, o);
;     return v;
; }
; __device__ __forceinline__ void phase_final(const _Float16* xin_h, const bf16_t* dl, const float* g, float* out) {
;     ...
;         for (int q = 0; q < 2; ++q) { const int row = min(row0 + q * NW, MTOK - 1); const f16x4* xr = (const f16x4*)(xin_h + (size_t)row * XH_PITCH) + lane; const u32x2* dr = (const u32x2*)(dl + (size_t)row * DM) + lane;
; #pragma unroll
;             for (int j = 0; j < 8; ++j) { const f16x4 t = xr[64 * j]; v[q][j] = (f32x4){(float)t.x, (float)t.y, (float)t.z, (float)t.w}; d[q][j] = dr[64 * j]; } }
;         asm volatile("s_waitcnt vmcnt(0)" ::: "memory");
; #pragma unroll
;         for (int q = 0; q < 2; ++q) { const int row = row0 + q * NW; float s = 0.f;
;             if (row >= MTOK) break;
; #pragma unroll
;             for (int j = 0; j < 8; ++j) { v[q][j].x += bf_lo(d[q][j].x); v[q][j].y += bf_hi(d[q][j].x); v[q][j].z += bf_lo(d[q][j].y); v[q][j].w += bf_hi(d[q][j].y);
;                 s += (v[q][j].x * v[q][j].x + v[q][j].y * v[q][j].y) + (v[q][j].z * v[q][j].z + v[q][j].w * v[q][j].w); }
;             const float rstd = 1.f / sqrtf(wave_sum(s) * (1.f / DM) + 1e-6f);
;             f32x4* o = (f32x4*)(out + (size_t)row * DM) + lane;
; #pragma unroll
;             for (int j = 0; j < 8; ++j) o[64 * j] = v[q][j] * rstd * *(const f32x4*)(g + 4 * lane + 256 * j); }
	v_and_b32_e32 v45, 0xffff0000, v77
	v_pk_add_f32 v[72:73], v[48:49], v[44:45]
	v_mov_b32_e32 v46, v71
	v_mov_b32_e32 v47, v73
	v_mov_b32_e32 v44, v70
	v_mov_b32_e32 v45, v72
	v_pk_mul_f32 v[46:47], v[46:47], v[46:47]
	v_lshlrev_b32_e32 v48, 16, v78
	v_pk_fma_f32 v[44:45], v[44:45], v[44:45], v[46:47]
	v_cvt_f32_f16_e32 v46, v74
	v_cvt_f32_f16_sdwa v47, v74 dst_sel:DWORD dst_unused:UNUSED_PAD src0_sel:WORD_1
	v_and_b32_e32 v49, 0xffff0000, v78
	v_cvt_f32_f16_e32 v76, v75
	v_cvt_f32_f16_sdwa v77, v75 dst_sel:DWORD dst_unused:UNUSED_PAD src0_sel:WORD_1
	v_pk_add_f32 v[74:75], v[46:47], v[48:49]
	v_lshlrev_b32_e32 v46, 16, v79
	v_and_b32_e32 v47, 0xffff0000, v79
	v_cvt_f32_f16_e32 v78, v40
	v_cvt_f32_f16_sdwa v79, v40 dst_sel:DWORD dst_unused:UNUSED_PAD src0_sel:WORD_1
	v_cvt_f32_f16_e32 v40, v41
	v_cvt_f32_f16_sdwa v41, v41 dst_sel:DWORD dst_unused:UNUSED_PAD src0_sel:WORD_1
	v_pk_add_f32 v[76:77], v[76:77], v[46:47]
	v_mul_f32_e32 v0, v75, v75
	v_lshlrev_b32_e32 v80, 16, v38
	v_and_b32_e32 v81, 0xffff0000, v38
	v_lshlrev_b32_e32 v38, 16, v39
	v_and_b32_e32 v39, 0xffff0000, v39
	v_pk_fma_f32 v[46:47], v[74:75], v[74:75], v[0:1] op_sel_hi:[1,1,0]
	v_mul_f32_e32 v0, v77, v77
	v_pk_add_f32 v[78:79], v[78:79], v[80:81]
	v_pk_add_f32 v[80:81], v[40:41], v[38:39]
	v_pk_add_f32 v[42:43], v[42:43], v[42:43] op_sel:[0,1] op_sel_hi:[1,0]
	v_pk_add_f32 v[44:45], v[44:45], v[44:45] op_sel:[0,1] op_sel_hi:[1,0]
	v_pk_fma_f32 v[48:49], v[76:77], v[76:77], v[0:1] op_sel_hi:[1,1,0]
	v_pk_mul_f32 v[38:39], v[78:79], v[78:79]
	v_pk_mul_f32 v[40:41], v[80:81], v[80:81]
	v_and_b32_e32 v0, 64, v182
	v_mov_b32_e32 v43, v38
	v_mov_b32_e32 v45, v39
	v_mov_b32_e32 v47, v40
	v_mov_b32_e32 v49, v41
	v_add_u32_e32 v86, 64, v0
	v_xor_b32_e32 v0, 1, v182
	v_pk_add_f32 v[38:39], v[42:43], v[44:45]
	v_pk_add_f32 v[40:41], v[46:47], v[48:49]
	v_cmp_lt_i32_e32 vcc, v0, v86
	v_pk_add_f32 v[38:39], v[38:39], v[40:41]
	s_nop 0
	v_cndmask_b32_e32 v0, v182, v0, vcc
	v_add_f32_e32 v40, v38, v39
	v_lshlrev_b32_e32 v0, 2, v0
	ds_bpermute_b32 v41, v0, v40
	global_load_dwordx2 v[46:47], v[34:35], off offset:2048
	global_load_dwordx2 v[42:43], v[34:35], off offset:2560
	global_load_dwordx2 v[38:39], v[34:35], off offset:3072
	s_nop 0
	global_load_dwordx2 v[34:35], v[34:35], off offset:3584
	s_waitcnt lgkmcnt(0)
	v_add_f32_e32 v83, v40, v41
	v_xor_b32_e32 v40, 2, v182
	v_cmp_lt_i32_e32 vcc, v40, v86
	s_nop 1
	v_cndmask_b32_e32 v40, v182, v40, vcc
	v_lshlrev_b32_e32 v82, 2, v40
	global_load_dwordx2 v[48:49], v[36:37], off offset:2048
	global_load_dwordx2 v[44:45], v[36:37], off offset:2560
	global_load_dwordx2 v[40:41], v[36:37], off offset:3072
	s_nop 0
	global_load_dwordx2 v[36:37], v[36:37], off offset:3584
	s_waitcnt vmcnt(0)
	global_load_dwordx4 v[88:91], v[8:9], off
	ds_bpermute_b32 v84, v82, v83
	s_waitcnt lgkmcnt(0)
	v_add_f32_e32 v84, v83, v84
	v_xor_b32_e32 v83, 4, v182
	v_cmp_lt_i32_e32 vcc, v83, v86
	s_nop 1
	v_cndmask_b32_e32 v83, v182, v83, vcc
	v_lshlrev_b32_e32 v83, 2, v83
	ds_bpermute_b32 v85, v83, v84
	s_waitcnt lgkmcnt(0)
	v_add_f32_e32 v85, v84, v85
	v_xor_b32_e32 v84, 8, v182
	v_cmp_lt_i32_e32 vcc, v84, v86
	s_nop 1
	v_cndmask_b32_e32 v84, v182, v84, vcc
	v_lshlrev_b32_e32 v84, 2, v84
	ds_bpermute_b32 v87, v84, v85
	s_waitcnt lgkmcnt(0)
	v_add_f32_e32 v87, v85, v87
	v_xor_b32_e32 v85, 16, v182
	v_cmp_lt_i32_e32 vcc, v85, v86
	s_nop 1
	v_cndmask_b32_e32 v85, v182, v85, vcc
	v_lshlrev_b32_e32 v85, 2, v85
	ds_bpermute_b32 v92, v85, v87
	s_waitcnt lgkmcnt(0)
	v_add_f32_e32 v87, v87, v92
	v_xor_b32_e32 v92, 32, v182
	v_cmp_lt_i32_e32 vcc, v92, v86
	s_nop 1
	v_cndmask_b32_e32 v86, v182, v92, vcc
	v_lshlrev_b32_e32 v86, 2, v86
	ds_bpermute_b32 v92, v86, v87
	s_waitcnt lgkmcnt(0)
	v_add_f32_e32 v87, v87, v92
	v_fmamk_f32 v87, v87, 0x3a000000, v181
	v_mul_f32_e32 v92, 0x4f800000, v87
	v_cmp_gt_f32_e32 vcc, s7, v87
	s_nop 1
	v_cndmask_b32_e32 v87, v87, v92, vcc
	v_sqrt_f32_e32 v92, v87
	s_nop 0
	v_add_u32_e32 v93, -1, v92
	v_fma_f32 v94, -v93, v92, v87
	v_cmp_ge_f32_e64 s[40:41], 0, v94
	v_add_u32_e32 v94, 1, v92
	s_nop 0
	v_cndmask_b32_e64 v93, v92, v93, s[40:41]
	v_fma_f32 v92, -v94, v92, v87
	v_cmp_lt_f32_e64 s[40:41], 0, v92
	s_nop 1
	v_cndmask_b32_e64 v92, v93, v94, s[40:41]
	v_mul_f32_e32 v93, 0x37800000, v92
	v_cndmask_b32_e32 v92, v92, v93, vcc
	v_cmp_class_f32_e32 vcc, v87, v180
	s_nop 1
	v_cndmask_b32_e32 v87, v92, v87, vcc
	v_div_scale_f32 v92, s[2:3], v87, v87, 1.0
	v_rcp_f32_e32 v93, v92
	s_nop 0
	v_fma_f32 v94, -v92, v93, 1.0
	v_fmac_f32_e32 v93, v94, v93
	v_div_scale_f32 v94, vcc, 1.0, v87, 1.0
	v_mul_f32_e32 v95, v94, v93
	v_fma_f32 v96, -v92, v95, v94
	v_fmac_f32_e32 v95, v96, v93
	v_fma_f32 v92, -v92, v95, v94
	v_div_fmas_f32 v92, v92, v93, v95
	v_div_fixup_f32 v92, v92, v87, 1.0
	v_pk_mul_f32 v[66:67], v[66:67], v[92:93] op_sel_hi:[1,0]
	v_pk_mul_f32 v[68:69], v[68:69], v[92:93] op_sel_hi:[1,0]
	v_lshl_add_u64 v[94:95], v[6:7], 0, s[16:17]
	s_waitcnt vmcnt(0)
	v_pk_mul_f32 v[68:69], v[90:91], v[68:69]
	v_pk_mul_f32 v[66:67], v[88:89], v[66:67]
	global_store_dwordx4 v[94:95], v[66:69], off
	global_load_dwordx4 v[66:69], v[8:9], off offset:1024
	v_pk_mul_f32 v[60:61], v[60:61], v[92:93] op_sel_hi:[1,0]
	v_pk_mul_f32 v[58:59], v[58:59], v[92:93] op_sel_hi:[1,0]
	v_pk_mul_f32 v[52:53], v[52:53], v[92:93] op_sel_hi:[1,0]
	v_pk_mul_f32 v[50:51], v[50:51], v[92:93] op_sel_hi:[1,0]
	v_pk_mul_f32 v[54:55], v[54:55], v[92:93] op_sel_hi:[1,0]
	v_pk_mul_f32 v[56:57], v[56:57], v[92:93] op_sel_hi:[1,0]
	s_waitcnt vmcnt(0)
	v_pk_mul_f32 v[58:59], v[66:67], v[58:59]
	v_pk_mul_f32 v[60:61], v[68:69], v[60:61]
	global_store_dwordx4 v[94:95], v[58:61], off offset:1024
	global_load_dwordx4 v[58:61], v[8:9], off offset:2048
	s_waitcnt vmcnt(0)
; __device__ __forceinline__ float bf_lo(unsigned u) { return __uint_as_float(u << 16); }
; __device__ __forceinline__ float bf_hi(unsigned u) { return __uint_as_float(u & 0xffff0000u); }
; __device__ __forceinline__ void phase_final(const _Float16* xin_h, const bf16_t* dl, const float* g, float* out) {
;     ...
;         for (int q = 0; q < 2; ++q) { const int row = row0 + q * NW; float s = 0.f;
;             if (row >= MTOK) break;
; #pragma unroll
;             for (int j = 0; j < 8; ++j) { v[q][j].x += bf_lo(d[q][j].x); v[q][j].y += bf_hi(d[q][j].x); v[q][j].z += bf_lo(d[q][j].y); v[q][j].w += bf_hi(d[q][j].y);
;                 s += (v[q][j].x * v[q][j].x + v[q][j].y * v[q][j].y) + (v[q][j].z * v[q][j].z + v[q][j].w * v[q][j].w); }
;             const float rstd = 1.f / sqrtf(wave_sum(s) * (1.f / DM) + 1e-6f);
;             f32x4* o = (f32x4*)(out + (size_t)row * DM) + lane;
; #pragma unroll
;             for (int j = 0; j < 8; ++j) o[64 * j] = v[q][j] * rstd * *(const f32x4*)(g + 4 * lane + 256 * j); }
	v_pk_mul_f32 v[50:51], v[58:59], v[50:51]
	v_pk_mul_f32 v[52:53], v[60:61], v[52:53]
	global_store_dwordx4 v[94:95], v[50:53], off offset:2048
	global_load_dwordx4 v[50:53], v[8:9], off offset:3072
	v_pk_mul_f32 v[58:59], v[62:63], v[92:93] op_sel_hi:[1,0]
	s_waitcnt vmcnt(0)
	v_pk_mul_f32 v[50:51], v[50:51], v[54:55]
	v_pk_mul_f32 v[52:53], v[52:53], v[58:59]
	global_store_dwordx4 v[94:95], v[50:53], off offset:3072
	global_load_dwordx4 v[50:53], v[10:11], off
	v_add_co_u32_e32 v54, vcc, s6, v94
	v_pk_mul_f32 v[58:59], v[64:65], v[92:93] op_sel_hi:[1,0]
	s_nop 0
	v_addc_co_u32_e32 v55, vcc, 0, v95, vcc
	s_waitcnt vmcnt(0)
	v_pk_mul_f32 v[50:51], v[56:57], v[50:51]
	v_pk_mul_f32 v[52:53], v[58:59], v[52:53]
	global_store_dwordx4 v[54:55], v[50:53], off
	global_load_dwordx4 v[50:53], v[12:13], off
	v_pk_mul_f32 v[56:57], v[72:73], v[92:93] op_sel_hi:[1,0]
	v_pk_mul_f32 v[58:59], v[70:71], v[92:93] op_sel_hi:[1,0]
	s_waitcnt vmcnt(0)
	v_pk_mul_f32 v[52:53], v[56:57], v[52:53]
	v_pk_mul_f32 v[50:51], v[58:59], v[50:51]
	global_store_dwordx4 v[54:55], v[50:53], off offset:1024
	global_load_dwordx4 v[50:53], v[14:15], off
	v_pk_mul_f32 v[56:57], v[76:77], v[92:93] op_sel_hi:[1,0]
	v_pk_mul_f32 v[58:59], v[74:75], v[92:93] op_sel_hi:[1,0]
	s_waitcnt vmcnt(0)
	v_pk_mul_f32 v[52:53], v[56:57], v[52:53]
	v_pk_mul_f32 v[50:51], v[58:59], v[50:51]
	global_store_dwordx4 v[54:55], v[50:53], off offset:2048
	global_load_dwordx4 v[50:53], v[16:17], off
	v_pk_mul_f32 v[56:57], v[80:81], v[92:93] op_sel_hi:[1,0]
	v_pk_mul_f32 v[58:59], v[78:79], v[92:93] op_sel_hi:[1,0]
	s_waitcnt vmcnt(0)
	v_pk_mul_f32 v[52:53], v[56:57], v[52:53]
	v_pk_mul_f32 v[50:51], v[58:59], v[50:51]
	global_store_dwordx4 v[54:55], v[50:53], off offset:3072
	s_cbranch_scc1 .LBB0_754
	s_nop 0
	v_cvt_f32_f16_sdwa v51, v30 dst_sel:DWORD dst_unused:UNUSED_PAD src0_sel:WORD_1
	v_cvt_f32_f16_e32 v50, v30
	v_cvt_f32_f16_sdwa v55, v31 dst_sel:DWORD dst_unused:UNUSED_PAD src0_sel:WORD_1
	v_cvt_f32_f16_e32 v54, v31
	v_lshlrev_b32_e32 v52, 16, v32
	v_and_b32_e32 v53, 0xffff0000, v32
	v_pk_add_f32 v[30:31], v[50:51], v[52:53]
	v_lshlrev_b32_e32 v32, 16, v33
	v_and_b32_e32 v33, 0xffff0000, v33
	v_cvt_f32_f16_sdwa v51, v26 dst_sel:DWORD dst_unused:UNUSED_PAD src0_sel:WORD_1
	v_cvt_f32_f16_e32 v50, v26
	v_pk_add_f32 v[32:33], v[54:55], v[32:33]
	v_cvt_f32_f16_sdwa v55, v27 dst_sel:DWORD dst_unused:UNUSED_PAD src0_sel:WORD_1
	v_cvt_f32_f16_e32 v54, v27
	v_lshlrev_b32_e32 v52, 16, v28
	v_and_b32_e32 v53, 0xffff0000, v28
	v_pk_add_f32 v[26:27], v[50:51], v[52:53]
	v_lshlrev_b32_e32 v28, 16, v29
	v_and_b32_e32 v29, 0xffff0000, v29
	v_pk_add_f32 v[28:29], v[54:55], v[28:29]
	v_mov_b32_e32 v52, v31
	v_mov_b32_e32 v53, v27
	v_mov_b32_e32 v50, v30
	v_mov_b32_e32 v51, v26
	v_pk_mul_f32 v[52:53], v[52:53], v[52:53]
	v_mov_b32_e32 v54, v33
	v_mov_b32_e32 v55, v29
	v_pk_fma_f32 v[50:51], v[50:51], v[50:51], v[52:53]
	v_mov_b32_e32 v52, v32
	v_mov_b32_e32 v53, v28
	v_pk_mul_f32 v[54:55], v[54:55], v[54:55]
	v_cvt_f32_f16_sdwa v57, v23 dst_sel:DWORD dst_unused:UNUSED_PAD src0_sel:WORD_1
	v_pk_fma_f32 v[52:53], v[52:53], v[52:53], v[54:55]
	v_cvt_f32_f16_e32 v56, v23
	v_pk_add_f32 v[50:51], v[50:51], v[52:53]
	v_lshlrev_b32_e32 v54, 16, v24
	v_pk_add_f32 v[52:53], v[50:51], v[50:51] op_sel:[0,1] op_sel_hi:[1,0]
	v_cvt_f32_f16_sdwa v51, v22 dst_sel:DWORD dst_unused:UNUSED_PAD src0_sel:WORD_1
	v_cvt_f32_f16_e32 v50, v22
	v_and_b32_e32 v55, 0xffff0000, v24
	v_lshlrev_b32_e32 v24, 16, v25
	v_and_b32_e32 v25, 0xffff0000, v25
	v_pk_add_f32 v[22:23], v[50:51], v[54:55]
	v_pk_add_f32 v[24:25], v[56:57], v[24:25]
	v_mov_b32_e32 v54, v23
	v_mov_b32_e32 v55, v25
	v_mov_b32_e32 v50, v22
	v_mov_b32_e32 v51, v24
	v_pk_mul_f32 v[54:55], v[54:55], v[54:55]
	v_cvt_f32_f16_sdwa v59, v21 dst_sel:DWORD dst_unused:UNUSED_PAD src0_sel:WORD_1
	v_pk_fma_f32 v[50:51], v[50:51], v[50:51], v[54:55]
	v_cvt_f32_f16_e32 v58, v21
	v_pk_add_f32 v[54:55], v[50:51], v[50:51] op_sel:[0,1] op_sel_hi:[1,0]
	v_cvt_f32_f16_sdwa v51, v20 dst_sel:DWORD dst_unused:UNUSED_PAD src0_sel:WORD_1
	v_cvt_f32_f16_e32 v50, v20
	v_lshlrev_b32_e32 v56, 16, v18
	v_and_b32_e32 v57, 0xffff0000, v18
	v_lshlrev_b32_e32 v18, 16, v19
	v_pk_add_f32 v[20:21], v[50:51], v[56:57]
	v_and_b32_e32 v19, 0xffff0000, v19
	v_pk_add_f32 v[50:51], v[58:59], v[18:19]
	v_mul_f32_e32 v18, v21, v21
	v_pk_fma_f32 v[56:57], v[20:21], v[20:21], v[18:19] op_sel_hi:[1,1,0]
	v_mul_f32_e32 v18, v51, v51
	v_pk_fma_f32 v[58:59], v[50:51], v[50:51], v[18:19] op_sel_hi:[1,1,0]
	v_cvt_f32_f16_sdwa v19, v46 dst_sel:DWORD dst_unused:UNUSED_PAD src0_sel:WORD_1
	v_cvt_f32_f16_e32 v18, v46
	v_cvt_f32_f16_sdwa v63, v47 dst_sel:DWORD dst_unused:UNUSED_PAD src0_sel:WORD_1
	v_cvt_f32_f16_e32 v62, v47
	v_lshlrev_b32_e32 v60, 16, v48
	v_and_b32_e32 v61, 0xffff0000, v48
	v_lshlrev_b32_e32 v46, 16, v49
	v_and_b32_e32 v47, 0xffff0000, v49
	v_pk_add_f32 v[18:19], v[18:19], v[60:61]
	v_pk_add_f32 v[46:47], v[62:63], v[46:47]
	v_pk_mul_f32 v[48:49], v[18:19], v[18:19]
	v_pk_mul_f32 v[60:61], v[46:47], v[46:47]
	v_mov_b32_e32 v53, v48
	v_mov_b32_e32 v55, v49
	v_mov_b32_e32 v57, v60
	v_mov_b32_e32 v59, v61
	v_pk_add_f32 v[48:49], v[52:53], v[54:55]
	v_pk_add_f32 v[52:53], v[56:57], v[58:59]
	v_cvt_f32_f16_sdwa v57, v43 dst_sel:DWORD dst_unused:UNUSED_PAD src0_sel:WORD_1
	v_pk_add_f32 v[48:49], v[48:49], v[52:53]
	v_cvt_f32_f16_sdwa v53, v42 dst_sel:DWORD dst_unused:UNUSED_PAD src0_sel:WORD_1
	v_cvt_f32_f16_e32 v52, v42
	v_cvt_f32_f16_e32 v56, v43
	v_lshlrev_b32_e32 v54, 16, v44
	v_and_b32_e32 v55, 0xffff0000, v44
	v_lshlrev_b32_e32 v44, 16, v45
	v_and_b32_e32 v45, 0xffff0000, v45
	v_pk_add_f32 v[42:43], v[52:53], v[54:55]
; __device__ __forceinline__ float bf_lo(unsigned u) { return __uint_as_float(u << 16); }
; __device__ __forceinline__ float bf_hi(unsigned u) { return __uint_as_float(u & 0xffff0000u); }
; __device__ __forceinline__ void phase_final(const _Float16* xin_h, const bf16_t* dl, const float* g, float* out) {
;     ...
;             for (int j = 0; j < 8; ++j) { v[q][j].x += bf_lo(d[q][j].x); v[q][j].y += bf_hi(d[q][j].x); v[q][j].z += bf_lo(d[q][j].y); v[q][j].w += bf_hi(d[q][j].y);
;                 s += (v[q][j].x * v[q][j].x + v[q][j].y * v[q][j].y) + (v[q][j].z * v[q][j].z + v[q][j].w * v[q][j].w); }
;             const float rstd = 1.f / sqrtf(wave_sum(s) * (1.f / DM) + 1e-6f);
;             f32x4* o = (f32x4*)(out + (size_t)row * DM) + lane;
; #pragma unroll
;             for (int j = 0; j < 8; ++j) o[64 * j] = v[q][j] * rstd * *(const f32x4*)(g + 4 * lane + 256 * j); }
	v_pk_add_f32 v[44:45], v[56:57], v[44:45]
	v_cvt_f32_f16_sdwa v59, v39 dst_sel:DWORD dst_unused:UNUSED_PAD src0_sel:WORD_1
	v_cvt_f32_f16_e32 v58, v39
	v_mov_b32_e32 v54, v43
	v_mov_b32_e32 v55, v45
	v_mov_b32_e32 v52, v42
	v_mov_b32_e32 v53, v44
	v_pk_mul_f32 v[54:55], v[54:55], v[54:55]
	v_lshlrev_b32_e32 v56, 16, v40
	v_pk_fma_f32 v[52:53], v[52:53], v[52:53], v[54:55]
	v_cvt_f32_f16_sdwa v55, v38 dst_sel:DWORD dst_unused:UNUSED_PAD src0_sel:WORD_1
	v_cvt_f32_f16_e32 v54, v38
	v_and_b32_e32 v57, 0xffff0000, v40
	v_lshlrev_b32_e32 v40, 16, v41
	v_and_b32_e32 v41, 0xffff0000, v41
	v_pk_add_f32 v[40:41], v[58:59], v[40:41]
	v_cvt_f32_f16_sdwa v59, v34 dst_sel:DWORD dst_unused:UNUSED_PAD src0_sel:WORD_1
	v_cvt_f32_f16_e32 v58, v34
	v_cvt_f32_f16_sdwa v63, v35 dst_sel:DWORD dst_unused:UNUSED_PAD src0_sel:WORD_1
	v_cvt_f32_f16_e32 v62, v35
	v_pk_add_f32 v[38:39], v[54:55], v[56:57]
	v_lshlrev_b32_e32 v60, 16, v36
	v_and_b32_e32 v61, 0xffff0000, v36
	v_lshlrev_b32_e32 v34, 16, v37
	v_and_b32_e32 v35, 0xffff0000, v37
	v_mul_f32_e32 v54, v39, v39
	v_mul_f32_e32 v56, v41, v41
	v_pk_add_f32 v[58:59], v[58:59], v[60:61]
	v_pk_add_f32 v[60:61], v[62:63], v[34:35]
	v_pk_add_f32 v[48:49], v[48:49], v[48:49] op_sel:[0,1] op_sel_hi:[1,0]
	v_pk_add_f32 v[52:53], v[52:53], v[52:53] op_sel:[0,1] op_sel_hi:[1,0]
	v_pk_fma_f32 v[54:55], v[38:39], v[38:39], v[54:55] op_sel_hi:[1,1,0]
	v_pk_fma_f32 v[56:57], v[40:41], v[40:41], v[56:57] op_sel_hi:[1,1,0]
	v_pk_mul_f32 v[34:35], v[58:59], v[58:59]
	v_pk_mul_f32 v[36:37], v[60:61], v[60:61]
	v_mov_b32_e32 v49, v34
	v_mov_b32_e32 v53, v35
	v_mov_b32_e32 v55, v36
	v_mov_b32_e32 v57, v37
	v_pk_add_f32 v[34:35], v[48:49], v[52:53]
	v_pk_add_f32 v[36:37], v[54:55], v[56:57]
	s_ashr_i32 s13, s12, 31
	v_pk_add_f32 v[48:49], v[34:35], v[36:37]
	global_load_dwordx4 v[34:37], v[8:9], off
	v_add_f32_e32 v48, v48, v49
	ds_bpermute_b32 v0, v0, v48
	s_waitcnt lgkmcnt(0)
	v_add_f32_e32 v0, v48, v0
	ds_bpermute_b32 v48, v82, v0
	s_waitcnt lgkmcnt(0)
	v_add_f32_e32 v0, v0, v48
	ds_bpermute_b32 v48, v83, v0
	s_waitcnt lgkmcnt(0)
	v_add_f32_e32 v0, v0, v48
	ds_bpermute_b32 v48, v84, v0
	s_waitcnt lgkmcnt(0)
	v_add_f32_e32 v0, v0, v48
	ds_bpermute_b32 v48, v85, v0
	s_waitcnt lgkmcnt(0)
	v_add_f32_e32 v0, v0, v48
	ds_bpermute_b32 v48, v86, v0
	s_waitcnt lgkmcnt(0)
	v_add_f32_e32 v0, v0, v48
	v_fmamk_f32 v0, v0, 0x3a000000, v181
	v_mul_f32_e32 v48, 0x4f800000, v0
	v_cmp_gt_f32_e32 vcc, s7, v0
	s_nop 1
	v_cndmask_b32_e32 v0, v0, v48, vcc
	v_sqrt_f32_e32 v48, v0
	s_nop 0
	v_add_u32_e32 v49, -1, v48
	v_fma_f32 v52, -v49, v48, v0
	v_cmp_ge_f32_e64 s[40:41], 0, v52
	v_add_u32_e32 v52, 1, v48
	s_nop 0
	v_cndmask_b32_e64 v49, v48, v49, s[40:41]
	v_fma_f32 v48, -v52, v48, v0
	v_cmp_lt_f32_e64 s[40:41], 0, v48
	s_nop 1
	v_cndmask_b32_e64 v48, v49, v52, s[40:41]
	v_mul_f32_e32 v49, 0x37800000, v48
	v_cndmask_b32_e32 v48, v48, v49, vcc
	v_cmp_class_f32_e32 vcc, v0, v180
	s_nop 1
	v_cndmask_b32_e32 v0, v48, v0, vcc
	v_div_scale_f32 v48, s[2:3], v0, v0, 1.0
	v_rcp_f32_e32 v49, v48
	s_lshl_b64 s[2:3], s[12:13], 13
	v_fma_f32 v52, -v48, v49, 1.0
	v_fmac_f32_e32 v49, v52, v49
	v_div_scale_f32 v52, vcc, 1.0, v0, 1.0
	v_mul_f32_e32 v53, v52, v49
	v_fma_f32 v54, -v48, v53, v52
	v_fmac_f32_e32 v53, v54, v49
	v_fma_f32 v48, -v48, v53, v52
	v_div_fmas_f32 v48, v48, v49, v53
	v_div_fixup_f32 v0, v48, v0, 1.0
	v_pk_mul_f32 v[30:31], v[30:31], v[0:1] op_sel_hi:[1,0]
	v_pk_mul_f32 v[32:33], v[32:33], v[0:1] op_sel_hi:[1,0]
	v_lshl_add_u64 v[48:49], v[6:7], 0, s[2:3]
	s_waitcnt vmcnt(0)
	v_pk_mul_f32 v[32:33], v[36:37], v[32:33]
	v_pk_mul_f32 v[30:31], v[34:35], v[30:31]
	global_store_dwordx4 v[48:49], v[30:33], off
	global_load_dwordx4 v[30:33], v[8:9], off offset:1024
	v_pk_mul_f32 v[28:29], v[28:29], v[0:1] op_sel_hi:[1,0]
	v_pk_mul_f32 v[26:27], v[26:27], v[0:1] op_sel_hi:[1,0]
	v_pk_mul_f32 v[24:25], v[24:25], v[0:1] op_sel_hi:[1,0]
	v_pk_mul_f32 v[22:23], v[22:23], v[0:1] op_sel_hi:[1,0]
	v_pk_mul_f32 v[20:21], v[20:21], v[0:1] op_sel_hi:[1,0]
	v_pk_mul_f32 v[18:19], v[18:19], v[0:1] op_sel_hi:[1,0]
	s_waitcnt vmcnt(0)
	v_pk_mul_f32 v[26:27], v[30:31], v[26:27]
	v_pk_mul_f32 v[28:29], v[32:33], v[28:29]
	global_store_dwordx4 v[48:49], v[26:29], off offset:1024
	global_load_dwordx4 v[26:29], v[8:9], off offset:2048
	s_waitcnt vmcnt(0)
	v_pk_mul_f32 v[22:23], v[26:27], v[22:23]
	v_pk_mul_f32 v[24:25], v[28:29], v[24:25]
	global_store_dwordx4 v[48:49], v[22:25], off offset:2048
	global_load_dwordx4 v[22:25], v[8:9], off offset:3072
	v_pk_mul_f32 v[26:27], v[50:51], v[0:1] op_sel_hi:[1,0]
	s_waitcnt vmcnt(0)
	v_pk_mul_f32 v[20:21], v[22:23], v[20:21]
	v_pk_mul_f32 v[22:23], v[24:25], v[26:27]
	global_store_dwordx4 v[48:49], v[20:23], off offset:3072
	global_load_dwordx4 v[20:23], v[10:11], off
	v_add_co_u32_e32 v24, vcc, s6, v48
	v_pk_mul_f32 v[26:27], v[46:47], v[0:1] op_sel_hi:[1,0]
	s_nop 0
	v_addc_co_u32_e32 v25, vcc, 0, v49, vcc
	s_waitcnt vmcnt(0)
	v_pk_mul_f32 v[18:19], v[18:19], v[20:21]
	v_pk_mul_f32 v[20:21], v[26:27], v[22:23]
	global_store_dwordx4 v[24:25], v[18:21], off
	global_load_dwordx4 v[18:21], v[12:13], off
	v_pk_mul_f32 v[22:23], v[44:45], v[0:1] op_sel_hi:[1,0]
	v_pk_mul_f32 v[26:27], v[42:43], v[0:1] op_sel_hi:[1,0]
	s_waitcnt vmcnt(0)
	v_pk_mul_f32 v[20:21], v[22:23], v[20:21]
	v_pk_mul_f32 v[18:19], v[26:27], v[18:19]
	global_store_dwordx4 v[24:25], v[18:21], off offset:1024
	global_load_dwordx4 v[18:21], v[14:15], off
	v_pk_mul_f32 v[22:23], v[40:41], v[0:1] op_sel_hi:[1,0]
	v_pk_mul_f32 v[26:27], v[38:39], v[0:1] op_sel_hi:[1,0]
	s_waitcnt vmcnt(0)
	v_pk_mul_f32 v[20:21], v[22:23], v[20:21]
	v_pk_mul_f32 v[18:19], v[26:27], v[18:19]
	global_store_dwordx4 v[24:25], v[18:21], off offset:2048
	global_load_dwordx4 v[18:21], v[16:17], off
	v_pk_mul_f32 v[22:23], v[60:61], v[0:1] op_sel_hi:[1,0]
	v_pk_mul_f32 v[26:27], v[58:59], v[0:1] op_sel_hi:[1,0]
	s_waitcnt vmcnt(0)
	v_pk_mul_f32 v[20:21], v[22:23], v[20:21]
	v_pk_mul_f32 v[18:19], v[26:27], v[18:19]
	global_store_dwordx4 v[24:25], v[18:21], off offset:3072
	s_branch .LBB0_754

; #define LAS __attribute__((address_space(3)))
; __device__ __forceinline__ void p0_transpose_item(const float* W, int N, bf16_t* WT, int k0, int n0, int nsrc0, LAS float* scr, int lane) {
;     float t[32];
;     const float* wp = W + (size_t)(k0 + (lane >> 5)) * N + nsrc0 + (lane & 31);
; #pragma unroll
;     for (int i = 0; i < 32; ++i) t[i] = wp[(size_t)(2 * i) * N];
; #pragma unroll
.LBB0_761:
	s_lshl_b32 s24, s20, 6
	v_or_b32_e32 v0, s24, v5
	s_ashr_i32 s25, s24, 31
	s_mul_i32 s20, s25, s2
	v_mad_u64_u32 v[12:13], s[26:27], v0, s2, 0
	v_add_u32_e32 v13, s20, v13
	v_lshl_add_u64 v[12:13], v[12:13], 2, s[22:23]
	s_ashr_i32 s41, s40, 31
	v_lshl_add_u64 v[12:13], s[40:41], 2, v[12:13]
	v_lshlrev_b32_e32 v0, 2, v25
	v_lshl_add_u64 v[12:13], v[12:13], 0, v[0:1]
	s_lshl_b32 s30, s2, 1
	v_lshl_add_u64 v[14:15], s[30:31], 2, v[12:13]
	s_lshl_b32 s30, s2, 2
	v_lshl_add_u64 v[16:17], s[30:31], 2, v[12:13]
	s_mul_i32 s30, s2, 6
	v_lshl_add_u64 v[18:19], s[30:31], 2, v[12:13]
	s_lshl_b32 s30, s2, 3
	v_lshl_add_u64 v[22:23], s[30:31], 2, v[12:13]
	s_mul_i32 s30, s2, 10
	v_lshl_add_u64 v[26:27], s[30:31], 2, v[12:13]
	s_mul_i32 s30, s2, 12
	v_lshl_add_u64 v[28:29], s[30:31], 2, v[12:13]
	s_mul_i32 s30, s2, 14
	v_lshl_add_u64 v[30:31], s[30:31], 2, v[12:13]
	s_lshl_b32 s30, s2, 4
	global_load_dword v0, v[12:13], off
	global_load_dword v3, v[14:15], off
	global_load_dword v20, v[16:17], off
	global_load_dword v34, v[18:19], off
	global_load_dword v35, v[22:23], off
	global_load_dword v36, v[26:27], off
	global_load_dword v37, v[28:29], off
	global_load_dword v38, v[30:31], off
	v_lshl_add_u64 v[14:15], s[30:31], 2, v[12:13]
	s_mul_i32 s30, s2, 18
	v_lshl_add_u64 v[16:17], s[30:31], 2, v[12:13]
	s_mul_i32 s30, s2, 20
	v_lshl_add_u64 v[18:19], s[30:31], 2, v[12:13]
	s_mul_i32 s30, s2, 22
	v_lshl_add_u64 v[22:23], s[30:31], 2, v[12:13]
	s_mul_i32 s30, s2, 24
	v_lshl_add_u64 v[26:27], s[30:31], 2, v[12:13]
	s_mul_i32 s30, s2, 26
	v_lshl_add_u64 v[28:29], s[30:31], 2, v[12:13]
	s_mul_i32 s30, s2, 28
	v_lshl_add_u64 v[30:31], s[30:31], 2, v[12:13]
	s_mul_i32 s30, s2, 30
	v_lshl_add_u64 v[32:33], s[30:31], 2, v[12:13]
	s_lshl_b32 s30, s2, 5
	global_load_dword v39, v[14:15], off
	global_load_dword v40, v[16:17], off
	global_load_dword v41, v[18:19], off
	global_load_dword v42, v[22:23], off
	global_load_dword v43, v[26:27], off
	global_load_dword v44, v[28:29], off
	global_load_dword v45, v[30:31], off
	global_load_dword v46, v[32:33], off
	v_lshl_add_u64 v[14:15], s[30:31], 2, v[12:13]
	s_mul_i32 s30, s2, 34
	v_lshl_add_u64 v[16:17], s[30:31], 2, v[12:13]
	s_mul_i32 s30, s2, 36
	v_lshl_add_u64 v[18:19], s[30:31], 2, v[12:13]
	s_mul_i32 s30, s2, 38
	v_lshl_add_u64 v[22:23], s[30:31], 2, v[12:13]
	s_mul_i32 s30, s2, 40
	v_lshl_add_u64 v[26:27], s[30:31], 2, v[12:13]
	s_mul_i32 s30, s2, 42
	v_lshl_add_u64 v[28:29], s[30:31], 2, v[12:13]
	s_mul_i32 s30, s2, 44
	v_lshl_add_u64 v[30:31], s[30:31], 2, v[12:13]
	s_mul_i32 s30, s2, 46
	v_lshl_add_u64 v[32:33], s[30:31], 2, v[12:13]
	s_mul_i32 s30, s2, 48
	global_load_dword v47, v[14:15], off
	global_load_dword v48, v[16:17], off
	global_load_dword v49, v[18:19], off
	global_load_dword v50, v[22:23], off
	global_load_dword v51, v[26:27], off
	global_load_dword v52, v[28:29], off
	global_load_dword v53, v[30:31], off
	s_nop 0
	global_load_dword v32, v[32:33], off
	v_lshl_add_u64 v[14:15], s[30:31], 2, v[12:13]
	s_mul_i32 s30, s2, 50
	v_lshl_add_u64 v[16:17], s[30:31], 2, v[12:13]
	s_mul_i32 s30, s2, 52
	v_lshl_add_u64 v[18:19], s[30:31], 2, v[12:13]
	s_mul_i32 s30, s2, 54
	v_lshl_add_u64 v[22:23], s[30:31], 2, v[12:13]
	s_mul_i32 s30, s2, 56
	v_lshl_add_u64 v[26:27], s[30:31], 2, v[12:13]
	s_mul_i32 s30, s2, 58
	v_lshl_add_u64 v[28:29], s[30:31], 2, v[12:13]
	s_mul_i32 s30, s2, 60
	v_lshl_add_u64 v[30:31], s[30:31], 2, v[12:13]
	s_mul_i32 s30, s2, 62
	v_lshl_add_u64 v[12:13], s[30:31], 2, v[12:13]
	global_load_dword v14, v[14:15], off
	s_nop 0
	global_load_dword v15, v[16:17], off
	s_nop 0
	global_load_dword v16, v[18:19], off
	global_load_dword v17, v[22:23], off
	s_nop 0
	global_load_dword v18, v[26:27], off
	global_load_dword v19, v[28:29], off
	global_load_dword v22, v[30:31], off
	s_nop 0
	global_load_dword v12, v[12:13], off
	s_lshl_b64 s[22:23], s[24:25], 1
	s_add_u32 s16, s16, s22
	s_addc_u32 s17, s17, s23
	s_add_i32 s4, s4, s21
	s_cmp_gt_i32 s4, 0x8fff
	s_waitcnt vmcnt(0)
; #define LAS __attribute__((address_space(3)))
; __device__ __forceinline__ unsigned pk2(float lo, float hi) { unsigned r; asm("v_cvt_pk_bf16_f32 %0, %1, %2" : "=v"(r) : "v"(lo), "v"(hi)); return r; }
; __device__ __forceinline__ void lds_wait() { asm volatile("s_waitcnt lgkmcnt(0)" ::: "memory"); }
; __device__ __forceinline__ void p0_transpose_item(const float* W, int N, bf16_t* WT, int k0, int n0, int nsrc0, LAS float* scr, int lane) {
;     ...
;     for (int i = 0; i < 32; ++i) scr[(2 * i + (lane >> 5)) * 33 + (lane & 31)] = t[i];
;     lds_wait();
;     const int c = lane & 7;
; #pragma unroll
;     for (int j = 0; j < 4; ++j) { const int n = (lane >> 3) + 8 * j; const LAS float* s = scr + (8 * c) * 33 + n;
;         u32x4 o; o.x = pk2(s[0 * 33], s[1 * 33]); o.y = pk2(s[2 * 33], s[3 * 33]); o.z = pk2(s[4 * 33], s[5 * 33]); o.w = pk2(s[6 * 33], s[7 * 33]);
;         *(u32x4*)(WT + (size_t)(n0 + n) * DM + k0 + 8 * c) = o; }
;     lds_wait();
	ds_write2_b32 v11, v0, v3 offset1:66
	ds_write2_b32 v11, v20, v34 offset0:132 offset1:198
	v_add_u32_e32 v0, 0x400, v11
	ds_write2_b32 v0, v35, v36 offset0:8 offset1:74
	ds_write2_b32 v0, v37, v38 offset0:140 offset1:206
	v_add_u32_e32 v0, 0x800, v11
	ds_write2_b32 v0, v39, v40 offset0:16 offset1:82
	ds_write2_b32 v0, v41, v42 offset0:148 offset1:214
	v_add_u32_e32 v0, 0xc00, v11
	ds_write2_b32 v0, v43, v44 offset0:24 offset1:90
	ds_write2_b32 v0, v45, v46 offset0:156 offset1:222
	v_add_u32_e32 v0, 0x1000, v11
	ds_write2_b32 v0, v47, v48 offset0:32 offset1:98
	ds_write2_b32 v0, v49, v50 offset0:164 offset1:230
	v_add_u32_e32 v0, 0x1400, v11
	ds_write2_b32 v0, v51, v52 offset0:40 offset1:106
	ds_write2_b32 v0, v53, v32 offset0:172 offset1:238
	v_add_u32_e32 v0, 0x1800, v11
	ds_write2_b32 v0, v14, v15 offset0:48 offset1:114
	ds_write2_b32 v0, v16, v17 offset0:180 offset1:246
	v_add_u32_e32 v0, 0x1c00, v11
	ds_write2_b32 v0, v18, v19 offset0:56 offset1:122
	ds_write2_b32 v0, v22, v12 offset0:188 offset1:254
	s_waitcnt lgkmcnt(0)
	ds_read_b32 v0, v7
	ds_read_b32 v12, v7 offset:132
	ds_read_b32 v13, v7 offset:264
	ds_read_b32 v14, v7 offset:396
	ds_read_b32 v15, v7 offset:528
	ds_read_b32 v18, v7 offset:660
	ds_read_b32 v19, v7 offset:792
	ds_read_b32 v20, v7 offset:924
	s_waitcnt lgkmcnt(0)
	v_cvt_pk_bf16_f32 v13, v13, v14
	s_waitcnt lgkmcnt(2)
	v_cvt_pk_bf16_f32 v14, v15, v18
	v_or_b32_e32 v18, s3, v6
	v_mov_b32_e32 v3, v1
	s_waitcnt lgkmcnt(0)
	v_cvt_pk_bf16_f32 v15, v19, v20
	v_ashrrev_i32_e32 v19, 31, v18
	v_lshl_add_u64 v[16:17], s[16:17], 0, v[2:3]
	v_lshlrev_b64 v[18:19], 12, v[18:19]
	v_lshl_add_u64 v[18:19], v[16:17], 0, v[18:19]
	v_cvt_pk_bf16_f32 v12, v0, v12
	global_store_dwordx4 v[18:19], v[12:15], off
	ds_read_b32 v0, v7 offset:32
	ds_read_b32 v3, v7 offset:164
	ds_read_b32 v13, v7 offset:296
	ds_read_b32 v14, v7 offset:428
	ds_read_b32 v15, v7 offset:560
	ds_read_b32 v18, v7 offset:692
	ds_read_b32 v19, v7 offset:824
	ds_read_b32 v20, v7 offset:956
	s_waitcnt lgkmcnt(0)
	v_cvt_pk_bf16_f32 v13, v13, v14
	v_cvt_pk_bf16_f32 v14, v15, v18
	v_or_b32_e32 v18, s3, v8
	v_cvt_pk_bf16_f32 v15, v19, v20
	v_ashrrev_i32_e32 v19, 31, v18
	v_lshlrev_b64 v[18:19], 12, v[18:19]
	v_lshl_add_u64 v[18:19], v[16:17], 0, v[18:19]
	v_cvt_pk_bf16_f32 v12, v0, v3
	global_store_dwordx4 v[18:19], v[12:15], off
	ds_read_b32 v0, v7 offset:64
	ds_read_b32 v3, v7 offset:196
	ds_read_b32 v13, v7 offset:328
	ds_read_b32 v14, v7 offset:460
	ds_read_b32 v15, v7 offset:592
	ds_read_b32 v18, v7 offset:724
	ds_read_b32 v19, v7 offset:856
	ds_read_b32 v20, v7 offset:988
	s_waitcnt lgkmcnt(0)
	v_cvt_pk_bf16_f32 v13, v13, v14
	v_cvt_pk_bf16_f32 v14, v15, v18
	v_or_b32_e32 v18, s3, v9
	v_cvt_pk_bf16_f32 v15, v19, v20
	v_ashrrev_i32_e32 v19, 31, v18
	v_lshlrev_b64 v[18:19], 12, v[18:19]
	v_lshl_add_u64 v[18:19], v[16:17], 0, v[18:19]
	v_cvt_pk_bf16_f32 v12, v0, v3
	global_store_dwordx4 v[18:19], v[12:15], off
	ds_read_b32 v0, v7 offset:96
	ds_read_b32 v3, v7 offset:228
	ds_read_b32 v13, v7 offset:360
	ds_read_b32 v14, v7 offset:492
	ds_read_b32 v15, v7 offset:624
	ds_read_b32 v18, v7 offset:756
	ds_read_b32 v19, v7 offset:888
	ds_read_b32 v20, v7 offset:1020
	s_waitcnt lgkmcnt(0)
	v_cvt_pk_bf16_f32 v13, v13, v14
	v_cvt_pk_bf16_f32 v14, v15, v18
	v_or_b32_e32 v18, s3, v10
	v_cvt_pk_bf16_f32 v15, v19, v20
	v_ashrrev_i32_e32 v19, 31, v18
	v_lshlrev_b64 v[18:19], 12, v[18:19]
	v_lshl_add_u64 v[16:17], v[16:17], 0, v[18:19]
	v_cvt_pk_bf16_f32 v12, v0, v3
	global_store_dwordx4 v[16:17], v[12:15], off
	s_waitcnt lgkmcnt(0)
	s_cbranch_scc1 .LBB0_788

; #define LAS __attribute__((address_space(3)))
; __device__ __forceinline__ void phase_prologue(const Params& P, LAS unsigned char* lds) {
;     ...
;         for (int b = 0; b < 4; ++b) *(LAS f32x4*)(red + ((wave * 4 + b) * 64 + lane) * 16) = a[b];
;         __syncthreads();
; #pragma unroll
;         for (int q = 0; q < 2; ++q) { const int o = tid + 512 * q, b = o >> 8, c = o & 255; float s = 0.f;
; #pragma unroll
;             for (int w = 0; w < 8; ++w) s += *(const LAS float*)(red + ((w * 4 + b) * 64 + (c >> 2)) * 16 + (c & 3) * 4);
;             atomicAdd(mod + ((size_t)L * 4 + b) * 6144 + cgp * 256 + c, s); }
;         __syncthreads();
.LBB0_790:
	v_add_u32_e32 v22, s5, v27
	ds_write_b128 v22, v[2:5]
	v_add_u32_e32 v2, s6, v27
	ds_write_b128 v2, v[14:17]
	v_add_u32_e32 v2, s7, v27
	ds_write_b128 v2, v[10:13]
	v_add_u32_e32 v2, s8, v27
	ds_write_b128 v2, v[6:9]
	s_waitcnt lgkmcnt(0)
	s_barrier
	ds_read2st64_b32 v[2:3], v28 offset1:16
	ds_read2st64_b32 v[6:7], v28 offset0:32 offset1:48
	ds_read2st64_b32 v[8:9], v28 offset0:64 offset1:80
	s_lshl_b32 s20, s30, 2
	s_ashr_i32 s23, s22, 31
	s_waitcnt lgkmcnt(2)
	v_add_f32_e32 v2, 0, v2
	v_add_f32_e32 v10, v2, v3
	ds_read2st64_b32 v[2:3], v28 offset0:96 offset1:112
	s_waitcnt lgkmcnt(2)
	v_add_f32_e32 v6, v10, v6
	v_add_f32_e32 v6, v6, v7
	s_waitcnt lgkmcnt(1)
	v_add_f32_e32 v6, v6, v8
	v_add_f32_e32 v6, v6, v9
	s_waitcnt lgkmcnt(0)
	v_add_f32_e32 v2, v6, v2
	v_lshl_add_u64 v[4:5], s[22:23], 2, v[18:19]
	v_add_f32_e32 v6, v2, v3
	v_add_u32_e32 v2, s20, v20
	v_mad_i64_i32 v[2:3], s[2:3], v2, s63, v[4:5]
	global_atomic_add_f32 v[2:3], v6, off
	ds_read2st64_b32 v[2:3], v29 offset1:16
	ds_read2st64_b32 v[6:7], v29 offset0:32 offset1:48
	ds_read2st64_b32 v[8:9], v29 offset0:64 offset1:80
	s_add_i32 s9, s9, s62
	s_cmpk_gt_i32 s9, 0x2ff
	s_waitcnt lgkmcnt(0)
	v_add_f32_e32 v2, 0, v2
	v_add_f32_e32 v10, v2, v3
	ds_read2st64_b32 v[2:3], v29 offset0:96 offset1:112
	v_add_f32_e32 v6, v10, v6
	v_add_f32_e32 v6, v6, v7
	v_add_f32_e32 v6, v6, v8
	v_add_f32_e32 v6, v6, v9
	s_waitcnt lgkmcnt(0)
	v_add_f32_e32 v2, v6, v2
	v_add_f32_e32 v6, v2, v3
	v_add_u32_e32 v2, s20, v0
	v_mad_i64_i32 v[2:3], s[2:3], v2, s63, v[4:5]
	global_atomic_add_f32 v[2:3], v6, off
	s_waitcnt lgkmcnt(0)
	s_barrier
	s_cbranch_scc1 .LBB0_801

; __device__ __forceinline__ const float* inp(const Params& P, int i) { asm volatile("" : "+s"(i)); return P.in[i]; }
; __device__ __forceinline__ unsigned pk2(float lo, float hi) { unsigned r; asm("v_cvt_pk_bf16_f32 %0, %1, %2" : "=v"(r) : "v"(lo), "v"(hi)); return r; }
; __device__ __forceinline__ void phase_prologue(const Params& P, LAS unsigned char* lds) {
;     ...
;     for (int idx = blockIdx.x * NTHR + tid; idx < 4096 * 64; idx += gridDim.x * NTHR) {
;         const int pos = idx >> 6, i = idx & 63;
;         const double rev = (double)pos * kInvFreq[i] * 0.15915494309189535;
;         const float fr = (float)(rev - floor(rev));
;         cosT[idx] = __builtin_amdgcn_cosf(fr); sinT[idx] = __builtin_amdgcn_sinf(fr);
;         const float w0 = inp(P, I_SG_WS)[idx];
;         wsb[idx] = (bf16_t)(pk2(w0, 0.f) & 0xffffu);
;     }
.LBB0_803:
	v_ashrrev_i32_e32 v0, 6, v2
	v_cvt_f64_i32_e32 v[6:7], v0
	s_waitcnt vmcnt(0)
	v_mul_f64 v[6:7], v[4:5], v[6:7]
	v_mul_f64 v[12:13], v[6:7], s[18:19]
	v_floor_f64_e32 v[12:13], v[12:13]
	v_fma_f64 v[6:7], v[6:7], s[18:19], -v[12:13]
	v_cvt_f32_f64_e32 v0, v[6:7]
	v_cos_f32_e32 v12, v0
	v_ashrrev_i32_e32 v3, 31, v2
	v_sin_f32_e32 v0, v0
	v_lshlrev_b64 v[8:9], 2, v[2:3]
	s_mov_b32 s2, 14
	v_lshl_add_u64 v[10:11], s[22:23], 0, v[8:9]
	v_lshl_add_u64 v[6:7], s[24:25], 0, v[8:9]
	global_store_dword v[10:11], v12, off
	global_store_dword v[6:7], v0, off
	s_ashr_i32 s3, s2, 31
	s_lshl_b64 s[2:3], s[2:3], 3
	s_add_u32 s2, s0, s2
	s_addc_u32 s3, s1, s3
	s_load_dwordx2 s[2:3], s[2:3], 0x0
	s_waitcnt lgkmcnt(0)
	v_lshl_add_u64 v[6:7], s[2:3], 0, v[8:9]
	global_load_dword v0, v[6:7], off
	v_lshl_add_u64 v[6:7], v[2:3], 1, s[12:13]
	v_add_u32_e32 v2, s74, v2
	s_mov_b32 s2, 0x3ffff
	v_cmp_lt_i32_e32 vcc, s2, v2
	s_or_b64 s[26:27], vcc, s[26:27]
	s_waitcnt vmcnt(0)
	v_cvt_pk_bf16_f32 v0, v0, v1
	global_store_short v[6:7], v0, off
	s_andn2_b64 exec, exec, s[26:27]
	s_cbranch_execnz .LBB0_803
	s_branch .LBB0_7
